# v40 plus s_nop 5 before the first MFMA of each burst (partner's two tail MFMAs drain first)
# speedup vs baseline: 1.0012x; 1.0012x over previous
.LBB0_379:
	v_add_u32_e32 v14, s56, v140
	v_add_u32_e32 v30, s57, v140
	ds_read_b128 v[2:5], v14
	ds_read_b128 v[6:9], v14 offset:1024
	ds_read_b128 v[10:13], v14 offset:2048
	ds_read_b128 v[14:17], v14 offset:3072
	ds_read_b128 v[18:21], v30
	ds_read_b128 v[22:25], v30 offset:1024
	ds_read_b128 v[26:29], v30 offset:2048
	ds_read_b128 v[30:33], v30 offset:3072
	v_add_u32_e32 v141, 0, v1
	ds_read_b128 v[34:37], v141
	ds_read_b128 v[38:41], v141 offset:1024
	ds_read_b128 v[42:45], v141 offset:2048
	ds_read_b128 v[46:49], v141 offset:3072
	ds_read_b128 v[50:53], v141 offset:4096
	ds_read_b128 v[54:57], v141 offset:5120
	ds_read_b128 v[58:61], v141 offset:6144
	ds_read_b128 v[62:65], v141 offset:7168
	s_waitcnt vmcnt(8)
	s_waitcnt lgkmcnt(0)
	s_barrier
	s_setprio 1
	s_waitcnt lgkmcnt(0)
	s_nop 5
	v_mfma_f32_16x16x32_bf16 v[66:69], v[2:5], v[34:37], 0
	v_mfma_f32_16x16x32_bf16 v[66:69], v[6:9], v[38:41], v[66:69]
	v_mfma_f32_16x16x32_bf16 v[70:73], v[10:13], v[34:37], 0
	v_mfma_f32_16x16x32_bf16 v[70:73], v[14:17], v[38:41], v[70:73]
	v_mfma_f32_16x16x32_bf16 v[78:81], v[10:13], v[42:45], 0
	v_mfma_f32_16x16x32_bf16 v[78:81], v[14:17], v[46:49], v[78:81]
	v_mfma_f32_16x16x32_bf16 v[74:77], v[2:5], v[42:45], 0
	v_mfma_f32_16x16x32_bf16 v[74:77], v[6:9], v[46:49], v[74:77]
	v_mfma_f32_16x16x32_bf16 v[82:85], v[2:5], v[50:53], 0
	v_mfma_f32_16x16x32_bf16 v[82:85], v[6:9], v[54:57], v[82:85]
	v_mfma_f32_16x16x32_bf16 v[86:89], v[10:13], v[50:53], 0
	v_mfma_f32_16x16x32_bf16 v[86:89], v[14:17], v[54:57], v[86:89]
	v_mfma_f32_16x16x32_bf16 v[94:97], v[10:13], v[58:61], 0
	v_mfma_f32_16x16x32_bf16 v[94:97], v[14:17], v[62:65], v[94:97]
	v_mfma_f32_16x16x32_bf16 v[90:93], v[2:5], v[58:61], 0
	v_mfma_f32_16x16x32_bf16 v[90:93], v[6:9], v[62:65], v[90:93]
	s_setprio 0
	s_setprio 1
	v_mfma_f32_16x16x32_bf16 v[98:101], v[18:21], v[34:37], 0
	v_mfma_f32_16x16x32_bf16 v[34:37], v[26:29], v[34:37], 0
	v_mfma_f32_16x16x32_bf16 v[102:105], v[18:21], v[42:45], 0
	v_mfma_f32_16x16x32_bf16 v[42:45], v[26:29], v[42:45], 0
	v_mfma_f32_16x16x32_bf16 v[106:109], v[18:21], v[50:53], 0
	v_mfma_f32_16x16x32_bf16 v[50:53], v[26:29], v[50:53], 0
	v_mfma_f32_16x16x32_bf16 v[110:113], v[18:21], v[58:61], 0
	v_mfma_f32_16x16x32_bf16 v[58:61], v[26:29], v[58:61], 0
	v_mfma_f32_16x16x32_bf16 v[98:101], v[22:25], v[38:41], v[98:101]
	v_mfma_f32_16x16x32_bf16 v[38:41], v[30:33], v[38:41], v[34:37]
	v_mfma_f32_16x16x32_bf16 v[102:105], v[22:25], v[46:49], v[102:105]
	v_mfma_f32_16x16x32_bf16 v[46:49], v[30:33], v[46:49], v[42:45]
	v_mfma_f32_16x16x32_bf16 v[106:109], v[22:25], v[54:57], v[106:109]
	v_mfma_f32_16x16x32_bf16 v[54:57], v[30:33], v[54:57], v[50:53]
	s_setprio 2
	s_barrier
	v_mfma_f32_16x16x32_bf16 v[110:113], v[22:25], v[62:65], v[110:113]
	v_mfma_f32_16x16x32_bf16 v[62:65], v[30:33], v[62:65], v[58:61]
	s_setprio 0
	v_lshl_add_u64 v[136:137], s[38:39], 0, v[130:131]
	s_add_i32 s60, s56, s21
	v_mov_b32_e32 v135, v131
	v_lshl_add_u64 v[142:143], v[136:137], 0, s[10:11]
	s_mov_b32 m0, s60
	v_lshl_add_u64 v[244:245], s[38:39], 0, v[134:135]
	ds_read_b128 v[34:37], v141 offset:16384
	ds_read_b128 v[42:45], v141 offset:17408
	ds_read_b128 v[50:53], v141 offset:18432
	ds_read_b128 v[58:61], v141 offset:19456
	ds_read_b128 v[114:117], v141 offset:20480
	ds_read_b128 v[118:121], v141 offset:21504
	ds_read_b128 v[122:125], v141 offset:22528
	ds_read_b128 v[126:129], v141 offset:23552
	global_load_lds_dwordx4 v[142:143], off
	v_lshl_add_u64 v[142:143], v[244:245], 0, s[10:11]
	s_add_i32 m0, s60, 0x2000
	s_add_i32 s60, s57, s21
	global_load_lds_dwordx4 v[142:143], off
	s_mov_b32 m0, s60
	v_mov_b32_e32 v139, v131
	global_load_lds_dwordx4 v130, s[40:41]
	s_add_i32 m0, s60, 0x2000
	v_lshl_add_u64 v[246:247], s[36:37], 0, v[138:139]
	v_mov_b32_e32 v133, v131
	global_load_lds_dwordx4 v134, s[40:41]
	v_lshl_add_u64 v[142:143], v[246:247], 0, s[10:11]
	s_mov_b32 m0, s33
	v_lshl_add_u64 v[248:249], s[36:37], 0, v[132:133]
	global_load_lds_dwordx4 v[142:143], off
	v_lshl_add_u64 v[142:143], v[248:249], 0, s[10:11]
	s_mov_b32 m0, s46
	s_nop 0
	global_load_lds_dwordx4 v[142:143], off
	s_waitcnt vmcnt(8)
	s_waitcnt lgkmcnt(0)
	s_barrier
	s_setprio 1
	s_waitcnt lgkmcnt(0)
	s_nop 5
	v_mfma_f32_16x16x32_bf16 v[142:145], v[2:5], v[34:37], 0
	v_mfma_f32_16x16x32_bf16 v[148:151], v[10:13], v[34:37], 0
	v_mfma_f32_16x16x32_bf16 v[152:155], v[2:5], v[50:53], 0
	v_mfma_f32_16x16x32_bf16 v[156:159], v[10:13], v[50:53], 0
	v_mfma_f32_16x16x32_bf16 v[160:163], v[2:5], v[114:117], 0
	v_mfma_f32_16x16x32_bf16 v[164:167], v[10:13], v[114:117], 0
	v_mfma_f32_16x16x32_bf16 v[2:5], v[2:5], v[122:125], 0
	v_mfma_f32_16x16x32_bf16 v[10:13], v[10:13], v[122:125], 0
	v_mfma_f32_16x16x32_bf16 v[142:145], v[6:9], v[42:45], v[142:145]
	v_mfma_f32_16x16x32_bf16 v[148:151], v[14:17], v[42:45], v[148:151]
	v_mfma_f32_16x16x32_bf16 v[152:155], v[6:9], v[58:61], v[152:155]
	v_mfma_f32_16x16x32_bf16 v[156:159], v[14:17], v[58:61], v[156:159]
	v_mfma_f32_16x16x32_bf16 v[160:163], v[6:9], v[118:121], v[160:163]
	v_mfma_f32_16x16x32_bf16 v[164:167], v[14:17], v[118:121], v[164:167]
	v_mfma_f32_16x16x32_bf16 v[168:171], v[6:9], v[126:129], v[2:5]
	v_mfma_f32_16x16x32_bf16 v[172:175], v[14:17], v[126:129], v[10:13]
	s_setprio 0
	s_setprio 1
	v_mfma_f32_16x16x32_bf16 v[2:5], v[18:21], v[34:37], 0
	v_mfma_f32_16x16x32_bf16 v[6:9], v[26:29], v[34:37], 0
	v_mfma_f32_16x16x32_bf16 v[10:13], v[18:21], v[50:53], 0
	v_mfma_f32_16x16x32_bf16 v[14:17], v[26:29], v[50:53], 0
	v_mfma_f32_16x16x32_bf16 v[34:37], v[18:21], v[114:117], 0
	v_mfma_f32_16x16x32_bf16 v[50:53], v[26:29], v[114:117], 0
	v_mfma_f32_16x16x32_bf16 v[18:21], v[18:21], v[122:125], 0
	v_mfma_f32_16x16x32_bf16 v[26:29], v[26:29], v[122:125], 0
	v_mfma_f32_16x16x32_bf16 v[114:117], v[22:25], v[42:45], v[2:5]
	v_mfma_f32_16x16x32_bf16 v[188:191], v[22:25], v[118:121], v[34:37]
	v_mfma_f32_16x16x32_bf16 v[118:121], v[30:33], v[118:121], v[50:53]
	v_mfma_f32_16x16x32_bf16 v[176:179], v[30:33], v[42:45], v[6:9]
	v_mfma_f32_16x16x32_bf16 v[180:183], v[22:25], v[58:61], v[10:13]
	v_mfma_f32_16x16x32_bf16 v[184:187], v[30:33], v[58:61], v[14:17]
	s_setprio 2
	s_barrier
	v_mfma_f32_16x16x32_bf16 v[192:195], v[22:25], v[126:129], v[18:21]
	v_mfma_f32_16x16x32_bf16 v[196:199], v[30:33], v[126:129], v[26:29]
	s_setprio 0
	s_add_i32 s60, 0, 0x18000
	v_add_u32_e32 v2, s60, v140
	s_add_i32 s61, 0, 0x1c000
	ds_read_b128 v[200:203], v2
	ds_read_b128 v[204:207], v2 offset:1024
	ds_read_b128 v[208:211], v2 offset:2048
	ds_read_b128 v[212:215], v2 offset:3072
	v_add_u32_e32 v2, s61, v140
	ds_read_b128 v[216:219], v2
	ds_read_b128 v[220:223], v2 offset:1024
	ds_read_b128 v[224:227], v2 offset:2048
	ds_read_b128 v[228:231], v2 offset:3072
	s_mov_b32 m0, s47
	ds_read_b128 v[42:45], v141 offset:32768
	ds_read_b128 v[50:53], v141 offset:33792
	ds_read_b128 v[58:61], v141 offset:34816
	ds_read_b128 v[122:125], v141 offset:35840
	ds_read_b128 v[126:129], v141 offset:36864
	ds_read_b128 v[232:235], v141 offset:37888
	ds_read_b128 v[236:239], v141 offset:38912
	ds_read_b128 v[240:243], v141 offset:39936
	global_load_lds_dwordx4 v138, s[42:43]
	s_mov_b32 m0, s48
	s_nop 0
	global_load_lds_dwordx4 v132, s[42:43]
	s_waitcnt vmcnt(8)
	s_waitcnt lgkmcnt(0)
	s_barrier
	s_setprio 1
	s_waitcnt lgkmcnt(0)
	s_nop 5
	v_mfma_f32_16x16x32_bf16 v[2:5], v[200:203], v[42:45], v[66:69]
	v_mfma_f32_16x16x32_bf16 v[6:9], v[208:211], v[42:45], v[70:73]
	v_mfma_f32_16x16x32_bf16 v[10:13], v[200:203], v[58:61], v[74:77]
	v_mfma_f32_16x16x32_bf16 v[14:17], v[208:211], v[58:61], v[78:81]
	v_mfma_f32_16x16x32_bf16 v[18:21], v[200:203], v[126:129], v[82:85]
	v_mfma_f32_16x16x32_bf16 v[22:25], v[208:211], v[126:129], v[86:89]
	v_mfma_f32_16x16x32_bf16 v[26:29], v[200:203], v[236:239], v[90:93]
	v_mfma_f32_16x16x32_bf16 v[30:33], v[208:211], v[236:239], v[94:97]
	v_mfma_f32_16x16x32_bf16 v[2:5], v[204:207], v[50:53], v[2:5]
	v_mfma_f32_16x16x32_bf16 v[6:9], v[212:215], v[50:53], v[6:9]
	v_mfma_f32_16x16x32_bf16 v[10:13], v[204:207], v[122:125], v[10:13]
	v_mfma_f32_16x16x32_bf16 v[14:17], v[212:215], v[122:125], v[14:17]
	v_mfma_f32_16x16x32_bf16 v[18:21], v[204:207], v[232:235], v[18:21]
	v_mfma_f32_16x16x32_bf16 v[22:25], v[212:215], v[232:235], v[22:25]
	v_mfma_f32_16x16x32_bf16 v[26:29], v[204:207], v[240:243], v[26:29]
	v_mfma_f32_16x16x32_bf16 v[30:33], v[212:215], v[240:243], v[30:33]
	s_setprio 0
	s_setprio 1
	v_mfma_f32_16x16x32_bf16 v[34:37], v[216:219], v[42:45], v[98:101]
	v_mfma_f32_16x16x32_bf16 v[38:41], v[224:227], v[42:45], v[38:41]
	v_mfma_f32_16x16x32_bf16 v[34:37], v[220:223], v[50:53], v[34:37]
	v_mfma_f32_16x16x32_bf16 v[38:41], v[228:231], v[50:53], v[38:41]
	v_mfma_f32_16x16x32_bf16 v[42:45], v[216:219], v[58:61], v[102:105]
	v_mfma_f32_16x16x32_bf16 v[46:49], v[224:227], v[58:61], v[46:49]
	v_mfma_f32_16x16x32_bf16 v[50:53], v[216:219], v[126:129], v[106:109]
	v_mfma_f32_16x16x32_bf16 v[54:57], v[224:227], v[126:129], v[54:57]
	v_mfma_f32_16x16x32_bf16 v[58:61], v[216:219], v[236:239], v[110:113]
	v_mfma_f32_16x16x32_bf16 v[62:65], v[224:227], v[236:239], v[62:65]
	v_mfma_f32_16x16x32_bf16 v[42:45], v[220:223], v[122:125], v[42:45]
	v_mfma_f32_16x16x32_bf16 v[46:49], v[228:231], v[122:125], v[46:49]
	v_mfma_f32_16x16x32_bf16 v[50:53], v[220:223], v[232:235], v[50:53]
	v_mfma_f32_16x16x32_bf16 v[54:57], v[228:231], v[232:235], v[54:57]
	s_setprio 2
	s_barrier
	v_mfma_f32_16x16x32_bf16 v[58:61], v[220:223], v[240:243], v[58:61]
	v_mfma_f32_16x16x32_bf16 v[62:65], v[228:231], v[240:243], v[62:65]
	s_setprio 0
	s_add_i32 s60, s60, s21
	v_lshl_add_u64 v[66:67], v[136:137], 0, s[12:13]
	s_mov_b32 m0, s60
	ds_read_b128 v[94:97], v141 offset:49152
	ds_read_b128 v[98:101], v141 offset:50176
	ds_read_b128 v[102:105], v141 offset:51200
	ds_read_b128 v[106:109], v141 offset:52224
	ds_read_b128 v[110:113], v141 offset:53248
	ds_read_b128 v[232:235], v141 offset:54272
	ds_read_b128 v[236:239], v141 offset:55296
	ds_read_b128 v[240:243], v141 offset:56320
	global_load_lds_dwordx4 v[66:67], off
	v_lshl_add_u64 v[66:67], v[244:245], 0, s[12:13]
	s_add_i32 m0, s60, 0x2000
	s_add_i32 s60, s61, s21
	global_load_lds_dwordx4 v[66:67], off
	s_mov_b32 m0, s60
	v_lshl_add_u64 v[66:67], v[246:247], 0, s[12:13]
	global_load_lds_dwordx4 v130, s[44:45]
	s_add_i32 m0, s60, 0x2000
	s_nop 0
	global_load_lds_dwordx4 v134, s[44:45]
	s_mov_b32 m0, s52
	s_nop 0
	global_load_lds_dwordx4 v[66:67], off
	v_lshl_add_u64 v[66:67], v[248:249], 0, s[12:13]
	s_mov_b32 m0, s53
	s_nop 0
	global_load_lds_dwordx4 v[66:67], off
	s_waitcnt vmcnt(8)
	s_waitcnt lgkmcnt(0)
	s_barrier
	s_setprio 1
	s_waitcnt lgkmcnt(0)
	s_nop 5
	v_mfma_f32_16x16x32_bf16 v[66:69], v[200:203], v[94:97], v[142:145]
	v_mfma_f32_16x16x32_bf16 v[122:125], v[204:207], v[98:101], v[66:69]
	v_mfma_f32_16x16x32_bf16 v[66:69], v[208:211], v[94:97], v[148:151]
	v_mfma_f32_16x16x32_bf16 v[126:129], v[212:215], v[98:101], v[66:69]
	v_mfma_f32_16x16x32_bf16 v[66:69], v[200:203], v[102:105], v[152:155]
	v_mfma_f32_16x16x32_bf16 v[70:73], v[208:211], v[102:105], v[156:159]
	v_mfma_f32_16x16x32_bf16 v[74:77], v[200:203], v[110:113], v[160:163]
	v_mfma_f32_16x16x32_bf16 v[78:81], v[208:211], v[110:113], v[164:167]
	v_mfma_f32_16x16x32_bf16 v[82:85], v[200:203], v[236:239], v[168:171]
	v_mfma_f32_16x16x32_bf16 v[86:89], v[208:211], v[236:239], v[172:175]
	v_mfma_f32_16x16x32_bf16 v[66:69], v[204:207], v[106:109], v[66:69]
	v_mfma_f32_16x16x32_bf16 v[70:73], v[212:215], v[106:109], v[70:73]
	v_mfma_f32_16x16x32_bf16 v[74:77], v[204:207], v[232:235], v[74:77]
	v_mfma_f32_16x16x32_bf16 v[78:81], v[212:215], v[232:235], v[78:81]
	v_mfma_f32_16x16x32_bf16 v[82:85], v[204:207], v[240:243], v[82:85]
	v_mfma_f32_16x16x32_bf16 v[86:89], v[212:215], v[240:243], v[86:89]
	s_setprio 0
	s_setprio 1
	v_mfma_f32_16x16x32_bf16 v[90:93], v[216:219], v[94:97], v[114:117]
	v_mfma_f32_16x16x32_bf16 v[94:97], v[224:227], v[94:97], v[176:179]
	v_mfma_f32_16x16x32_bf16 v[90:93], v[220:223], v[98:101], v[90:93]
	v_mfma_f32_16x16x32_bf16 v[94:97], v[228:231], v[98:101], v[94:97]
	v_mfma_f32_16x16x32_bf16 v[98:101], v[216:219], v[102:105], v[180:183]
	v_mfma_f32_16x16x32_bf16 v[102:105], v[224:227], v[102:105], v[184:187]
	v_mfma_f32_16x16x32_bf16 v[98:101], v[220:223], v[106:109], v[98:101]
	v_mfma_f32_16x16x32_bf16 v[102:105], v[228:231], v[106:109], v[102:105]
	v_mfma_f32_16x16x32_bf16 v[106:109], v[216:219], v[110:113], v[188:191]
	v_mfma_f32_16x16x32_bf16 v[110:113], v[224:227], v[110:113], v[118:121]
	v_mfma_f32_16x16x32_bf16 v[114:117], v[216:219], v[236:239], v[192:195]
	v_mfma_f32_16x16x32_bf16 v[118:121], v[224:227], v[236:239], v[196:199]
	v_mfma_f32_16x16x32_bf16 v[106:109], v[220:223], v[232:235], v[106:109]
	v_mfma_f32_16x16x32_bf16 v[110:113], v[228:231], v[232:235], v[110:113]
	s_setprio 2
	s_barrier
	v_mfma_f32_16x16x32_bf16 v[114:117], v[220:223], v[240:243], v[114:117]
	v_mfma_f32_16x16x32_bf16 v[118:121], v[228:231], v[240:243], v[118:121]
	s_setprio 0
	s_add_i32 s59, s59, 2
	s_cmp_ge_i32 s59, s15
	s_cbranch_scc0 .LBB0_379
	v_mov_b32_e32 v136, v130
	s_branch .LBB0_382

.LBB0_383:
	v_add_u32_e32 v133, s56, v140
	ds_read_b128 v[142:145], v133
	ds_read_b128 v[148:151], v133 offset:1024
	ds_read_b128 v[152:155], v133 offset:2048
	ds_read_b128 v[156:159], v133 offset:3072
	v_add_u32_e32 v133, s57, v140
	ds_read_b128 v[160:163], v133
	ds_read_b128 v[164:167], v133 offset:1024
	ds_read_b128 v[168:171], v133 offset:2048
	ds_read_b128 v[172:175], v133 offset:3072
	s_add_u32 s38, s36, 0xfff80080
	s_addc_u32 s39, s37, -1
	s_cmp_eq_u32 s43, 28
	s_cselect_b32 s41, s31, s39
	s_cselect_b32 s40, s30, s38
	s_cselect_b32 s39, s35, s42
	s_cselect_b32 s38, s34, s15
	s_mov_b32 m0, s54
	v_add_u32_e32 v141, 0, v1
	ds_read_b128 v[176:179], v141
	ds_read_b128 v[180:183], v141 offset:1024
	ds_read_b128 v[184:187], v141 offset:2048
	ds_read_b128 v[188:191], v141 offset:3072
	ds_read_b128 v[192:195], v141 offset:4096
	ds_read_b128 v[196:199], v141 offset:5120
	ds_read_b128 v[200:203], v141 offset:6144
	ds_read_b128 v[204:207], v141 offset:7168
	global_load_lds_dwordx4 v130, s[36:37]
	s_mov_b32 m0, s55
	v_mov_b32_e32 v133, v131
	global_load_lds_dwordx4 v132, s[36:37]
	s_waitcnt vmcnt(8)
	s_waitcnt lgkmcnt(0)
	s_barrier
	s_setprio 1
	s_waitcnt lgkmcnt(0)
	s_nop 5
	v_mfma_f32_16x16x32_bf16 v[2:5], v[142:145], v[176:179], v[2:5]
	v_mfma_f32_16x16x32_bf16 v[2:5], v[148:151], v[180:183], v[2:5]
	v_mfma_f32_16x16x32_bf16 v[6:9], v[156:159], v[180:183], v[6:9]
	v_mfma_f32_16x16x32_bf16 v[6:9], v[152:155], v[176:179], v[6:9]
	v_mfma_f32_16x16x32_bf16 v[14:17], v[152:155], v[184:187], v[14:17]
	v_mfma_f32_16x16x32_bf16 v[14:17], v[156:159], v[188:191], v[14:17]
	v_mfma_f32_16x16x32_bf16 v[10:13], v[148:151], v[188:191], v[10:13]
	v_mfma_f32_16x16x32_bf16 v[10:13], v[142:145], v[184:187], v[10:13]
	v_mfma_f32_16x16x32_bf16 v[18:21], v[142:145], v[192:195], v[18:21]
	v_mfma_f32_16x16x32_bf16 v[18:21], v[148:151], v[196:199], v[18:21]
	v_mfma_f32_16x16x32_bf16 v[22:25], v[156:159], v[196:199], v[22:25]
	v_mfma_f32_16x16x32_bf16 v[22:25], v[152:155], v[192:195], v[22:25]
	v_mfma_f32_16x16x32_bf16 v[30:33], v[152:155], v[200:203], v[30:33]
	v_mfma_f32_16x16x32_bf16 v[30:33], v[156:159], v[204:207], v[30:33]
	v_mfma_f32_16x16x32_bf16 v[26:29], v[148:151], v[204:207], v[26:29]
	v_mfma_f32_16x16x32_bf16 v[26:29], v[142:145], v[200:203], v[26:29]
	s_setprio 0
	s_setprio 1
	v_mfma_f32_16x16x32_bf16 v[34:37], v[160:163], v[176:179], v[34:37]
	v_mfma_f32_16x16x32_bf16 v[34:37], v[164:167], v[180:183], v[34:37]
	v_mfma_f32_16x16x32_bf16 v[38:41], v[172:175], v[180:183], v[38:41]
	v_mfma_f32_16x16x32_bf16 v[38:41], v[168:171], v[176:179], v[38:41]
	v_mfma_f32_16x16x32_bf16 v[46:49], v[168:171], v[184:187], v[46:49]
	v_mfma_f32_16x16x32_bf16 v[46:49], v[172:175], v[188:191], v[46:49]
	v_mfma_f32_16x16x32_bf16 v[42:45], v[164:167], v[188:191], v[42:45]
	v_mfma_f32_16x16x32_bf16 v[42:45], v[160:163], v[184:187], v[42:45]
	v_mfma_f32_16x16x32_bf16 v[50:53], v[160:163], v[192:195], v[50:53]
	v_mfma_f32_16x16x32_bf16 v[50:53], v[164:167], v[196:199], v[50:53]
	v_mfma_f32_16x16x32_bf16 v[54:57], v[172:175], v[196:199], v[54:57]
	v_mfma_f32_16x16x32_bf16 v[54:57], v[168:171], v[192:195], v[54:57]
	v_mfma_f32_16x16x32_bf16 v[62:65], v[168:171], v[200:203], v[62:65]
	v_mfma_f32_16x16x32_bf16 v[62:65], v[172:175], v[204:207], v[62:65]
	s_setprio 2
	s_barrier
	v_mfma_f32_16x16x32_bf16 v[58:61], v[164:167], v[204:207], v[58:61]
	v_mfma_f32_16x16x32_bf16 v[58:61], v[160:163], v[200:203], v[58:61]
	s_setprio 0
	s_add_i32 s44, s56, s21
	s_mov_b32 m0, s44
	ds_read_b128 v[176:179], v141 offset:16384
	ds_read_b128 v[180:183], v141 offset:17408
	ds_read_b128 v[184:187], v141 offset:18432
	ds_read_b128 v[188:191], v141 offset:19456
	ds_read_b128 v[192:195], v141 offset:20480
	ds_read_b128 v[196:199], v141 offset:21504
	ds_read_b128 v[200:203], v141 offset:22528
	ds_read_b128 v[204:207], v141 offset:23552
	global_load_lds_dwordx4 v136, s[38:39]
	s_add_i32 m0, s44, 0x2000
	s_add_u32 s44, s38, 0x80000
	s_addc_u32 s45, s39, 0
	s_add_i32 s59, s57, s21
	global_load_lds_dwordx4 v134, s[38:39]
	s_mov_b32 m0, s59
	v_mov_b32_e32 v137, v131
	global_load_lds_dwordx4 v136, s[44:45]
	s_add_i32 m0, s59, 0x2000
	v_mov_b32_e32 v135, v131
	global_load_lds_dwordx4 v134, s[44:45]
	s_mov_b32 m0, s33
	v_lshl_add_u64 v[138:139], s[38:39], 0, v[136:137]
	global_load_lds_dwordx4 v130, s[40:41]
	s_mov_b32 m0, s46
	v_lshl_add_u64 v[208:209], s[38:39], 0, v[134:135]
	global_load_lds_dwordx4 v132, s[40:41]
	s_waitcnt vmcnt(8)
	s_waitcnt lgkmcnt(0)
	v_lshl_add_u64 v[210:211], s[40:41], 0, v[130:131]
	v_lshl_add_u64 v[212:213], s[40:41], 0, v[132:133]
	s_barrier
	s_setprio 1
	s_waitcnt lgkmcnt(0)
	s_nop 5
	v_mfma_f32_16x16x32_bf16 v[122:125], v[142:145], v[176:179], v[122:125]
	v_mfma_f32_16x16x32_bf16 v[122:125], v[148:151], v[180:183], v[122:125]
	v_mfma_f32_16x16x32_bf16 v[126:129], v[156:159], v[180:183], v[126:129]
	v_mfma_f32_16x16x32_bf16 v[126:129], v[152:155], v[176:179], v[126:129]
	v_mfma_f32_16x16x32_bf16 v[70:73], v[152:155], v[184:187], v[70:73]
	v_mfma_f32_16x16x32_bf16 v[70:73], v[156:159], v[188:191], v[70:73]
	v_mfma_f32_16x16x32_bf16 v[66:69], v[148:151], v[188:191], v[66:69]
	v_mfma_f32_16x16x32_bf16 v[66:69], v[142:145], v[184:187], v[66:69]
	v_mfma_f32_16x16x32_bf16 v[74:77], v[142:145], v[192:195], v[74:77]
	v_mfma_f32_16x16x32_bf16 v[74:77], v[148:151], v[196:199], v[74:77]
	v_mfma_f32_16x16x32_bf16 v[78:81], v[156:159], v[196:199], v[78:81]
	v_mfma_f32_16x16x32_bf16 v[78:81], v[152:155], v[192:195], v[78:81]
	v_mfma_f32_16x16x32_bf16 v[86:89], v[152:155], v[200:203], v[86:89]
	v_mfma_f32_16x16x32_bf16 v[86:89], v[156:159], v[204:207], v[86:89]
	v_mfma_f32_16x16x32_bf16 v[82:85], v[148:151], v[204:207], v[82:85]
	v_mfma_f32_16x16x32_bf16 v[82:85], v[142:145], v[200:203], v[82:85]
	s_setprio 0
	s_setprio 1
	v_mfma_f32_16x16x32_bf16 v[90:93], v[160:163], v[176:179], v[90:93]
	v_mfma_f32_16x16x32_bf16 v[90:93], v[164:167], v[180:183], v[90:93]
	v_mfma_f32_16x16x32_bf16 v[94:97], v[172:175], v[180:183], v[94:97]
	v_mfma_f32_16x16x32_bf16 v[94:97], v[168:171], v[176:179], v[94:97]
	v_mfma_f32_16x16x32_bf16 v[102:105], v[168:171], v[184:187], v[102:105]
	v_mfma_f32_16x16x32_bf16 v[102:105], v[172:175], v[188:191], v[102:105]
	v_mfma_f32_16x16x32_bf16 v[98:101], v[164:167], v[188:191], v[98:101]
	v_mfma_f32_16x16x32_bf16 v[98:101], v[160:163], v[184:187], v[98:101]
	v_mfma_f32_16x16x32_bf16 v[106:109], v[160:163], v[192:195], v[106:109]
	v_mfma_f32_16x16x32_bf16 v[106:109], v[164:167], v[196:199], v[106:109]
	v_mfma_f32_16x16x32_bf16 v[110:113], v[172:175], v[196:199], v[110:113]
	v_mfma_f32_16x16x32_bf16 v[110:113], v[168:171], v[192:195], v[110:113]
	v_mfma_f32_16x16x32_bf16 v[118:121], v[168:171], v[200:203], v[118:121]
	v_mfma_f32_16x16x32_bf16 v[118:121], v[172:175], v[204:207], v[118:121]
	s_setprio 2
	s_barrier
	v_mfma_f32_16x16x32_bf16 v[114:117], v[164:167], v[204:207], v[114:117]
	v_mfma_f32_16x16x32_bf16 v[114:117], v[160:163], v[200:203], v[114:117]
	s_setprio 0
	s_add_i32 s44, 0, 0x18000
	v_add_u32_e32 v135, s44, v140
	s_add_i32 s45, 0, 0x1c000
	ds_read_b128 v[142:145], v135
	ds_read_b128 v[148:151], v135 offset:1024
	ds_read_b128 v[152:155], v135 offset:2048
	ds_read_b128 v[156:159], v135 offset:3072
	v_add_u32_e32 v135, s45, v140
	ds_read_b128 v[160:163], v135
	ds_read_b128 v[164:167], v135 offset:1024
	ds_read_b128 v[168:171], v135 offset:2048
	ds_read_b128 v[172:175], v135 offset:3072
	s_add_u32 s40, s40, 0x80000
	s_addc_u32 s41, s41, 0
	s_mov_b32 m0, s47
	ds_read_b128 v[176:179], v141 offset:32768
	ds_read_b128 v[180:183], v141 offset:33792
	ds_read_b128 v[184:187], v141 offset:34816
	ds_read_b128 v[188:191], v141 offset:35840
	ds_read_b128 v[192:195], v141 offset:36864
	ds_read_b128 v[196:199], v141 offset:37888
	ds_read_b128 v[200:203], v141 offset:38912
	ds_read_b128 v[204:207], v141 offset:39936
	global_load_lds_dwordx4 v130, s[40:41]
	s_mov_b32 m0, s48
	s_nop 0
	global_load_lds_dwordx4 v132, s[40:41]
	s_waitcnt vmcnt(8)
	s_waitcnt lgkmcnt(0)
	s_barrier
	s_setprio 1
	s_waitcnt lgkmcnt(0)
	s_nop 5
	v_mfma_f32_16x16x32_bf16 v[2:5], v[142:145], v[176:179], v[2:5]
	v_mfma_f32_16x16x32_bf16 v[2:5], v[148:151], v[180:183], v[2:5]
	v_mfma_f32_16x16x32_bf16 v[6:9], v[156:159], v[180:183], v[6:9]
	v_mfma_f32_16x16x32_bf16 v[6:9], v[152:155], v[176:179], v[6:9]
	v_mfma_f32_16x16x32_bf16 v[14:17], v[152:155], v[184:187], v[14:17]
	v_mfma_f32_16x16x32_bf16 v[14:17], v[156:159], v[188:191], v[14:17]
	v_mfma_f32_16x16x32_bf16 v[10:13], v[148:151], v[188:191], v[10:13]
	v_mfma_f32_16x16x32_bf16 v[10:13], v[142:145], v[184:187], v[10:13]
	v_mfma_f32_16x16x32_bf16 v[18:21], v[142:145], v[192:195], v[18:21]
	v_mfma_f32_16x16x32_bf16 v[18:21], v[148:151], v[196:199], v[18:21]
	v_mfma_f32_16x16x32_bf16 v[22:25], v[156:159], v[196:199], v[22:25]
	v_mfma_f32_16x16x32_bf16 v[22:25], v[152:155], v[192:195], v[22:25]
	v_mfma_f32_16x16x32_bf16 v[30:33], v[152:155], v[200:203], v[30:33]
	v_mfma_f32_16x16x32_bf16 v[30:33], v[156:159], v[204:207], v[30:33]
	v_mfma_f32_16x16x32_bf16 v[26:29], v[148:151], v[204:207], v[26:29]
	v_mfma_f32_16x16x32_bf16 v[26:29], v[142:145], v[200:203], v[26:29]
	s_setprio 0
	s_setprio 1
	v_mfma_f32_16x16x32_bf16 v[34:37], v[160:163], v[176:179], v[34:37]
	v_mfma_f32_16x16x32_bf16 v[34:37], v[164:167], v[180:183], v[34:37]
	v_mfma_f32_16x16x32_bf16 v[38:41], v[172:175], v[180:183], v[38:41]
	v_mfma_f32_16x16x32_bf16 v[38:41], v[168:171], v[176:179], v[38:41]
	v_mfma_f32_16x16x32_bf16 v[46:49], v[168:171], v[184:187], v[46:49]
	v_mfma_f32_16x16x32_bf16 v[46:49], v[172:175], v[188:191], v[46:49]
	v_mfma_f32_16x16x32_bf16 v[42:45], v[164:167], v[188:191], v[42:45]
	v_mfma_f32_16x16x32_bf16 v[42:45], v[160:163], v[184:187], v[42:45]
	v_mfma_f32_16x16x32_bf16 v[50:53], v[160:163], v[192:195], v[50:53]
	v_mfma_f32_16x16x32_bf16 v[50:53], v[164:167], v[196:199], v[50:53]
	v_mfma_f32_16x16x32_bf16 v[54:57], v[172:175], v[196:199], v[54:57]
	v_mfma_f32_16x16x32_bf16 v[54:57], v[168:171], v[192:195], v[54:57]
	v_mfma_f32_16x16x32_bf16 v[62:65], v[168:171], v[200:203], v[62:65]
	v_mfma_f32_16x16x32_bf16 v[62:65], v[172:175], v[204:207], v[62:65]
	s_setprio 2
	s_barrier
	v_mfma_f32_16x16x32_bf16 v[58:61], v[164:167], v[204:207], v[58:61]
	v_mfma_f32_16x16x32_bf16 v[58:61], v[160:163], v[200:203], v[58:61]
	s_setprio 0
	s_add_i32 s40, s44, s21
	v_lshl_add_u64 v[138:139], v[138:139], 0, s[6:7]
	s_mov_b32 m0, s40
	ds_read_b128 v[176:179], v141 offset:49152
	ds_read_b128 v[180:183], v141 offset:50176
	ds_read_b128 v[184:187], v141 offset:51200
	ds_read_b128 v[188:191], v141 offset:52224
	ds_read_b128 v[192:195], v141 offset:53248
	ds_read_b128 v[196:199], v141 offset:54272
	ds_read_b128 v[200:203], v141 offset:55296
	ds_read_b128 v[204:207], v141 offset:56320
	global_load_lds_dwordx4 v[138:139], off
	s_add_i32 m0, s40, 0x2000
	s_add_u32 s38, s38, 0x80080
	v_lshl_add_u64 v[138:139], v[208:209], 0, s[6:7]
	s_addc_u32 s39, s39, 0
	s_add_i32 s40, s45, s21
	global_load_lds_dwordx4 v[138:139], off
	s_mov_b32 m0, s40
	v_lshl_add_u64 v[138:139], v[210:211], 0, s[6:7]
	global_load_lds_dwordx4 v136, s[38:39]
	s_add_i32 m0, s40, 0x2000
	s_nop 0
	global_load_lds_dwordx4 v134, s[38:39]
	s_mov_b32 m0, s52
	s_nop 0
	global_load_lds_dwordx4 v[138:139], off
	v_lshl_add_u64 v[138:139], v[212:213], 0, s[6:7]
	s_mov_b32 m0, s53
	s_nop 0
	global_load_lds_dwordx4 v[138:139], off
	s_waitcnt vmcnt(8)
	s_waitcnt lgkmcnt(0)
	s_barrier
	s_setprio 1
	s_waitcnt lgkmcnt(0)
	s_nop 5
	v_mfma_f32_16x16x32_bf16 v[122:125], v[142:145], v[176:179], v[122:125]
	v_mfma_f32_16x16x32_bf16 v[122:125], v[148:151], v[180:183], v[122:125]
	v_mfma_f32_16x16x32_bf16 v[126:129], v[156:159], v[180:183], v[126:129]
	v_mfma_f32_16x16x32_bf16 v[126:129], v[152:155], v[176:179], v[126:129]
	v_mfma_f32_16x16x32_bf16 v[70:73], v[152:155], v[184:187], v[70:73]
	v_mfma_f32_16x16x32_bf16 v[70:73], v[156:159], v[188:191], v[70:73]
	v_mfma_f32_16x16x32_bf16 v[66:69], v[148:151], v[188:191], v[66:69]
	v_mfma_f32_16x16x32_bf16 v[66:69], v[142:145], v[184:187], v[66:69]
	v_mfma_f32_16x16x32_bf16 v[74:77], v[142:145], v[192:195], v[74:77]
	v_mfma_f32_16x16x32_bf16 v[74:77], v[148:151], v[196:199], v[74:77]
	v_mfma_f32_16x16x32_bf16 v[78:81], v[156:159], v[196:199], v[78:81]
	v_mfma_f32_16x16x32_bf16 v[78:81], v[152:155], v[192:195], v[78:81]
	v_mfma_f32_16x16x32_bf16 v[86:89], v[152:155], v[200:203], v[86:89]
	v_mfma_f32_16x16x32_bf16 v[86:89], v[156:159], v[204:207], v[86:89]
	v_mfma_f32_16x16x32_bf16 v[82:85], v[148:151], v[204:207], v[82:85]
	v_mfma_f32_16x16x32_bf16 v[82:85], v[142:145], v[200:203], v[82:85]
	s_setprio 0
	s_setprio 1
	v_mfma_f32_16x16x32_bf16 v[90:93], v[160:163], v[176:179], v[90:93]
	v_mfma_f32_16x16x32_bf16 v[90:93], v[164:167], v[180:183], v[90:93]
	v_mfma_f32_16x16x32_bf16 v[94:97], v[172:175], v[180:183], v[94:97]
	v_mfma_f32_16x16x32_bf16 v[94:97], v[168:171], v[176:179], v[94:97]
	v_mfma_f32_16x16x32_bf16 v[102:105], v[168:171], v[184:187], v[102:105]
	v_mfma_f32_16x16x32_bf16 v[102:105], v[172:175], v[188:191], v[102:105]
	v_mfma_f32_16x16x32_bf16 v[98:101], v[164:167], v[188:191], v[98:101]
	v_mfma_f32_16x16x32_bf16 v[98:101], v[160:163], v[184:187], v[98:101]
	v_mfma_f32_16x16x32_bf16 v[106:109], v[160:163], v[192:195], v[106:109]
	v_mfma_f32_16x16x32_bf16 v[106:109], v[164:167], v[196:199], v[106:109]
	v_mfma_f32_16x16x32_bf16 v[110:113], v[172:175], v[196:199], v[110:113]
	v_mfma_f32_16x16x32_bf16 v[110:113], v[168:171], v[192:195], v[110:113]
	v_mfma_f32_16x16x32_bf16 v[118:121], v[168:171], v[200:203], v[118:121]
	v_mfma_f32_16x16x32_bf16 v[118:121], v[172:175], v[204:207], v[118:121]
	s_setprio 2
	s_barrier
	v_mfma_f32_16x16x32_bf16 v[114:117], v[164:167], v[204:207], v[114:117]
	v_mfma_f32_16x16x32_bf16 v[114:117], v[160:163], v[200:203], v[114:117]
	s_setprio 0
	s_add_i32 s43, s43, 2
	s_add_u32 s36, s36, 0x100
	s_addc_u32 s37, s37, 0
	s_add_u32 s15, s15, 0x100
	s_addc_u32 s42, s42, 0
	s_cmp_gt_u32 s43, 29
	s_cbranch_scc0 .LBB0_383
	s_and_b64 vcc, exec, s[8:9]
	s_cbranch_vccz .LBB0_386
	s_barrier

.LBB0_462:
	v_add_u32_e32 v14, s54, v140
	v_add_u32_e32 v30, s55, v140
	ds_read_b128 v[2:5], v14
	ds_read_b128 v[6:9], v14 offset:1024
	ds_read_b128 v[10:13], v14 offset:2048
	ds_read_b128 v[14:17], v14 offset:3072
	ds_read_b128 v[18:21], v30
	ds_read_b128 v[22:25], v30 offset:1024
	ds_read_b128 v[26:29], v30 offset:2048
	ds_read_b128 v[30:33], v30 offset:3072
	v_add_u32_e32 v141, 0, v1
	ds_read_b128 v[34:37], v141
	ds_read_b128 v[38:41], v141 offset:1024
	ds_read_b128 v[42:45], v141 offset:2048
	ds_read_b128 v[46:49], v141 offset:3072
	ds_read_b128 v[50:53], v141 offset:4096
	ds_read_b128 v[54:57], v141 offset:5120
	ds_read_b128 v[58:61], v141 offset:6144
	ds_read_b128 v[62:65], v141 offset:7168
	s_waitcnt vmcnt(8)
	s_waitcnt lgkmcnt(0)
	s_barrier
	s_setprio 1
	s_waitcnt lgkmcnt(0)
	s_nop 5
	v_mfma_f32_16x16x32_bf16 v[66:69], v[2:5], v[34:37], 0
	v_mfma_f32_16x16x32_bf16 v[66:69], v[6:9], v[38:41], v[66:69]
	v_mfma_f32_16x16x32_bf16 v[70:73], v[10:13], v[34:37], 0
	v_mfma_f32_16x16x32_bf16 v[70:73], v[14:17], v[38:41], v[70:73]
	v_mfma_f32_16x16x32_bf16 v[78:81], v[10:13], v[42:45], 0
	v_mfma_f32_16x16x32_bf16 v[78:81], v[14:17], v[46:49], v[78:81]
	v_mfma_f32_16x16x32_bf16 v[74:77], v[2:5], v[42:45], 0
	v_mfma_f32_16x16x32_bf16 v[74:77], v[6:9], v[46:49], v[74:77]
	v_mfma_f32_16x16x32_bf16 v[82:85], v[2:5], v[50:53], 0
	v_mfma_f32_16x16x32_bf16 v[82:85], v[6:9], v[54:57], v[82:85]
	v_mfma_f32_16x16x32_bf16 v[86:89], v[10:13], v[50:53], 0
	v_mfma_f32_16x16x32_bf16 v[86:89], v[14:17], v[54:57], v[86:89]
	v_mfma_f32_16x16x32_bf16 v[94:97], v[10:13], v[58:61], 0
	v_mfma_f32_16x16x32_bf16 v[94:97], v[14:17], v[62:65], v[94:97]
	v_mfma_f32_16x16x32_bf16 v[90:93], v[2:5], v[58:61], 0
	v_mfma_f32_16x16x32_bf16 v[90:93], v[6:9], v[62:65], v[90:93]
	s_setprio 0
	s_setprio 1
	v_mfma_f32_16x16x32_bf16 v[98:101], v[18:21], v[34:37], 0
	v_mfma_f32_16x16x32_bf16 v[34:37], v[26:29], v[34:37], 0
	v_mfma_f32_16x16x32_bf16 v[102:105], v[18:21], v[42:45], 0
	v_mfma_f32_16x16x32_bf16 v[42:45], v[26:29], v[42:45], 0
	v_mfma_f32_16x16x32_bf16 v[106:109], v[18:21], v[50:53], 0
	v_mfma_f32_16x16x32_bf16 v[50:53], v[26:29], v[50:53], 0
	v_mfma_f32_16x16x32_bf16 v[110:113], v[18:21], v[58:61], 0
	v_mfma_f32_16x16x32_bf16 v[58:61], v[26:29], v[58:61], 0
	v_mfma_f32_16x16x32_bf16 v[98:101], v[22:25], v[38:41], v[98:101]
	v_mfma_f32_16x16x32_bf16 v[38:41], v[30:33], v[38:41], v[34:37]
	v_mfma_f32_16x16x32_bf16 v[102:105], v[22:25], v[46:49], v[102:105]
	v_mfma_f32_16x16x32_bf16 v[46:49], v[30:33], v[46:49], v[42:45]
	v_mfma_f32_16x16x32_bf16 v[106:109], v[22:25], v[54:57], v[106:109]
	v_mfma_f32_16x16x32_bf16 v[54:57], v[30:33], v[54:57], v[50:53]
	s_setprio 2
	s_barrier
	v_mfma_f32_16x16x32_bf16 v[110:113], v[22:25], v[62:65], v[110:113]
	v_mfma_f32_16x16x32_bf16 v[62:65], v[30:33], v[62:65], v[58:61]
	s_setprio 0
	v_lshl_add_u64 v[136:137], s[36:37], 0, v[130:131]
	s_add_i32 s62, s54, s21
	v_mov_b32_e32 v135, v131
	v_lshl_add_u64 v[142:143], v[136:137], 0, s[12:13]
	s_mov_b32 m0, s62
	v_lshl_add_u64 v[244:245], s[36:37], 0, v[134:135]
	ds_read_b128 v[34:37], v141 offset:16384
	ds_read_b128 v[42:45], v141 offset:17408
	ds_read_b128 v[50:53], v141 offset:18432
	ds_read_b128 v[58:61], v141 offset:19456
	ds_read_b128 v[114:117], v141 offset:20480
	ds_read_b128 v[118:121], v141 offset:21504
	ds_read_b128 v[122:125], v141 offset:22528
	ds_read_b128 v[126:129], v141 offset:23552
	global_load_lds_dwordx4 v[142:143], off
	v_lshl_add_u64 v[142:143], v[244:245], 0, s[12:13]
	s_add_i32 m0, s62, 0x2000
	s_add_i32 s62, s55, s21
	global_load_lds_dwordx4 v[142:143], off
	s_mov_b32 m0, s62
	v_mov_b32_e32 v139, v131
	global_load_lds_dwordx4 v130, s[38:39]
	s_add_i32 m0, s62, 0x2000
	v_lshl_add_u64 v[246:247], s[34:35], 0, v[138:139]
	v_mov_b32_e32 v133, v131
	global_load_lds_dwordx4 v134, s[38:39]
	v_lshl_add_u64 v[142:143], v[246:247], 0, s[12:13]
	s_mov_b32 m0, s33
	v_lshl_add_u64 v[248:249], s[34:35], 0, v[132:133]
	global_load_lds_dwordx4 v[142:143], off
	v_lshl_add_u64 v[142:143], v[248:249], 0, s[12:13]
	s_mov_b32 m0, s44
	s_nop 0
	global_load_lds_dwordx4 v[142:143], off
	s_waitcnt vmcnt(8)
	s_waitcnt lgkmcnt(0)
	s_barrier
	s_setprio 1
	s_waitcnt lgkmcnt(0)
	s_nop 5
	v_mfma_f32_16x16x32_bf16 v[142:145], v[2:5], v[34:37], 0
	v_mfma_f32_16x16x32_bf16 v[148:151], v[10:13], v[34:37], 0
	v_mfma_f32_16x16x32_bf16 v[152:155], v[2:5], v[50:53], 0
	v_mfma_f32_16x16x32_bf16 v[156:159], v[10:13], v[50:53], 0
	v_mfma_f32_16x16x32_bf16 v[160:163], v[2:5], v[114:117], 0
	v_mfma_f32_16x16x32_bf16 v[164:167], v[10:13], v[114:117], 0
	v_mfma_f32_16x16x32_bf16 v[2:5], v[2:5], v[122:125], 0
	v_mfma_f32_16x16x32_bf16 v[10:13], v[10:13], v[122:125], 0
	v_mfma_f32_16x16x32_bf16 v[142:145], v[6:9], v[42:45], v[142:145]
	v_mfma_f32_16x16x32_bf16 v[148:151], v[14:17], v[42:45], v[148:151]
	v_mfma_f32_16x16x32_bf16 v[152:155], v[6:9], v[58:61], v[152:155]
	v_mfma_f32_16x16x32_bf16 v[156:159], v[14:17], v[58:61], v[156:159]
	v_mfma_f32_16x16x32_bf16 v[160:163], v[6:9], v[118:121], v[160:163]
	v_mfma_f32_16x16x32_bf16 v[164:167], v[14:17], v[118:121], v[164:167]
	v_mfma_f32_16x16x32_bf16 v[168:171], v[6:9], v[126:129], v[2:5]
	v_mfma_f32_16x16x32_bf16 v[172:175], v[14:17], v[126:129], v[10:13]
	s_setprio 0
	s_setprio 1
	v_mfma_f32_16x16x32_bf16 v[2:5], v[18:21], v[34:37], 0
	v_mfma_f32_16x16x32_bf16 v[6:9], v[26:29], v[34:37], 0
	v_mfma_f32_16x16x32_bf16 v[10:13], v[18:21], v[50:53], 0
	v_mfma_f32_16x16x32_bf16 v[14:17], v[26:29], v[50:53], 0
	v_mfma_f32_16x16x32_bf16 v[34:37], v[18:21], v[114:117], 0
	v_mfma_f32_16x16x32_bf16 v[50:53], v[26:29], v[114:117], 0
	v_mfma_f32_16x16x32_bf16 v[18:21], v[18:21], v[122:125], 0
	v_mfma_f32_16x16x32_bf16 v[26:29], v[26:29], v[122:125], 0
	v_mfma_f32_16x16x32_bf16 v[114:117], v[22:25], v[42:45], v[2:5]
	v_mfma_f32_16x16x32_bf16 v[122:125], v[30:33], v[42:45], v[6:9]
	v_mfma_f32_16x16x32_bf16 v[184:187], v[22:25], v[118:121], v[34:37]
	v_mfma_f32_16x16x32_bf16 v[118:121], v[30:33], v[118:121], v[50:53]
	v_mfma_f32_16x16x32_bf16 v[188:191], v[22:25], v[126:129], v[18:21]
	v_mfma_f32_16x16x32_bf16 v[126:129], v[30:33], v[126:129], v[26:29]
	s_setprio 2
	s_barrier
	v_mfma_f32_16x16x32_bf16 v[176:179], v[22:25], v[58:61], v[10:13]
	v_mfma_f32_16x16x32_bf16 v[180:183], v[30:33], v[58:61], v[14:17]
	s_setprio 0
	s_add_i32 s62, 0, 0x18000
	v_add_u32_e32 v2, s62, v140
	s_add_i32 s63, 0, 0x1c000
	ds_read_b128 v[192:195], v2
	ds_read_b128 v[196:199], v2 offset:1024
	ds_read_b128 v[200:203], v2 offset:2048
	ds_read_b128 v[204:207], v2 offset:3072
	v_add_u32_e32 v2, s63, v140
	ds_read_b128 v[208:211], v2
	ds_read_b128 v[212:215], v2 offset:1024
	ds_read_b128 v[216:219], v2 offset:2048
	ds_read_b128 v[220:223], v2 offset:3072
	s_mov_b32 m0, s45
	ds_read_b128 v[42:45], v141 offset:32768
	ds_read_b128 v[50:53], v141 offset:33792
	ds_read_b128 v[58:61], v141 offset:34816
	ds_read_b128 v[224:227], v141 offset:35840
	ds_read_b128 v[228:231], v141 offset:36864
	ds_read_b128 v[232:235], v141 offset:37888
	ds_read_b128 v[236:239], v141 offset:38912
	ds_read_b128 v[240:243], v141 offset:39936
	global_load_lds_dwordx4 v138, s[40:41]
	s_mov_b32 m0, s46
	s_nop 0
	global_load_lds_dwordx4 v132, s[40:41]
	s_waitcnt vmcnt(8)
	s_waitcnt lgkmcnt(0)
	s_barrier
	s_setprio 1
	s_waitcnt lgkmcnt(0)
	s_nop 5
	v_mfma_f32_16x16x32_bf16 v[2:5], v[192:195], v[42:45], v[66:69]
	v_mfma_f32_16x16x32_bf16 v[6:9], v[200:203], v[42:45], v[70:73]
	v_mfma_f32_16x16x32_bf16 v[10:13], v[192:195], v[58:61], v[74:77]
	v_mfma_f32_16x16x32_bf16 v[14:17], v[200:203], v[58:61], v[78:81]
	v_mfma_f32_16x16x32_bf16 v[18:21], v[192:195], v[228:231], v[82:85]
	v_mfma_f32_16x16x32_bf16 v[22:25], v[200:203], v[228:231], v[86:89]
	v_mfma_f32_16x16x32_bf16 v[26:29], v[192:195], v[236:239], v[90:93]
	v_mfma_f32_16x16x32_bf16 v[30:33], v[200:203], v[236:239], v[94:97]
	v_mfma_f32_16x16x32_bf16 v[2:5], v[196:199], v[50:53], v[2:5]
	v_mfma_f32_16x16x32_bf16 v[6:9], v[204:207], v[50:53], v[6:9]
	v_mfma_f32_16x16x32_bf16 v[10:13], v[196:199], v[224:227], v[10:13]
	v_mfma_f32_16x16x32_bf16 v[14:17], v[204:207], v[224:227], v[14:17]
	v_mfma_f32_16x16x32_bf16 v[18:21], v[196:199], v[232:235], v[18:21]
	v_mfma_f32_16x16x32_bf16 v[22:25], v[204:207], v[232:235], v[22:25]
	v_mfma_f32_16x16x32_bf16 v[26:29], v[196:199], v[240:243], v[26:29]
	v_mfma_f32_16x16x32_bf16 v[30:33], v[204:207], v[240:243], v[30:33]
	s_setprio 0
	s_setprio 1
	v_mfma_f32_16x16x32_bf16 v[34:37], v[208:211], v[42:45], v[98:101]
	v_mfma_f32_16x16x32_bf16 v[38:41], v[216:219], v[42:45], v[38:41]
	v_mfma_f32_16x16x32_bf16 v[34:37], v[212:215], v[50:53], v[34:37]
	v_mfma_f32_16x16x32_bf16 v[38:41], v[220:223], v[50:53], v[38:41]
	v_mfma_f32_16x16x32_bf16 v[42:45], v[208:211], v[58:61], v[102:105]
	v_mfma_f32_16x16x32_bf16 v[46:49], v[216:219], v[58:61], v[46:49]
	v_mfma_f32_16x16x32_bf16 v[50:53], v[208:211], v[228:231], v[106:109]
	v_mfma_f32_16x16x32_bf16 v[54:57], v[216:219], v[228:231], v[54:57]
	v_mfma_f32_16x16x32_bf16 v[58:61], v[208:211], v[236:239], v[110:113]
	v_mfma_f32_16x16x32_bf16 v[62:65], v[216:219], v[236:239], v[62:65]
	v_mfma_f32_16x16x32_bf16 v[42:45], v[212:215], v[224:227], v[42:45]
	v_mfma_f32_16x16x32_bf16 v[46:49], v[220:223], v[224:227], v[46:49]
	v_mfma_f32_16x16x32_bf16 v[50:53], v[212:215], v[232:235], v[50:53]
	v_mfma_f32_16x16x32_bf16 v[54:57], v[220:223], v[232:235], v[54:57]
	s_setprio 2
	s_barrier
	v_mfma_f32_16x16x32_bf16 v[58:61], v[212:215], v[240:243], v[58:61]
	v_mfma_f32_16x16x32_bf16 v[62:65], v[220:223], v[240:243], v[62:65]
	s_setprio 0
	s_add_i32 s62, s62, s21
	v_lshl_add_u64 v[66:67], v[136:137], 0, s[14:15]
	s_mov_b32 m0, s62
	ds_read_b128 v[102:105], v141 offset:49152
	ds_read_b128 v[106:109], v141 offset:50176
	ds_read_b128 v[110:113], v141 offset:51200
	ds_read_b128 v[224:227], v141 offset:52224
	ds_read_b128 v[228:231], v141 offset:53248
	ds_read_b128 v[232:235], v141 offset:54272
	ds_read_b128 v[236:239], v141 offset:55296
	ds_read_b128 v[240:243], v141 offset:56320
	global_load_lds_dwordx4 v[66:67], off
	v_lshl_add_u64 v[66:67], v[244:245], 0, s[14:15]
	s_add_i32 m0, s62, 0x2000
	s_add_i32 s62, s63, s21
	global_load_lds_dwordx4 v[66:67], off
	s_mov_b32 m0, s62
	v_lshl_add_u64 v[66:67], v[246:247], 0, s[14:15]
	global_load_lds_dwordx4 v130, s[42:43]
	s_add_i32 m0, s62, 0x2000
	s_nop 0
	global_load_lds_dwordx4 v134, s[42:43]
	s_mov_b32 m0, s50
	s_nop 0
	global_load_lds_dwordx4 v[66:67], off
	v_lshl_add_u64 v[66:67], v[248:249], 0, s[14:15]
	s_mov_b32 m0, s51
	s_nop 0
	global_load_lds_dwordx4 v[66:67], off
	s_waitcnt vmcnt(8)
	s_waitcnt lgkmcnt(0)
	s_barrier
	s_setprio 1
	s_waitcnt lgkmcnt(0)
	s_nop 5
	v_mfma_f32_16x16x32_bf16 v[66:69], v[192:195], v[102:105], v[142:145]
	v_mfma_f32_16x16x32_bf16 v[70:73], v[200:203], v[102:105], v[148:151]
	v_mfma_f32_16x16x32_bf16 v[74:77], v[192:195], v[110:113], v[152:155]
	v_mfma_f32_16x16x32_bf16 v[78:81], v[200:203], v[110:113], v[156:159]
	v_mfma_f32_16x16x32_bf16 v[82:85], v[192:195], v[228:231], v[160:163]
	v_mfma_f32_16x16x32_bf16 v[86:89], v[200:203], v[228:231], v[164:167]
	v_mfma_f32_16x16x32_bf16 v[90:93], v[192:195], v[236:239], v[168:171]
	v_mfma_f32_16x16x32_bf16 v[94:97], v[200:203], v[236:239], v[172:175]
	v_mfma_f32_16x16x32_bf16 v[66:69], v[196:199], v[106:109], v[66:69]
	v_mfma_f32_16x16x32_bf16 v[70:73], v[204:207], v[106:109], v[70:73]
	v_mfma_f32_16x16x32_bf16 v[74:77], v[196:199], v[224:227], v[74:77]
	v_mfma_f32_16x16x32_bf16 v[78:81], v[204:207], v[224:227], v[78:81]
	v_mfma_f32_16x16x32_bf16 v[82:85], v[196:199], v[232:235], v[82:85]
	v_mfma_f32_16x16x32_bf16 v[86:89], v[204:207], v[232:235], v[86:89]
	v_mfma_f32_16x16x32_bf16 v[90:93], v[196:199], v[240:243], v[90:93]
	v_mfma_f32_16x16x32_bf16 v[94:97], v[204:207], v[240:243], v[94:97]
	s_setprio 0
	s_setprio 1
	v_mfma_f32_16x16x32_bf16 v[98:101], v[208:211], v[102:105], v[114:117]
	v_mfma_f32_16x16x32_bf16 v[102:105], v[216:219], v[102:105], v[122:125]
	v_mfma_f32_16x16x32_bf16 v[98:101], v[212:215], v[106:109], v[98:101]
	v_mfma_f32_16x16x32_bf16 v[102:105], v[220:223], v[106:109], v[102:105]
	v_mfma_f32_16x16x32_bf16 v[106:109], v[208:211], v[110:113], v[176:179]
	v_mfma_f32_16x16x32_bf16 v[110:113], v[216:219], v[110:113], v[180:183]
	v_mfma_f32_16x16x32_bf16 v[114:117], v[208:211], v[228:231], v[184:187]
	v_mfma_f32_16x16x32_bf16 v[118:121], v[216:219], v[228:231], v[118:121]
	v_mfma_f32_16x16x32_bf16 v[122:125], v[208:211], v[236:239], v[188:191]
	v_mfma_f32_16x16x32_bf16 v[126:129], v[216:219], v[236:239], v[126:129]
	v_mfma_f32_16x16x32_bf16 v[106:109], v[212:215], v[224:227], v[106:109]
	v_mfma_f32_16x16x32_bf16 v[110:113], v[220:223], v[224:227], v[110:113]
	v_mfma_f32_16x16x32_bf16 v[114:117], v[212:215], v[232:235], v[114:117]
	v_mfma_f32_16x16x32_bf16 v[118:121], v[220:223], v[232:235], v[118:121]
	s_setprio 2
	s_barrier
	v_mfma_f32_16x16x32_bf16 v[122:125], v[212:215], v[240:243], v[122:125]
	v_mfma_f32_16x16x32_bf16 v[126:129], v[220:223], v[240:243], v[126:129]
	s_setprio 0
	s_add_i32 s61, s61, 2
	s_cmp_ge_i32 s61, s60
	s_cbranch_scc0 .LBB0_462
	v_mov_b32_e32 v136, v130
	s_branch .LBB0_465

.LBB0_466:
	v_add_u32_e32 v133, s54, v140
	ds_read_b128 v[142:145], v133
	ds_read_b128 v[148:151], v133 offset:1024
	ds_read_b128 v[152:155], v133 offset:2048
	ds_read_b128 v[156:159], v133 offset:3072
	v_add_u32_e32 v133, s55, v140
	ds_read_b128 v[160:163], v133
	ds_read_b128 v[164:167], v133 offset:1024
	ds_read_b128 v[168:171], v133 offset:2048
	ds_read_b128 v[172:175], v133 offset:3072
	s_add_u32 s36, s34, 0xffc00080
	s_addc_u32 s37, s35, -1
	s_cmp_eq_u32 s42, 4
	s_cselect_b32 s39, s29, s37
	s_cselect_b32 s38, s28, s36
	s_cselect_b32 s37, s31, s41
	s_cselect_b32 s36, s30, s40
	s_mov_b32 m0, s52
	v_add_u32_e32 v141, 0, v1
	ds_read_b128 v[176:179], v141
	ds_read_b128 v[180:183], v141 offset:1024
	ds_read_b128 v[184:187], v141 offset:2048
	ds_read_b128 v[188:191], v141 offset:3072
	ds_read_b128 v[192:195], v141 offset:4096
	ds_read_b128 v[196:199], v141 offset:5120
	ds_read_b128 v[200:203], v141 offset:6144
	ds_read_b128 v[204:207], v141 offset:7168
	global_load_lds_dwordx4 v130, s[34:35]
	s_mov_b32 m0, s53
	v_mov_b32_e32 v133, v131
	global_load_lds_dwordx4 v132, s[34:35]
	s_waitcnt vmcnt(8)
	s_waitcnt lgkmcnt(0)
	s_barrier
	s_setprio 1
	s_waitcnt lgkmcnt(0)
	s_nop 5
	v_mfma_f32_16x16x32_bf16 v[2:5], v[142:145], v[176:179], v[2:5]
	v_mfma_f32_16x16x32_bf16 v[2:5], v[148:151], v[180:183], v[2:5]
	v_mfma_f32_16x16x32_bf16 v[6:9], v[156:159], v[180:183], v[6:9]
	v_mfma_f32_16x16x32_bf16 v[6:9], v[152:155], v[176:179], v[6:9]
	v_mfma_f32_16x16x32_bf16 v[14:17], v[152:155], v[184:187], v[14:17]
	v_mfma_f32_16x16x32_bf16 v[14:17], v[156:159], v[188:191], v[14:17]
	v_mfma_f32_16x16x32_bf16 v[10:13], v[148:151], v[188:191], v[10:13]
	v_mfma_f32_16x16x32_bf16 v[10:13], v[142:145], v[184:187], v[10:13]
	v_mfma_f32_16x16x32_bf16 v[18:21], v[142:145], v[192:195], v[18:21]
	v_mfma_f32_16x16x32_bf16 v[18:21], v[148:151], v[196:199], v[18:21]
	v_mfma_f32_16x16x32_bf16 v[22:25], v[156:159], v[196:199], v[22:25]
	v_mfma_f32_16x16x32_bf16 v[22:25], v[152:155], v[192:195], v[22:25]
	v_mfma_f32_16x16x32_bf16 v[30:33], v[152:155], v[200:203], v[30:33]
	v_mfma_f32_16x16x32_bf16 v[30:33], v[156:159], v[204:207], v[30:33]
	v_mfma_f32_16x16x32_bf16 v[26:29], v[148:151], v[204:207], v[26:29]
	v_mfma_f32_16x16x32_bf16 v[26:29], v[142:145], v[200:203], v[26:29]
	s_setprio 0
	s_setprio 1
	v_mfma_f32_16x16x32_bf16 v[34:37], v[160:163], v[176:179], v[34:37]
	v_mfma_f32_16x16x32_bf16 v[34:37], v[164:167], v[180:183], v[34:37]
	v_mfma_f32_16x16x32_bf16 v[38:41], v[172:175], v[180:183], v[38:41]
	v_mfma_f32_16x16x32_bf16 v[38:41], v[168:171], v[176:179], v[38:41]
	v_mfma_f32_16x16x32_bf16 v[46:49], v[168:171], v[184:187], v[46:49]
	v_mfma_f32_16x16x32_bf16 v[46:49], v[172:175], v[188:191], v[46:49]
	v_mfma_f32_16x16x32_bf16 v[42:45], v[164:167], v[188:191], v[42:45]
	v_mfma_f32_16x16x32_bf16 v[42:45], v[160:163], v[184:187], v[42:45]
	v_mfma_f32_16x16x32_bf16 v[50:53], v[160:163], v[192:195], v[50:53]
	v_mfma_f32_16x16x32_bf16 v[50:53], v[164:167], v[196:199], v[50:53]
	v_mfma_f32_16x16x32_bf16 v[54:57], v[172:175], v[196:199], v[54:57]
	v_mfma_f32_16x16x32_bf16 v[54:57], v[168:171], v[192:195], v[54:57]
	v_mfma_f32_16x16x32_bf16 v[62:65], v[168:171], v[200:203], v[62:65]
	v_mfma_f32_16x16x32_bf16 v[62:65], v[172:175], v[204:207], v[62:65]
	s_setprio 2
	s_barrier
	v_mfma_f32_16x16x32_bf16 v[58:61], v[164:167], v[204:207], v[58:61]
	v_mfma_f32_16x16x32_bf16 v[58:61], v[160:163], v[200:203], v[58:61]
	s_setprio 0
	s_add_i32 s43, s54, s21
	s_mov_b32 m0, s43
	ds_read_b128 v[176:179], v141 offset:16384
	ds_read_b128 v[180:183], v141 offset:17408
	ds_read_b128 v[184:187], v141 offset:18432
	ds_read_b128 v[188:191], v141 offset:19456
	ds_read_b128 v[192:195], v141 offset:20480
	ds_read_b128 v[196:199], v141 offset:21504
	ds_read_b128 v[200:203], v141 offset:22528
	ds_read_b128 v[204:207], v141 offset:23552
	global_load_lds_dwordx4 v136, s[36:37]
	s_add_i32 m0, s43, 0x2000
	s_add_u32 s60, s36, 0x80000
	s_addc_u32 s61, s37, 0
	s_add_i32 s43, s55, s21
	global_load_lds_dwordx4 v134, s[36:37]
	s_mov_b32 m0, s43
	v_mov_b32_e32 v137, v131
	global_load_lds_dwordx4 v136, s[60:61]
	s_add_i32 m0, s43, 0x2000
	v_mov_b32_e32 v135, v131
	global_load_lds_dwordx4 v134, s[60:61]
	s_mov_b32 m0, s33
	v_lshl_add_u64 v[138:139], s[36:37], 0, v[136:137]
	global_load_lds_dwordx4 v130, s[38:39]
	s_mov_b32 m0, s44
	v_lshl_add_u64 v[208:209], s[36:37], 0, v[134:135]
	global_load_lds_dwordx4 v132, s[38:39]
	s_waitcnt vmcnt(8)
	s_waitcnt lgkmcnt(0)
	v_lshl_add_u64 v[210:211], s[38:39], 0, v[130:131]
	v_lshl_add_u64 v[212:213], s[38:39], 0, v[132:133]
	s_barrier
	s_setprio 1
	s_waitcnt lgkmcnt(0)
	s_nop 5
	v_mfma_f32_16x16x32_bf16 v[66:69], v[142:145], v[176:179], v[66:69]
	v_mfma_f32_16x16x32_bf16 v[66:69], v[148:151], v[180:183], v[66:69]
	v_mfma_f32_16x16x32_bf16 v[70:73], v[156:159], v[180:183], v[70:73]
	v_mfma_f32_16x16x32_bf16 v[70:73], v[152:155], v[176:179], v[70:73]
	v_mfma_f32_16x16x32_bf16 v[78:81], v[152:155], v[184:187], v[78:81]
	v_mfma_f32_16x16x32_bf16 v[78:81], v[156:159], v[188:191], v[78:81]
	v_mfma_f32_16x16x32_bf16 v[74:77], v[148:151], v[188:191], v[74:77]
	v_mfma_f32_16x16x32_bf16 v[74:77], v[142:145], v[184:187], v[74:77]
	v_mfma_f32_16x16x32_bf16 v[82:85], v[142:145], v[192:195], v[82:85]
	v_mfma_f32_16x16x32_bf16 v[82:85], v[148:151], v[196:199], v[82:85]
	v_mfma_f32_16x16x32_bf16 v[86:89], v[156:159], v[196:199], v[86:89]
	v_mfma_f32_16x16x32_bf16 v[86:89], v[152:155], v[192:195], v[86:89]
	v_mfma_f32_16x16x32_bf16 v[94:97], v[152:155], v[200:203], v[94:97]
	v_mfma_f32_16x16x32_bf16 v[94:97], v[156:159], v[204:207], v[94:97]
	v_mfma_f32_16x16x32_bf16 v[90:93], v[148:151], v[204:207], v[90:93]
	v_mfma_f32_16x16x32_bf16 v[90:93], v[142:145], v[200:203], v[90:93]
	s_setprio 0
	s_setprio 1
	v_mfma_f32_16x16x32_bf16 v[98:101], v[160:163], v[176:179], v[98:101]
	v_mfma_f32_16x16x32_bf16 v[98:101], v[164:167], v[180:183], v[98:101]
	v_mfma_f32_16x16x32_bf16 v[102:105], v[172:175], v[180:183], v[102:105]
	v_mfma_f32_16x16x32_bf16 v[102:105], v[168:171], v[176:179], v[102:105]
	v_mfma_f32_16x16x32_bf16 v[110:113], v[168:171], v[184:187], v[110:113]
	v_mfma_f32_16x16x32_bf16 v[110:113], v[172:175], v[188:191], v[110:113]
	v_mfma_f32_16x16x32_bf16 v[106:109], v[164:167], v[188:191], v[106:109]
	v_mfma_f32_16x16x32_bf16 v[106:109], v[160:163], v[184:187], v[106:109]
	v_mfma_f32_16x16x32_bf16 v[114:117], v[160:163], v[192:195], v[114:117]
	v_mfma_f32_16x16x32_bf16 v[114:117], v[164:167], v[196:199], v[114:117]
	v_mfma_f32_16x16x32_bf16 v[118:121], v[172:175], v[196:199], v[118:121]
	v_mfma_f32_16x16x32_bf16 v[118:121], v[168:171], v[192:195], v[118:121]
	v_mfma_f32_16x16x32_bf16 v[126:129], v[168:171], v[200:203], v[126:129]
	v_mfma_f32_16x16x32_bf16 v[126:129], v[172:175], v[204:207], v[126:129]
	s_setprio 2
	s_barrier
	v_mfma_f32_16x16x32_bf16 v[122:125], v[164:167], v[204:207], v[122:125]
	v_mfma_f32_16x16x32_bf16 v[122:125], v[160:163], v[200:203], v[122:125]
	s_setprio 0
	s_add_i32 s43, 0, 0x18000
	v_add_u32_e32 v135, s43, v140
	s_add_i32 s60, 0, 0x1c000
	ds_read_b128 v[142:145], v135
	ds_read_b128 v[148:151], v135 offset:1024
	ds_read_b128 v[152:155], v135 offset:2048
	ds_read_b128 v[156:159], v135 offset:3072
	v_add_u32_e32 v135, s60, v140
	ds_read_b128 v[160:163], v135
	ds_read_b128 v[164:167], v135 offset:1024
	ds_read_b128 v[168:171], v135 offset:2048
	ds_read_b128 v[172:175], v135 offset:3072
	s_add_u32 s38, s38, 0x400000
	s_addc_u32 s39, s39, 0
	s_mov_b32 m0, s45
	ds_read_b128 v[176:179], v141 offset:32768
	ds_read_b128 v[180:183], v141 offset:33792
	ds_read_b128 v[184:187], v141 offset:34816
	ds_read_b128 v[188:191], v141 offset:35840
	ds_read_b128 v[192:195], v141 offset:36864
	ds_read_b128 v[196:199], v141 offset:37888
	ds_read_b128 v[200:203], v141 offset:38912
	ds_read_b128 v[204:207], v141 offset:39936
	global_load_lds_dwordx4 v130, s[38:39]
	s_mov_b32 m0, s46
	s_nop 0
	global_load_lds_dwordx4 v132, s[38:39]
	s_waitcnt vmcnt(8)
	s_waitcnt lgkmcnt(0)
	s_barrier
	s_setprio 1
	s_waitcnt lgkmcnt(0)
	s_nop 5
	v_mfma_f32_16x16x32_bf16 v[2:5], v[142:145], v[176:179], v[2:5]
	v_mfma_f32_16x16x32_bf16 v[2:5], v[148:151], v[180:183], v[2:5]
	v_mfma_f32_16x16x32_bf16 v[6:9], v[156:159], v[180:183], v[6:9]
	v_mfma_f32_16x16x32_bf16 v[6:9], v[152:155], v[176:179], v[6:9]
	v_mfma_f32_16x16x32_bf16 v[14:17], v[152:155], v[184:187], v[14:17]
	v_mfma_f32_16x16x32_bf16 v[14:17], v[156:159], v[188:191], v[14:17]
	v_mfma_f32_16x16x32_bf16 v[10:13], v[148:151], v[188:191], v[10:13]
	v_mfma_f32_16x16x32_bf16 v[10:13], v[142:145], v[184:187], v[10:13]
	v_mfma_f32_16x16x32_bf16 v[18:21], v[142:145], v[192:195], v[18:21]
	v_mfma_f32_16x16x32_bf16 v[18:21], v[148:151], v[196:199], v[18:21]
	v_mfma_f32_16x16x32_bf16 v[22:25], v[156:159], v[196:199], v[22:25]
	v_mfma_f32_16x16x32_bf16 v[22:25], v[152:155], v[192:195], v[22:25]
	v_mfma_f32_16x16x32_bf16 v[30:33], v[152:155], v[200:203], v[30:33]
	v_mfma_f32_16x16x32_bf16 v[30:33], v[156:159], v[204:207], v[30:33]
	v_mfma_f32_16x16x32_bf16 v[26:29], v[148:151], v[204:207], v[26:29]
	v_mfma_f32_16x16x32_bf16 v[26:29], v[142:145], v[200:203], v[26:29]
	s_setprio 0
	s_setprio 1
	v_mfma_f32_16x16x32_bf16 v[34:37], v[160:163], v[176:179], v[34:37]
	v_mfma_f32_16x16x32_bf16 v[34:37], v[164:167], v[180:183], v[34:37]
	v_mfma_f32_16x16x32_bf16 v[38:41], v[172:175], v[180:183], v[38:41]
	v_mfma_f32_16x16x32_bf16 v[38:41], v[168:171], v[176:179], v[38:41]
	v_mfma_f32_16x16x32_bf16 v[46:49], v[168:171], v[184:187], v[46:49]
	v_mfma_f32_16x16x32_bf16 v[46:49], v[172:175], v[188:191], v[46:49]
	v_mfma_f32_16x16x32_bf16 v[42:45], v[164:167], v[188:191], v[42:45]
	v_mfma_f32_16x16x32_bf16 v[42:45], v[160:163], v[184:187], v[42:45]
	v_mfma_f32_16x16x32_bf16 v[50:53], v[160:163], v[192:195], v[50:53]
	v_mfma_f32_16x16x32_bf16 v[50:53], v[164:167], v[196:199], v[50:53]
	v_mfma_f32_16x16x32_bf16 v[54:57], v[172:175], v[196:199], v[54:57]
	v_mfma_f32_16x16x32_bf16 v[54:57], v[168:171], v[192:195], v[54:57]
	v_mfma_f32_16x16x32_bf16 v[62:65], v[168:171], v[200:203], v[62:65]
	v_mfma_f32_16x16x32_bf16 v[62:65], v[172:175], v[204:207], v[62:65]
	s_setprio 2
	s_barrier
	v_mfma_f32_16x16x32_bf16 v[58:61], v[164:167], v[204:207], v[58:61]
	v_mfma_f32_16x16x32_bf16 v[58:61], v[160:163], v[200:203], v[58:61]
	s_setprio 0
	s_add_i32 s38, s43, s21
	v_lshl_add_u64 v[138:139], v[138:139], 0, s[8:9]
	s_mov_b32 m0, s38
	ds_read_b128 v[176:179], v141 offset:49152
	ds_read_b128 v[180:183], v141 offset:50176
	ds_read_b128 v[184:187], v141 offset:51200
	ds_read_b128 v[188:191], v141 offset:52224
	ds_read_b128 v[192:195], v141 offset:53248
	ds_read_b128 v[196:199], v141 offset:54272
	ds_read_b128 v[200:203], v141 offset:55296
	ds_read_b128 v[204:207], v141 offset:56320
	global_load_lds_dwordx4 v[138:139], off
	s_add_i32 m0, s38, 0x2000
	s_add_u32 s36, s36, 0x80080
	v_lshl_add_u64 v[138:139], v[208:209], 0, s[8:9]
	s_addc_u32 s37, s37, 0
	s_add_i32 s38, s60, s21
	global_load_lds_dwordx4 v[138:139], off
	s_mov_b32 m0, s38
	v_lshl_add_u64 v[138:139], v[210:211], 0, s[8:9]
	global_load_lds_dwordx4 v136, s[36:37]
	s_add_i32 m0, s38, 0x2000
	s_nop 0
	global_load_lds_dwordx4 v134, s[36:37]
	s_mov_b32 m0, s50
	s_nop 0
	global_load_lds_dwordx4 v[138:139], off
	v_lshl_add_u64 v[138:139], v[212:213], 0, s[8:9]
	s_mov_b32 m0, s51
	s_nop 0
	global_load_lds_dwordx4 v[138:139], off
	s_waitcnt vmcnt(8)
	s_waitcnt lgkmcnt(0)
	s_barrier
	s_setprio 1
	s_waitcnt lgkmcnt(0)
	s_nop 5
	v_mfma_f32_16x16x32_bf16 v[66:69], v[142:145], v[176:179], v[66:69]
	v_mfma_f32_16x16x32_bf16 v[66:69], v[148:151], v[180:183], v[66:69]
	v_mfma_f32_16x16x32_bf16 v[70:73], v[156:159], v[180:183], v[70:73]
	v_mfma_f32_16x16x32_bf16 v[70:73], v[152:155], v[176:179], v[70:73]
	v_mfma_f32_16x16x32_bf16 v[78:81], v[152:155], v[184:187], v[78:81]
	v_mfma_f32_16x16x32_bf16 v[78:81], v[156:159], v[188:191], v[78:81]
	v_mfma_f32_16x16x32_bf16 v[74:77], v[148:151], v[188:191], v[74:77]
	v_mfma_f32_16x16x32_bf16 v[74:77], v[142:145], v[184:187], v[74:77]
	v_mfma_f32_16x16x32_bf16 v[82:85], v[142:145], v[192:195], v[82:85]
	v_mfma_f32_16x16x32_bf16 v[82:85], v[148:151], v[196:199], v[82:85]
	v_mfma_f32_16x16x32_bf16 v[86:89], v[156:159], v[196:199], v[86:89]
	v_mfma_f32_16x16x32_bf16 v[86:89], v[152:155], v[192:195], v[86:89]
	v_mfma_f32_16x16x32_bf16 v[94:97], v[152:155], v[200:203], v[94:97]
	v_mfma_f32_16x16x32_bf16 v[94:97], v[156:159], v[204:207], v[94:97]
	v_mfma_f32_16x16x32_bf16 v[90:93], v[148:151], v[204:207], v[90:93]
	v_mfma_f32_16x16x32_bf16 v[90:93], v[142:145], v[200:203], v[90:93]
	s_setprio 0
	s_setprio 1
	v_mfma_f32_16x16x32_bf16 v[98:101], v[160:163], v[176:179], v[98:101]
	v_mfma_f32_16x16x32_bf16 v[98:101], v[164:167], v[180:183], v[98:101]
	v_mfma_f32_16x16x32_bf16 v[102:105], v[172:175], v[180:183], v[102:105]
	v_mfma_f32_16x16x32_bf16 v[102:105], v[168:171], v[176:179], v[102:105]
	v_mfma_f32_16x16x32_bf16 v[110:113], v[168:171], v[184:187], v[110:113]
	v_mfma_f32_16x16x32_bf16 v[110:113], v[172:175], v[188:191], v[110:113]
	v_mfma_f32_16x16x32_bf16 v[106:109], v[164:167], v[188:191], v[106:109]
	v_mfma_f32_16x16x32_bf16 v[106:109], v[160:163], v[184:187], v[106:109]
	v_mfma_f32_16x16x32_bf16 v[114:117], v[160:163], v[192:195], v[114:117]
	v_mfma_f32_16x16x32_bf16 v[114:117], v[164:167], v[196:199], v[114:117]
	v_mfma_f32_16x16x32_bf16 v[118:121], v[172:175], v[196:199], v[118:121]
	v_mfma_f32_16x16x32_bf16 v[118:121], v[168:171], v[192:195], v[118:121]
	v_mfma_f32_16x16x32_bf16 v[126:129], v[168:171], v[200:203], v[126:129]
	v_mfma_f32_16x16x32_bf16 v[126:129], v[172:175], v[204:207], v[126:129]
	s_setprio 2
	s_barrier
	v_mfma_f32_16x16x32_bf16 v[122:125], v[164:167], v[204:207], v[122:125]
	v_mfma_f32_16x16x32_bf16 v[122:125], v[160:163], v[200:203], v[122:125]
	s_setprio 0
	s_add_i32 s42, s42, 2
	s_add_u32 s34, s34, 0x100
	s_addc_u32 s35, s35, 0
	s_add_u32 s40, s40, 0x100
	s_addc_u32 s41, s41, 0
	s_cmp_gt_u32 s42, 5
	s_cbranch_scc0 .LBB0_466
	s_and_b64 vcc, exec, s[10:11]
	s_cbranch_vccz .LBB0_469
	s_barrier

.LBB0_495:
	v_add_u32_e32 v14, s58, v140
	v_add_u32_e32 v30, s59, v140
	ds_read_b128 v[2:5], v14
	ds_read_b128 v[6:9], v14 offset:1024
	ds_read_b128 v[10:13], v14 offset:2048
	ds_read_b128 v[14:17], v14 offset:3072
	ds_read_b128 v[18:21], v30
	ds_read_b128 v[22:25], v30 offset:1024
	ds_read_b128 v[26:29], v30 offset:2048
	ds_read_b128 v[30:33], v30 offset:3072
	v_add_u32_e32 v141, 0, v1
	ds_read_b128 v[34:37], v141
	ds_read_b128 v[38:41], v141 offset:1024
	ds_read_b128 v[42:45], v141 offset:2048
	ds_read_b128 v[46:49], v141 offset:3072
	ds_read_b128 v[50:53], v141 offset:4096
	ds_read_b128 v[54:57], v141 offset:5120
	ds_read_b128 v[58:61], v141 offset:6144
	ds_read_b128 v[62:65], v141 offset:7168
	s_waitcnt vmcnt(8)
	s_waitcnt lgkmcnt(0)
	s_barrier
	s_setprio 1
	s_waitcnt lgkmcnt(0)
	s_nop 5
	v_mfma_f32_16x16x32_bf16 v[66:69], v[2:5], v[34:37], 0
	v_mfma_f32_16x16x32_bf16 v[66:69], v[6:9], v[38:41], v[66:69]
	v_mfma_f32_16x16x32_bf16 v[70:73], v[10:13], v[34:37], 0
	v_mfma_f32_16x16x32_bf16 v[70:73], v[14:17], v[38:41], v[70:73]
	v_mfma_f32_16x16x32_bf16 v[78:81], v[10:13], v[42:45], 0
	v_mfma_f32_16x16x32_bf16 v[78:81], v[14:17], v[46:49], v[78:81]
	v_mfma_f32_16x16x32_bf16 v[74:77], v[2:5], v[42:45], 0
	v_mfma_f32_16x16x32_bf16 v[74:77], v[6:9], v[46:49], v[74:77]
	v_mfma_f32_16x16x32_bf16 v[82:85], v[2:5], v[50:53], 0
	v_mfma_f32_16x16x32_bf16 v[82:85], v[6:9], v[54:57], v[82:85]
	v_mfma_f32_16x16x32_bf16 v[86:89], v[10:13], v[50:53], 0
	v_mfma_f32_16x16x32_bf16 v[86:89], v[14:17], v[54:57], v[86:89]
	v_mfma_f32_16x16x32_bf16 v[94:97], v[10:13], v[58:61], 0
	v_mfma_f32_16x16x32_bf16 v[94:97], v[14:17], v[62:65], v[94:97]
	v_mfma_f32_16x16x32_bf16 v[90:93], v[2:5], v[58:61], 0
	v_mfma_f32_16x16x32_bf16 v[90:93], v[6:9], v[62:65], v[90:93]
	s_setprio 0
	s_setprio 1
	v_mfma_f32_16x16x32_bf16 v[98:101], v[18:21], v[34:37], 0
	v_mfma_f32_16x16x32_bf16 v[34:37], v[26:29], v[34:37], 0
	v_mfma_f32_16x16x32_bf16 v[102:105], v[18:21], v[42:45], 0
	v_mfma_f32_16x16x32_bf16 v[42:45], v[26:29], v[42:45], 0
	v_mfma_f32_16x16x32_bf16 v[106:109], v[18:21], v[50:53], 0
	v_mfma_f32_16x16x32_bf16 v[50:53], v[26:29], v[50:53], 0
	v_mfma_f32_16x16x32_bf16 v[110:113], v[18:21], v[58:61], 0
	v_mfma_f32_16x16x32_bf16 v[58:61], v[26:29], v[58:61], 0
	v_mfma_f32_16x16x32_bf16 v[98:101], v[22:25], v[38:41], v[98:101]
	v_mfma_f32_16x16x32_bf16 v[38:41], v[30:33], v[38:41], v[34:37]
	v_mfma_f32_16x16x32_bf16 v[102:105], v[22:25], v[46:49], v[102:105]
	v_mfma_f32_16x16x32_bf16 v[46:49], v[30:33], v[46:49], v[42:45]
	v_mfma_f32_16x16x32_bf16 v[106:109], v[22:25], v[54:57], v[106:109]
	v_mfma_f32_16x16x32_bf16 v[54:57], v[30:33], v[54:57], v[50:53]
	s_setprio 2
	s_barrier
	v_mfma_f32_16x16x32_bf16 v[110:113], v[22:25], v[62:65], v[110:113]
	v_mfma_f32_16x16x32_bf16 v[62:65], v[30:33], v[62:65], v[58:61]
	s_setprio 0
	v_lshl_add_u64 v[136:137], s[38:39], 0, v[130:131]
	s_add_i32 s62, s58, s46
	v_mov_b32_e32 v135, v131
	v_lshl_add_u64 v[142:143], v[136:137], 0, s[10:11]
	s_mov_b32 m0, s62
	v_lshl_add_u64 v[244:245], s[38:39], 0, v[134:135]
	ds_read_b128 v[34:37], v141 offset:16384
	ds_read_b128 v[42:45], v141 offset:17408
	ds_read_b128 v[50:53], v141 offset:18432
	ds_read_b128 v[58:61], v141 offset:19456
	ds_read_b128 v[114:117], v141 offset:20480
	ds_read_b128 v[118:121], v141 offset:21504
	ds_read_b128 v[122:125], v141 offset:22528
	ds_read_b128 v[126:129], v141 offset:23552
	global_load_lds_dwordx4 v[142:143], off
	v_lshl_add_u64 v[142:143], v[244:245], 0, s[10:11]
	s_add_i32 m0, s62, 0x2000
	s_add_i32 s62, s59, s46
	global_load_lds_dwordx4 v[142:143], off
	s_mov_b32 m0, s62
	v_mov_b32_e32 v139, v131
	global_load_lds_dwordx4 v130, s[40:41]
	s_add_i32 m0, s62, 0x2000
	v_lshl_add_u64 v[246:247], s[36:37], 0, v[138:139]
	v_mov_b32_e32 v133, v131
	global_load_lds_dwordx4 v134, s[40:41]
	v_lshl_add_u64 v[142:143], v[246:247], 0, s[10:11]
	s_mov_b32 m0, s47
	v_lshl_add_u64 v[248:249], s[36:37], 0, v[132:133]
	global_load_lds_dwordx4 v[142:143], off
	v_lshl_add_u64 v[142:143], v[248:249], 0, s[10:11]
	s_mov_b32 m0, s48
	s_nop 0
	global_load_lds_dwordx4 v[142:143], off
	s_waitcnt vmcnt(8)
	s_waitcnt lgkmcnt(0)
	s_barrier
	s_setprio 1
	s_waitcnt lgkmcnt(0)
	s_nop 5
	v_mfma_f32_16x16x32_bf16 v[142:145], v[2:5], v[34:37], 0
	v_mfma_f32_16x16x32_bf16 v[148:151], v[10:13], v[34:37], 0
	v_mfma_f32_16x16x32_bf16 v[152:155], v[2:5], v[50:53], 0
	v_mfma_f32_16x16x32_bf16 v[156:159], v[10:13], v[50:53], 0
	v_mfma_f32_16x16x32_bf16 v[160:163], v[2:5], v[114:117], 0
	v_mfma_f32_16x16x32_bf16 v[164:167], v[10:13], v[114:117], 0
	v_mfma_f32_16x16x32_bf16 v[2:5], v[2:5], v[122:125], 0
	v_mfma_f32_16x16x32_bf16 v[10:13], v[10:13], v[122:125], 0
	v_mfma_f32_16x16x32_bf16 v[142:145], v[6:9], v[42:45], v[142:145]
	v_mfma_f32_16x16x32_bf16 v[148:151], v[14:17], v[42:45], v[148:151]
	v_mfma_f32_16x16x32_bf16 v[152:155], v[6:9], v[58:61], v[152:155]
	v_mfma_f32_16x16x32_bf16 v[156:159], v[14:17], v[58:61], v[156:159]
	v_mfma_f32_16x16x32_bf16 v[160:163], v[6:9], v[118:121], v[160:163]
	v_mfma_f32_16x16x32_bf16 v[164:167], v[14:17], v[118:121], v[164:167]
	v_mfma_f32_16x16x32_bf16 v[168:171], v[6:9], v[126:129], v[2:5]
	v_mfma_f32_16x16x32_bf16 v[172:175], v[14:17], v[126:129], v[10:13]
	s_setprio 0
	s_setprio 1
	v_mfma_f32_16x16x32_bf16 v[2:5], v[18:21], v[34:37], 0
	v_mfma_f32_16x16x32_bf16 v[6:9], v[26:29], v[34:37], 0
	v_mfma_f32_16x16x32_bf16 v[10:13], v[18:21], v[50:53], 0
	v_mfma_f32_16x16x32_bf16 v[14:17], v[26:29], v[50:53], 0
	v_mfma_f32_16x16x32_bf16 v[34:37], v[18:21], v[114:117], 0
	v_mfma_f32_16x16x32_bf16 v[50:53], v[26:29], v[114:117], 0
	v_mfma_f32_16x16x32_bf16 v[18:21], v[18:21], v[122:125], 0
	v_mfma_f32_16x16x32_bf16 v[26:29], v[26:29], v[122:125], 0
	v_mfma_f32_16x16x32_bf16 v[114:117], v[22:25], v[42:45], v[2:5]
	v_mfma_f32_16x16x32_bf16 v[122:125], v[30:33], v[42:45], v[6:9]
	v_mfma_f32_16x16x32_bf16 v[184:187], v[22:25], v[118:121], v[34:37]
	v_mfma_f32_16x16x32_bf16 v[118:121], v[30:33], v[118:121], v[50:53]
	v_mfma_f32_16x16x32_bf16 v[188:191], v[22:25], v[126:129], v[18:21]
	v_mfma_f32_16x16x32_bf16 v[126:129], v[30:33], v[126:129], v[26:29]
	s_setprio 2
	s_barrier
	v_mfma_f32_16x16x32_bf16 v[176:179], v[22:25], v[58:61], v[10:13]
	v_mfma_f32_16x16x32_bf16 v[180:183], v[30:33], v[58:61], v[14:17]
	s_setprio 0
	s_add_i32 s62, 0, 0x18000
	v_add_u32_e32 v2, s62, v140
	s_add_i32 s63, 0, 0x1c000
	ds_read_b128 v[192:195], v2
	ds_read_b128 v[196:199], v2 offset:1024
	ds_read_b128 v[200:203], v2 offset:2048
	ds_read_b128 v[204:207], v2 offset:3072
	v_add_u32_e32 v2, s63, v140
	ds_read_b128 v[208:211], v2
	ds_read_b128 v[212:215], v2 offset:1024
	ds_read_b128 v[216:219], v2 offset:2048
	ds_read_b128 v[220:223], v2 offset:3072
	s_mov_b32 m0, s49
	ds_read_b128 v[42:45], v141 offset:32768
	ds_read_b128 v[50:53], v141 offset:33792
	ds_read_b128 v[58:61], v141 offset:34816
	ds_read_b128 v[224:227], v141 offset:35840
	ds_read_b128 v[228:231], v141 offset:36864
	ds_read_b128 v[232:235], v141 offset:37888
	ds_read_b128 v[236:239], v141 offset:38912
	ds_read_b128 v[240:243], v141 offset:39936
	global_load_lds_dwordx4 v138, s[42:43]
	s_mov_b32 m0, s50
	s_nop 0
	global_load_lds_dwordx4 v132, s[42:43]
	s_waitcnt vmcnt(8)
	s_waitcnt lgkmcnt(0)
	s_barrier
	s_setprio 1
	s_waitcnt lgkmcnt(0)
	s_nop 5
	v_mfma_f32_16x16x32_bf16 v[2:5], v[192:195], v[42:45], v[66:69]
	v_mfma_f32_16x16x32_bf16 v[6:9], v[200:203], v[42:45], v[70:73]
	v_mfma_f32_16x16x32_bf16 v[10:13], v[192:195], v[58:61], v[74:77]
	v_mfma_f32_16x16x32_bf16 v[14:17], v[200:203], v[58:61], v[78:81]
	v_mfma_f32_16x16x32_bf16 v[18:21], v[192:195], v[228:231], v[82:85]
	v_mfma_f32_16x16x32_bf16 v[22:25], v[200:203], v[228:231], v[86:89]
	v_mfma_f32_16x16x32_bf16 v[26:29], v[192:195], v[236:239], v[90:93]
	v_mfma_f32_16x16x32_bf16 v[30:33], v[200:203], v[236:239], v[94:97]
	v_mfma_f32_16x16x32_bf16 v[2:5], v[196:199], v[50:53], v[2:5]
	v_mfma_f32_16x16x32_bf16 v[6:9], v[204:207], v[50:53], v[6:9]
	v_mfma_f32_16x16x32_bf16 v[10:13], v[196:199], v[224:227], v[10:13]
	v_mfma_f32_16x16x32_bf16 v[14:17], v[204:207], v[224:227], v[14:17]
	v_mfma_f32_16x16x32_bf16 v[18:21], v[196:199], v[232:235], v[18:21]
	v_mfma_f32_16x16x32_bf16 v[22:25], v[204:207], v[232:235], v[22:25]
	v_mfma_f32_16x16x32_bf16 v[26:29], v[196:199], v[240:243], v[26:29]
	v_mfma_f32_16x16x32_bf16 v[30:33], v[204:207], v[240:243], v[30:33]
	s_setprio 0
	s_setprio 1
	v_mfma_f32_16x16x32_bf16 v[34:37], v[208:211], v[42:45], v[98:101]
	v_mfma_f32_16x16x32_bf16 v[38:41], v[216:219], v[42:45], v[38:41]
	v_mfma_f32_16x16x32_bf16 v[34:37], v[212:215], v[50:53], v[34:37]
	v_mfma_f32_16x16x32_bf16 v[38:41], v[220:223], v[50:53], v[38:41]
	v_mfma_f32_16x16x32_bf16 v[42:45], v[208:211], v[58:61], v[102:105]
	v_mfma_f32_16x16x32_bf16 v[46:49], v[216:219], v[58:61], v[46:49]
	v_mfma_f32_16x16x32_bf16 v[50:53], v[208:211], v[228:231], v[106:109]
	v_mfma_f32_16x16x32_bf16 v[54:57], v[216:219], v[228:231], v[54:57]
	v_mfma_f32_16x16x32_bf16 v[58:61], v[208:211], v[236:239], v[110:113]
	v_mfma_f32_16x16x32_bf16 v[62:65], v[216:219], v[236:239], v[62:65]
	v_mfma_f32_16x16x32_bf16 v[42:45], v[212:215], v[224:227], v[42:45]
	v_mfma_f32_16x16x32_bf16 v[46:49], v[220:223], v[224:227], v[46:49]
	v_mfma_f32_16x16x32_bf16 v[50:53], v[212:215], v[232:235], v[50:53]
	v_mfma_f32_16x16x32_bf16 v[54:57], v[220:223], v[232:235], v[54:57]
	s_setprio 2
	s_barrier
	v_mfma_f32_16x16x32_bf16 v[58:61], v[212:215], v[240:243], v[58:61]
	v_mfma_f32_16x16x32_bf16 v[62:65], v[220:223], v[240:243], v[62:65]
	s_setprio 0
	s_add_i32 s62, s62, s46
	v_lshl_add_u64 v[66:67], v[136:137], 0, s[12:13]
	s_mov_b32 m0, s62
	ds_read_b128 v[102:105], v141 offset:49152
	ds_read_b128 v[106:109], v141 offset:50176
	ds_read_b128 v[110:113], v141 offset:51200
	ds_read_b128 v[224:227], v141 offset:52224
	ds_read_b128 v[228:231], v141 offset:53248
	ds_read_b128 v[232:235], v141 offset:54272
	ds_read_b128 v[236:239], v141 offset:55296
	ds_read_b128 v[240:243], v141 offset:56320
	global_load_lds_dwordx4 v[66:67], off
	v_lshl_add_u64 v[66:67], v[244:245], 0, s[12:13]
	s_add_i32 m0, s62, 0x2000
	s_add_i32 s62, s63, s46
	global_load_lds_dwordx4 v[66:67], off
	s_mov_b32 m0, s62
	v_lshl_add_u64 v[66:67], v[246:247], 0, s[12:13]
	global_load_lds_dwordx4 v130, s[44:45]
	s_add_i32 m0, s62, 0x2000
	s_nop 0
	global_load_lds_dwordx4 v134, s[44:45]
	s_mov_b32 m0, s54
	s_nop 0
	global_load_lds_dwordx4 v[66:67], off
	v_lshl_add_u64 v[66:67], v[248:249], 0, s[12:13]
	s_mov_b32 m0, s55
	s_nop 0
	global_load_lds_dwordx4 v[66:67], off
	s_waitcnt vmcnt(8)
	s_waitcnt lgkmcnt(0)
	s_barrier
	s_setprio 1
	s_waitcnt lgkmcnt(0)
	s_nop 5
	v_mfma_f32_16x16x32_bf16 v[66:69], v[192:195], v[102:105], v[142:145]
	v_mfma_f32_16x16x32_bf16 v[70:73], v[200:203], v[102:105], v[148:151]
	v_mfma_f32_16x16x32_bf16 v[74:77], v[192:195], v[110:113], v[152:155]
	v_mfma_f32_16x16x32_bf16 v[78:81], v[200:203], v[110:113], v[156:159]
	v_mfma_f32_16x16x32_bf16 v[82:85], v[192:195], v[228:231], v[160:163]
	v_mfma_f32_16x16x32_bf16 v[86:89], v[200:203], v[228:231], v[164:167]
	v_mfma_f32_16x16x32_bf16 v[90:93], v[192:195], v[236:239], v[168:171]
	v_mfma_f32_16x16x32_bf16 v[94:97], v[200:203], v[236:239], v[172:175]
	v_mfma_f32_16x16x32_bf16 v[66:69], v[196:199], v[106:109], v[66:69]
	v_mfma_f32_16x16x32_bf16 v[70:73], v[204:207], v[106:109], v[70:73]
	v_mfma_f32_16x16x32_bf16 v[74:77], v[196:199], v[224:227], v[74:77]
	v_mfma_f32_16x16x32_bf16 v[78:81], v[204:207], v[224:227], v[78:81]
	v_mfma_f32_16x16x32_bf16 v[82:85], v[196:199], v[232:235], v[82:85]
	v_mfma_f32_16x16x32_bf16 v[86:89], v[204:207], v[232:235], v[86:89]
	v_mfma_f32_16x16x32_bf16 v[90:93], v[196:199], v[240:243], v[90:93]
	v_mfma_f32_16x16x32_bf16 v[94:97], v[204:207], v[240:243], v[94:97]
	s_setprio 0
	s_setprio 1
	v_mfma_f32_16x16x32_bf16 v[98:101], v[208:211], v[102:105], v[114:117]
	v_mfma_f32_16x16x32_bf16 v[102:105], v[216:219], v[102:105], v[122:125]
	v_mfma_f32_16x16x32_bf16 v[98:101], v[212:215], v[106:109], v[98:101]
	v_mfma_f32_16x16x32_bf16 v[102:105], v[220:223], v[106:109], v[102:105]
	v_mfma_f32_16x16x32_bf16 v[106:109], v[208:211], v[110:113], v[176:179]
	v_mfma_f32_16x16x32_bf16 v[110:113], v[216:219], v[110:113], v[180:183]
	v_mfma_f32_16x16x32_bf16 v[114:117], v[208:211], v[228:231], v[184:187]
	v_mfma_f32_16x16x32_bf16 v[118:121], v[216:219], v[228:231], v[118:121]
	v_mfma_f32_16x16x32_bf16 v[122:125], v[208:211], v[236:239], v[188:191]
	v_mfma_f32_16x16x32_bf16 v[126:129], v[216:219], v[236:239], v[126:129]
	v_mfma_f32_16x16x32_bf16 v[106:109], v[212:215], v[224:227], v[106:109]
	v_mfma_f32_16x16x32_bf16 v[110:113], v[220:223], v[224:227], v[110:113]
	v_mfma_f32_16x16x32_bf16 v[114:117], v[212:215], v[232:235], v[114:117]
	v_mfma_f32_16x16x32_bf16 v[118:121], v[220:223], v[232:235], v[118:121]
	s_setprio 2
	s_barrier
	v_mfma_f32_16x16x32_bf16 v[122:125], v[212:215], v[240:243], v[122:125]
	v_mfma_f32_16x16x32_bf16 v[126:129], v[220:223], v[240:243], v[126:129]
	s_setprio 0
	s_add_i32 s27, s27, 2
	s_cmp_ge_i32 s27, s15
	s_cbranch_scc0 .LBB0_495
	v_mov_b32_e32 v136, v130
	s_branch .LBB0_498

.LBB0_499:
	v_add_u32_e32 v133, s58, v140
	ds_read_b128 v[142:145], v133
	ds_read_b128 v[148:151], v133 offset:1024
	ds_read_b128 v[152:155], v133 offset:2048
	ds_read_b128 v[156:159], v133 offset:3072
	v_add_u32_e32 v133, s59, v140
	ds_read_b128 v[160:163], v133
	ds_read_b128 v[164:167], v133 offset:1024
	ds_read_b128 v[168:171], v133 offset:2048
	ds_read_b128 v[172:175], v133 offset:3072
	s_add_u32 s38, s36, 0xfff80080
	s_addc_u32 s39, s37, -1
	s_cmp_eq_u32 s42, 4
	s_cselect_b32 s41, s31, s39
	s_cselect_b32 s40, s30, s38
	s_cselect_b32 s39, s35, s27
	s_cselect_b32 s38, s34, s15
	s_mov_b32 m0, s56
	v_add_u32_e32 v141, 0, v1
	ds_read_b128 v[176:179], v141
	ds_read_b128 v[180:183], v141 offset:1024
	ds_read_b128 v[184:187], v141 offset:2048
	ds_read_b128 v[188:191], v141 offset:3072
	ds_read_b128 v[192:195], v141 offset:4096
	ds_read_b128 v[196:199], v141 offset:5120
	ds_read_b128 v[200:203], v141 offset:6144
	ds_read_b128 v[204:207], v141 offset:7168
	global_load_lds_dwordx4 v130, s[36:37]
	s_mov_b32 m0, s57
	v_mov_b32_e32 v133, v131
	global_load_lds_dwordx4 v132, s[36:37]
	s_waitcnt vmcnt(8)
	s_waitcnt lgkmcnt(0)
	s_barrier
	s_setprio 1
	s_waitcnt lgkmcnt(0)
	s_nop 5
	v_mfma_f32_16x16x32_bf16 v[2:5], v[142:145], v[176:179], v[2:5]
	v_mfma_f32_16x16x32_bf16 v[2:5], v[148:151], v[180:183], v[2:5]
	v_mfma_f32_16x16x32_bf16 v[6:9], v[156:159], v[180:183], v[6:9]
	v_mfma_f32_16x16x32_bf16 v[6:9], v[152:155], v[176:179], v[6:9]
	v_mfma_f32_16x16x32_bf16 v[14:17], v[152:155], v[184:187], v[14:17]
	v_mfma_f32_16x16x32_bf16 v[14:17], v[156:159], v[188:191], v[14:17]
	v_mfma_f32_16x16x32_bf16 v[10:13], v[148:151], v[188:191], v[10:13]
	v_mfma_f32_16x16x32_bf16 v[10:13], v[142:145], v[184:187], v[10:13]
	v_mfma_f32_16x16x32_bf16 v[18:21], v[142:145], v[192:195], v[18:21]
	v_mfma_f32_16x16x32_bf16 v[18:21], v[148:151], v[196:199], v[18:21]
	v_mfma_f32_16x16x32_bf16 v[22:25], v[156:159], v[196:199], v[22:25]
	v_mfma_f32_16x16x32_bf16 v[22:25], v[152:155], v[192:195], v[22:25]
	v_mfma_f32_16x16x32_bf16 v[30:33], v[152:155], v[200:203], v[30:33]
	v_mfma_f32_16x16x32_bf16 v[30:33], v[156:159], v[204:207], v[30:33]
	v_mfma_f32_16x16x32_bf16 v[26:29], v[148:151], v[204:207], v[26:29]
	v_mfma_f32_16x16x32_bf16 v[26:29], v[142:145], v[200:203], v[26:29]
	s_setprio 0
	s_setprio 1
	v_mfma_f32_16x16x32_bf16 v[34:37], v[160:163], v[176:179], v[34:37]
	v_mfma_f32_16x16x32_bf16 v[34:37], v[164:167], v[180:183], v[34:37]
	v_mfma_f32_16x16x32_bf16 v[38:41], v[172:175], v[180:183], v[38:41]
	v_mfma_f32_16x16x32_bf16 v[38:41], v[168:171], v[176:179], v[38:41]
	v_mfma_f32_16x16x32_bf16 v[46:49], v[168:171], v[184:187], v[46:49]
	v_mfma_f32_16x16x32_bf16 v[46:49], v[172:175], v[188:191], v[46:49]
	v_mfma_f32_16x16x32_bf16 v[42:45], v[164:167], v[188:191], v[42:45]
	v_mfma_f32_16x16x32_bf16 v[42:45], v[160:163], v[184:187], v[42:45]
	v_mfma_f32_16x16x32_bf16 v[50:53], v[160:163], v[192:195], v[50:53]
	v_mfma_f32_16x16x32_bf16 v[50:53], v[164:167], v[196:199], v[50:53]
	v_mfma_f32_16x16x32_bf16 v[54:57], v[172:175], v[196:199], v[54:57]
	v_mfma_f32_16x16x32_bf16 v[54:57], v[168:171], v[192:195], v[54:57]
	v_mfma_f32_16x16x32_bf16 v[62:65], v[168:171], v[200:203], v[62:65]
	v_mfma_f32_16x16x32_bf16 v[62:65], v[172:175], v[204:207], v[62:65]
	s_setprio 2
	s_barrier
	v_mfma_f32_16x16x32_bf16 v[58:61], v[164:167], v[204:207], v[58:61]
	v_mfma_f32_16x16x32_bf16 v[58:61], v[160:163], v[200:203], v[58:61]
	s_setprio 0
	s_add_i32 s43, s58, s46
	s_mov_b32 m0, s43
	ds_read_b128 v[176:179], v141 offset:16384
	ds_read_b128 v[180:183], v141 offset:17408
	ds_read_b128 v[184:187], v141 offset:18432
	ds_read_b128 v[188:191], v141 offset:19456
	ds_read_b128 v[192:195], v141 offset:20480
	ds_read_b128 v[196:199], v141 offset:21504
	ds_read_b128 v[200:203], v141 offset:22528
	ds_read_b128 v[204:207], v141 offset:23552
	global_load_lds_dwordx4 v136, s[38:39]
	s_add_i32 m0, s43, 0x2000
	s_add_u32 s44, s38, 0x400000
	s_addc_u32 s45, s39, 0
	s_add_i32 s43, s59, s46
	global_load_lds_dwordx4 v134, s[38:39]
	s_mov_b32 m0, s43
	v_mov_b32_e32 v137, v131
	global_load_lds_dwordx4 v136, s[44:45]
	s_add_i32 m0, s43, 0x2000
	v_mov_b32_e32 v135, v131
	global_load_lds_dwordx4 v134, s[44:45]
	s_mov_b32 m0, s47
	v_lshl_add_u64 v[138:139], s[38:39], 0, v[136:137]
	global_load_lds_dwordx4 v130, s[40:41]
	s_mov_b32 m0, s48
	v_lshl_add_u64 v[208:209], s[38:39], 0, v[134:135]
	global_load_lds_dwordx4 v132, s[40:41]
	s_waitcnt vmcnt(8)
	s_waitcnt lgkmcnt(0)
	v_lshl_add_u64 v[210:211], s[40:41], 0, v[130:131]
	v_lshl_add_u64 v[212:213], s[40:41], 0, v[132:133]
	s_barrier
	s_setprio 1
	s_waitcnt lgkmcnt(0)
	s_nop 5
	v_mfma_f32_16x16x32_bf16 v[66:69], v[142:145], v[176:179], v[66:69]
	v_mfma_f32_16x16x32_bf16 v[66:69], v[148:151], v[180:183], v[66:69]
	v_mfma_f32_16x16x32_bf16 v[70:73], v[156:159], v[180:183], v[70:73]
	v_mfma_f32_16x16x32_bf16 v[70:73], v[152:155], v[176:179], v[70:73]
	v_mfma_f32_16x16x32_bf16 v[78:81], v[152:155], v[184:187], v[78:81]
	v_mfma_f32_16x16x32_bf16 v[78:81], v[156:159], v[188:191], v[78:81]
	v_mfma_f32_16x16x32_bf16 v[74:77], v[148:151], v[188:191], v[74:77]
	v_mfma_f32_16x16x32_bf16 v[74:77], v[142:145], v[184:187], v[74:77]
	v_mfma_f32_16x16x32_bf16 v[82:85], v[142:145], v[192:195], v[82:85]
	v_mfma_f32_16x16x32_bf16 v[82:85], v[148:151], v[196:199], v[82:85]
	v_mfma_f32_16x16x32_bf16 v[86:89], v[156:159], v[196:199], v[86:89]
	v_mfma_f32_16x16x32_bf16 v[86:89], v[152:155], v[192:195], v[86:89]
	v_mfma_f32_16x16x32_bf16 v[94:97], v[152:155], v[200:203], v[94:97]
	v_mfma_f32_16x16x32_bf16 v[94:97], v[156:159], v[204:207], v[94:97]
	v_mfma_f32_16x16x32_bf16 v[90:93], v[148:151], v[204:207], v[90:93]
	v_mfma_f32_16x16x32_bf16 v[90:93], v[142:145], v[200:203], v[90:93]
	s_setprio 0
	s_setprio 1
	v_mfma_f32_16x16x32_bf16 v[98:101], v[160:163], v[176:179], v[98:101]
	v_mfma_f32_16x16x32_bf16 v[98:101], v[164:167], v[180:183], v[98:101]
	v_mfma_f32_16x16x32_bf16 v[102:105], v[172:175], v[180:183], v[102:105]
	v_mfma_f32_16x16x32_bf16 v[102:105], v[168:171], v[176:179], v[102:105]
	v_mfma_f32_16x16x32_bf16 v[110:113], v[168:171], v[184:187], v[110:113]
	v_mfma_f32_16x16x32_bf16 v[110:113], v[172:175], v[188:191], v[110:113]
	v_mfma_f32_16x16x32_bf16 v[106:109], v[164:167], v[188:191], v[106:109]
	v_mfma_f32_16x16x32_bf16 v[106:109], v[160:163], v[184:187], v[106:109]
	v_mfma_f32_16x16x32_bf16 v[114:117], v[160:163], v[192:195], v[114:117]
	v_mfma_f32_16x16x32_bf16 v[114:117], v[164:167], v[196:199], v[114:117]
	v_mfma_f32_16x16x32_bf16 v[118:121], v[172:175], v[196:199], v[118:121]
	v_mfma_f32_16x16x32_bf16 v[118:121], v[168:171], v[192:195], v[118:121]
	v_mfma_f32_16x16x32_bf16 v[126:129], v[168:171], v[200:203], v[126:129]
	v_mfma_f32_16x16x32_bf16 v[126:129], v[172:175], v[204:207], v[126:129]
	s_setprio 2
	s_barrier
	v_mfma_f32_16x16x32_bf16 v[122:125], v[164:167], v[204:207], v[122:125]
	v_mfma_f32_16x16x32_bf16 v[122:125], v[160:163], v[200:203], v[122:125]
	s_setprio 0
	s_add_i32 s43, 0, 0x18000
	v_add_u32_e32 v135, s43, v140
	s_add_i32 s44, 0, 0x1c000
	ds_read_b128 v[142:145], v135
	ds_read_b128 v[148:151], v135 offset:1024
	ds_read_b128 v[152:155], v135 offset:2048
	ds_read_b128 v[156:159], v135 offset:3072
	v_add_u32_e32 v135, s44, v140
	ds_read_b128 v[160:163], v135
	ds_read_b128 v[164:167], v135 offset:1024
	ds_read_b128 v[168:171], v135 offset:2048
	ds_read_b128 v[172:175], v135 offset:3072
	s_add_u32 s40, s40, 0x80000
	s_addc_u32 s41, s41, 0
	s_mov_b32 m0, s49
	ds_read_b128 v[176:179], v141 offset:32768
	ds_read_b128 v[180:183], v141 offset:33792
	ds_read_b128 v[184:187], v141 offset:34816
	ds_read_b128 v[188:191], v141 offset:35840
	ds_read_b128 v[192:195], v141 offset:36864
	ds_read_b128 v[196:199], v141 offset:37888
	ds_read_b128 v[200:203], v141 offset:38912
	ds_read_b128 v[204:207], v141 offset:39936
	global_load_lds_dwordx4 v130, s[40:41]
	s_mov_b32 m0, s50
	s_nop 0
	global_load_lds_dwordx4 v132, s[40:41]
	s_waitcnt vmcnt(8)
	s_waitcnt lgkmcnt(0)
	s_barrier
	s_setprio 1
	s_waitcnt lgkmcnt(0)
	s_nop 5
	v_mfma_f32_16x16x32_bf16 v[2:5], v[142:145], v[176:179], v[2:5]
	v_mfma_f32_16x16x32_bf16 v[2:5], v[148:151], v[180:183], v[2:5]
	v_mfma_f32_16x16x32_bf16 v[6:9], v[156:159], v[180:183], v[6:9]
	v_mfma_f32_16x16x32_bf16 v[6:9], v[152:155], v[176:179], v[6:9]
	v_mfma_f32_16x16x32_bf16 v[14:17], v[152:155], v[184:187], v[14:17]
	v_mfma_f32_16x16x32_bf16 v[14:17], v[156:159], v[188:191], v[14:17]
	v_mfma_f32_16x16x32_bf16 v[10:13], v[148:151], v[188:191], v[10:13]
	v_mfma_f32_16x16x32_bf16 v[10:13], v[142:145], v[184:187], v[10:13]
	v_mfma_f32_16x16x32_bf16 v[18:21], v[142:145], v[192:195], v[18:21]
	v_mfma_f32_16x16x32_bf16 v[18:21], v[148:151], v[196:199], v[18:21]
	v_mfma_f32_16x16x32_bf16 v[22:25], v[156:159], v[196:199], v[22:25]
	v_mfma_f32_16x16x32_bf16 v[22:25], v[152:155], v[192:195], v[22:25]
	v_mfma_f32_16x16x32_bf16 v[30:33], v[152:155], v[200:203], v[30:33]
	v_mfma_f32_16x16x32_bf16 v[30:33], v[156:159], v[204:207], v[30:33]
	v_mfma_f32_16x16x32_bf16 v[26:29], v[148:151], v[204:207], v[26:29]
	v_mfma_f32_16x16x32_bf16 v[26:29], v[142:145], v[200:203], v[26:29]
	s_setprio 0
	s_setprio 1
	v_mfma_f32_16x16x32_bf16 v[34:37], v[160:163], v[176:179], v[34:37]
	v_mfma_f32_16x16x32_bf16 v[34:37], v[164:167], v[180:183], v[34:37]
	v_mfma_f32_16x16x32_bf16 v[38:41], v[172:175], v[180:183], v[38:41]
	v_mfma_f32_16x16x32_bf16 v[38:41], v[168:171], v[176:179], v[38:41]
	v_mfma_f32_16x16x32_bf16 v[46:49], v[168:171], v[184:187], v[46:49]
	v_mfma_f32_16x16x32_bf16 v[46:49], v[172:175], v[188:191], v[46:49]
	v_mfma_f32_16x16x32_bf16 v[42:45], v[164:167], v[188:191], v[42:45]
	v_mfma_f32_16x16x32_bf16 v[42:45], v[160:163], v[184:187], v[42:45]
	v_mfma_f32_16x16x32_bf16 v[50:53], v[160:163], v[192:195], v[50:53]
	v_mfma_f32_16x16x32_bf16 v[50:53], v[164:167], v[196:199], v[50:53]
	v_mfma_f32_16x16x32_bf16 v[54:57], v[172:175], v[196:199], v[54:57]
	v_mfma_f32_16x16x32_bf16 v[54:57], v[168:171], v[192:195], v[54:57]
	v_mfma_f32_16x16x32_bf16 v[62:65], v[168:171], v[200:203], v[62:65]
	v_mfma_f32_16x16x32_bf16 v[62:65], v[172:175], v[204:207], v[62:65]
	s_setprio 2
	s_barrier
	v_mfma_f32_16x16x32_bf16 v[58:61], v[164:167], v[204:207], v[58:61]
	v_mfma_f32_16x16x32_bf16 v[58:61], v[160:163], v[200:203], v[58:61]
	s_setprio 0
	s_add_i32 s40, s43, s46
	v_lshl_add_u64 v[138:139], v[138:139], 0, s[6:7]
	s_mov_b32 m0, s40
	ds_read_b128 v[176:179], v141 offset:49152
	ds_read_b128 v[180:183], v141 offset:50176
	ds_read_b128 v[184:187], v141 offset:51200
	ds_read_b128 v[188:191], v141 offset:52224
	ds_read_b128 v[192:195], v141 offset:53248
	ds_read_b128 v[196:199], v141 offset:54272
	ds_read_b128 v[200:203], v141 offset:55296
	ds_read_b128 v[204:207], v141 offset:56320
	global_load_lds_dwordx4 v[138:139], off
	s_add_i32 m0, s40, 0x2000
	s_add_u32 s38, s38, 0x400080
	v_lshl_add_u64 v[138:139], v[208:209], 0, s[6:7]
	s_addc_u32 s39, s39, 0
	s_add_i32 s40, s44, s46
	global_load_lds_dwordx4 v[138:139], off
	s_mov_b32 m0, s40
	v_lshl_add_u64 v[138:139], v[210:211], 0, s[6:7]
	global_load_lds_dwordx4 v136, s[38:39]
	s_add_i32 m0, s40, 0x2000
	s_nop 0
	global_load_lds_dwordx4 v134, s[38:39]
	s_mov_b32 m0, s54
	s_nop 0
	global_load_lds_dwordx4 v[138:139], off
	v_lshl_add_u64 v[138:139], v[212:213], 0, s[6:7]
	s_mov_b32 m0, s55
	s_nop 0
	global_load_lds_dwordx4 v[138:139], off
	s_waitcnt vmcnt(8)
	s_waitcnt lgkmcnt(0)
	s_barrier
	s_setprio 1
	s_waitcnt lgkmcnt(0)
	s_nop 5
	v_mfma_f32_16x16x32_bf16 v[66:69], v[142:145], v[176:179], v[66:69]
	v_mfma_f32_16x16x32_bf16 v[66:69], v[148:151], v[180:183], v[66:69]
	v_mfma_f32_16x16x32_bf16 v[70:73], v[156:159], v[180:183], v[70:73]
	v_mfma_f32_16x16x32_bf16 v[70:73], v[152:155], v[176:179], v[70:73]
	v_mfma_f32_16x16x32_bf16 v[78:81], v[152:155], v[184:187], v[78:81]
	v_mfma_f32_16x16x32_bf16 v[78:81], v[156:159], v[188:191], v[78:81]
	v_mfma_f32_16x16x32_bf16 v[74:77], v[148:151], v[188:191], v[74:77]
	v_mfma_f32_16x16x32_bf16 v[74:77], v[142:145], v[184:187], v[74:77]
	v_mfma_f32_16x16x32_bf16 v[82:85], v[142:145], v[192:195], v[82:85]
	v_mfma_f32_16x16x32_bf16 v[82:85], v[148:151], v[196:199], v[82:85]
	v_mfma_f32_16x16x32_bf16 v[86:89], v[156:159], v[196:199], v[86:89]
	v_mfma_f32_16x16x32_bf16 v[86:89], v[152:155], v[192:195], v[86:89]
	v_mfma_f32_16x16x32_bf16 v[94:97], v[152:155], v[200:203], v[94:97]
	v_mfma_f32_16x16x32_bf16 v[94:97], v[156:159], v[204:207], v[94:97]
	v_mfma_f32_16x16x32_bf16 v[90:93], v[148:151], v[204:207], v[90:93]
	v_mfma_f32_16x16x32_bf16 v[90:93], v[142:145], v[200:203], v[90:93]
	s_setprio 0
	s_setprio 1
	v_mfma_f32_16x16x32_bf16 v[98:101], v[160:163], v[176:179], v[98:101]
	v_mfma_f32_16x16x32_bf16 v[98:101], v[164:167], v[180:183], v[98:101]
	v_mfma_f32_16x16x32_bf16 v[102:105], v[172:175], v[180:183], v[102:105]
	v_mfma_f32_16x16x32_bf16 v[102:105], v[168:171], v[176:179], v[102:105]
	v_mfma_f32_16x16x32_bf16 v[110:113], v[168:171], v[184:187], v[110:113]
	v_mfma_f32_16x16x32_bf16 v[110:113], v[172:175], v[188:191], v[110:113]
	v_mfma_f32_16x16x32_bf16 v[106:109], v[164:167], v[188:191], v[106:109]
	v_mfma_f32_16x16x32_bf16 v[106:109], v[160:163], v[184:187], v[106:109]
	v_mfma_f32_16x16x32_bf16 v[114:117], v[160:163], v[192:195], v[114:117]
	v_mfma_f32_16x16x32_bf16 v[114:117], v[164:167], v[196:199], v[114:117]
	v_mfma_f32_16x16x32_bf16 v[118:121], v[172:175], v[196:199], v[118:121]
	v_mfma_f32_16x16x32_bf16 v[118:121], v[168:171], v[192:195], v[118:121]
	v_mfma_f32_16x16x32_bf16 v[126:129], v[168:171], v[200:203], v[126:129]
	v_mfma_f32_16x16x32_bf16 v[126:129], v[172:175], v[204:207], v[126:129]
	s_setprio 2
	s_barrier
	v_mfma_f32_16x16x32_bf16 v[122:125], v[164:167], v[204:207], v[122:125]
	v_mfma_f32_16x16x32_bf16 v[122:125], v[160:163], v[200:203], v[122:125]
	s_setprio 0
	s_add_i32 s42, s42, 2
	s_add_u32 s36, s36, 0x100
	s_addc_u32 s37, s37, 0
	s_add_u32 s15, s15, 0x100
	s_addc_u32 s27, s27, 0
	s_cmp_gt_u32 s42, 5
	s_cbranch_scc0 .LBB0_499
	s_and_b64 vcc, exec, s[8:9]
	s_cbranch_vccz .LBB0_502
	s_barrier

.LBB0_528:
	s_add_i32 s53, 0, 0x10000
	s_add_i32 s72, 0, 0x14000
	v_add_u32_e32 v16, s53, v147
	v_add_u32_e32 v32, s72, v147
	ds_read_b128 v[4:7], v16
	ds_read_b128 v[8:11], v16 offset:1024
	ds_read_b128 v[12:15], v16 offset:2048
	ds_read_b128 v[16:19], v16 offset:3072
	ds_read_b128 v[20:23], v32
	ds_read_b128 v[24:27], v32 offset:1024
	ds_read_b128 v[28:31], v32 offset:2048
	ds_read_b128 v[32:35], v32 offset:3072
	v_add_u32_e32 v231, 0, v146
	ds_read_b128 v[36:39], v231
	ds_read_b128 v[40:43], v231 offset:1024
	ds_read_b128 v[44:47], v231 offset:2048
	ds_read_b128 v[48:51], v231 offset:3072
	ds_read_b128 v[52:55], v231 offset:4096
	ds_read_b128 v[56:59], v231 offset:5120
	ds_read_b128 v[60:63], v231 offset:6144
	ds_read_b128 v[64:67], v231 offset:7168
	s_waitcnt vmcnt(8)
	s_waitcnt lgkmcnt(0)
	s_barrier
	s_setprio 1
	s_waitcnt lgkmcnt(0)
	s_nop 5
	v_mfma_f32_16x16x32_f16 v[68:71], v[4:7], v[36:39], 0
	v_mfma_f32_16x16x32_f16 v[68:71], v[8:11], v[40:43], v[68:71]
	v_mfma_f32_16x16x32_f16 v[72:75], v[12:15], v[36:39], 0
	v_mfma_f32_16x16x32_f16 v[72:75], v[16:19], v[40:43], v[72:75]
	v_mfma_f32_16x16x32_f16 v[80:83], v[12:15], v[44:47], 0
	v_mfma_f32_16x16x32_f16 v[80:83], v[16:19], v[48:51], v[80:83]
	v_mfma_f32_16x16x32_f16 v[76:79], v[4:7], v[44:47], 0
	v_mfma_f32_16x16x32_f16 v[76:79], v[8:11], v[48:51], v[76:79]
	v_mfma_f32_16x16x32_f16 v[84:87], v[4:7], v[52:55], 0
	v_mfma_f32_16x16x32_f16 v[84:87], v[8:11], v[56:59], v[84:87]
	v_mfma_f32_16x16x32_f16 v[88:91], v[12:15], v[52:55], 0
	v_mfma_f32_16x16x32_f16 v[88:91], v[16:19], v[56:59], v[88:91]
	v_mfma_f32_16x16x32_f16 v[96:99], v[12:15], v[60:63], 0
	v_mfma_f32_16x16x32_f16 v[96:99], v[16:19], v[64:67], v[96:99]
	v_mfma_f32_16x16x32_f16 v[92:95], v[4:7], v[60:63], 0
	v_mfma_f32_16x16x32_f16 v[92:95], v[8:11], v[64:67], v[92:95]
	s_setprio 0
	s_setprio 1
	v_mfma_f32_16x16x32_f16 v[100:103], v[20:23], v[36:39], 0
	v_mfma_f32_16x16x32_f16 v[36:39], v[28:31], v[36:39], 0
	v_mfma_f32_16x16x32_f16 v[104:107], v[20:23], v[44:47], 0
	v_mfma_f32_16x16x32_f16 v[44:47], v[28:31], v[44:47], 0
	v_mfma_f32_16x16x32_f16 v[108:111], v[20:23], v[52:55], 0
	v_mfma_f32_16x16x32_f16 v[52:55], v[28:31], v[52:55], 0
	v_mfma_f32_16x16x32_f16 v[112:115], v[20:23], v[60:63], 0
	v_mfma_f32_16x16x32_f16 v[60:63], v[28:31], v[60:63], 0
	v_mfma_f32_16x16x32_f16 v[100:103], v[24:27], v[40:43], v[100:103]
	v_mfma_f32_16x16x32_f16 v[40:43], v[32:35], v[40:43], v[36:39]
	v_mfma_f32_16x16x32_f16 v[104:107], v[24:27], v[48:51], v[104:107]
	v_mfma_f32_16x16x32_f16 v[48:51], v[32:35], v[48:51], v[44:47]
	v_mfma_f32_16x16x32_f16 v[108:111], v[24:27], v[56:59], v[108:111]
	v_mfma_f32_16x16x32_f16 v[56:59], v[32:35], v[56:59], v[52:55]
	s_setprio 2
	s_barrier
	v_mfma_f32_16x16x32_f16 v[112:115], v[24:27], v[64:67], v[112:115]
	v_mfma_f32_16x16x32_f16 v[64:67], v[32:35], v[64:67], v[60:63]
	s_setprio 0
	v_lshl_add_u64 v[136:137], s[6:7], 0, v[2:3]
	s_add_i32 s53, s53, s38
	v_mov_b32_e32 v135, v3
	v_lshl_add_u64 v[140:141], v[136:137], 0, s[74:75]
	s_mov_b32 m0, s53
	v_lshl_add_u64 v[144:145], s[6:7], 0, v[134:135]
	ds_read_b128 v[36:39], v231 offset:16384
	ds_read_b128 v[44:47], v231 offset:17408
	ds_read_b128 v[52:55], v231 offset:18432
	ds_read_b128 v[60:63], v231 offset:19456
	ds_read_b128 v[116:119], v231 offset:20480
	ds_read_b128 v[120:123], v231 offset:21504
	ds_read_b128 v[124:127], v231 offset:22528
	ds_read_b128 v[128:131], v231 offset:23552
	global_load_lds_dwordx4 v[140:141], off
	v_lshl_add_u64 v[140:141], v[144:145], 0, s[74:75]
	s_add_i32 m0, s53, 0x2000
	s_add_i32 s53, s72, s38
	global_load_lds_dwordx4 v[140:141], off
	s_mov_b32 m0, s53
	v_mov_b32_e32 v139, v3
	global_load_lds_dwordx4 v2, s[16:17]
	s_add_i32 m0, s53, 0x2000
	v_lshl_add_u64 v[248:249], s[8:9], 0, v[138:139]
	v_mov_b32_e32 v133, v3
	global_load_lds_dwordx4 v134, s[16:17]
	v_lshl_add_u64 v[140:141], v[248:249], 0, s[74:75]
	s_mov_b32 m0, s58
	v_lshl_add_u64 v[250:251], s[8:9], 0, v[132:133]
	global_load_lds_dwordx4 v[140:141], off
	v_lshl_add_u64 v[140:141], v[250:251], 0, s[74:75]
	s_mov_b32 m0, s59
	s_nop 0
	global_load_lds_dwordx4 v[140:141], off
	s_waitcnt vmcnt(8)
	s_waitcnt lgkmcnt(0)
	s_barrier
	s_setprio 1
	s_waitcnt lgkmcnt(0)
	s_nop 5
	v_mfma_f32_16x16x32_f16 v[140:143], v[4:7], v[36:39], 0
	v_mfma_f32_16x16x32_f16 v[148:151], v[12:15], v[36:39], 0
	v_mfma_f32_16x16x32_f16 v[152:155], v[4:7], v[52:55], 0
	v_mfma_f32_16x16x32_f16 v[156:159], v[12:15], v[52:55], 0
	v_mfma_f32_16x16x32_f16 v[160:163], v[4:7], v[116:119], 0
	v_mfma_f32_16x16x32_f16 v[164:167], v[12:15], v[116:119], 0
	v_mfma_f32_16x16x32_f16 v[4:7], v[4:7], v[124:127], 0
	v_mfma_f32_16x16x32_f16 v[12:15], v[12:15], v[124:127], 0
	v_mfma_f32_16x16x32_f16 v[140:143], v[8:11], v[44:47], v[140:143]
	v_mfma_f32_16x16x32_f16 v[148:151], v[16:19], v[44:47], v[148:151]
	v_mfma_f32_16x16x32_f16 v[152:155], v[8:11], v[60:63], v[152:155]
	v_mfma_f32_16x16x32_f16 v[156:159], v[16:19], v[60:63], v[156:159]
	v_mfma_f32_16x16x32_f16 v[160:163], v[8:11], v[120:123], v[160:163]
	v_mfma_f32_16x16x32_f16 v[164:167], v[16:19], v[120:123], v[164:167]
	v_mfma_f32_16x16x32_f16 v[168:171], v[8:11], v[128:131], v[4:7]
	v_mfma_f32_16x16x32_f16 v[172:175], v[16:19], v[128:131], v[12:15]
	s_setprio 0
	s_setprio 1
	v_mfma_f32_16x16x32_f16 v[4:7], v[20:23], v[36:39], 0
	v_mfma_f32_16x16x32_f16 v[8:11], v[28:31], v[36:39], 0
	v_mfma_f32_16x16x32_f16 v[12:15], v[20:23], v[52:55], 0
	v_mfma_f32_16x16x32_f16 v[16:19], v[28:31], v[52:55], 0
	v_mfma_f32_16x16x32_f16 v[36:39], v[20:23], v[116:119], 0
	v_mfma_f32_16x16x32_f16 v[52:55], v[28:31], v[116:119], 0
	v_mfma_f32_16x16x32_f16 v[20:23], v[20:23], v[124:127], 0
	v_mfma_f32_16x16x32_f16 v[28:31], v[28:31], v[124:127], 0
	v_mfma_f32_16x16x32_f16 v[116:119], v[24:27], v[44:47], v[4:7]
	v_mfma_f32_16x16x32_f16 v[124:127], v[32:35], v[44:47], v[8:11]
	v_mfma_f32_16x16x32_f16 v[184:187], v[24:27], v[120:123], v[36:39]
	v_mfma_f32_16x16x32_f16 v[120:123], v[32:35], v[120:123], v[52:55]
	v_mfma_f32_16x16x32_f16 v[188:191], v[24:27], v[128:131], v[20:23]
	v_mfma_f32_16x16x32_f16 v[128:131], v[32:35], v[128:131], v[28:31]
	s_setprio 2
	s_barrier
	v_mfma_f32_16x16x32_f16 v[176:179], v[24:27], v[60:63], v[12:15]
	v_mfma_f32_16x16x32_f16 v[180:183], v[32:35], v[60:63], v[16:19]
	s_setprio 0
	s_add_i32 s53, 0, 0x18000
	v_add_u32_e32 v4, s53, v147
	s_add_i32 s72, 0, 0x1c000
	ds_read_b128 v[192:195], v4
	ds_read_b128 v[196:199], v4 offset:1024
	ds_read_b128 v[200:203], v4 offset:2048
	ds_read_b128 v[204:207], v4 offset:3072
	v_add_u32_e32 v4, s72, v147
	ds_read_b128 v[208:211], v4
	ds_read_b128 v[212:215], v4 offset:1024
	ds_read_b128 v[216:219], v4 offset:2048
	ds_read_b128 v[220:223], v4 offset:3072
	s_mov_b32 m0, s60
	ds_read_b128 v[44:47], v231 offset:32768
	ds_read_b128 v[52:55], v231 offset:33792
	ds_read_b128 v[60:63], v231 offset:34816
	ds_read_b128 v[224:227], v231 offset:35840
	ds_read_b128 v[232:235], v231 offset:36864
	ds_read_b128 v[236:239], v231 offset:37888
	ds_read_b128 v[240:243], v231 offset:38912
	ds_read_b128 v[244:247], v231 offset:39936
	global_load_lds_dwordx4 v138, s[26:27]
	s_mov_b32 m0, s61
	s_nop 0
	global_load_lds_dwordx4 v132, s[26:27]
	s_waitcnt vmcnt(8)
	s_waitcnt lgkmcnt(0)
	s_barrier
	s_setprio 1
	s_waitcnt lgkmcnt(0)
	s_nop 5
	v_mfma_f32_16x16x32_f16 v[4:7], v[192:195], v[44:47], v[68:71]
	v_mfma_f32_16x16x32_f16 v[8:11], v[200:203], v[44:47], v[72:75]
	v_mfma_f32_16x16x32_f16 v[12:15], v[192:195], v[60:63], v[76:79]
	v_mfma_f32_16x16x32_f16 v[16:19], v[200:203], v[60:63], v[80:83]
	v_mfma_f32_16x16x32_f16 v[20:23], v[192:195], v[232:235], v[84:87]
	v_mfma_f32_16x16x32_f16 v[24:27], v[200:203], v[232:235], v[88:91]
	v_mfma_f32_16x16x32_f16 v[28:31], v[192:195], v[240:243], v[92:95]
	v_mfma_f32_16x16x32_f16 v[32:35], v[200:203], v[240:243], v[96:99]
	v_mfma_f32_16x16x32_f16 v[4:7], v[196:199], v[52:55], v[4:7]
	v_mfma_f32_16x16x32_f16 v[8:11], v[204:207], v[52:55], v[8:11]
	v_mfma_f32_16x16x32_f16 v[12:15], v[196:199], v[224:227], v[12:15]
	v_mfma_f32_16x16x32_f16 v[16:19], v[204:207], v[224:227], v[16:19]
	v_mfma_f32_16x16x32_f16 v[20:23], v[196:199], v[236:239], v[20:23]
	v_mfma_f32_16x16x32_f16 v[24:27], v[204:207], v[236:239], v[24:27]
	v_mfma_f32_16x16x32_f16 v[28:31], v[196:199], v[244:247], v[28:31]
	v_mfma_f32_16x16x32_f16 v[32:35], v[204:207], v[244:247], v[32:35]
	s_setprio 0
	s_setprio 1
	v_mfma_f32_16x16x32_f16 v[36:39], v[208:211], v[44:47], v[100:103]
	v_mfma_f32_16x16x32_f16 v[40:43], v[216:219], v[44:47], v[40:43]
	v_mfma_f32_16x16x32_f16 v[36:39], v[212:215], v[52:55], v[36:39]
	v_mfma_f32_16x16x32_f16 v[40:43], v[220:223], v[52:55], v[40:43]
	v_mfma_f32_16x16x32_f16 v[44:47], v[208:211], v[60:63], v[104:107]
	v_mfma_f32_16x16x32_f16 v[48:51], v[216:219], v[60:63], v[48:51]
	v_mfma_f32_16x16x32_f16 v[52:55], v[208:211], v[232:235], v[108:111]
	v_mfma_f32_16x16x32_f16 v[56:59], v[216:219], v[232:235], v[56:59]
	v_mfma_f32_16x16x32_f16 v[60:63], v[208:211], v[240:243], v[112:115]
	v_mfma_f32_16x16x32_f16 v[64:67], v[216:219], v[240:243], v[64:67]
	v_mfma_f32_16x16x32_f16 v[44:47], v[212:215], v[224:227], v[44:47]
	v_mfma_f32_16x16x32_f16 v[48:51], v[220:223], v[224:227], v[48:51]
	v_mfma_f32_16x16x32_f16 v[52:55], v[212:215], v[236:239], v[52:55]
	v_mfma_f32_16x16x32_f16 v[56:59], v[220:223], v[236:239], v[56:59]
	s_setprio 2
	s_barrier
	v_mfma_f32_16x16x32_f16 v[60:63], v[212:215], v[244:247], v[60:63]
	v_mfma_f32_16x16x32_f16 v[64:67], v[220:223], v[244:247], v[64:67]
	s_setprio 0
	s_add_i32 s53, s53, s38
	v_lshl_add_u64 v[68:69], v[136:137], 0, s[24:25]
	s_mov_b32 m0, s53
	ds_read_b128 v[104:107], v231 offset:49152
	ds_read_b128 v[108:111], v231 offset:50176
	ds_read_b128 v[112:115], v231 offset:51200
	ds_read_b128 v[224:227], v231 offset:52224
	ds_read_b128 v[232:235], v231 offset:53248
	ds_read_b128 v[236:239], v231 offset:54272
	ds_read_b128 v[240:243], v231 offset:55296
	ds_read_b128 v[244:247], v231 offset:56320
	global_load_lds_dwordx4 v[68:69], off
	v_lshl_add_u64 v[68:69], v[144:145], 0, s[24:25]
	s_add_i32 m0, s53, 0x2000
	s_add_i32 s53, s72, s38
	global_load_lds_dwordx4 v[68:69], off
	s_mov_b32 m0, s53
	v_lshl_add_u64 v[68:69], v[248:249], 0, s[24:25]
	global_load_lds_dwordx4 v2, s[28:29]
	s_add_i32 m0, s53, 0x2000
	s_nop 0
	global_load_lds_dwordx4 v134, s[28:29]
	s_mov_b32 m0, s64
	s_nop 0
	global_load_lds_dwordx4 v[68:69], off
	v_lshl_add_u64 v[68:69], v[250:251], 0, s[24:25]
	s_mov_b32 m0, s65
	s_nop 0
	global_load_lds_dwordx4 v[68:69], off
	s_waitcnt vmcnt(8)
	s_waitcnt lgkmcnt(0)
	s_barrier
	s_setprio 1
	s_waitcnt lgkmcnt(0)
	s_nop 5
	v_mfma_f32_16x16x32_f16 v[68:71], v[192:195], v[104:107], v[140:143]
	v_mfma_f32_16x16x32_f16 v[72:75], v[200:203], v[104:107], v[148:151]
	v_mfma_f32_16x16x32_f16 v[76:79], v[192:195], v[112:115], v[152:155]
	v_mfma_f32_16x16x32_f16 v[80:83], v[200:203], v[112:115], v[156:159]
	v_mfma_f32_16x16x32_f16 v[84:87], v[192:195], v[232:235], v[160:163]
	v_mfma_f32_16x16x32_f16 v[88:91], v[200:203], v[232:235], v[164:167]
	v_mfma_f32_16x16x32_f16 v[92:95], v[192:195], v[240:243], v[168:171]
	v_mfma_f32_16x16x32_f16 v[96:99], v[200:203], v[240:243], v[172:175]
	v_mfma_f32_16x16x32_f16 v[68:71], v[196:199], v[108:111], v[68:71]
	v_mfma_f32_16x16x32_f16 v[72:75], v[204:207], v[108:111], v[72:75]
	v_mfma_f32_16x16x32_f16 v[76:79], v[196:199], v[224:227], v[76:79]
	v_mfma_f32_16x16x32_f16 v[80:83], v[204:207], v[224:227], v[80:83]
	v_mfma_f32_16x16x32_f16 v[84:87], v[196:199], v[236:239], v[84:87]
	v_mfma_f32_16x16x32_f16 v[88:91], v[204:207], v[236:239], v[88:91]
	v_mfma_f32_16x16x32_f16 v[92:95], v[196:199], v[244:247], v[92:95]
	v_mfma_f32_16x16x32_f16 v[96:99], v[204:207], v[244:247], v[96:99]
	s_setprio 0
	s_setprio 1
	v_mfma_f32_16x16x32_f16 v[100:103], v[208:211], v[104:107], v[116:119]
	v_mfma_f32_16x16x32_f16 v[104:107], v[216:219], v[104:107], v[124:127]
	v_mfma_f32_16x16x32_f16 v[100:103], v[212:215], v[108:111], v[100:103]
	v_mfma_f32_16x16x32_f16 v[104:107], v[220:223], v[108:111], v[104:107]
	v_mfma_f32_16x16x32_f16 v[108:111], v[208:211], v[112:115], v[176:179]
	v_mfma_f32_16x16x32_f16 v[112:115], v[216:219], v[112:115], v[180:183]
	v_mfma_f32_16x16x32_f16 v[116:119], v[208:211], v[232:235], v[184:187]
	v_mfma_f32_16x16x32_f16 v[120:123], v[216:219], v[232:235], v[120:123]
	v_mfma_f32_16x16x32_f16 v[124:127], v[208:211], v[240:243], v[188:191]
	v_mfma_f32_16x16x32_f16 v[128:131], v[216:219], v[240:243], v[128:131]
	v_mfma_f32_16x16x32_f16 v[108:111], v[212:215], v[224:227], v[108:111]
	v_mfma_f32_16x16x32_f16 v[112:115], v[220:223], v[224:227], v[112:115]
	v_mfma_f32_16x16x32_f16 v[116:119], v[212:215], v[236:239], v[116:119]
	v_mfma_f32_16x16x32_f16 v[120:123], v[220:223], v[236:239], v[120:123]
	s_setprio 2
	s_barrier
	v_mfma_f32_16x16x32_f16 v[124:127], v[212:215], v[244:247], v[124:127]
	v_mfma_f32_16x16x32_f16 v[128:131], v[220:223], v[244:247], v[128:131]
	s_setprio 0
	s_add_i32 s41, s41, 2
	s_cmp_ge_i32 s41, s40
	s_cbranch_scc0 .LBB0_528
	v_mov_b32_e32 v136, v2
	s_branch .LBB0_531

.LBB0_532:
	s_add_u32 s6, s8, 0xfff80080
	s_addc_u32 s7, s9, -1
	s_add_i32 s29, 0, 0x10000
	s_cmp_eq_u32 s28, 28
	s_cselect_b32 s17, s13, s7
	s_cselect_b32 s16, s12, s6
	s_cselect_b32 s7, s15, s27
	s_cselect_b32 s6, s14, s26
	s_add_i32 s53, 0, 0x14000
	ds_read_b128 v[138:141], v240
	ds_read_b128 v[142:145], v240 offset:1024
	ds_read_b128 v[148:151], v240 offset:2048
	ds_read_b128 v[152:155], v240 offset:3072
	ds_read_b128 v[156:159], v240 offset:16384
	ds_read_b128 v[160:163], v240 offset:17408
	ds_read_b128 v[164:167], v240 offset:18432
	ds_read_b128 v[168:171], v240 offset:19456
	s_mov_b32 m0, s66
	ds_read_b128 v[172:175], v146
	ds_read_b128 v[176:179], v146 offset:1024
	ds_read_b128 v[180:183], v146 offset:2048
	ds_read_b128 v[184:187], v146 offset:3072
	ds_read_b128 v[188:191], v146 offset:4096
	ds_read_b128 v[192:195], v146 offset:5120
	ds_read_b128 v[196:199], v146 offset:6144
	ds_read_b128 v[200:203], v146 offset:7168
	global_load_lds_dwordx4 v2, s[8:9]
	s_mov_b32 m0, s67
	v_mov_b32_e32 v133, v3
	global_load_lds_dwordx4 v132, s[8:9]
	s_waitcnt vmcnt(8)
	s_waitcnt lgkmcnt(0)
	s_barrier
	s_setprio 1
	s_waitcnt lgkmcnt(0)
	s_nop 5
	v_mfma_f32_16x16x32_f16 v[4:7], v[138:141], v[172:175], v[4:7]
	v_mfma_f32_16x16x32_f16 v[4:7], v[142:145], v[176:179], v[4:7]
	v_mfma_f32_16x16x32_f16 v[8:11], v[152:155], v[176:179], v[8:11]
	v_mfma_f32_16x16x32_f16 v[8:11], v[148:151], v[172:175], v[8:11]
	v_mfma_f32_16x16x32_f16 v[16:19], v[148:151], v[180:183], v[16:19]
	v_mfma_f32_16x16x32_f16 v[16:19], v[152:155], v[184:187], v[16:19]
	v_mfma_f32_16x16x32_f16 v[12:15], v[142:145], v[184:187], v[12:15]
	v_mfma_f32_16x16x32_f16 v[12:15], v[138:141], v[180:183], v[12:15]
	v_mfma_f32_16x16x32_f16 v[20:23], v[138:141], v[188:191], v[20:23]
	v_mfma_f32_16x16x32_f16 v[20:23], v[142:145], v[192:195], v[20:23]
	v_mfma_f32_16x16x32_f16 v[24:27], v[152:155], v[192:195], v[24:27]
	v_mfma_f32_16x16x32_f16 v[24:27], v[148:151], v[188:191], v[24:27]
	v_mfma_f32_16x16x32_f16 v[32:35], v[148:151], v[196:199], v[32:35]
	v_mfma_f32_16x16x32_f16 v[32:35], v[152:155], v[200:203], v[32:35]
	v_mfma_f32_16x16x32_f16 v[28:31], v[142:145], v[200:203], v[28:31]
	v_mfma_f32_16x16x32_f16 v[28:31], v[138:141], v[196:199], v[28:31]
	s_setprio 0
	s_setprio 1
	v_mfma_f32_16x16x32_f16 v[36:39], v[156:159], v[172:175], v[36:39]
	v_mfma_f32_16x16x32_f16 v[36:39], v[160:163], v[176:179], v[36:39]
	v_mfma_f32_16x16x32_f16 v[40:43], v[168:171], v[176:179], v[40:43]
	v_mfma_f32_16x16x32_f16 v[40:43], v[164:167], v[172:175], v[40:43]
	v_mfma_f32_16x16x32_f16 v[48:51], v[164:167], v[180:183], v[48:51]
	v_mfma_f32_16x16x32_f16 v[48:51], v[168:171], v[184:187], v[48:51]
	v_mfma_f32_16x16x32_f16 v[44:47], v[160:163], v[184:187], v[44:47]
	v_mfma_f32_16x16x32_f16 v[44:47], v[156:159], v[180:183], v[44:47]
	v_mfma_f32_16x16x32_f16 v[52:55], v[156:159], v[188:191], v[52:55]
	v_mfma_f32_16x16x32_f16 v[52:55], v[160:163], v[192:195], v[52:55]
	v_mfma_f32_16x16x32_f16 v[56:59], v[168:171], v[192:195], v[56:59]
	v_mfma_f32_16x16x32_f16 v[56:59], v[164:167], v[188:191], v[56:59]
	v_mfma_f32_16x16x32_f16 v[64:67], v[164:167], v[196:199], v[64:67]
	v_mfma_f32_16x16x32_f16 v[64:67], v[168:171], v[200:203], v[64:67]
	s_setprio 2
	s_barrier
	v_mfma_f32_16x16x32_f16 v[60:63], v[160:163], v[200:203], v[60:63]
	v_mfma_f32_16x16x32_f16 v[60:63], v[156:159], v[196:199], v[60:63]
	s_setprio 0
	s_add_i32 s29, s29, s38
	s_mov_b32 m0, s29
	ds_read_b128 v[172:175], v146 offset:16384
	ds_read_b128 v[176:179], v146 offset:17408
	ds_read_b128 v[180:183], v146 offset:18432
	ds_read_b128 v[184:187], v146 offset:19456
	ds_read_b128 v[188:191], v146 offset:20480
	ds_read_b128 v[192:195], v146 offset:21504
	ds_read_b128 v[196:199], v146 offset:22528
	ds_read_b128 v[200:203], v146 offset:23552
	global_load_lds_dwordx4 v136, s[6:7]
	s_add_i32 m0, s29, 0x2000
	s_add_u32 s40, s6, 0x80000
	s_addc_u32 s41, s7, 0
	s_add_i32 s29, s53, s38
	global_load_lds_dwordx4 v134, s[6:7]
	s_mov_b32 m0, s29
	v_mov_b32_e32 v137, v3
	global_load_lds_dwordx4 v136, s[40:41]
	s_add_i32 m0, s29, 0x2000
	v_mov_b32_e32 v135, v3
	global_load_lds_dwordx4 v134, s[40:41]
	s_mov_b32 m0, s58
	s_nop 0
	global_load_lds_dwordx4 v2, s[16:17]
	s_mov_b32 m0, s59
	s_nop 0
	global_load_lds_dwordx4 v132, s[16:17]
	s_waitcnt vmcnt(8)
	s_waitcnt lgkmcnt(0)
	s_add_u32 s88, s6, s86
	s_addc_u32 s89, s7, s87
	s_add_u32 s90, s16, s86
	s_addc_u32 s91, s17, s87
	s_barrier
	s_setprio 1
	s_waitcnt lgkmcnt(0)
	s_nop 5
	v_mfma_f32_16x16x32_f16 v[68:71], v[138:141], v[172:175], v[68:71]
	v_mfma_f32_16x16x32_f16 v[68:71], v[142:145], v[176:179], v[68:71]
	v_mfma_f32_16x16x32_f16 v[72:75], v[152:155], v[176:179], v[72:75]
	v_mfma_f32_16x16x32_f16 v[72:75], v[148:151], v[172:175], v[72:75]
	v_mfma_f32_16x16x32_f16 v[80:83], v[148:151], v[180:183], v[80:83]
	v_mfma_f32_16x16x32_f16 v[80:83], v[152:155], v[184:187], v[80:83]
	v_mfma_f32_16x16x32_f16 v[76:79], v[142:145], v[184:187], v[76:79]
	v_mfma_f32_16x16x32_f16 v[76:79], v[138:141], v[180:183], v[76:79]
	v_mfma_f32_16x16x32_f16 v[84:87], v[138:141], v[188:191], v[84:87]
	v_mfma_f32_16x16x32_f16 v[84:87], v[142:145], v[192:195], v[84:87]
	v_mfma_f32_16x16x32_f16 v[88:91], v[152:155], v[192:195], v[88:91]
	v_mfma_f32_16x16x32_f16 v[88:91], v[148:151], v[188:191], v[88:91]
	v_mfma_f32_16x16x32_f16 v[96:99], v[148:151], v[196:199], v[96:99]
	v_mfma_f32_16x16x32_f16 v[96:99], v[152:155], v[200:203], v[96:99]
	v_mfma_f32_16x16x32_f16 v[92:95], v[142:145], v[200:203], v[92:95]
	v_mfma_f32_16x16x32_f16 v[92:95], v[138:141], v[196:199], v[92:95]
	s_setprio 0
	s_setprio 1
	v_mfma_f32_16x16x32_f16 v[100:103], v[156:159], v[172:175], v[100:103]
	v_mfma_f32_16x16x32_f16 v[100:103], v[160:163], v[176:179], v[100:103]
	v_mfma_f32_16x16x32_f16 v[104:107], v[168:171], v[176:179], v[104:107]
	v_mfma_f32_16x16x32_f16 v[104:107], v[164:167], v[172:175], v[104:107]
	v_mfma_f32_16x16x32_f16 v[112:115], v[164:167], v[180:183], v[112:115]
	v_mfma_f32_16x16x32_f16 v[112:115], v[168:171], v[184:187], v[112:115]
	v_mfma_f32_16x16x32_f16 v[108:111], v[160:163], v[184:187], v[108:111]
	v_mfma_f32_16x16x32_f16 v[108:111], v[156:159], v[180:183], v[108:111]
	v_mfma_f32_16x16x32_f16 v[116:119], v[156:159], v[188:191], v[116:119]
	v_mfma_f32_16x16x32_f16 v[116:119], v[160:163], v[192:195], v[116:119]
	v_mfma_f32_16x16x32_f16 v[120:123], v[168:171], v[192:195], v[120:123]
	v_mfma_f32_16x16x32_f16 v[120:123], v[164:167], v[188:191], v[120:123]
	v_mfma_f32_16x16x32_f16 v[128:131], v[164:167], v[196:199], v[128:131]
	v_mfma_f32_16x16x32_f16 v[128:131], v[168:171], v[200:203], v[128:131]
	s_setprio 2
	s_barrier
	v_mfma_f32_16x16x32_f16 v[124:127], v[160:163], v[200:203], v[124:127]
	v_mfma_f32_16x16x32_f16 v[124:127], v[156:159], v[196:199], v[124:127]
	s_setprio 0
	s_add_i32 s29, 0, 0x18000
	s_add_i32 s40, 0, 0x1c000
	ds_read_b128 v[138:141], v240 offset:32768
	ds_read_b128 v[142:145], v240 offset:33792
	ds_read_b128 v[148:151], v240 offset:34816
	ds_read_b128 v[152:155], v240 offset:35840
	ds_read_b128 v[156:159], v240 offset:49152
	ds_read_b128 v[160:163], v240 offset:50176
	ds_read_b128 v[164:167], v240 offset:51200
	ds_read_b128 v[168:171], v240 offset:52224
	s_add_u32 s16, s16, 0x80000
	s_addc_u32 s17, s17, 0
	s_mov_b32 m0, s60
	ds_read_b128 v[172:175], v146 offset:32768
	ds_read_b128 v[176:179], v146 offset:33792
	ds_read_b128 v[180:183], v146 offset:34816
	ds_read_b128 v[184:187], v146 offset:35840
	ds_read_b128 v[188:191], v146 offset:36864
	ds_read_b128 v[192:195], v146 offset:37888
	ds_read_b128 v[196:199], v146 offset:38912
	ds_read_b128 v[200:203], v146 offset:39936
	global_load_lds_dwordx4 v2, s[16:17]
	s_mov_b32 m0, s61
	s_nop 0
	global_load_lds_dwordx4 v132, s[16:17]
	s_waitcnt vmcnt(8)
	s_waitcnt lgkmcnt(0)
	s_barrier
	s_setprio 1
	s_waitcnt lgkmcnt(0)
	s_nop 5
	v_mfma_f32_16x16x32_f16 v[4:7], v[138:141], v[172:175], v[4:7]
	v_mfma_f32_16x16x32_f16 v[4:7], v[142:145], v[176:179], v[4:7]
	v_mfma_f32_16x16x32_f16 v[8:11], v[152:155], v[176:179], v[8:11]
	v_mfma_f32_16x16x32_f16 v[8:11], v[148:151], v[172:175], v[8:11]
	v_mfma_f32_16x16x32_f16 v[16:19], v[148:151], v[180:183], v[16:19]
	v_mfma_f32_16x16x32_f16 v[16:19], v[152:155], v[184:187], v[16:19]
	v_mfma_f32_16x16x32_f16 v[12:15], v[142:145], v[184:187], v[12:15]
	v_mfma_f32_16x16x32_f16 v[12:15], v[138:141], v[180:183], v[12:15]
	v_mfma_f32_16x16x32_f16 v[20:23], v[138:141], v[188:191], v[20:23]
	v_mfma_f32_16x16x32_f16 v[20:23], v[142:145], v[192:195], v[20:23]
	v_mfma_f32_16x16x32_f16 v[24:27], v[152:155], v[192:195], v[24:27]
	v_mfma_f32_16x16x32_f16 v[24:27], v[148:151], v[188:191], v[24:27]
	v_mfma_f32_16x16x32_f16 v[32:35], v[148:151], v[196:199], v[32:35]
	v_mfma_f32_16x16x32_f16 v[32:35], v[152:155], v[200:203], v[32:35]
	v_mfma_f32_16x16x32_f16 v[28:31], v[142:145], v[200:203], v[28:31]
	v_mfma_f32_16x16x32_f16 v[28:31], v[138:141], v[196:199], v[28:31]
	s_setprio 0
	s_setprio 1
	v_mfma_f32_16x16x32_f16 v[36:39], v[156:159], v[172:175], v[36:39]
	v_mfma_f32_16x16x32_f16 v[36:39], v[160:163], v[176:179], v[36:39]
	v_mfma_f32_16x16x32_f16 v[40:43], v[168:171], v[176:179], v[40:43]
	v_mfma_f32_16x16x32_f16 v[40:43], v[164:167], v[172:175], v[40:43]
	v_mfma_f32_16x16x32_f16 v[48:51], v[164:167], v[180:183], v[48:51]
	v_mfma_f32_16x16x32_f16 v[48:51], v[168:171], v[184:187], v[48:51]
	v_mfma_f32_16x16x32_f16 v[44:47], v[160:163], v[184:187], v[44:47]
	v_mfma_f32_16x16x32_f16 v[44:47], v[156:159], v[180:183], v[44:47]
	v_mfma_f32_16x16x32_f16 v[52:55], v[156:159], v[188:191], v[52:55]
	v_mfma_f32_16x16x32_f16 v[52:55], v[160:163], v[192:195], v[52:55]
	v_mfma_f32_16x16x32_f16 v[56:59], v[168:171], v[192:195], v[56:59]
	v_mfma_f32_16x16x32_f16 v[56:59], v[164:167], v[188:191], v[56:59]
	v_mfma_f32_16x16x32_f16 v[64:67], v[164:167], v[196:199], v[64:67]
	v_mfma_f32_16x16x32_f16 v[64:67], v[168:171], v[200:203], v[64:67]
	s_setprio 2
	s_barrier
	v_mfma_f32_16x16x32_f16 v[60:63], v[160:163], v[200:203], v[60:63]
	v_mfma_f32_16x16x32_f16 v[60:63], v[156:159], v[196:199], v[60:63]
	s_setprio 0
	s_add_i32 s16, s29, s38
	s_mov_b32 m0, s16
	ds_read_b128 v[172:175], v146 offset:49152
	ds_read_b128 v[176:179], v146 offset:50176
	ds_read_b128 v[180:183], v146 offset:51200
	ds_read_b128 v[184:187], v146 offset:52224
	ds_read_b128 v[188:191], v146 offset:53248
	ds_read_b128 v[192:195], v146 offset:54272
	ds_read_b128 v[196:199], v146 offset:55296
	ds_read_b128 v[200:203], v146 offset:56320
	global_load_lds_dwordx4 v136, s[88:89]
	s_add_i32 m0, s16, 0x2000
	s_add_u32 s6, s6, 0x80080
	s_addc_u32 s7, s7, 0
	s_add_i32 s16, s40, s38
	global_load_lds_dwordx4 v134, s[88:89]
	s_mov_b32 m0, s16
	s_nop 0
	global_load_lds_dwordx4 v136, s[6:7]
	s_add_i32 m0, s16, 0x2000
	s_nop 0
	global_load_lds_dwordx4 v134, s[6:7]
	s_mov_b32 m0, s64
	s_nop 0
	global_load_lds_dwordx4 v2, s[90:91]
	s_mov_b32 m0, s65
	s_nop 0
	global_load_lds_dwordx4 v132, s[90:91]
	s_waitcnt vmcnt(8)
	s_waitcnt lgkmcnt(0)
	s_barrier
	s_setprio 1
	s_waitcnt lgkmcnt(0)
	s_nop 5
	v_mfma_f32_16x16x32_f16 v[68:71], v[138:141], v[172:175], v[68:71]
	v_mfma_f32_16x16x32_f16 v[68:71], v[142:145], v[176:179], v[68:71]
	v_mfma_f32_16x16x32_f16 v[72:75], v[152:155], v[176:179], v[72:75]
	v_mfma_f32_16x16x32_f16 v[72:75], v[148:151], v[172:175], v[72:75]
	v_mfma_f32_16x16x32_f16 v[80:83], v[148:151], v[180:183], v[80:83]
	v_mfma_f32_16x16x32_f16 v[80:83], v[152:155], v[184:187], v[80:83]
	v_mfma_f32_16x16x32_f16 v[76:79], v[142:145], v[184:187], v[76:79]
	v_mfma_f32_16x16x32_f16 v[76:79], v[138:141], v[180:183], v[76:79]
	v_mfma_f32_16x16x32_f16 v[84:87], v[138:141], v[188:191], v[84:87]
	v_mfma_f32_16x16x32_f16 v[84:87], v[142:145], v[192:195], v[84:87]
	v_mfma_f32_16x16x32_f16 v[88:91], v[152:155], v[192:195], v[88:91]
	v_mfma_f32_16x16x32_f16 v[88:91], v[148:151], v[188:191], v[88:91]
	v_mfma_f32_16x16x32_f16 v[96:99], v[148:151], v[196:199], v[96:99]
	v_mfma_f32_16x16x32_f16 v[96:99], v[152:155], v[200:203], v[96:99]
	v_mfma_f32_16x16x32_f16 v[92:95], v[142:145], v[200:203], v[92:95]
	v_mfma_f32_16x16x32_f16 v[92:95], v[138:141], v[196:199], v[92:95]
	s_setprio 0
	s_setprio 1
	v_mfma_f32_16x16x32_f16 v[100:103], v[156:159], v[172:175], v[100:103]
	v_mfma_f32_16x16x32_f16 v[100:103], v[160:163], v[176:179], v[100:103]
	v_mfma_f32_16x16x32_f16 v[104:107], v[168:171], v[176:179], v[104:107]
	v_mfma_f32_16x16x32_f16 v[104:107], v[164:167], v[172:175], v[104:107]
	v_mfma_f32_16x16x32_f16 v[112:115], v[164:167], v[180:183], v[112:115]
	v_mfma_f32_16x16x32_f16 v[112:115], v[168:171], v[184:187], v[112:115]
	v_mfma_f32_16x16x32_f16 v[108:111], v[160:163], v[184:187], v[108:111]
	v_mfma_f32_16x16x32_f16 v[108:111], v[156:159], v[180:183], v[108:111]
	v_mfma_f32_16x16x32_f16 v[116:119], v[156:159], v[188:191], v[116:119]
	v_mfma_f32_16x16x32_f16 v[116:119], v[160:163], v[192:195], v[116:119]
	v_mfma_f32_16x16x32_f16 v[120:123], v[168:171], v[192:195], v[120:123]
	v_mfma_f32_16x16x32_f16 v[120:123], v[164:167], v[188:191], v[120:123]
	v_mfma_f32_16x16x32_f16 v[128:131], v[164:167], v[196:199], v[128:131]
	v_mfma_f32_16x16x32_f16 v[128:131], v[168:171], v[200:203], v[128:131]
	s_setprio 2
	s_barrier
	v_mfma_f32_16x16x32_f16 v[124:127], v[160:163], v[200:203], v[124:127]
	v_mfma_f32_16x16x32_f16 v[124:127], v[156:159], v[196:199], v[124:127]
	s_setprio 0
	s_add_i32 s28, s28, 2
	s_add_u32 s8, s8, 0x100
	s_addc_u32 s9, s9, 0
	s_add_u32 s26, s26, 0x100
	s_addc_u32 s27, s27, 0
	s_cmp_gt_u32 s28, 29
	s_cbranch_scc0 .LBB0_532
	s_and_b64 vcc, exec, s[50:51]
	s_cbranch_vccz .LBB0_535
	s_barrier

.LBB0_641:
	s_add_i32 s43, 0, 0x10000
	s_add_i32 s71, 0, 0x14000
	v_add_u32_e32 v16, s43, v232
	v_add_u32_e32 v32, s71, v232
	ds_read_b128 v[4:7], v16
	ds_read_b128 v[8:11], v16 offset:1024
	ds_read_b128 v[12:15], v16 offset:2048
	ds_read_b128 v[16:19], v16 offset:3072
	ds_read_b128 v[20:23], v32
	ds_read_b128 v[24:27], v32 offset:1024
	ds_read_b128 v[28:31], v32 offset:2048
	ds_read_b128 v[32:35], v32 offset:3072
	v_add_u32_e32 v233, 0, v231
	ds_read_b128 v[36:39], v233
	ds_read_b128 v[40:43], v233 offset:1024
	ds_read_b128 v[44:47], v233 offset:2048
	ds_read_b128 v[48:51], v233 offset:3072
	ds_read_b128 v[52:55], v233 offset:4096
	ds_read_b128 v[56:59], v233 offset:5120
	ds_read_b128 v[60:63], v233 offset:6144
	ds_read_b128 v[64:67], v233 offset:7168
	s_waitcnt vmcnt(8)
	s_waitcnt lgkmcnt(0)
	s_barrier
	s_setprio 1
	s_waitcnt lgkmcnt(0)
	s_nop 5
	v_mfma_f32_16x16x32_bf16 v[68:71], v[4:7], v[36:39], 0
	v_mfma_f32_16x16x32_bf16 v[68:71], v[8:11], v[40:43], v[68:71]
	v_mfma_f32_16x16x32_bf16 v[72:75], v[12:15], v[36:39], 0
	v_mfma_f32_16x16x32_bf16 v[72:75], v[16:19], v[40:43], v[72:75]
	v_mfma_f32_16x16x32_bf16 v[80:83], v[12:15], v[44:47], 0
	v_mfma_f32_16x16x32_bf16 v[80:83], v[16:19], v[48:51], v[80:83]
	v_mfma_f32_16x16x32_bf16 v[76:79], v[4:7], v[44:47], 0
	v_mfma_f32_16x16x32_bf16 v[76:79], v[8:11], v[48:51], v[76:79]
	v_mfma_f32_16x16x32_bf16 v[84:87], v[4:7], v[52:55], 0
	v_mfma_f32_16x16x32_bf16 v[84:87], v[8:11], v[56:59], v[84:87]
	v_mfma_f32_16x16x32_bf16 v[88:91], v[12:15], v[52:55], 0
	v_mfma_f32_16x16x32_bf16 v[88:91], v[16:19], v[56:59], v[88:91]
	v_mfma_f32_16x16x32_bf16 v[96:99], v[12:15], v[60:63], 0
	v_mfma_f32_16x16x32_bf16 v[96:99], v[16:19], v[64:67], v[96:99]
	v_mfma_f32_16x16x32_bf16 v[92:95], v[4:7], v[60:63], 0
	v_mfma_f32_16x16x32_bf16 v[92:95], v[8:11], v[64:67], v[92:95]
	s_setprio 0
	s_setprio 1
	v_mfma_f32_16x16x32_bf16 v[100:103], v[20:23], v[36:39], 0
	v_mfma_f32_16x16x32_bf16 v[36:39], v[28:31], v[36:39], 0
	v_mfma_f32_16x16x32_bf16 v[104:107], v[20:23], v[44:47], 0
	v_mfma_f32_16x16x32_bf16 v[44:47], v[28:31], v[44:47], 0
	v_mfma_f32_16x16x32_bf16 v[108:111], v[20:23], v[52:55], 0
	v_mfma_f32_16x16x32_bf16 v[52:55], v[28:31], v[52:55], 0
	v_mfma_f32_16x16x32_bf16 v[112:115], v[20:23], v[60:63], 0
	v_mfma_f32_16x16x32_bf16 v[60:63], v[28:31], v[60:63], 0
	v_mfma_f32_16x16x32_bf16 v[100:103], v[24:27], v[40:43], v[100:103]
	v_mfma_f32_16x16x32_bf16 v[40:43], v[32:35], v[40:43], v[36:39]
	v_mfma_f32_16x16x32_bf16 v[104:107], v[24:27], v[48:51], v[104:107]
	v_mfma_f32_16x16x32_bf16 v[48:51], v[32:35], v[48:51], v[44:47]
	v_mfma_f32_16x16x32_bf16 v[108:111], v[24:27], v[56:59], v[108:111]
	v_mfma_f32_16x16x32_bf16 v[56:59], v[32:35], v[56:59], v[52:55]
	s_setprio 2
	s_barrier
	v_mfma_f32_16x16x32_bf16 v[112:115], v[24:27], v[64:67], v[112:115]
	v_mfma_f32_16x16x32_bf16 v[64:67], v[32:35], v[64:67], v[60:63]
	s_setprio 0
	v_lshl_add_u64 v[186:187], s[8:9], 0, v[2:3]
	s_add_i32 s43, s43, s54
	v_mov_b32_e32 v191, v3
	v_lshl_add_u64 v[134:135], v[186:187], 0, s[80:81]
	s_mov_b32 m0, s43
	v_lshl_add_u64 v[246:247], s[8:9], 0, v[190:191]
	ds_read_b128 v[36:39], v233 offset:16384
	ds_read_b128 v[44:47], v233 offset:17408
	ds_read_b128 v[52:55], v233 offset:18432
	ds_read_b128 v[60:63], v233 offset:19456
	ds_read_b128 v[116:119], v233 offset:20480
	ds_read_b128 v[120:123], v233 offset:21504
	ds_read_b128 v[124:127], v233 offset:22528
	ds_read_b128 v[128:131], v233 offset:23552
	global_load_lds_dwordx4 v[134:135], off
	v_lshl_add_u64 v[134:135], v[246:247], 0, s[80:81]
	s_add_i32 m0, s43, 0x2000
	s_add_i32 s43, s71, s54
	global_load_lds_dwordx4 v[134:135], off
	s_mov_b32 m0, s43
	v_mov_b32_e32 v133, v3
	global_load_lds_dwordx4 v2, s[16:17]
	s_add_i32 m0, s43, 0x2000
	v_lshl_add_u64 v[248:249], s[6:7], 0, v[132:133]
	v_mov_b32_e32 v189, v3
	global_load_lds_dwordx4 v190, s[16:17]
	v_lshl_add_u64 v[134:135], v[248:249], 0, s[80:81]
	s_mov_b32 m0, s55
	v_lshl_add_u64 v[250:251], s[6:7], 0, v[188:189]
	global_load_lds_dwordx4 v[134:135], off
	v_lshl_add_u64 v[134:135], v[250:251], 0, s[80:81]
	s_mov_b32 m0, s56
	s_nop 0
	global_load_lds_dwordx4 v[134:135], off
	s_waitcnt vmcnt(8)
	s_waitcnt lgkmcnt(0)
	s_barrier
	s_setprio 1
	s_waitcnt lgkmcnt(0)
	s_nop 5
	v_mfma_f32_16x16x32_bf16 v[134:137], v[4:7], v[36:39], 0
	v_mfma_f32_16x16x32_bf16 v[138:141], v[12:15], v[36:39], 0
	v_mfma_f32_16x16x32_bf16 v[142:145], v[4:7], v[52:55], 0
	v_mfma_f32_16x16x32_bf16 v[146:149], v[12:15], v[52:55], 0
	v_mfma_f32_16x16x32_bf16 v[150:153], v[4:7], v[116:119], 0
	v_mfma_f32_16x16x32_bf16 v[154:157], v[12:15], v[116:119], 0
	v_mfma_f32_16x16x32_bf16 v[4:7], v[4:7], v[124:127], 0
	v_mfma_f32_16x16x32_bf16 v[12:15], v[12:15], v[124:127], 0
	v_mfma_f32_16x16x32_bf16 v[134:137], v[8:11], v[44:47], v[134:137]
	v_mfma_f32_16x16x32_bf16 v[138:141], v[16:19], v[44:47], v[138:141]
	v_mfma_f32_16x16x32_bf16 v[142:145], v[8:11], v[60:63], v[142:145]
	v_mfma_f32_16x16x32_bf16 v[146:149], v[16:19], v[60:63], v[146:149]
	v_mfma_f32_16x16x32_bf16 v[150:153], v[8:11], v[120:123], v[150:153]
	v_mfma_f32_16x16x32_bf16 v[154:157], v[16:19], v[120:123], v[154:157]
	v_mfma_f32_16x16x32_bf16 v[158:161], v[8:11], v[128:131], v[4:7]
	v_mfma_f32_16x16x32_bf16 v[162:165], v[16:19], v[128:131], v[12:15]
	s_setprio 0
	s_setprio 1
	v_mfma_f32_16x16x32_bf16 v[4:7], v[20:23], v[36:39], 0
	v_mfma_f32_16x16x32_bf16 v[8:11], v[28:31], v[36:39], 0
	v_mfma_f32_16x16x32_bf16 v[12:15], v[20:23], v[52:55], 0
	v_mfma_f32_16x16x32_bf16 v[16:19], v[28:31], v[52:55], 0
	v_mfma_f32_16x16x32_bf16 v[36:39], v[20:23], v[116:119], 0
	v_mfma_f32_16x16x32_bf16 v[52:55], v[28:31], v[116:119], 0
	v_mfma_f32_16x16x32_bf16 v[20:23], v[20:23], v[124:127], 0
	v_mfma_f32_16x16x32_bf16 v[28:31], v[28:31], v[124:127], 0
	v_mfma_f32_16x16x32_bf16 v[116:119], v[24:27], v[44:47], v[4:7]
	v_mfma_f32_16x16x32_bf16 v[124:127], v[32:35], v[44:47], v[8:11]
	v_mfma_f32_16x16x32_bf16 v[174:177], v[24:27], v[120:123], v[36:39]
	v_mfma_f32_16x16x32_bf16 v[120:123], v[32:35], v[120:123], v[52:55]
	v_mfma_f32_16x16x32_bf16 v[178:181], v[24:27], v[128:131], v[20:23]
	v_mfma_f32_16x16x32_bf16 v[128:131], v[32:35], v[128:131], v[28:31]
	s_setprio 2
	s_barrier
	v_mfma_f32_16x16x32_bf16 v[166:169], v[24:27], v[60:63], v[12:15]
	v_mfma_f32_16x16x32_bf16 v[170:173], v[32:35], v[60:63], v[16:19]
	s_setprio 0
	s_add_i32 s43, 0, 0x18000
	v_add_u32_e32 v4, s43, v232
	s_add_i32 s71, 0, 0x1c000
	ds_read_b128 v[182:185], v4
	ds_read_b128 v[192:195], v4 offset:1024
	ds_read_b128 v[196:199], v4 offset:2048
	ds_read_b128 v[200:203], v4 offset:3072
	v_add_u32_e32 v4, s71, v232
	ds_read_b128 v[204:207], v4
	ds_read_b128 v[208:211], v4 offset:1024
	ds_read_b128 v[212:215], v4 offset:2048
	ds_read_b128 v[216:219], v4 offset:3072
	s_mov_b32 m0, s57
	ds_read_b128 v[44:47], v233 offset:32768
	ds_read_b128 v[52:55], v233 offset:33792
	ds_read_b128 v[60:63], v233 offset:34816
	ds_read_b128 v[220:223], v233 offset:35840
	ds_read_b128 v[224:227], v233 offset:36864
	ds_read_b128 v[234:237], v233 offset:37888
	ds_read_b128 v[238:241], v233 offset:38912
	ds_read_b128 v[242:245], v233 offset:39936
	global_load_lds_dwordx4 v132, s[26:27]
	s_mov_b32 m0, s58
	s_nop 0
	global_load_lds_dwordx4 v188, s[26:27]
	s_waitcnt vmcnt(8)
	s_waitcnt lgkmcnt(0)
	s_barrier
	s_setprio 1
	s_waitcnt lgkmcnt(0)
	s_nop 5
	v_mfma_f32_16x16x32_bf16 v[4:7], v[182:185], v[44:47], v[68:71]
	v_mfma_f32_16x16x32_bf16 v[8:11], v[196:199], v[44:47], v[72:75]
	v_mfma_f32_16x16x32_bf16 v[12:15], v[182:185], v[60:63], v[76:79]
	v_mfma_f32_16x16x32_bf16 v[16:19], v[196:199], v[60:63], v[80:83]
	v_mfma_f32_16x16x32_bf16 v[20:23], v[182:185], v[224:227], v[84:87]
	v_mfma_f32_16x16x32_bf16 v[24:27], v[196:199], v[224:227], v[88:91]
	v_mfma_f32_16x16x32_bf16 v[28:31], v[182:185], v[238:241], v[92:95]
	v_mfma_f32_16x16x32_bf16 v[32:35], v[196:199], v[238:241], v[96:99]
	v_mfma_f32_16x16x32_bf16 v[4:7], v[192:195], v[52:55], v[4:7]
	v_mfma_f32_16x16x32_bf16 v[8:11], v[200:203], v[52:55], v[8:11]
	v_mfma_f32_16x16x32_bf16 v[12:15], v[192:195], v[220:223], v[12:15]
	v_mfma_f32_16x16x32_bf16 v[16:19], v[200:203], v[220:223], v[16:19]
	v_mfma_f32_16x16x32_bf16 v[20:23], v[192:195], v[234:237], v[20:23]
	v_mfma_f32_16x16x32_bf16 v[24:27], v[200:203], v[234:237], v[24:27]
	v_mfma_f32_16x16x32_bf16 v[28:31], v[192:195], v[242:245], v[28:31]
	v_mfma_f32_16x16x32_bf16 v[32:35], v[200:203], v[242:245], v[32:35]
	s_setprio 0
	s_setprio 1
	v_mfma_f32_16x16x32_bf16 v[36:39], v[204:207], v[44:47], v[100:103]
	v_mfma_f32_16x16x32_bf16 v[40:43], v[212:215], v[44:47], v[40:43]
	v_mfma_f32_16x16x32_bf16 v[36:39], v[208:211], v[52:55], v[36:39]
	v_mfma_f32_16x16x32_bf16 v[40:43], v[216:219], v[52:55], v[40:43]
	v_mfma_f32_16x16x32_bf16 v[44:47], v[204:207], v[60:63], v[104:107]
	v_mfma_f32_16x16x32_bf16 v[48:51], v[212:215], v[60:63], v[48:51]
	v_mfma_f32_16x16x32_bf16 v[52:55], v[204:207], v[224:227], v[108:111]
	v_mfma_f32_16x16x32_bf16 v[56:59], v[212:215], v[224:227], v[56:59]
	v_mfma_f32_16x16x32_bf16 v[60:63], v[204:207], v[238:241], v[112:115]
	v_mfma_f32_16x16x32_bf16 v[64:67], v[212:215], v[238:241], v[64:67]
	v_mfma_f32_16x16x32_bf16 v[44:47], v[208:211], v[220:223], v[44:47]
	v_mfma_f32_16x16x32_bf16 v[48:51], v[216:219], v[220:223], v[48:51]
	v_mfma_f32_16x16x32_bf16 v[52:55], v[208:211], v[234:237], v[52:55]
	v_mfma_f32_16x16x32_bf16 v[56:59], v[216:219], v[234:237], v[56:59]
	s_setprio 2
	s_barrier
	v_mfma_f32_16x16x32_bf16 v[60:63], v[208:211], v[242:245], v[60:63]
	v_mfma_f32_16x16x32_bf16 v[64:67], v[216:219], v[242:245], v[64:67]
	s_setprio 0
	s_add_i32 s43, s43, s54
	v_lshl_add_u64 v[68:69], v[186:187], 0, s[0:1]
	s_mov_b32 m0, s43
	ds_read_b128 v[104:107], v233 offset:49152
	ds_read_b128 v[108:111], v233 offset:50176
	ds_read_b128 v[112:115], v233 offset:51200
	ds_read_b128 v[220:223], v233 offset:52224
	ds_read_b128 v[224:227], v233 offset:53248
	ds_read_b128 v[234:237], v233 offset:54272
	ds_read_b128 v[238:241], v233 offset:55296
	ds_read_b128 v[242:245], v233 offset:56320
	global_load_lds_dwordx4 v[68:69], off
	v_lshl_add_u64 v[68:69], v[246:247], 0, s[0:1]
	s_add_i32 m0, s43, 0x2000
	s_add_i32 s43, s71, s54
	global_load_lds_dwordx4 v[68:69], off
	s_mov_b32 m0, s43
	v_lshl_add_u64 v[68:69], v[248:249], 0, s[0:1]
	global_load_lds_dwordx4 v2, s[28:29]
	s_add_i32 m0, s43, 0x2000
	s_nop 0
	global_load_lds_dwordx4 v190, s[28:29]
	s_mov_b32 m0, s62
	s_nop 0
	global_load_lds_dwordx4 v[68:69], off
	v_lshl_add_u64 v[68:69], v[250:251], 0, s[0:1]
	s_mov_b32 m0, s63
	s_nop 0
	global_load_lds_dwordx4 v[68:69], off
	s_waitcnt vmcnt(8)
	s_waitcnt lgkmcnt(0)
	s_barrier
	s_setprio 1
	s_waitcnt lgkmcnt(0)
	s_nop 5
	v_mfma_f32_16x16x32_bf16 v[68:71], v[182:185], v[104:107], v[134:137]
	v_mfma_f32_16x16x32_bf16 v[72:75], v[196:199], v[104:107], v[138:141]
	v_mfma_f32_16x16x32_bf16 v[76:79], v[182:185], v[112:115], v[142:145]
	v_mfma_f32_16x16x32_bf16 v[80:83], v[196:199], v[112:115], v[146:149]
	v_mfma_f32_16x16x32_bf16 v[84:87], v[182:185], v[224:227], v[150:153]
	v_mfma_f32_16x16x32_bf16 v[88:91], v[196:199], v[224:227], v[154:157]
	v_mfma_f32_16x16x32_bf16 v[92:95], v[182:185], v[238:241], v[158:161]
	v_mfma_f32_16x16x32_bf16 v[96:99], v[196:199], v[238:241], v[162:165]
	v_mfma_f32_16x16x32_bf16 v[68:71], v[192:195], v[108:111], v[68:71]
	v_mfma_f32_16x16x32_bf16 v[72:75], v[200:203], v[108:111], v[72:75]
	v_mfma_f32_16x16x32_bf16 v[76:79], v[192:195], v[220:223], v[76:79]
	v_mfma_f32_16x16x32_bf16 v[80:83], v[200:203], v[220:223], v[80:83]
	v_mfma_f32_16x16x32_bf16 v[84:87], v[192:195], v[234:237], v[84:87]
	v_mfma_f32_16x16x32_bf16 v[88:91], v[200:203], v[234:237], v[88:91]
	v_mfma_f32_16x16x32_bf16 v[92:95], v[192:195], v[242:245], v[92:95]
	v_mfma_f32_16x16x32_bf16 v[96:99], v[200:203], v[242:245], v[96:99]
	s_setprio 0
	s_setprio 1
	v_mfma_f32_16x16x32_bf16 v[100:103], v[204:207], v[104:107], v[116:119]
	v_mfma_f32_16x16x32_bf16 v[104:107], v[212:215], v[104:107], v[124:127]
	v_mfma_f32_16x16x32_bf16 v[100:103], v[208:211], v[108:111], v[100:103]
	v_mfma_f32_16x16x32_bf16 v[104:107], v[216:219], v[108:111], v[104:107]
	v_mfma_f32_16x16x32_bf16 v[108:111], v[204:207], v[112:115], v[166:169]
	v_mfma_f32_16x16x32_bf16 v[112:115], v[212:215], v[112:115], v[170:173]
	v_mfma_f32_16x16x32_bf16 v[116:119], v[204:207], v[224:227], v[174:177]
	v_mfma_f32_16x16x32_bf16 v[120:123], v[212:215], v[224:227], v[120:123]
	v_mfma_f32_16x16x32_bf16 v[124:127], v[204:207], v[238:241], v[178:181]
	v_mfma_f32_16x16x32_bf16 v[128:131], v[212:215], v[238:241], v[128:131]
	v_mfma_f32_16x16x32_bf16 v[108:111], v[208:211], v[220:223], v[108:111]
	v_mfma_f32_16x16x32_bf16 v[112:115], v[216:219], v[220:223], v[112:115]
	v_mfma_f32_16x16x32_bf16 v[116:119], v[208:211], v[234:237], v[116:119]
	v_mfma_f32_16x16x32_bf16 v[120:123], v[216:219], v[234:237], v[120:123]
	s_setprio 2
	s_barrier
	v_mfma_f32_16x16x32_bf16 v[124:127], v[208:211], v[242:245], v[124:127]
	v_mfma_f32_16x16x32_bf16 v[128:131], v[216:219], v[242:245], v[128:131]
	s_setprio 0
	s_add_i32 s42, s42, 2
	s_cmp_ge_i32 s42, s38
	s_cbranch_scc0 .LBB0_641
	v_mov_b32_e32 v192, v2
	s_branch .LBB0_644

.LBB0_649:
	s_or_b32 s38, s28, 1
	s_lshl_b64 s[42:43], s[38:39], 7
	s_sub_u32 s38, 0, s42
	s_subb_u32 s42, 0, s43
	s_add_u32 s38, s6, s38
	s_addc_u32 s43, s7, s42
	s_add_i32 s71, 0, 0x10000
	s_add_i32 s72, 0, 0x14000
	s_waitcnt lgkmcnt(0)
	ds_read_b128 v[132:135], v240
	ds_read_b128 v[136:139], v240 offset:1024
	ds_read_b128 v[140:143], v240 offset:2048
	ds_read_b128 v[144:147], v240 offset:3072
	ds_read_b128 v[148:151], v240 offset:16384
	ds_read_b128 v[152:155], v240 offset:17408
	ds_read_b128 v[156:159], v240 offset:18432
	ds_read_b128 v[160:163], v240 offset:19456
	s_add_u32 s42, s38, 0x160000
	s_mov_b32 m0, s64
	s_addc_u32 s43, s43, 0
	ds_read_b128 v[164:167], v231
	ds_read_b128 v[168:171], v231 offset:1024
	ds_read_b128 v[172:175], v231 offset:2048
	ds_read_b128 v[176:179], v231 offset:3072
	ds_read_b128 v[180:183], v231 offset:4096
	ds_read_b128 v[184:187], v231 offset:5120
	ds_read_b128 v[194:197], v231 offset:6144
	ds_read_b128 v[198:201], v231 offset:7168
	global_load_lds_dwordx4 v2, s[42:43]
	s_mov_b32 m0, s65
	v_mov_b32_e32 v189, v3
	global_load_lds_dwordx4 v188, s[42:43]
	s_waitcnt vmcnt(8)
	s_waitcnt lgkmcnt(0)
	s_barrier
	s_setprio 1
	s_waitcnt lgkmcnt(0)
	s_nop 5
	v_mfma_f32_16x16x32_bf16 v[4:7], v[132:135], v[164:167], v[4:7]
	v_mfma_f32_16x16x32_bf16 v[4:7], v[136:139], v[168:171], v[4:7]
	v_mfma_f32_16x16x32_bf16 v[8:11], v[144:147], v[168:171], v[8:11]
	v_mfma_f32_16x16x32_bf16 v[8:11], v[140:143], v[164:167], v[8:11]
	v_mfma_f32_16x16x32_bf16 v[16:19], v[140:143], v[172:175], v[16:19]
	v_mfma_f32_16x16x32_bf16 v[16:19], v[144:147], v[176:179], v[16:19]
	v_mfma_f32_16x16x32_bf16 v[12:15], v[136:139], v[176:179], v[12:15]
	v_mfma_f32_16x16x32_bf16 v[12:15], v[132:135], v[172:175], v[12:15]
	v_mfma_f32_16x16x32_bf16 v[20:23], v[132:135], v[180:183], v[20:23]
	v_mfma_f32_16x16x32_bf16 v[20:23], v[136:139], v[184:187], v[20:23]
	v_mfma_f32_16x16x32_bf16 v[24:27], v[144:147], v[184:187], v[24:27]
	v_mfma_f32_16x16x32_bf16 v[24:27], v[140:143], v[180:183], v[24:27]
	v_mfma_f32_16x16x32_bf16 v[32:35], v[140:143], v[194:197], v[32:35]
	v_mfma_f32_16x16x32_bf16 v[32:35], v[144:147], v[198:201], v[32:35]
	v_mfma_f32_16x16x32_bf16 v[28:31], v[136:139], v[198:201], v[28:31]
	v_mfma_f32_16x16x32_bf16 v[28:31], v[132:135], v[194:197], v[28:31]
	s_setprio 0
	s_setprio 1
	v_mfma_f32_16x16x32_bf16 v[36:39], v[148:151], v[164:167], v[36:39]
	v_mfma_f32_16x16x32_bf16 v[36:39], v[152:155], v[168:171], v[36:39]
	v_mfma_f32_16x16x32_bf16 v[40:43], v[160:163], v[168:171], v[40:43]
	v_mfma_f32_16x16x32_bf16 v[40:43], v[156:159], v[164:167], v[40:43]
	v_mfma_f32_16x16x32_bf16 v[48:51], v[156:159], v[172:175], v[48:51]
	v_mfma_f32_16x16x32_bf16 v[48:51], v[160:163], v[176:179], v[48:51]
	v_mfma_f32_16x16x32_bf16 v[44:47], v[152:155], v[176:179], v[44:47]
	v_mfma_f32_16x16x32_bf16 v[44:47], v[148:151], v[172:175], v[44:47]
	v_mfma_f32_16x16x32_bf16 v[52:55], v[148:151], v[180:183], v[52:55]
	v_mfma_f32_16x16x32_bf16 v[52:55], v[152:155], v[184:187], v[52:55]
	v_mfma_f32_16x16x32_bf16 v[56:59], v[160:163], v[184:187], v[56:59]
	v_mfma_f32_16x16x32_bf16 v[56:59], v[156:159], v[180:183], v[56:59]
	v_mfma_f32_16x16x32_bf16 v[64:67], v[156:159], v[194:197], v[64:67]
	v_mfma_f32_16x16x32_bf16 v[64:67], v[160:163], v[198:201], v[64:67]
	s_setprio 2
	s_barrier
	v_mfma_f32_16x16x32_bf16 v[60:63], v[152:155], v[198:201], v[60:63]
	v_mfma_f32_16x16x32_bf16 v[60:63], v[148:151], v[194:197], v[60:63]
	s_setprio 0
	s_add_i32 s38, s71, s54
	s_mov_b32 m0, s38
	ds_read_b128 v[164:167], v231 offset:16384
	ds_read_b128 v[168:171], v231 offset:17408
	ds_read_b128 v[172:175], v231 offset:18432
	ds_read_b128 v[176:179], v231 offset:19456
	ds_read_b128 v[180:183], v231 offset:20480
	ds_read_b128 v[184:187], v231 offset:21504
	ds_read_b128 v[194:197], v231 offset:22528
	ds_read_b128 v[198:201], v231 offset:23552
	global_load_lds_dwordx4 v192, s[16:17]
	s_add_i32 m0, s38, 0x2000
	s_add_u32 s42, s16, 0x160000
	s_addc_u32 s43, s17, 0
	s_add_i32 s38, s72, s54
	global_load_lds_dwordx4 v190, s[16:17]
	s_mov_b32 m0, s38
	v_mov_b32_e32 v193, v3
	global_load_lds_dwordx4 v192, s[42:43]
	s_add_i32 m0, s38, 0x2000
	v_mov_b32_e32 v191, v3
	global_load_lds_dwordx4 v190, s[42:43]
	s_mov_b32 m0, s55
	v_lshl_add_u64 v[202:203], s[16:17], 0, v[192:193]
	global_load_lds_dwordx4 v2, s[26:27]
	s_mov_b32 m0, s56
	v_lshl_add_u64 v[204:205], s[16:17], 0, v[190:191]
	global_load_lds_dwordx4 v188, s[26:27]
	s_waitcnt vmcnt(8)
	s_waitcnt lgkmcnt(0)
	v_lshl_add_u64 v[206:207], s[26:27], 0, v[2:3]
	v_lshl_add_u64 v[208:209], s[26:27], 0, v[188:189]
	s_barrier
	s_setprio 1
	s_waitcnt lgkmcnt(0)
	s_nop 5
	v_mfma_f32_16x16x32_bf16 v[68:71], v[132:135], v[164:167], v[68:71]
	v_mfma_f32_16x16x32_bf16 v[68:71], v[136:139], v[168:171], v[68:71]
	v_mfma_f32_16x16x32_bf16 v[72:75], v[144:147], v[168:171], v[72:75]
	v_mfma_f32_16x16x32_bf16 v[72:75], v[140:143], v[164:167], v[72:75]
	v_mfma_f32_16x16x32_bf16 v[80:83], v[140:143], v[172:175], v[80:83]
	v_mfma_f32_16x16x32_bf16 v[80:83], v[144:147], v[176:179], v[80:83]
	v_mfma_f32_16x16x32_bf16 v[76:79], v[136:139], v[176:179], v[76:79]
	v_mfma_f32_16x16x32_bf16 v[76:79], v[132:135], v[172:175], v[76:79]
	v_mfma_f32_16x16x32_bf16 v[84:87], v[132:135], v[180:183], v[84:87]
	v_mfma_f32_16x16x32_bf16 v[84:87], v[136:139], v[184:187], v[84:87]
	v_mfma_f32_16x16x32_bf16 v[88:91], v[144:147], v[184:187], v[88:91]
	v_mfma_f32_16x16x32_bf16 v[88:91], v[140:143], v[180:183], v[88:91]
	v_mfma_f32_16x16x32_bf16 v[96:99], v[140:143], v[194:197], v[96:99]
	v_mfma_f32_16x16x32_bf16 v[96:99], v[144:147], v[198:201], v[96:99]
	v_mfma_f32_16x16x32_bf16 v[92:95], v[136:139], v[198:201], v[92:95]
	v_mfma_f32_16x16x32_bf16 v[92:95], v[132:135], v[194:197], v[92:95]
	s_setprio 0
	s_setprio 1
	v_mfma_f32_16x16x32_bf16 v[100:103], v[148:151], v[164:167], v[100:103]
	v_mfma_f32_16x16x32_bf16 v[100:103], v[152:155], v[168:171], v[100:103]
	v_mfma_f32_16x16x32_bf16 v[104:107], v[160:163], v[168:171], v[104:107]
	v_mfma_f32_16x16x32_bf16 v[104:107], v[156:159], v[164:167], v[104:107]
	v_mfma_f32_16x16x32_bf16 v[112:115], v[156:159], v[172:175], v[112:115]
	v_mfma_f32_16x16x32_bf16 v[112:115], v[160:163], v[176:179], v[112:115]
	v_mfma_f32_16x16x32_bf16 v[108:111], v[152:155], v[176:179], v[108:111]
	v_mfma_f32_16x16x32_bf16 v[108:111], v[148:151], v[172:175], v[108:111]
	v_mfma_f32_16x16x32_bf16 v[116:119], v[148:151], v[180:183], v[116:119]
	v_mfma_f32_16x16x32_bf16 v[116:119], v[152:155], v[184:187], v[116:119]
	v_mfma_f32_16x16x32_bf16 v[120:123], v[160:163], v[184:187], v[120:123]
	v_mfma_f32_16x16x32_bf16 v[120:123], v[156:159], v[180:183], v[120:123]
	v_mfma_f32_16x16x32_bf16 v[128:131], v[156:159], v[194:197], v[128:131]
	v_mfma_f32_16x16x32_bf16 v[128:131], v[160:163], v[198:201], v[128:131]
	s_setprio 2
	s_barrier
	v_mfma_f32_16x16x32_bf16 v[124:127], v[152:155], v[198:201], v[124:127]
	v_mfma_f32_16x16x32_bf16 v[124:127], v[148:151], v[194:197], v[124:127]
	s_setprio 0
	s_add_i32 s38, 0, 0x18000
	s_add_i32 s42, 0, 0x1c000
	ds_read_b128 v[132:135], v240 offset:32768
	ds_read_b128 v[136:139], v240 offset:33792
	ds_read_b128 v[140:143], v240 offset:34816
	ds_read_b128 v[144:147], v240 offset:35840
	ds_read_b128 v[148:151], v240 offset:49152
	ds_read_b128 v[152:155], v240 offset:50176
	ds_read_b128 v[156:159], v240 offset:51200
	ds_read_b128 v[160:163], v240 offset:52224
	s_add_u32 s26, s26, 0x160000
	s_addc_u32 s27, s27, 0
	s_mov_b32 m0, s57
	ds_read_b128 v[164:167], v231 offset:32768
	ds_read_b128 v[168:171], v231 offset:33792
	ds_read_b128 v[172:175], v231 offset:34816
	ds_read_b128 v[176:179], v231 offset:35840
	ds_read_b128 v[180:183], v231 offset:36864
	ds_read_b128 v[184:187], v231 offset:37888
	ds_read_b128 v[194:197], v231 offset:38912
	ds_read_b128 v[198:201], v231 offset:39936
	global_load_lds_dwordx4 v2, s[26:27]
	s_mov_b32 m0, s58
	s_nop 0
	global_load_lds_dwordx4 v188, s[26:27]
	s_waitcnt vmcnt(8)
	s_waitcnt lgkmcnt(0)
	s_barrier
	s_setprio 1
	s_waitcnt lgkmcnt(0)
	s_nop 5
	v_mfma_f32_16x16x32_bf16 v[4:7], v[132:135], v[164:167], v[4:7]
	v_mfma_f32_16x16x32_bf16 v[4:7], v[136:139], v[168:171], v[4:7]
	v_mfma_f32_16x16x32_bf16 v[8:11], v[144:147], v[168:171], v[8:11]
	v_mfma_f32_16x16x32_bf16 v[8:11], v[140:143], v[164:167], v[8:11]
	v_mfma_f32_16x16x32_bf16 v[16:19], v[140:143], v[172:175], v[16:19]
	v_mfma_f32_16x16x32_bf16 v[16:19], v[144:147], v[176:179], v[16:19]
	v_mfma_f32_16x16x32_bf16 v[12:15], v[136:139], v[176:179], v[12:15]
	v_mfma_f32_16x16x32_bf16 v[12:15], v[132:135], v[172:175], v[12:15]
	v_mfma_f32_16x16x32_bf16 v[20:23], v[132:135], v[180:183], v[20:23]
	v_mfma_f32_16x16x32_bf16 v[20:23], v[136:139], v[184:187], v[20:23]
	v_mfma_f32_16x16x32_bf16 v[24:27], v[144:147], v[184:187], v[24:27]
	v_mfma_f32_16x16x32_bf16 v[24:27], v[140:143], v[180:183], v[24:27]
	v_mfma_f32_16x16x32_bf16 v[32:35], v[140:143], v[194:197], v[32:35]
	v_mfma_f32_16x16x32_bf16 v[32:35], v[144:147], v[198:201], v[32:35]
	v_mfma_f32_16x16x32_bf16 v[28:31], v[136:139], v[198:201], v[28:31]
	v_mfma_f32_16x16x32_bf16 v[28:31], v[132:135], v[194:197], v[28:31]
	s_setprio 0
	s_setprio 1
	v_mfma_f32_16x16x32_bf16 v[36:39], v[148:151], v[164:167], v[36:39]
	v_mfma_f32_16x16x32_bf16 v[36:39], v[152:155], v[168:171], v[36:39]
	v_mfma_f32_16x16x32_bf16 v[40:43], v[160:163], v[168:171], v[40:43]
	v_mfma_f32_16x16x32_bf16 v[40:43], v[156:159], v[164:167], v[40:43]
	v_mfma_f32_16x16x32_bf16 v[48:51], v[156:159], v[172:175], v[48:51]
	v_mfma_f32_16x16x32_bf16 v[48:51], v[160:163], v[176:179], v[48:51]
	v_mfma_f32_16x16x32_bf16 v[44:47], v[152:155], v[176:179], v[44:47]
	v_mfma_f32_16x16x32_bf16 v[44:47], v[148:151], v[172:175], v[44:47]
	v_mfma_f32_16x16x32_bf16 v[52:55], v[148:151], v[180:183], v[52:55]
	v_mfma_f32_16x16x32_bf16 v[52:55], v[152:155], v[184:187], v[52:55]
	v_mfma_f32_16x16x32_bf16 v[56:59], v[160:163], v[184:187], v[56:59]
	v_mfma_f32_16x16x32_bf16 v[56:59], v[156:159], v[180:183], v[56:59]
	v_mfma_f32_16x16x32_bf16 v[64:67], v[156:159], v[194:197], v[64:67]
	v_mfma_f32_16x16x32_bf16 v[64:67], v[160:163], v[198:201], v[64:67]
	s_setprio 2
	s_barrier
	v_mfma_f32_16x16x32_bf16 v[60:63], v[152:155], v[198:201], v[60:63]
	v_mfma_f32_16x16x32_bf16 v[60:63], v[148:151], v[194:197], v[60:63]
	s_setprio 0
	s_add_i32 s26, s38, s54
	v_lshl_add_u64 v[202:203], v[202:203], 0, s[4:5]
	s_mov_b32 m0, s26
	ds_read_b128 v[164:167], v231 offset:49152
	ds_read_b128 v[168:171], v231 offset:50176
	ds_read_b128 v[172:175], v231 offset:51200
	ds_read_b128 v[176:179], v231 offset:52224
	ds_read_b128 v[180:183], v231 offset:53248
	ds_read_b128 v[184:187], v231 offset:54272
	ds_read_b128 v[194:197], v231 offset:55296
	ds_read_b128 v[198:201], v231 offset:56320
	global_load_lds_dwordx4 v[202:203], off
	s_add_i32 m0, s26, 0x2000
	s_add_u32 s16, s16, 0x15ff80
	v_lshl_add_u64 v[202:203], v[204:205], 0, s[4:5]
	s_addc_u32 s17, s17, 0
	s_add_i32 s26, s42, s54
	global_load_lds_dwordx4 v[202:203], off
	s_mov_b32 m0, s26
	v_lshl_add_u64 v[202:203], v[206:207], 0, s[4:5]
	global_load_lds_dwordx4 v192, s[16:17]
	s_add_i32 m0, s26, 0x2000
	s_nop 0
	global_load_lds_dwordx4 v190, s[16:17]
	s_mov_b32 m0, s62
	s_nop 0
	global_load_lds_dwordx4 v[202:203], off
	v_lshl_add_u64 v[202:203], v[208:209], 0, s[4:5]
	s_mov_b32 m0, s63
	s_nop 0
	global_load_lds_dwordx4 v[202:203], off
	s_waitcnt vmcnt(8)
	s_waitcnt lgkmcnt(0)
	s_barrier
	s_setprio 1
	s_waitcnt lgkmcnt(0)
	s_nop 5
	v_mfma_f32_16x16x32_bf16 v[68:71], v[132:135], v[164:167], v[68:71]
	v_mfma_f32_16x16x32_bf16 v[68:71], v[136:139], v[168:171], v[68:71]
	v_mfma_f32_16x16x32_bf16 v[72:75], v[144:147], v[168:171], v[72:75]
	v_mfma_f32_16x16x32_bf16 v[72:75], v[140:143], v[164:167], v[72:75]
	v_mfma_f32_16x16x32_bf16 v[80:83], v[140:143], v[172:175], v[80:83]
	v_mfma_f32_16x16x32_bf16 v[80:83], v[144:147], v[176:179], v[80:83]
	v_mfma_f32_16x16x32_bf16 v[76:79], v[136:139], v[176:179], v[76:79]
	v_mfma_f32_16x16x32_bf16 v[76:79], v[132:135], v[172:175], v[76:79]
	v_mfma_f32_16x16x32_bf16 v[84:87], v[132:135], v[180:183], v[84:87]
	v_mfma_f32_16x16x32_bf16 v[84:87], v[136:139], v[184:187], v[84:87]
	v_mfma_f32_16x16x32_bf16 v[88:91], v[144:147], v[184:187], v[88:91]
	v_mfma_f32_16x16x32_bf16 v[88:91], v[140:143], v[180:183], v[88:91]
	v_mfma_f32_16x16x32_bf16 v[96:99], v[140:143], v[194:197], v[96:99]
	v_mfma_f32_16x16x32_bf16 v[96:99], v[144:147], v[198:201], v[96:99]
	v_mfma_f32_16x16x32_bf16 v[92:95], v[136:139], v[198:201], v[92:95]
	v_mfma_f32_16x16x32_bf16 v[92:95], v[132:135], v[194:197], v[92:95]
	s_setprio 0
	s_setprio 1
	v_mfma_f32_16x16x32_bf16 v[100:103], v[148:151], v[164:167], v[100:103]
	v_mfma_f32_16x16x32_bf16 v[100:103], v[152:155], v[168:171], v[100:103]
	v_mfma_f32_16x16x32_bf16 v[104:107], v[160:163], v[168:171], v[104:107]
	v_mfma_f32_16x16x32_bf16 v[104:107], v[156:159], v[164:167], v[104:107]
	v_mfma_f32_16x16x32_bf16 v[112:115], v[156:159], v[172:175], v[112:115]
	v_mfma_f32_16x16x32_bf16 v[112:115], v[160:163], v[176:179], v[112:115]
	v_mfma_f32_16x16x32_bf16 v[108:111], v[152:155], v[176:179], v[108:111]
	v_mfma_f32_16x16x32_bf16 v[108:111], v[148:151], v[172:175], v[108:111]
	v_mfma_f32_16x16x32_bf16 v[116:119], v[148:151], v[180:183], v[116:119]
	v_mfma_f32_16x16x32_bf16 v[116:119], v[152:155], v[184:187], v[116:119]
	v_mfma_f32_16x16x32_bf16 v[120:123], v[160:163], v[184:187], v[120:123]
	v_mfma_f32_16x16x32_bf16 v[120:123], v[156:159], v[180:183], v[120:123]
	v_mfma_f32_16x16x32_bf16 v[128:131], v[156:159], v[194:197], v[128:131]
	v_mfma_f32_16x16x32_bf16 v[128:131], v[160:163], v[198:201], v[128:131]
	s_setprio 2
	s_barrier
	v_mfma_f32_16x16x32_bf16 v[124:127], v[152:155], v[198:201], v[124:127]
	v_mfma_f32_16x16x32_bf16 v[124:127], v[148:151], v[194:197], v[124:127]
	s_setprio 0
	s_cmpk_gt_u32 s28, 0x55
	s_cbranch_scc1 .LBB0_651
	s_mov_b32 s28, s29
	s_branch .LBB0_645

.LBB0_749:
	s_add_i32 s47, 0, 0x10000
	s_add_i32 s49, 0, 0x14000
	v_add_u32_e32 v16, s47, v147
	v_add_u32_e32 v32, s49, v147
	ds_read_b128 v[4:7], v16
	ds_read_b128 v[8:11], v16 offset:1024
	ds_read_b128 v[12:15], v16 offset:2048
	ds_read_b128 v[16:19], v16 offset:3072
	ds_read_b128 v[20:23], v32
	ds_read_b128 v[24:27], v32 offset:1024
	ds_read_b128 v[28:31], v32 offset:2048
	ds_read_b128 v[32:35], v32 offset:3072
	v_add_u32_e32 v231, 0, v146
	ds_read_b128 v[36:39], v231
	ds_read_b128 v[40:43], v231 offset:1024
	ds_read_b128 v[44:47], v231 offset:2048
	ds_read_b128 v[48:51], v231 offset:3072
	ds_read_b128 v[52:55], v231 offset:4096
	ds_read_b128 v[56:59], v231 offset:5120
	ds_read_b128 v[60:63], v231 offset:6144
	ds_read_b128 v[64:67], v231 offset:7168
	s_waitcnt vmcnt(8)
	s_waitcnt lgkmcnt(0)
	s_barrier
	s_setprio 1
	s_waitcnt lgkmcnt(0)
	s_nop 5
	v_mfma_f32_16x16x32_f16 v[68:71], v[4:7], v[36:39], 0
	v_mfma_f32_16x16x32_f16 v[68:71], v[8:11], v[40:43], v[68:71]
	v_mfma_f32_16x16x32_f16 v[72:75], v[12:15], v[36:39], 0
	v_mfma_f32_16x16x32_f16 v[72:75], v[16:19], v[40:43], v[72:75]
	v_mfma_f32_16x16x32_f16 v[80:83], v[12:15], v[44:47], 0
	v_mfma_f32_16x16x32_f16 v[80:83], v[16:19], v[48:51], v[80:83]
	v_mfma_f32_16x16x32_f16 v[76:79], v[4:7], v[44:47], 0
	v_mfma_f32_16x16x32_f16 v[76:79], v[8:11], v[48:51], v[76:79]
	v_mfma_f32_16x16x32_f16 v[84:87], v[4:7], v[52:55], 0
	v_mfma_f32_16x16x32_f16 v[84:87], v[8:11], v[56:59], v[84:87]
	v_mfma_f32_16x16x32_f16 v[88:91], v[12:15], v[52:55], 0
	v_mfma_f32_16x16x32_f16 v[88:91], v[16:19], v[56:59], v[88:91]
	v_mfma_f32_16x16x32_f16 v[96:99], v[12:15], v[60:63], 0
	v_mfma_f32_16x16x32_f16 v[96:99], v[16:19], v[64:67], v[96:99]
	v_mfma_f32_16x16x32_f16 v[92:95], v[4:7], v[60:63], 0
	v_mfma_f32_16x16x32_f16 v[92:95], v[8:11], v[64:67], v[92:95]
	s_setprio 0
	s_setprio 1
	v_mfma_f32_16x16x32_f16 v[100:103], v[20:23], v[36:39], 0
	v_mfma_f32_16x16x32_f16 v[36:39], v[28:31], v[36:39], 0
	v_mfma_f32_16x16x32_f16 v[104:107], v[20:23], v[44:47], 0
	v_mfma_f32_16x16x32_f16 v[44:47], v[28:31], v[44:47], 0
	v_mfma_f32_16x16x32_f16 v[108:111], v[20:23], v[52:55], 0
	v_mfma_f32_16x16x32_f16 v[52:55], v[28:31], v[52:55], 0
	v_mfma_f32_16x16x32_f16 v[112:115], v[20:23], v[60:63], 0
	v_mfma_f32_16x16x32_f16 v[60:63], v[28:31], v[60:63], 0
	v_mfma_f32_16x16x32_f16 v[100:103], v[24:27], v[40:43], v[100:103]
	v_mfma_f32_16x16x32_f16 v[40:43], v[32:35], v[40:43], v[36:39]
	v_mfma_f32_16x16x32_f16 v[104:107], v[24:27], v[48:51], v[104:107]
	v_mfma_f32_16x16x32_f16 v[48:51], v[32:35], v[48:51], v[44:47]
	v_mfma_f32_16x16x32_f16 v[108:111], v[24:27], v[56:59], v[108:111]
	v_mfma_f32_16x16x32_f16 v[56:59], v[32:35], v[56:59], v[52:55]
	s_setprio 2
	s_barrier
	v_mfma_f32_16x16x32_f16 v[112:115], v[24:27], v[64:67], v[112:115]
	v_mfma_f32_16x16x32_f16 v[64:67], v[32:35], v[64:67], v[60:63]
	s_setprio 0
	v_lshl_add_u64 v[136:137], s[6:7], 0, v[2:3]
	s_add_i32 s47, s47, s62
	v_mov_b32_e32 v135, v3
	v_lshl_add_u64 v[140:141], v[136:137], 0, s[74:75]
	s_mov_b32 m0, s47
	v_lshl_add_u64 v[144:145], s[6:7], 0, v[134:135]
	ds_read_b128 v[36:39], v231 offset:16384
	ds_read_b128 v[44:47], v231 offset:17408
	ds_read_b128 v[52:55], v231 offset:18432
	ds_read_b128 v[60:63], v231 offset:19456
	ds_read_b128 v[116:119], v231 offset:20480
	ds_read_b128 v[120:123], v231 offset:21504
	ds_read_b128 v[124:127], v231 offset:22528
	ds_read_b128 v[128:131], v231 offset:23552
	global_load_lds_dwordx4 v[140:141], off
	v_lshl_add_u64 v[140:141], v[144:145], 0, s[74:75]
	s_add_i32 m0, s47, 0x2000
	s_add_i32 s47, s49, s62
	global_load_lds_dwordx4 v[140:141], off
	s_mov_b32 m0, s47
	v_mov_b32_e32 v139, v3
	global_load_lds_dwordx4 v2, s[16:17]
	s_add_i32 m0, s47, 0x2000
	v_lshl_add_u64 v[248:249], s[8:9], 0, v[138:139]
	v_mov_b32_e32 v133, v3
	global_load_lds_dwordx4 v134, s[16:17]
	v_lshl_add_u64 v[140:141], v[248:249], 0, s[74:75]
	s_mov_b32 m0, s63
	v_lshl_add_u64 v[250:251], s[8:9], 0, v[132:133]
	global_load_lds_dwordx4 v[140:141], off
	v_lshl_add_u64 v[140:141], v[250:251], 0, s[74:75]
	s_mov_b32 m0, s64
	s_nop 0
	global_load_lds_dwordx4 v[140:141], off
	s_waitcnt vmcnt(8)
	s_waitcnt lgkmcnt(0)
	s_barrier
	s_setprio 1
	s_waitcnt lgkmcnt(0)
	s_nop 5
	v_mfma_f32_16x16x32_f16 v[140:143], v[4:7], v[36:39], 0
	v_mfma_f32_16x16x32_f16 v[148:151], v[12:15], v[36:39], 0
	v_mfma_f32_16x16x32_f16 v[152:155], v[4:7], v[52:55], 0
	v_mfma_f32_16x16x32_f16 v[156:159], v[12:15], v[52:55], 0
	v_mfma_f32_16x16x32_f16 v[160:163], v[4:7], v[116:119], 0
	v_mfma_f32_16x16x32_f16 v[164:167], v[12:15], v[116:119], 0
	v_mfma_f32_16x16x32_f16 v[4:7], v[4:7], v[124:127], 0
	v_mfma_f32_16x16x32_f16 v[12:15], v[12:15], v[124:127], 0
	v_mfma_f32_16x16x32_f16 v[140:143], v[8:11], v[44:47], v[140:143]
	v_mfma_f32_16x16x32_f16 v[148:151], v[16:19], v[44:47], v[148:151]
	v_mfma_f32_16x16x32_f16 v[152:155], v[8:11], v[60:63], v[152:155]
	v_mfma_f32_16x16x32_f16 v[156:159], v[16:19], v[60:63], v[156:159]
	v_mfma_f32_16x16x32_f16 v[160:163], v[8:11], v[120:123], v[160:163]
	v_mfma_f32_16x16x32_f16 v[164:167], v[16:19], v[120:123], v[164:167]
	v_mfma_f32_16x16x32_f16 v[168:171], v[8:11], v[128:131], v[4:7]
	v_mfma_f32_16x16x32_f16 v[172:175], v[16:19], v[128:131], v[12:15]
	s_setprio 0
	s_setprio 1
	v_mfma_f32_16x16x32_f16 v[4:7], v[20:23], v[36:39], 0
	v_mfma_f32_16x16x32_f16 v[8:11], v[28:31], v[36:39], 0
	v_mfma_f32_16x16x32_f16 v[12:15], v[20:23], v[52:55], 0
	v_mfma_f32_16x16x32_f16 v[16:19], v[28:31], v[52:55], 0
	v_mfma_f32_16x16x32_f16 v[36:39], v[20:23], v[116:119], 0
	v_mfma_f32_16x16x32_f16 v[52:55], v[28:31], v[116:119], 0
	v_mfma_f32_16x16x32_f16 v[20:23], v[20:23], v[124:127], 0
	v_mfma_f32_16x16x32_f16 v[28:31], v[28:31], v[124:127], 0
	v_mfma_f32_16x16x32_f16 v[116:119], v[24:27], v[44:47], v[4:7]
	v_mfma_f32_16x16x32_f16 v[124:127], v[32:35], v[44:47], v[8:11]
	v_mfma_f32_16x16x32_f16 v[184:187], v[24:27], v[120:123], v[36:39]
	v_mfma_f32_16x16x32_f16 v[120:123], v[32:35], v[120:123], v[52:55]
	v_mfma_f32_16x16x32_f16 v[188:191], v[24:27], v[128:131], v[20:23]
	v_mfma_f32_16x16x32_f16 v[128:131], v[32:35], v[128:131], v[28:31]
	s_setprio 2
	s_barrier
	v_mfma_f32_16x16x32_f16 v[176:179], v[24:27], v[60:63], v[12:15]
	v_mfma_f32_16x16x32_f16 v[180:183], v[32:35], v[60:63], v[16:19]
	s_setprio 0
	s_add_i32 s47, 0, 0x18000
	v_add_u32_e32 v4, s47, v147
	s_add_i32 s49, 0, 0x1c000
	ds_read_b128 v[192:195], v4
	ds_read_b128 v[196:199], v4 offset:1024
	ds_read_b128 v[200:203], v4 offset:2048
	ds_read_b128 v[204:207], v4 offset:3072
	v_add_u32_e32 v4, s49, v147
	ds_read_b128 v[208:211], v4
	ds_read_b128 v[212:215], v4 offset:1024
	ds_read_b128 v[216:219], v4 offset:2048
	ds_read_b128 v[220:223], v4 offset:3072
	s_mov_b32 m0, s65
	ds_read_b128 v[44:47], v231 offset:32768
	ds_read_b128 v[52:55], v231 offset:33792
	ds_read_b128 v[60:63], v231 offset:34816
	ds_read_b128 v[224:227], v231 offset:35840
	ds_read_b128 v[232:235], v231 offset:36864
	ds_read_b128 v[236:239], v231 offset:37888
	ds_read_b128 v[240:243], v231 offset:38912
	ds_read_b128 v[244:247], v231 offset:39936
	global_load_lds_dwordx4 v138, s[26:27]
	s_mov_b32 m0, s66
	s_nop 0
	global_load_lds_dwordx4 v132, s[26:27]
	s_waitcnt vmcnt(8)
	s_waitcnt lgkmcnt(0)
	s_barrier
	s_setprio 1
	s_waitcnt lgkmcnt(0)
	s_nop 5
	v_mfma_f32_16x16x32_f16 v[4:7], v[192:195], v[44:47], v[68:71]
	v_mfma_f32_16x16x32_f16 v[8:11], v[200:203], v[44:47], v[72:75]
	v_mfma_f32_16x16x32_f16 v[12:15], v[192:195], v[60:63], v[76:79]
	v_mfma_f32_16x16x32_f16 v[16:19], v[200:203], v[60:63], v[80:83]
	v_mfma_f32_16x16x32_f16 v[20:23], v[192:195], v[232:235], v[84:87]
	v_mfma_f32_16x16x32_f16 v[24:27], v[200:203], v[232:235], v[88:91]
	v_mfma_f32_16x16x32_f16 v[28:31], v[192:195], v[240:243], v[92:95]
	v_mfma_f32_16x16x32_f16 v[32:35], v[200:203], v[240:243], v[96:99]
	v_mfma_f32_16x16x32_f16 v[4:7], v[196:199], v[52:55], v[4:7]
	v_mfma_f32_16x16x32_f16 v[8:11], v[204:207], v[52:55], v[8:11]
	v_mfma_f32_16x16x32_f16 v[12:15], v[196:199], v[224:227], v[12:15]
	v_mfma_f32_16x16x32_f16 v[16:19], v[204:207], v[224:227], v[16:19]
	v_mfma_f32_16x16x32_f16 v[20:23], v[196:199], v[236:239], v[20:23]
	v_mfma_f32_16x16x32_f16 v[24:27], v[204:207], v[236:239], v[24:27]
	v_mfma_f32_16x16x32_f16 v[28:31], v[196:199], v[244:247], v[28:31]
	v_mfma_f32_16x16x32_f16 v[32:35], v[204:207], v[244:247], v[32:35]
	s_setprio 0
	s_setprio 1
	v_mfma_f32_16x16x32_f16 v[36:39], v[208:211], v[44:47], v[100:103]
	v_mfma_f32_16x16x32_f16 v[40:43], v[216:219], v[44:47], v[40:43]
	v_mfma_f32_16x16x32_f16 v[36:39], v[212:215], v[52:55], v[36:39]
	v_mfma_f32_16x16x32_f16 v[40:43], v[220:223], v[52:55], v[40:43]
	v_mfma_f32_16x16x32_f16 v[44:47], v[208:211], v[60:63], v[104:107]
	v_mfma_f32_16x16x32_f16 v[48:51], v[216:219], v[60:63], v[48:51]
	v_mfma_f32_16x16x32_f16 v[52:55], v[208:211], v[232:235], v[108:111]
	v_mfma_f32_16x16x32_f16 v[56:59], v[216:219], v[232:235], v[56:59]
	v_mfma_f32_16x16x32_f16 v[60:63], v[208:211], v[240:243], v[112:115]
	v_mfma_f32_16x16x32_f16 v[64:67], v[216:219], v[240:243], v[64:67]
	v_mfma_f32_16x16x32_f16 v[44:47], v[212:215], v[224:227], v[44:47]
	v_mfma_f32_16x16x32_f16 v[48:51], v[220:223], v[224:227], v[48:51]
	v_mfma_f32_16x16x32_f16 v[52:55], v[212:215], v[236:239], v[52:55]
	v_mfma_f32_16x16x32_f16 v[56:59], v[220:223], v[236:239], v[56:59]
	s_setprio 2
	s_barrier
	v_mfma_f32_16x16x32_f16 v[60:63], v[212:215], v[244:247], v[60:63]
	v_mfma_f32_16x16x32_f16 v[64:67], v[220:223], v[244:247], v[64:67]
	s_setprio 0
	s_add_i32 s47, s47, s62
	v_lshl_add_u64 v[68:69], v[136:137], 0, s[24:25]
	s_mov_b32 m0, s47
	ds_read_b128 v[104:107], v231 offset:49152
	ds_read_b128 v[108:111], v231 offset:50176
	ds_read_b128 v[112:115], v231 offset:51200
	ds_read_b128 v[224:227], v231 offset:52224
	ds_read_b128 v[232:235], v231 offset:53248
	ds_read_b128 v[236:239], v231 offset:54272
	ds_read_b128 v[240:243], v231 offset:55296
	ds_read_b128 v[244:247], v231 offset:56320
	global_load_lds_dwordx4 v[68:69], off
	v_lshl_add_u64 v[68:69], v[144:145], 0, s[24:25]
	s_add_i32 m0, s47, 0x2000
	s_add_i32 s47, s49, s62
	global_load_lds_dwordx4 v[68:69], off
	s_mov_b32 m0, s47
	v_lshl_add_u64 v[68:69], v[248:249], 0, s[24:25]
	global_load_lds_dwordx4 v2, s[28:29]
	s_add_i32 m0, s47, 0x2000
	s_nop 0
	global_load_lds_dwordx4 v134, s[28:29]
	s_mov_b32 m0, s69
	s_nop 0
	global_load_lds_dwordx4 v[68:69], off
	v_lshl_add_u64 v[68:69], v[250:251], 0, s[24:25]
	s_mov_b32 m0, s70
	s_nop 0
	global_load_lds_dwordx4 v[68:69], off
	s_waitcnt vmcnt(8)
	s_waitcnt lgkmcnt(0)
	s_barrier
	s_setprio 1
	s_waitcnt lgkmcnt(0)
	s_nop 5
	v_mfma_f32_16x16x32_f16 v[68:71], v[192:195], v[104:107], v[140:143]
	v_mfma_f32_16x16x32_f16 v[72:75], v[200:203], v[104:107], v[148:151]
	v_mfma_f32_16x16x32_f16 v[76:79], v[192:195], v[112:115], v[152:155]
	v_mfma_f32_16x16x32_f16 v[80:83], v[200:203], v[112:115], v[156:159]
	v_mfma_f32_16x16x32_f16 v[84:87], v[192:195], v[232:235], v[160:163]
	v_mfma_f32_16x16x32_f16 v[88:91], v[200:203], v[232:235], v[164:167]
	v_mfma_f32_16x16x32_f16 v[92:95], v[192:195], v[240:243], v[168:171]
	v_mfma_f32_16x16x32_f16 v[96:99], v[200:203], v[240:243], v[172:175]
	v_mfma_f32_16x16x32_f16 v[68:71], v[196:199], v[108:111], v[68:71]
	v_mfma_f32_16x16x32_f16 v[72:75], v[204:207], v[108:111], v[72:75]
	v_mfma_f32_16x16x32_f16 v[76:79], v[196:199], v[224:227], v[76:79]
	v_mfma_f32_16x16x32_f16 v[80:83], v[204:207], v[224:227], v[80:83]
	v_mfma_f32_16x16x32_f16 v[84:87], v[196:199], v[236:239], v[84:87]
	v_mfma_f32_16x16x32_f16 v[88:91], v[204:207], v[236:239], v[88:91]
	v_mfma_f32_16x16x32_f16 v[92:95], v[196:199], v[244:247], v[92:95]
	v_mfma_f32_16x16x32_f16 v[96:99], v[204:207], v[244:247], v[96:99]
	s_setprio 0
	s_setprio 1
	v_mfma_f32_16x16x32_f16 v[100:103], v[208:211], v[104:107], v[116:119]
	v_mfma_f32_16x16x32_f16 v[104:107], v[216:219], v[104:107], v[124:127]
	v_mfma_f32_16x16x32_f16 v[100:103], v[212:215], v[108:111], v[100:103]
	v_mfma_f32_16x16x32_f16 v[104:107], v[220:223], v[108:111], v[104:107]
	v_mfma_f32_16x16x32_f16 v[108:111], v[208:211], v[112:115], v[176:179]
	v_mfma_f32_16x16x32_f16 v[112:115], v[216:219], v[112:115], v[180:183]
	v_mfma_f32_16x16x32_f16 v[116:119], v[208:211], v[232:235], v[184:187]
	v_mfma_f32_16x16x32_f16 v[120:123], v[216:219], v[232:235], v[120:123]
	v_mfma_f32_16x16x32_f16 v[124:127], v[208:211], v[240:243], v[188:191]
	v_mfma_f32_16x16x32_f16 v[128:131], v[216:219], v[240:243], v[128:131]
	v_mfma_f32_16x16x32_f16 v[108:111], v[212:215], v[224:227], v[108:111]
	v_mfma_f32_16x16x32_f16 v[112:115], v[220:223], v[224:227], v[112:115]
	v_mfma_f32_16x16x32_f16 v[116:119], v[212:215], v[236:239], v[116:119]
	v_mfma_f32_16x16x32_f16 v[120:123], v[220:223], v[236:239], v[120:123]
	s_setprio 2
	s_barrier
	v_mfma_f32_16x16x32_f16 v[124:127], v[212:215], v[244:247], v[124:127]
	v_mfma_f32_16x16x32_f16 v[128:131], v[220:223], v[244:247], v[128:131]
	s_setprio 0
	s_add_i32 s45, s45, 2
	s_cmp_ge_i32 s45, s44
	s_cbranch_scc0 .LBB0_749
	v_mov_b32_e32 v136, v2
	s_branch .LBB0_752

.LBB0_753:
	s_add_u32 s6, s8, 0xfff80080
	s_addc_u32 s7, s9, -1
	s_add_i32 s29, 0, 0x10000
	s_cmp_eq_u32 s28, 28
	s_cselect_b32 s17, s13, s7
	s_cselect_b32 s16, s12, s6
	v_add_u32_e32 v133, s29, v147
	s_cselect_b32 s7, s15, s27
	s_cselect_b32 s6, s14, s26
	s_add_i32 s47, 0, 0x14000
	ds_read_b128 v[138:141], v133
	ds_read_b128 v[142:145], v133 offset:1024
	ds_read_b128 v[148:151], v133 offset:2048
	ds_read_b128 v[152:155], v133 offset:3072
	v_add_u32_e32 v133, s47, v147
	ds_read_b128 v[156:159], v133
	ds_read_b128 v[160:163], v133 offset:1024
	ds_read_b128 v[164:167], v133 offset:2048
	ds_read_b128 v[168:171], v133 offset:3072
	s_mov_b32 m0, s71
	v_add_u32_e32 v212, 0, v146
	ds_read_b128 v[172:175], v212
	ds_read_b128 v[176:179], v212 offset:1024
	ds_read_b128 v[180:183], v212 offset:2048
	ds_read_b128 v[184:187], v212 offset:3072
	ds_read_b128 v[188:191], v212 offset:4096
	ds_read_b128 v[192:195], v212 offset:5120
	ds_read_b128 v[196:199], v212 offset:6144
	ds_read_b128 v[200:203], v212 offset:7168
	global_load_lds_dwordx4 v2, s[8:9]
	s_mov_b32 m0, s72
	v_mov_b32_e32 v133, v3
	global_load_lds_dwordx4 v132, s[8:9]
	s_waitcnt vmcnt(8)
	s_waitcnt lgkmcnt(0)
	s_barrier
	s_setprio 1
	s_waitcnt lgkmcnt(0)
	s_nop 5
	v_mfma_f32_16x16x32_f16 v[4:7], v[138:141], v[172:175], v[4:7]
	v_mfma_f32_16x16x32_f16 v[4:7], v[142:145], v[176:179], v[4:7]
	v_mfma_f32_16x16x32_f16 v[8:11], v[152:155], v[176:179], v[8:11]
	v_mfma_f32_16x16x32_f16 v[8:11], v[148:151], v[172:175], v[8:11]
	v_mfma_f32_16x16x32_f16 v[16:19], v[148:151], v[180:183], v[16:19]
	v_mfma_f32_16x16x32_f16 v[16:19], v[152:155], v[184:187], v[16:19]
	v_mfma_f32_16x16x32_f16 v[12:15], v[142:145], v[184:187], v[12:15]
	v_mfma_f32_16x16x32_f16 v[12:15], v[138:141], v[180:183], v[12:15]
	v_mfma_f32_16x16x32_f16 v[20:23], v[138:141], v[188:191], v[20:23]
	v_mfma_f32_16x16x32_f16 v[20:23], v[142:145], v[192:195], v[20:23]
	v_mfma_f32_16x16x32_f16 v[24:27], v[152:155], v[192:195], v[24:27]
	v_mfma_f32_16x16x32_f16 v[24:27], v[148:151], v[188:191], v[24:27]
	v_mfma_f32_16x16x32_f16 v[32:35], v[148:151], v[196:199], v[32:35]
	v_mfma_f32_16x16x32_f16 v[32:35], v[152:155], v[200:203], v[32:35]
	v_mfma_f32_16x16x32_f16 v[28:31], v[142:145], v[200:203], v[28:31]
	v_mfma_f32_16x16x32_f16 v[28:31], v[138:141], v[196:199], v[28:31]
	s_setprio 0
	s_setprio 1
	v_mfma_f32_16x16x32_f16 v[36:39], v[156:159], v[172:175], v[36:39]
	v_mfma_f32_16x16x32_f16 v[36:39], v[160:163], v[176:179], v[36:39]
	v_mfma_f32_16x16x32_f16 v[40:43], v[168:171], v[176:179], v[40:43]
	v_mfma_f32_16x16x32_f16 v[40:43], v[164:167], v[172:175], v[40:43]
	v_mfma_f32_16x16x32_f16 v[48:51], v[164:167], v[180:183], v[48:51]
	v_mfma_f32_16x16x32_f16 v[48:51], v[168:171], v[184:187], v[48:51]
	v_mfma_f32_16x16x32_f16 v[44:47], v[160:163], v[184:187], v[44:47]
	v_mfma_f32_16x16x32_f16 v[44:47], v[156:159], v[180:183], v[44:47]
	v_mfma_f32_16x16x32_f16 v[52:55], v[156:159], v[188:191], v[52:55]
	v_mfma_f32_16x16x32_f16 v[52:55], v[160:163], v[192:195], v[52:55]
	v_mfma_f32_16x16x32_f16 v[56:59], v[168:171], v[192:195], v[56:59]
	v_mfma_f32_16x16x32_f16 v[56:59], v[164:167], v[188:191], v[56:59]
	v_mfma_f32_16x16x32_f16 v[64:67], v[164:167], v[196:199], v[64:67]
	v_mfma_f32_16x16x32_f16 v[64:67], v[168:171], v[200:203], v[64:67]
	s_setprio 2
	s_barrier
	v_mfma_f32_16x16x32_f16 v[60:63], v[160:163], v[200:203], v[60:63]
	v_mfma_f32_16x16x32_f16 v[60:63], v[156:159], v[196:199], v[60:63]
	s_setprio 0
	s_add_i32 s29, s29, s62
	s_mov_b32 m0, s29
	ds_read_b128 v[172:175], v212 offset:16384
	ds_read_b128 v[176:179], v212 offset:17408
	ds_read_b128 v[180:183], v212 offset:18432
	ds_read_b128 v[184:187], v212 offset:19456
	ds_read_b128 v[188:191], v212 offset:20480
	ds_read_b128 v[192:195], v212 offset:21504
	ds_read_b128 v[196:199], v212 offset:22528
	ds_read_b128 v[200:203], v212 offset:23552
	global_load_lds_dwordx4 v136, s[6:7]
	s_add_i32 m0, s29, 0x2000
	s_add_u32 s44, s6, 0x80000
	s_addc_u32 s45, s7, 0
	s_add_i32 s29, s47, s62
	global_load_lds_dwordx4 v134, s[6:7]
	s_mov_b32 m0, s29
	v_mov_b32_e32 v137, v3
	global_load_lds_dwordx4 v136, s[44:45]
	s_add_i32 m0, s29, 0x2000
	v_mov_b32_e32 v135, v3
	global_load_lds_dwordx4 v134, s[44:45]
	s_mov_b32 m0, s63
	v_lshl_add_u64 v[204:205], s[6:7], 0, v[136:137]
	global_load_lds_dwordx4 v2, s[16:17]
	s_mov_b32 m0, s64
	v_lshl_add_u64 v[206:207], s[6:7], 0, v[134:135]
	global_load_lds_dwordx4 v132, s[16:17]
	s_waitcnt vmcnt(8)
	s_waitcnt lgkmcnt(0)
	v_lshl_add_u64 v[208:209], s[16:17], 0, v[2:3]
	v_lshl_add_u64 v[210:211], s[16:17], 0, v[132:133]
	s_barrier
	s_setprio 1
	s_waitcnt lgkmcnt(0)
	s_nop 5
	v_mfma_f32_16x16x32_f16 v[68:71], v[138:141], v[172:175], v[68:71]
	v_mfma_f32_16x16x32_f16 v[68:71], v[142:145], v[176:179], v[68:71]
	v_mfma_f32_16x16x32_f16 v[72:75], v[152:155], v[176:179], v[72:75]
	v_mfma_f32_16x16x32_f16 v[72:75], v[148:151], v[172:175], v[72:75]
	v_mfma_f32_16x16x32_f16 v[80:83], v[148:151], v[180:183], v[80:83]
	v_mfma_f32_16x16x32_f16 v[80:83], v[152:155], v[184:187], v[80:83]
	v_mfma_f32_16x16x32_f16 v[76:79], v[142:145], v[184:187], v[76:79]
	v_mfma_f32_16x16x32_f16 v[76:79], v[138:141], v[180:183], v[76:79]
	v_mfma_f32_16x16x32_f16 v[84:87], v[138:141], v[188:191], v[84:87]
	v_mfma_f32_16x16x32_f16 v[84:87], v[142:145], v[192:195], v[84:87]
	v_mfma_f32_16x16x32_f16 v[88:91], v[152:155], v[192:195], v[88:91]
	v_mfma_f32_16x16x32_f16 v[88:91], v[148:151], v[188:191], v[88:91]
	v_mfma_f32_16x16x32_f16 v[96:99], v[148:151], v[196:199], v[96:99]
	v_mfma_f32_16x16x32_f16 v[96:99], v[152:155], v[200:203], v[96:99]
	v_mfma_f32_16x16x32_f16 v[92:95], v[142:145], v[200:203], v[92:95]
	v_mfma_f32_16x16x32_f16 v[92:95], v[138:141], v[196:199], v[92:95]
	s_setprio 0
	s_setprio 1
	v_mfma_f32_16x16x32_f16 v[100:103], v[156:159], v[172:175], v[100:103]
	v_mfma_f32_16x16x32_f16 v[100:103], v[160:163], v[176:179], v[100:103]
	v_mfma_f32_16x16x32_f16 v[104:107], v[168:171], v[176:179], v[104:107]
	v_mfma_f32_16x16x32_f16 v[104:107], v[164:167], v[172:175], v[104:107]
	v_mfma_f32_16x16x32_f16 v[112:115], v[164:167], v[180:183], v[112:115]
	v_mfma_f32_16x16x32_f16 v[112:115], v[168:171], v[184:187], v[112:115]
	v_mfma_f32_16x16x32_f16 v[108:111], v[160:163], v[184:187], v[108:111]
	v_mfma_f32_16x16x32_f16 v[108:111], v[156:159], v[180:183], v[108:111]
	v_mfma_f32_16x16x32_f16 v[116:119], v[156:159], v[188:191], v[116:119]
	v_mfma_f32_16x16x32_f16 v[116:119], v[160:163], v[192:195], v[116:119]
	v_mfma_f32_16x16x32_f16 v[120:123], v[168:171], v[192:195], v[120:123]
	v_mfma_f32_16x16x32_f16 v[120:123], v[164:167], v[188:191], v[120:123]
	v_mfma_f32_16x16x32_f16 v[128:131], v[164:167], v[196:199], v[128:131]
	v_mfma_f32_16x16x32_f16 v[128:131], v[168:171], v[200:203], v[128:131]
	s_setprio 2
	s_barrier
	v_mfma_f32_16x16x32_f16 v[124:127], v[160:163], v[200:203], v[124:127]
	v_mfma_f32_16x16x32_f16 v[124:127], v[156:159], v[196:199], v[124:127]
	s_setprio 0
	s_add_i32 s29, 0, 0x18000
	v_add_u32_e32 v135, s29, v147
	s_add_i32 s44, 0, 0x1c000
	ds_read_b128 v[138:141], v135
	ds_read_b128 v[142:145], v135 offset:1024
	ds_read_b128 v[148:151], v135 offset:2048
	ds_read_b128 v[152:155], v135 offset:3072
	v_add_u32_e32 v135, s44, v147
	ds_read_b128 v[156:159], v135
	ds_read_b128 v[160:163], v135 offset:1024
	ds_read_b128 v[164:167], v135 offset:2048
	ds_read_b128 v[168:171], v135 offset:3072
	s_add_u32 s16, s16, 0x80000
	s_addc_u32 s17, s17, 0
	s_mov_b32 m0, s65
	ds_read_b128 v[172:175], v212 offset:32768
	ds_read_b128 v[176:179], v212 offset:33792
	ds_read_b128 v[180:183], v212 offset:34816
	ds_read_b128 v[184:187], v212 offset:35840
	ds_read_b128 v[188:191], v212 offset:36864
	ds_read_b128 v[192:195], v212 offset:37888
	ds_read_b128 v[196:199], v212 offset:38912
	ds_read_b128 v[200:203], v212 offset:39936
	global_load_lds_dwordx4 v2, s[16:17]
	s_mov_b32 m0, s66
	s_nop 0
	global_load_lds_dwordx4 v132, s[16:17]
	s_waitcnt vmcnt(8)
	s_waitcnt lgkmcnt(0)
	s_barrier
	s_setprio 1
	s_waitcnt lgkmcnt(0)
	s_nop 5
	v_mfma_f32_16x16x32_f16 v[4:7], v[138:141], v[172:175], v[4:7]
	v_mfma_f32_16x16x32_f16 v[4:7], v[142:145], v[176:179], v[4:7]
	v_mfma_f32_16x16x32_f16 v[8:11], v[152:155], v[176:179], v[8:11]
	v_mfma_f32_16x16x32_f16 v[8:11], v[148:151], v[172:175], v[8:11]
	v_mfma_f32_16x16x32_f16 v[16:19], v[148:151], v[180:183], v[16:19]
	v_mfma_f32_16x16x32_f16 v[16:19], v[152:155], v[184:187], v[16:19]
	v_mfma_f32_16x16x32_f16 v[12:15], v[142:145], v[184:187], v[12:15]
	v_mfma_f32_16x16x32_f16 v[12:15], v[138:141], v[180:183], v[12:15]
	v_mfma_f32_16x16x32_f16 v[20:23], v[138:141], v[188:191], v[20:23]
	v_mfma_f32_16x16x32_f16 v[20:23], v[142:145], v[192:195], v[20:23]
	v_mfma_f32_16x16x32_f16 v[24:27], v[152:155], v[192:195], v[24:27]
	v_mfma_f32_16x16x32_f16 v[24:27], v[148:151], v[188:191], v[24:27]
	v_mfma_f32_16x16x32_f16 v[32:35], v[148:151], v[196:199], v[32:35]
	v_mfma_f32_16x16x32_f16 v[32:35], v[152:155], v[200:203], v[32:35]
	v_mfma_f32_16x16x32_f16 v[28:31], v[142:145], v[200:203], v[28:31]
	v_mfma_f32_16x16x32_f16 v[28:31], v[138:141], v[196:199], v[28:31]
	s_setprio 0
	s_setprio 1
	v_mfma_f32_16x16x32_f16 v[36:39], v[156:159], v[172:175], v[36:39]
	v_mfma_f32_16x16x32_f16 v[36:39], v[160:163], v[176:179], v[36:39]
	v_mfma_f32_16x16x32_f16 v[40:43], v[168:171], v[176:179], v[40:43]
	v_mfma_f32_16x16x32_f16 v[40:43], v[164:167], v[172:175], v[40:43]
	v_mfma_f32_16x16x32_f16 v[48:51], v[164:167], v[180:183], v[48:51]
	v_mfma_f32_16x16x32_f16 v[48:51], v[168:171], v[184:187], v[48:51]
	v_mfma_f32_16x16x32_f16 v[44:47], v[160:163], v[184:187], v[44:47]
	v_mfma_f32_16x16x32_f16 v[44:47], v[156:159], v[180:183], v[44:47]
	v_mfma_f32_16x16x32_f16 v[52:55], v[156:159], v[188:191], v[52:55]
	v_mfma_f32_16x16x32_f16 v[52:55], v[160:163], v[192:195], v[52:55]
	v_mfma_f32_16x16x32_f16 v[56:59], v[168:171], v[192:195], v[56:59]
	v_mfma_f32_16x16x32_f16 v[56:59], v[164:167], v[188:191], v[56:59]
	v_mfma_f32_16x16x32_f16 v[64:67], v[164:167], v[196:199], v[64:67]
	v_mfma_f32_16x16x32_f16 v[64:67], v[168:171], v[200:203], v[64:67]
	s_setprio 2
	s_barrier
	v_mfma_f32_16x16x32_f16 v[60:63], v[160:163], v[200:203], v[60:63]
	v_mfma_f32_16x16x32_f16 v[60:63], v[156:159], v[196:199], v[60:63]
	s_setprio 0
	s_add_i32 s16, s29, s62
	v_lshl_add_u64 v[204:205], v[204:205], 0, s[86:87]
	s_mov_b32 m0, s16
	ds_read_b128 v[172:175], v212 offset:49152
	ds_read_b128 v[176:179], v212 offset:50176
	ds_read_b128 v[180:183], v212 offset:51200
	ds_read_b128 v[184:187], v212 offset:52224
	ds_read_b128 v[188:191], v212 offset:53248
	ds_read_b128 v[192:195], v212 offset:54272
	ds_read_b128 v[196:199], v212 offset:55296
	ds_read_b128 v[200:203], v212 offset:56320
	global_load_lds_dwordx4 v[204:205], off
	s_add_i32 m0, s16, 0x2000
	s_add_u32 s6, s6, 0x80080
	v_lshl_add_u64 v[204:205], v[206:207], 0, s[86:87]
	s_addc_u32 s7, s7, 0
	s_add_i32 s16, s44, s62
	global_load_lds_dwordx4 v[204:205], off
	s_mov_b32 m0, s16
	v_lshl_add_u64 v[204:205], v[208:209], 0, s[86:87]
	global_load_lds_dwordx4 v136, s[6:7]
	s_add_i32 m0, s16, 0x2000
	s_nop 0
	global_load_lds_dwordx4 v134, s[6:7]
	s_mov_b32 m0, s69
	s_nop 0
	global_load_lds_dwordx4 v[204:205], off
	v_lshl_add_u64 v[204:205], v[210:211], 0, s[86:87]
	s_mov_b32 m0, s70
	s_nop 0
	global_load_lds_dwordx4 v[204:205], off
	s_waitcnt vmcnt(8)
	s_waitcnt lgkmcnt(0)
	s_barrier
	s_setprio 1
	s_waitcnt lgkmcnt(0)
	s_nop 5
	v_mfma_f32_16x16x32_f16 v[68:71], v[138:141], v[172:175], v[68:71]
	v_mfma_f32_16x16x32_f16 v[68:71], v[142:145], v[176:179], v[68:71]
	v_mfma_f32_16x16x32_f16 v[72:75], v[152:155], v[176:179], v[72:75]
	v_mfma_f32_16x16x32_f16 v[72:75], v[148:151], v[172:175], v[72:75]
	v_mfma_f32_16x16x32_f16 v[80:83], v[148:151], v[180:183], v[80:83]
	v_mfma_f32_16x16x32_f16 v[80:83], v[152:155], v[184:187], v[80:83]
	v_mfma_f32_16x16x32_f16 v[76:79], v[142:145], v[184:187], v[76:79]
	v_mfma_f32_16x16x32_f16 v[76:79], v[138:141], v[180:183], v[76:79]
	v_mfma_f32_16x16x32_f16 v[84:87], v[138:141], v[188:191], v[84:87]
	v_mfma_f32_16x16x32_f16 v[84:87], v[142:145], v[192:195], v[84:87]
	v_mfma_f32_16x16x32_f16 v[88:91], v[152:155], v[192:195], v[88:91]
	v_mfma_f32_16x16x32_f16 v[88:91], v[148:151], v[188:191], v[88:91]
	v_mfma_f32_16x16x32_f16 v[96:99], v[148:151], v[196:199], v[96:99]
	v_mfma_f32_16x16x32_f16 v[96:99], v[152:155], v[200:203], v[96:99]
	v_mfma_f32_16x16x32_f16 v[92:95], v[142:145], v[200:203], v[92:95]
	v_mfma_f32_16x16x32_f16 v[92:95], v[138:141], v[196:199], v[92:95]
	s_setprio 0
	s_setprio 1
	v_mfma_f32_16x16x32_f16 v[100:103], v[156:159], v[172:175], v[100:103]
	v_mfma_f32_16x16x32_f16 v[100:103], v[160:163], v[176:179], v[100:103]
	v_mfma_f32_16x16x32_f16 v[104:107], v[168:171], v[176:179], v[104:107]
	v_mfma_f32_16x16x32_f16 v[104:107], v[164:167], v[172:175], v[104:107]
	v_mfma_f32_16x16x32_f16 v[112:115], v[164:167], v[180:183], v[112:115]
	v_mfma_f32_16x16x32_f16 v[112:115], v[168:171], v[184:187], v[112:115]
	v_mfma_f32_16x16x32_f16 v[108:111], v[160:163], v[184:187], v[108:111]
	v_mfma_f32_16x16x32_f16 v[108:111], v[156:159], v[180:183], v[108:111]
	v_mfma_f32_16x16x32_f16 v[116:119], v[156:159], v[188:191], v[116:119]
	v_mfma_f32_16x16x32_f16 v[116:119], v[160:163], v[192:195], v[116:119]
	v_mfma_f32_16x16x32_f16 v[120:123], v[168:171], v[192:195], v[120:123]
	v_mfma_f32_16x16x32_f16 v[120:123], v[164:167], v[188:191], v[120:123]
	v_mfma_f32_16x16x32_f16 v[128:131], v[164:167], v[196:199], v[128:131]
	v_mfma_f32_16x16x32_f16 v[128:131], v[168:171], v[200:203], v[128:131]
	s_setprio 2
	s_barrier
	v_mfma_f32_16x16x32_f16 v[124:127], v[160:163], v[200:203], v[124:127]
	v_mfma_f32_16x16x32_f16 v[124:127], v[156:159], v[196:199], v[124:127]
	s_setprio 0
	s_add_i32 s28, s28, 2
	s_add_u32 s8, s8, 0x100
	s_addc_u32 s9, s9, 0
	s_add_u32 s26, s26, 0x100
	s_addc_u32 s27, s27, 0
	s_cmp_gt_u32 s28, 29
	s_cbranch_scc0 .LBB0_753
	s_and_b64 vcc, exec, s[52:53]
	s_cbranch_vccz .LBB0_756
	s_barrier

.LBB0_1175:
	s_add_i32 s61, 0, 0x10000
	s_add_i32 s79, 0, 0x14000
	v_add_u32_e32 v16, s61, v209
	v_add_u32_e32 v32, s79, v209
	ds_read_b128 v[4:7], v16
	ds_read_b128 v[8:11], v16 offset:1024
	ds_read_b128 v[12:15], v16 offset:2048
	ds_read_b128 v[16:19], v16 offset:3072
	ds_read_b128 v[20:23], v32
	ds_read_b128 v[24:27], v32 offset:1024
	ds_read_b128 v[28:31], v32 offset:2048
	ds_read_b128 v[32:35], v32 offset:3072
	v_add_u32_e32 v231, 0, v208
	ds_read_b128 v[36:39], v231
	ds_read_b128 v[40:43], v231 offset:1024
	ds_read_b128 v[44:47], v231 offset:2048
	ds_read_b128 v[48:51], v231 offset:3072
	ds_read_b128 v[52:55], v231 offset:4096
	ds_read_b128 v[56:59], v231 offset:5120
	ds_read_b128 v[60:63], v231 offset:6144
	ds_read_b128 v[64:67], v231 offset:7168
	s_waitcnt vmcnt(8)
	s_waitcnt lgkmcnt(0)
	s_barrier
	s_setprio 1
	s_waitcnt lgkmcnt(0)
	s_nop 5
	v_mfma_f32_16x16x32_bf16 v[68:71], v[4:7], v[36:39], 0
	v_mfma_f32_16x16x32_bf16 v[68:71], v[8:11], v[40:43], v[68:71]
	v_mfma_f32_16x16x32_bf16 v[72:75], v[12:15], v[36:39], 0
	v_mfma_f32_16x16x32_bf16 v[72:75], v[16:19], v[40:43], v[72:75]
	v_mfma_f32_16x16x32_bf16 v[80:83], v[12:15], v[44:47], 0
	v_mfma_f32_16x16x32_bf16 v[80:83], v[16:19], v[48:51], v[80:83]
	v_mfma_f32_16x16x32_bf16 v[76:79], v[4:7], v[44:47], 0
	v_mfma_f32_16x16x32_bf16 v[76:79], v[8:11], v[48:51], v[76:79]
	v_mfma_f32_16x16x32_bf16 v[84:87], v[4:7], v[52:55], 0
	v_mfma_f32_16x16x32_bf16 v[84:87], v[8:11], v[56:59], v[84:87]
	v_mfma_f32_16x16x32_bf16 v[88:91], v[12:15], v[52:55], 0
	v_mfma_f32_16x16x32_bf16 v[88:91], v[16:19], v[56:59], v[88:91]
	v_mfma_f32_16x16x32_bf16 v[96:99], v[12:15], v[60:63], 0
	v_mfma_f32_16x16x32_bf16 v[96:99], v[16:19], v[64:67], v[96:99]
	v_mfma_f32_16x16x32_bf16 v[92:95], v[4:7], v[60:63], 0
	v_mfma_f32_16x16x32_bf16 v[92:95], v[8:11], v[64:67], v[92:95]
	s_setprio 0
	s_setprio 1
	v_mfma_f32_16x16x32_bf16 v[100:103], v[20:23], v[36:39], 0
	v_mfma_f32_16x16x32_bf16 v[36:39], v[28:31], v[36:39], 0
	v_mfma_f32_16x16x32_bf16 v[104:107], v[20:23], v[44:47], 0
	v_mfma_f32_16x16x32_bf16 v[44:47], v[28:31], v[44:47], 0
	v_mfma_f32_16x16x32_bf16 v[108:111], v[20:23], v[52:55], 0
	v_mfma_f32_16x16x32_bf16 v[52:55], v[28:31], v[52:55], 0
	v_mfma_f32_16x16x32_bf16 v[112:115], v[20:23], v[60:63], 0
	v_mfma_f32_16x16x32_bf16 v[60:63], v[28:31], v[60:63], 0
	v_mfma_f32_16x16x32_bf16 v[100:103], v[24:27], v[40:43], v[100:103]
	v_mfma_f32_16x16x32_bf16 v[40:43], v[32:35], v[40:43], v[36:39]
	v_mfma_f32_16x16x32_bf16 v[104:107], v[24:27], v[48:51], v[104:107]
	v_mfma_f32_16x16x32_bf16 v[48:51], v[32:35], v[48:51], v[44:47]
	v_mfma_f32_16x16x32_bf16 v[108:111], v[24:27], v[56:59], v[108:111]
	v_mfma_f32_16x16x32_bf16 v[56:59], v[32:35], v[56:59], v[52:55]
	s_setprio 2
	s_barrier
	v_mfma_f32_16x16x32_bf16 v[112:115], v[24:27], v[64:67], v[112:115]
	v_mfma_f32_16x16x32_bf16 v[64:67], v[32:35], v[64:67], v[60:63]
	s_setprio 0
	v_lshl_add_u64 v[186:187], s[12:13], 0, v[2:3]
	s_add_i32 s61, s61, s36
	v_mov_b32_e32 v191, v3
	v_lshl_add_u64 v[134:135], v[186:187], 0, s[74:75]
	s_mov_b32 m0, s61
	v_lshl_add_u64 v[226:227], s[12:13], 0, v[190:191]
	ds_read_b128 v[36:39], v231 offset:16384
	ds_read_b128 v[44:47], v231 offset:17408
	ds_read_b128 v[52:55], v231 offset:18432
	ds_read_b128 v[60:63], v231 offset:19456
	ds_read_b128 v[116:119], v231 offset:20480
	ds_read_b128 v[120:123], v231 offset:21504
	ds_read_b128 v[124:127], v231 offset:22528
	ds_read_b128 v[128:131], v231 offset:23552
	global_load_lds_dwordx4 v[134:135], off
	v_lshl_add_u64 v[134:135], v[226:227], 0, s[74:75]
	s_add_i32 m0, s61, 0x2000
	s_add_i32 s61, s79, s36
	global_load_lds_dwordx4 v[134:135], off
	s_mov_b32 m0, s61
	v_mov_b32_e32 v133, v3
	global_load_lds_dwordx4 v2, s[16:17]
	s_add_i32 m0, s61, 0x2000
	v_lshl_add_u64 v[248:249], s[6:7], 0, v[132:133]
	v_mov_b32_e32 v189, v3
	global_load_lds_dwordx4 v190, s[16:17]
	v_lshl_add_u64 v[134:135], v[248:249], 0, s[74:75]
	s_mov_b32 m0, s37
	v_lshl_add_u64 v[250:251], s[6:7], 0, v[188:189]
	global_load_lds_dwordx4 v[134:135], off
	v_lshl_add_u64 v[134:135], v[250:251], 0, s[74:75]
	s_mov_b32 m0, s66
	s_nop 0
	global_load_lds_dwordx4 v[134:135], off
	s_waitcnt vmcnt(8)
	s_waitcnt lgkmcnt(0)
	s_barrier
	s_setprio 1
	s_waitcnt lgkmcnt(0)
	s_nop 5
	v_mfma_f32_16x16x32_bf16 v[134:137], v[4:7], v[36:39], 0
	v_mfma_f32_16x16x32_bf16 v[138:141], v[12:15], v[36:39], 0
	v_mfma_f32_16x16x32_bf16 v[142:145], v[4:7], v[52:55], 0
	v_mfma_f32_16x16x32_bf16 v[146:149], v[12:15], v[52:55], 0
	v_mfma_f32_16x16x32_bf16 v[150:153], v[4:7], v[116:119], 0
	v_mfma_f32_16x16x32_bf16 v[154:157], v[12:15], v[116:119], 0
	v_mfma_f32_16x16x32_bf16 v[4:7], v[4:7], v[124:127], 0
	v_mfma_f32_16x16x32_bf16 v[12:15], v[12:15], v[124:127], 0
	v_mfma_f32_16x16x32_bf16 v[134:137], v[8:11], v[44:47], v[134:137]
	v_mfma_f32_16x16x32_bf16 v[138:141], v[16:19], v[44:47], v[138:141]
	v_mfma_f32_16x16x32_bf16 v[142:145], v[8:11], v[60:63], v[142:145]
	v_mfma_f32_16x16x32_bf16 v[146:149], v[16:19], v[60:63], v[146:149]
	v_mfma_f32_16x16x32_bf16 v[150:153], v[8:11], v[120:123], v[150:153]
	v_mfma_f32_16x16x32_bf16 v[154:157], v[16:19], v[120:123], v[154:157]
	v_mfma_f32_16x16x32_bf16 v[158:161], v[8:11], v[128:131], v[4:7]
	v_mfma_f32_16x16x32_bf16 v[162:165], v[16:19], v[128:131], v[12:15]
	s_setprio 0
	s_setprio 1
	v_mfma_f32_16x16x32_bf16 v[4:7], v[20:23], v[36:39], 0
	v_mfma_f32_16x16x32_bf16 v[8:11], v[28:31], v[36:39], 0
	v_mfma_f32_16x16x32_bf16 v[12:15], v[20:23], v[52:55], 0
	v_mfma_f32_16x16x32_bf16 v[16:19], v[28:31], v[52:55], 0
	v_mfma_f32_16x16x32_bf16 v[36:39], v[20:23], v[116:119], 0
	v_mfma_f32_16x16x32_bf16 v[52:55], v[28:31], v[116:119], 0
	v_mfma_f32_16x16x32_bf16 v[20:23], v[20:23], v[124:127], 0
	v_mfma_f32_16x16x32_bf16 v[28:31], v[28:31], v[124:127], 0
	v_mfma_f32_16x16x32_bf16 v[116:119], v[24:27], v[44:47], v[4:7]
	v_mfma_f32_16x16x32_bf16 v[124:127], v[32:35], v[44:47], v[8:11]
	v_mfma_f32_16x16x32_bf16 v[174:177], v[24:27], v[120:123], v[36:39]
	v_mfma_f32_16x16x32_bf16 v[120:123], v[32:35], v[120:123], v[52:55]
	v_mfma_f32_16x16x32_bf16 v[178:181], v[24:27], v[128:131], v[20:23]
	v_mfma_f32_16x16x32_bf16 v[128:131], v[32:35], v[128:131], v[28:31]
	s_setprio 2
	s_barrier
	v_mfma_f32_16x16x32_bf16 v[166:169], v[24:27], v[60:63], v[12:15]
	v_mfma_f32_16x16x32_bf16 v[170:173], v[32:35], v[60:63], v[16:19]
	s_setprio 0
	s_add_i32 s61, 0, 0x18000
	v_add_u32_e32 v4, s61, v209
	s_add_i32 s79, 0, 0x1c000
	ds_read_b128 v[182:185], v4
	ds_read_b128 v[192:195], v4 offset:1024
	ds_read_b128 v[196:199], v4 offset:2048
	ds_read_b128 v[200:203], v4 offset:3072
	v_add_u32_e32 v4, s79, v209
	ds_read_b128 v[204:207], v4
	ds_read_b128 v[210:213], v4 offset:1024
	ds_read_b128 v[214:217], v4 offset:2048
	ds_read_b128 v[218:221], v4 offset:3072
	s_mov_b32 m0, s67
	ds_read_b128 v[44:47], v231 offset:32768
	ds_read_b128 v[52:55], v231 offset:33792
	ds_read_b128 v[60:63], v231 offset:34816
	ds_read_b128 v[222:225], v231 offset:35840
	ds_read_b128 v[232:235], v231 offset:36864
	ds_read_b128 v[236:239], v231 offset:37888
	ds_read_b128 v[240:243], v231 offset:38912
	ds_read_b128 v[244:247], v231 offset:39936
	global_load_lds_dwordx4 v132, s[26:27]
	s_mov_b32 m0, s68
	s_nop 0
	global_load_lds_dwordx4 v188, s[26:27]
	s_waitcnt vmcnt(8)
	s_waitcnt lgkmcnt(0)
	s_barrier
	s_setprio 1
	s_waitcnt lgkmcnt(0)
	s_nop 5
	v_mfma_f32_16x16x32_bf16 v[4:7], v[182:185], v[44:47], v[68:71]
	v_mfma_f32_16x16x32_bf16 v[8:11], v[196:199], v[44:47], v[72:75]
	v_mfma_f32_16x16x32_bf16 v[12:15], v[182:185], v[60:63], v[76:79]
	v_mfma_f32_16x16x32_bf16 v[16:19], v[196:199], v[60:63], v[80:83]
	v_mfma_f32_16x16x32_bf16 v[20:23], v[182:185], v[232:235], v[84:87]
	v_mfma_f32_16x16x32_bf16 v[24:27], v[196:199], v[232:235], v[88:91]
	v_mfma_f32_16x16x32_bf16 v[28:31], v[182:185], v[240:243], v[92:95]
	v_mfma_f32_16x16x32_bf16 v[32:35], v[196:199], v[240:243], v[96:99]
	v_mfma_f32_16x16x32_bf16 v[4:7], v[192:195], v[52:55], v[4:7]
	v_mfma_f32_16x16x32_bf16 v[8:11], v[200:203], v[52:55], v[8:11]
	v_mfma_f32_16x16x32_bf16 v[12:15], v[192:195], v[222:225], v[12:15]
	v_mfma_f32_16x16x32_bf16 v[16:19], v[200:203], v[222:225], v[16:19]
	v_mfma_f32_16x16x32_bf16 v[20:23], v[192:195], v[236:239], v[20:23]
	v_mfma_f32_16x16x32_bf16 v[24:27], v[200:203], v[236:239], v[24:27]
	v_mfma_f32_16x16x32_bf16 v[28:31], v[192:195], v[244:247], v[28:31]
	v_mfma_f32_16x16x32_bf16 v[32:35], v[200:203], v[244:247], v[32:35]
	s_setprio 0
	s_setprio 1
	v_mfma_f32_16x16x32_bf16 v[36:39], v[204:207], v[44:47], v[100:103]
	v_mfma_f32_16x16x32_bf16 v[40:43], v[214:217], v[44:47], v[40:43]
	v_mfma_f32_16x16x32_bf16 v[36:39], v[210:213], v[52:55], v[36:39]
	v_mfma_f32_16x16x32_bf16 v[40:43], v[218:221], v[52:55], v[40:43]
	v_mfma_f32_16x16x32_bf16 v[44:47], v[204:207], v[60:63], v[104:107]
	v_mfma_f32_16x16x32_bf16 v[48:51], v[214:217], v[60:63], v[48:51]
	v_mfma_f32_16x16x32_bf16 v[52:55], v[204:207], v[232:235], v[108:111]
	v_mfma_f32_16x16x32_bf16 v[56:59], v[214:217], v[232:235], v[56:59]
	v_mfma_f32_16x16x32_bf16 v[60:63], v[204:207], v[240:243], v[112:115]
	v_mfma_f32_16x16x32_bf16 v[64:67], v[214:217], v[240:243], v[64:67]
	v_mfma_f32_16x16x32_bf16 v[44:47], v[210:213], v[222:225], v[44:47]
	v_mfma_f32_16x16x32_bf16 v[48:51], v[218:221], v[222:225], v[48:51]
	v_mfma_f32_16x16x32_bf16 v[52:55], v[210:213], v[236:239], v[52:55]
	v_mfma_f32_16x16x32_bf16 v[56:59], v[218:221], v[236:239], v[56:59]
	s_setprio 2
	s_barrier
	v_mfma_f32_16x16x32_bf16 v[60:63], v[210:213], v[244:247], v[60:63]
	v_mfma_f32_16x16x32_bf16 v[64:67], v[218:221], v[244:247], v[64:67]
	s_setprio 0
	s_add_i32 s61, s61, s36
	v_lshl_add_u64 v[68:69], v[186:187], 0, s[24:25]
	s_mov_b32 m0, s61
	ds_read_b128 v[104:107], v231 offset:49152
	ds_read_b128 v[108:111], v231 offset:50176
	ds_read_b128 v[112:115], v231 offset:51200
	ds_read_b128 v[222:225], v231 offset:52224
	ds_read_b128 v[232:235], v231 offset:53248
	ds_read_b128 v[236:239], v231 offset:54272
	ds_read_b128 v[240:243], v231 offset:55296
	ds_read_b128 v[244:247], v231 offset:56320
	global_load_lds_dwordx4 v[68:69], off
	v_lshl_add_u64 v[68:69], v[226:227], 0, s[24:25]
	s_add_i32 m0, s61, 0x2000
	s_add_i32 s61, s79, s36
	global_load_lds_dwordx4 v[68:69], off
	s_mov_b32 m0, s61
	v_lshl_add_u64 v[68:69], v[248:249], 0, s[24:25]
	global_load_lds_dwordx4 v2, s[28:29]
	s_add_i32 m0, s61, 0x2000
	s_nop 0
	global_load_lds_dwordx4 v190, s[28:29]
	s_mov_b32 m0, s71
	s_nop 0
	global_load_lds_dwordx4 v[68:69], off
	v_lshl_add_u64 v[68:69], v[250:251], 0, s[24:25]
	s_mov_b32 m0, s72
	s_nop 0
	global_load_lds_dwordx4 v[68:69], off
	s_waitcnt vmcnt(8)
	s_waitcnt lgkmcnt(0)
	s_barrier
	s_setprio 1
	s_waitcnt lgkmcnt(0)
	s_nop 5
	v_mfma_f32_16x16x32_bf16 v[68:71], v[182:185], v[104:107], v[134:137]
	v_mfma_f32_16x16x32_bf16 v[72:75], v[196:199], v[104:107], v[138:141]
	v_mfma_f32_16x16x32_bf16 v[76:79], v[182:185], v[112:115], v[142:145]
	v_mfma_f32_16x16x32_bf16 v[80:83], v[196:199], v[112:115], v[146:149]
	v_mfma_f32_16x16x32_bf16 v[84:87], v[182:185], v[232:235], v[150:153]
	v_mfma_f32_16x16x32_bf16 v[88:91], v[196:199], v[232:235], v[154:157]
	v_mfma_f32_16x16x32_bf16 v[92:95], v[182:185], v[240:243], v[158:161]
	v_mfma_f32_16x16x32_bf16 v[96:99], v[196:199], v[240:243], v[162:165]
	v_mfma_f32_16x16x32_bf16 v[68:71], v[192:195], v[108:111], v[68:71]
	v_mfma_f32_16x16x32_bf16 v[72:75], v[200:203], v[108:111], v[72:75]
	v_mfma_f32_16x16x32_bf16 v[76:79], v[192:195], v[222:225], v[76:79]
	v_mfma_f32_16x16x32_bf16 v[80:83], v[200:203], v[222:225], v[80:83]
	v_mfma_f32_16x16x32_bf16 v[84:87], v[192:195], v[236:239], v[84:87]
	v_mfma_f32_16x16x32_bf16 v[88:91], v[200:203], v[236:239], v[88:91]
	v_mfma_f32_16x16x32_bf16 v[92:95], v[192:195], v[244:247], v[92:95]
	v_mfma_f32_16x16x32_bf16 v[96:99], v[200:203], v[244:247], v[96:99]
	s_setprio 0
	s_setprio 1
	v_mfma_f32_16x16x32_bf16 v[100:103], v[204:207], v[104:107], v[116:119]
	v_mfma_f32_16x16x32_bf16 v[104:107], v[214:217], v[104:107], v[124:127]
	v_mfma_f32_16x16x32_bf16 v[100:103], v[210:213], v[108:111], v[100:103]
	v_mfma_f32_16x16x32_bf16 v[104:107], v[218:221], v[108:111], v[104:107]
	v_mfma_f32_16x16x32_bf16 v[108:111], v[204:207], v[112:115], v[166:169]
	v_mfma_f32_16x16x32_bf16 v[112:115], v[214:217], v[112:115], v[170:173]
	v_mfma_f32_16x16x32_bf16 v[116:119], v[204:207], v[232:235], v[174:177]
	v_mfma_f32_16x16x32_bf16 v[120:123], v[214:217], v[232:235], v[120:123]
	v_mfma_f32_16x16x32_bf16 v[124:127], v[204:207], v[240:243], v[178:181]
	v_mfma_f32_16x16x32_bf16 v[128:131], v[214:217], v[240:243], v[128:131]
	v_mfma_f32_16x16x32_bf16 v[108:111], v[210:213], v[222:225], v[108:111]
	v_mfma_f32_16x16x32_bf16 v[112:115], v[218:221], v[222:225], v[112:115]
	v_mfma_f32_16x16x32_bf16 v[116:119], v[210:213], v[236:239], v[116:119]
	v_mfma_f32_16x16x32_bf16 v[120:123], v[218:221], v[236:239], v[120:123]
	s_setprio 2
	s_barrier
	v_mfma_f32_16x16x32_bf16 v[124:127], v[210:213], v[244:247], v[124:127]
	v_mfma_f32_16x16x32_bf16 v[128:131], v[218:221], v[244:247], v[128:131]
	s_setprio 0
	s_add_i32 s43, s43, 2
	s_cmp_ge_i32 s43, s42
	s_cbranch_scc0 .LBB0_1175
.LBB0_1176:
	s_add_i32 s12, 0, 0x10000
	s_add_i32 s13, 0, 0x14000
	v_mov_b32_e32 v192, v2
	v_mov_b32_e32 v2, v132
	v_add_u32_e32 v144, s12, v209
	v_add_u32_e32 v160, s13, v209
	ds_read_b128 v[132:135], v144
	ds_read_b128 v[136:139], v144 offset:1024
	ds_read_b128 v[140:143], v144 offset:2048
	ds_read_b128 v[144:147], v144 offset:3072
	ds_read_b128 v[148:151], v160
	ds_read_b128 v[152:155], v160 offset:1024
	ds_read_b128 v[156:159], v160 offset:2048
	ds_read_b128 v[160:163], v160 offset:3072
	s_add_u32 s6, s6, 0x80180
	s_mov_b32 m0, s73
	v_add_u32_e32 v212, 0, v208
	s_addc_u32 s7, s7, 0
	ds_read_b128 v[164:167], v212
	ds_read_b128 v[168:171], v212 offset:1024
	ds_read_b128 v[172:175], v212 offset:2048
	ds_read_b128 v[176:179], v212 offset:3072
	ds_read_b128 v[180:183], v212 offset:4096
	ds_read_b128 v[184:187], v212 offset:5120
	ds_read_b128 v[194:197], v212 offset:6144
	ds_read_b128 v[198:201], v212 offset:7168
	global_load_lds_dwordx4 v2, s[6:7]
	s_mov_b32 m0, s76
	v_mov_b32_e32 v189, v3
	global_load_lds_dwordx4 v188, s[6:7]
	s_waitcnt vmcnt(8)
	s_waitcnt lgkmcnt(0)
	s_barrier
	s_setprio 1
	s_waitcnt lgkmcnt(0)
	s_nop 5
	v_mfma_f32_16x16x32_bf16 v[4:7], v[132:135], v[164:167], v[4:7]
	v_mfma_f32_16x16x32_bf16 v[4:7], v[136:139], v[168:171], v[4:7]
	v_mfma_f32_16x16x32_bf16 v[8:11], v[144:147], v[168:171], v[8:11]
	v_mfma_f32_16x16x32_bf16 v[8:11], v[140:143], v[164:167], v[8:11]
	v_mfma_f32_16x16x32_bf16 v[16:19], v[140:143], v[172:175], v[16:19]
	v_mfma_f32_16x16x32_bf16 v[16:19], v[144:147], v[176:179], v[16:19]
	v_mfma_f32_16x16x32_bf16 v[12:15], v[136:139], v[176:179], v[12:15]
	v_mfma_f32_16x16x32_bf16 v[12:15], v[132:135], v[172:175], v[12:15]
	v_mfma_f32_16x16x32_bf16 v[20:23], v[132:135], v[180:183], v[20:23]
	v_mfma_f32_16x16x32_bf16 v[20:23], v[136:139], v[184:187], v[20:23]
	v_mfma_f32_16x16x32_bf16 v[24:27], v[144:147], v[184:187], v[24:27]
	v_mfma_f32_16x16x32_bf16 v[24:27], v[140:143], v[180:183], v[24:27]
	v_mfma_f32_16x16x32_bf16 v[32:35], v[140:143], v[194:197], v[32:35]
	v_mfma_f32_16x16x32_bf16 v[32:35], v[144:147], v[198:201], v[32:35]
	v_mfma_f32_16x16x32_bf16 v[28:31], v[136:139], v[198:201], v[28:31]
	v_mfma_f32_16x16x32_bf16 v[28:31], v[132:135], v[194:197], v[28:31]
	s_setprio 0
	s_setprio 1
	v_mfma_f32_16x16x32_bf16 v[36:39], v[148:151], v[164:167], v[36:39]
	v_mfma_f32_16x16x32_bf16 v[36:39], v[152:155], v[168:171], v[36:39]
	v_mfma_f32_16x16x32_bf16 v[40:43], v[160:163], v[168:171], v[40:43]
	v_mfma_f32_16x16x32_bf16 v[40:43], v[156:159], v[164:167], v[40:43]
	v_mfma_f32_16x16x32_bf16 v[48:51], v[156:159], v[172:175], v[48:51]
	v_mfma_f32_16x16x32_bf16 v[48:51], v[160:163], v[176:179], v[48:51]
	v_mfma_f32_16x16x32_bf16 v[44:47], v[152:155], v[176:179], v[44:47]
	v_mfma_f32_16x16x32_bf16 v[44:47], v[148:151], v[172:175], v[44:47]
	v_mfma_f32_16x16x32_bf16 v[52:55], v[148:151], v[180:183], v[52:55]
	v_mfma_f32_16x16x32_bf16 v[52:55], v[152:155], v[184:187], v[52:55]
	v_mfma_f32_16x16x32_bf16 v[56:59], v[160:163], v[184:187], v[56:59]
	v_mfma_f32_16x16x32_bf16 v[56:59], v[156:159], v[180:183], v[56:59]
	v_mfma_f32_16x16x32_bf16 v[64:67], v[156:159], v[194:197], v[64:67]
	v_mfma_f32_16x16x32_bf16 v[64:67], v[160:163], v[198:201], v[64:67]
	s_setprio 2
	s_barrier
	v_mfma_f32_16x16x32_bf16 v[60:63], v[152:155], v[198:201], v[60:63]
	v_mfma_f32_16x16x32_bf16 v[60:63], v[148:151], v[194:197], v[60:63]
	s_setprio 0
	s_add_i32 s6, s12, s36
	s_mov_b32 m0, s6
	ds_read_b128 v[164:167], v212 offset:16384
	ds_read_b128 v[168:171], v212 offset:17408
	ds_read_b128 v[172:175], v212 offset:18432
	ds_read_b128 v[176:179], v212 offset:19456
	ds_read_b128 v[180:183], v212 offset:20480
	ds_read_b128 v[184:187], v212 offset:21504
	ds_read_b128 v[194:197], v212 offset:22528
	ds_read_b128 v[198:201], v212 offset:23552
	global_load_lds_dwordx4 v192, s[14:15]
	s_add_i32 m0, s6, 0x2000
	s_add_u32 s6, s14, 0x10000
	s_addc_u32 s7, s15, 0
	s_add_i32 s12, s13, s36
	global_load_lds_dwordx4 v190, s[14:15]
	s_mov_b32 m0, s12
	v_mov_b32_e32 v193, v3
	global_load_lds_dwordx4 v192, s[6:7]
	s_add_i32 m0, s12, 0x2000
	v_mov_b32_e32 v191, v3
	global_load_lds_dwordx4 v190, s[6:7]
	s_mov_b32 m0, s37
	v_lshl_add_u64 v[202:203], s[14:15], 0, v[192:193]
	global_load_lds_dwordx4 v2, s[10:11]
	s_mov_b32 m0, s66
	v_lshl_add_u64 v[204:205], s[14:15], 0, v[190:191]
	global_load_lds_dwordx4 v188, s[10:11]
	s_waitcnt vmcnt(8)
	s_waitcnt lgkmcnt(0)
	v_lshl_add_u64 v[206:207], s[10:11], 0, v[2:3]
	v_lshl_add_u64 v[210:211], s[10:11], 0, v[188:189]
	s_barrier
	s_setprio 1
	s_waitcnt lgkmcnt(0)
	s_nop 5
	v_mfma_f32_16x16x32_bf16 v[68:71], v[132:135], v[164:167], v[68:71]
	v_mfma_f32_16x16x32_bf16 v[68:71], v[136:139], v[168:171], v[68:71]
	v_mfma_f32_16x16x32_bf16 v[72:75], v[144:147], v[168:171], v[72:75]
	v_mfma_f32_16x16x32_bf16 v[72:75], v[140:143], v[164:167], v[72:75]
	v_mfma_f32_16x16x32_bf16 v[80:83], v[140:143], v[172:175], v[80:83]
	v_mfma_f32_16x16x32_bf16 v[80:83], v[144:147], v[176:179], v[80:83]
	v_mfma_f32_16x16x32_bf16 v[76:79], v[136:139], v[176:179], v[76:79]
	v_mfma_f32_16x16x32_bf16 v[76:79], v[132:135], v[172:175], v[76:79]
	v_mfma_f32_16x16x32_bf16 v[84:87], v[132:135], v[180:183], v[84:87]
	v_mfma_f32_16x16x32_bf16 v[84:87], v[136:139], v[184:187], v[84:87]
	v_mfma_f32_16x16x32_bf16 v[88:91], v[144:147], v[184:187], v[88:91]
	v_mfma_f32_16x16x32_bf16 v[88:91], v[140:143], v[180:183], v[88:91]
	v_mfma_f32_16x16x32_bf16 v[96:99], v[140:143], v[194:197], v[96:99]
	v_mfma_f32_16x16x32_bf16 v[96:99], v[144:147], v[198:201], v[96:99]
	v_mfma_f32_16x16x32_bf16 v[92:95], v[136:139], v[198:201], v[92:95]
	v_mfma_f32_16x16x32_bf16 v[92:95], v[132:135], v[194:197], v[92:95]
	s_setprio 0
	s_setprio 1
	v_mfma_f32_16x16x32_bf16 v[100:103], v[148:151], v[164:167], v[100:103]
	v_mfma_f32_16x16x32_bf16 v[100:103], v[152:155], v[168:171], v[100:103]
	v_mfma_f32_16x16x32_bf16 v[104:107], v[160:163], v[168:171], v[104:107]
	v_mfma_f32_16x16x32_bf16 v[104:107], v[156:159], v[164:167], v[104:107]
	v_mfma_f32_16x16x32_bf16 v[112:115], v[156:159], v[172:175], v[112:115]
	v_mfma_f32_16x16x32_bf16 v[112:115], v[160:163], v[176:179], v[112:115]
	v_mfma_f32_16x16x32_bf16 v[108:111], v[152:155], v[176:179], v[108:111]
	v_mfma_f32_16x16x32_bf16 v[108:111], v[148:151], v[172:175], v[108:111]
	v_mfma_f32_16x16x32_bf16 v[116:119], v[148:151], v[180:183], v[116:119]
	v_mfma_f32_16x16x32_bf16 v[116:119], v[152:155], v[184:187], v[116:119]
	v_mfma_f32_16x16x32_bf16 v[120:123], v[160:163], v[184:187], v[120:123]
	v_mfma_f32_16x16x32_bf16 v[120:123], v[156:159], v[180:183], v[120:123]
	v_mfma_f32_16x16x32_bf16 v[128:131], v[156:159], v[194:197], v[128:131]
	v_mfma_f32_16x16x32_bf16 v[128:131], v[160:163], v[198:201], v[128:131]
	s_setprio 2
	s_barrier
	v_mfma_f32_16x16x32_bf16 v[124:127], v[152:155], v[198:201], v[124:127]
	v_mfma_f32_16x16x32_bf16 v[124:127], v[148:151], v[194:197], v[124:127]
	s_setprio 0
	s_add_i32 s12, 0, 0x18000
	s_add_i32 s13, 0, 0x1c000
	v_add_u32_e32 v144, s12, v209
	v_add_u32_e32 v160, s13, v209
	ds_read_b128 v[132:135], v144
	ds_read_b128 v[136:139], v144 offset:1024
	ds_read_b128 v[140:143], v144 offset:2048
	ds_read_b128 v[144:147], v144 offset:3072
	ds_read_b128 v[148:151], v160
	ds_read_b128 v[152:155], v160 offset:1024
	ds_read_b128 v[156:159], v160 offset:2048
	ds_read_b128 v[160:163], v160 offset:3072
	s_add_u32 s6, s10, 0x80000
	s_addc_u32 s7, s11, 0
	s_mov_b32 m0, s67
	ds_read_b128 v[164:167], v212 offset:32768
	ds_read_b128 v[168:171], v212 offset:33792
	ds_read_b128 v[172:175], v212 offset:34816
	ds_read_b128 v[176:179], v212 offset:35840
	ds_read_b128 v[180:183], v212 offset:36864
	ds_read_b128 v[184:187], v212 offset:37888
	ds_read_b128 v[194:197], v212 offset:38912
	ds_read_b128 v[198:201], v212 offset:39936
	global_load_lds_dwordx4 v2, s[6:7]
	s_mov_b32 m0, s68
	s_nop 0
	global_load_lds_dwordx4 v188, s[6:7]
	s_waitcnt vmcnt(8)
	s_waitcnt lgkmcnt(0)
	s_barrier
	s_setprio 1
	s_waitcnt lgkmcnt(0)
	s_nop 5
	v_mfma_f32_16x16x32_bf16 v[4:7], v[132:135], v[164:167], v[4:7]
	v_mfma_f32_16x16x32_bf16 v[4:7], v[136:139], v[168:171], v[4:7]
	v_mfma_f32_16x16x32_bf16 v[8:11], v[144:147], v[168:171], v[8:11]
	v_mfma_f32_16x16x32_bf16 v[8:11], v[140:143], v[164:167], v[8:11]
	v_mfma_f32_16x16x32_bf16 v[16:19], v[140:143], v[172:175], v[16:19]
	v_mfma_f32_16x16x32_bf16 v[16:19], v[144:147], v[176:179], v[16:19]
	v_mfma_f32_16x16x32_bf16 v[12:15], v[136:139], v[176:179], v[12:15]
	v_mfma_f32_16x16x32_bf16 v[12:15], v[132:135], v[172:175], v[12:15]
	v_mfma_f32_16x16x32_bf16 v[20:23], v[132:135], v[180:183], v[20:23]
	v_mfma_f32_16x16x32_bf16 v[20:23], v[136:139], v[184:187], v[20:23]
	v_mfma_f32_16x16x32_bf16 v[24:27], v[144:147], v[184:187], v[24:27]
	v_mfma_f32_16x16x32_bf16 v[24:27], v[140:143], v[180:183], v[24:27]
	v_mfma_f32_16x16x32_bf16 v[32:35], v[140:143], v[194:197], v[32:35]
	v_mfma_f32_16x16x32_bf16 v[32:35], v[144:147], v[198:201], v[32:35]
	v_mfma_f32_16x16x32_bf16 v[28:31], v[136:139], v[198:201], v[28:31]
	v_mfma_f32_16x16x32_bf16 v[28:31], v[132:135], v[194:197], v[28:31]
	s_setprio 0
	s_setprio 1
	v_mfma_f32_16x16x32_bf16 v[36:39], v[148:151], v[164:167], v[36:39]
	v_mfma_f32_16x16x32_bf16 v[36:39], v[152:155], v[168:171], v[36:39]
	v_mfma_f32_16x16x32_bf16 v[40:43], v[160:163], v[168:171], v[40:43]
	v_mfma_f32_16x16x32_bf16 v[40:43], v[156:159], v[164:167], v[40:43]
	v_mfma_f32_16x16x32_bf16 v[48:51], v[156:159], v[172:175], v[48:51]
	v_mfma_f32_16x16x32_bf16 v[48:51], v[160:163], v[176:179], v[48:51]
	v_mfma_f32_16x16x32_bf16 v[44:47], v[152:155], v[176:179], v[44:47]
	v_mfma_f32_16x16x32_bf16 v[44:47], v[148:151], v[172:175], v[44:47]
	v_mfma_f32_16x16x32_bf16 v[52:55], v[148:151], v[180:183], v[52:55]
	v_mfma_f32_16x16x32_bf16 v[52:55], v[152:155], v[184:187], v[52:55]
	v_mfma_f32_16x16x32_bf16 v[56:59], v[160:163], v[184:187], v[56:59]
	v_mfma_f32_16x16x32_bf16 v[56:59], v[156:159], v[180:183], v[56:59]
	v_mfma_f32_16x16x32_bf16 v[64:67], v[156:159], v[194:197], v[64:67]
	v_mfma_f32_16x16x32_bf16 v[64:67], v[160:163], v[198:201], v[64:67]
	s_setprio 2
	s_barrier
	v_mfma_f32_16x16x32_bf16 v[60:63], v[152:155], v[198:201], v[60:63]
	v_mfma_f32_16x16x32_bf16 v[60:63], v[148:151], v[194:197], v[60:63]
	s_setprio 0
	s_add_i32 s6, s12, s36
	v_lshl_add_u64 v[202:203], v[202:203], 0, s[86:87]
	s_mov_b32 m0, s6
	ds_read_b128 v[164:167], v212 offset:49152
	ds_read_b128 v[168:171], v212 offset:50176
	ds_read_b128 v[172:175], v212 offset:51200
	ds_read_b128 v[176:179], v212 offset:52224
	ds_read_b128 v[180:183], v212 offset:53248
	ds_read_b128 v[184:187], v212 offset:54272
	ds_read_b128 v[194:197], v212 offset:55296
	ds_read_b128 v[198:201], v212 offset:56320
	global_load_lds_dwordx4 v[202:203], off
	s_add_i32 m0, s6, 0x2000
	s_add_u32 s6, s14, 0x10080
	v_lshl_add_u64 v[202:203], v[204:205], 0, s[86:87]
	s_addc_u32 s7, s15, 0
	s_add_i32 s12, s13, s36
	global_load_lds_dwordx4 v[202:203], off
	s_mov_b32 m0, s12
	v_lshl_add_u64 v[202:203], v[206:207], 0, s[86:87]
	global_load_lds_dwordx4 v192, s[6:7]
	s_add_i32 m0, s12, 0x2000
	s_nop 0
	global_load_lds_dwordx4 v190, s[6:7]
	s_mov_b32 m0, s71
	s_nop 0
	global_load_lds_dwordx4 v[202:203], off
	v_lshl_add_u64 v[202:203], v[210:211], 0, s[86:87]
	s_mov_b32 m0, s72
	s_nop 0
	global_load_lds_dwordx4 v[202:203], off
	s_waitcnt vmcnt(8)
	s_waitcnt lgkmcnt(0)
	s_barrier
	s_setprio 1
	s_waitcnt lgkmcnt(0)
	s_nop 5
	v_mfma_f32_16x16x32_bf16 v[68:71], v[132:135], v[164:167], v[68:71]
	v_mfma_f32_16x16x32_bf16 v[68:71], v[136:139], v[168:171], v[68:71]
	v_mfma_f32_16x16x32_bf16 v[72:75], v[144:147], v[168:171], v[72:75]
	v_mfma_f32_16x16x32_bf16 v[72:75], v[140:143], v[164:167], v[72:75]
	v_mfma_f32_16x16x32_bf16 v[80:83], v[140:143], v[172:175], v[80:83]
	v_mfma_f32_16x16x32_bf16 v[80:83], v[144:147], v[176:179], v[80:83]
	v_mfma_f32_16x16x32_bf16 v[76:79], v[136:139], v[176:179], v[76:79]
	v_mfma_f32_16x16x32_bf16 v[76:79], v[132:135], v[172:175], v[76:79]
	v_mfma_f32_16x16x32_bf16 v[84:87], v[132:135], v[180:183], v[84:87]
	v_mfma_f32_16x16x32_bf16 v[84:87], v[136:139], v[184:187], v[84:87]
	v_mfma_f32_16x16x32_bf16 v[88:91], v[144:147], v[184:187], v[88:91]
	v_mfma_f32_16x16x32_bf16 v[88:91], v[140:143], v[180:183], v[88:91]
	v_mfma_f32_16x16x32_bf16 v[96:99], v[140:143], v[194:197], v[96:99]
	v_mfma_f32_16x16x32_bf16 v[96:99], v[144:147], v[198:201], v[96:99]
	v_mfma_f32_16x16x32_bf16 v[92:95], v[136:139], v[198:201], v[92:95]
	v_mfma_f32_16x16x32_bf16 v[92:95], v[132:135], v[194:197], v[92:95]
	s_setprio 0
	s_setprio 1
	v_mfma_f32_16x16x32_bf16 v[100:103], v[148:151], v[164:167], v[100:103]
	v_mfma_f32_16x16x32_bf16 v[100:103], v[152:155], v[168:171], v[100:103]
	v_mfma_f32_16x16x32_bf16 v[104:107], v[160:163], v[168:171], v[104:107]
	v_mfma_f32_16x16x32_bf16 v[104:107], v[156:159], v[164:167], v[104:107]
	v_mfma_f32_16x16x32_bf16 v[112:115], v[156:159], v[172:175], v[112:115]
	v_mfma_f32_16x16x32_bf16 v[112:115], v[160:163], v[176:179], v[112:115]
	v_mfma_f32_16x16x32_bf16 v[108:111], v[152:155], v[176:179], v[108:111]
	v_mfma_f32_16x16x32_bf16 v[108:111], v[148:151], v[172:175], v[108:111]
	v_mfma_f32_16x16x32_bf16 v[116:119], v[148:151], v[180:183], v[116:119]
	v_mfma_f32_16x16x32_bf16 v[116:119], v[152:155], v[184:187], v[116:119]
	v_mfma_f32_16x16x32_bf16 v[120:123], v[160:163], v[184:187], v[120:123]
	v_mfma_f32_16x16x32_bf16 v[120:123], v[156:159], v[180:183], v[120:123]
	v_mfma_f32_16x16x32_bf16 v[128:131], v[156:159], v[194:197], v[128:131]
	v_mfma_f32_16x16x32_bf16 v[128:131], v[160:163], v[198:201], v[128:131]
	s_setprio 2
	s_barrier
	v_mfma_f32_16x16x32_bf16 v[124:127], v[152:155], v[198:201], v[124:127]
	v_mfma_f32_16x16x32_bf16 v[124:127], v[148:151], v[194:197], v[124:127]
	s_setprio 0
	s_and_b64 vcc, exec, s[58:59]
	s_cbranch_vccz .LBB0_1178
	s_barrier

.LBB0_1625:
	s_add_i32 s51, 0, 0x10000
	s_add_i32 s72, 0, 0x14000
	v_add_u32_e32 v16, s51, v232
	v_add_u32_e32 v32, s72, v232
	ds_read_b128 v[4:7], v16
	ds_read_b128 v[8:11], v16 offset:1024
	ds_read_b128 v[12:15], v16 offset:2048
	ds_read_b128 v[16:19], v16 offset:3072
	ds_read_b128 v[20:23], v32
	ds_read_b128 v[24:27], v32 offset:1024
	ds_read_b128 v[28:31], v32 offset:2048
	ds_read_b128 v[32:35], v32 offset:3072
	v_add_u32_e32 v233, 0, v231
	ds_read_b128 v[36:39], v233
	ds_read_b128 v[40:43], v233 offset:1024
	ds_read_b128 v[44:47], v233 offset:2048
	ds_read_b128 v[48:51], v233 offset:3072
	ds_read_b128 v[52:55], v233 offset:4096
	ds_read_b128 v[56:59], v233 offset:5120
	ds_read_b128 v[60:63], v233 offset:6144
	ds_read_b128 v[64:67], v233 offset:7168
	s_waitcnt vmcnt(8)
	s_waitcnt lgkmcnt(0)
	s_barrier
	s_setprio 1
	s_waitcnt lgkmcnt(0)
	s_nop 5
	v_mfma_f32_16x16x32_bf16 v[68:71], v[4:7], v[36:39], 0
	v_mfma_f32_16x16x32_bf16 v[68:71], v[8:11], v[40:43], v[68:71]
	v_mfma_f32_16x16x32_bf16 v[72:75], v[12:15], v[36:39], 0
	v_mfma_f32_16x16x32_bf16 v[72:75], v[16:19], v[40:43], v[72:75]
	v_mfma_f32_16x16x32_bf16 v[80:83], v[12:15], v[44:47], 0
	v_mfma_f32_16x16x32_bf16 v[80:83], v[16:19], v[48:51], v[80:83]
	v_mfma_f32_16x16x32_bf16 v[76:79], v[4:7], v[44:47], 0
	v_mfma_f32_16x16x32_bf16 v[76:79], v[8:11], v[48:51], v[76:79]
	v_mfma_f32_16x16x32_bf16 v[84:87], v[4:7], v[52:55], 0
	v_mfma_f32_16x16x32_bf16 v[84:87], v[8:11], v[56:59], v[84:87]
	v_mfma_f32_16x16x32_bf16 v[88:91], v[12:15], v[52:55], 0
	v_mfma_f32_16x16x32_bf16 v[88:91], v[16:19], v[56:59], v[88:91]
	v_mfma_f32_16x16x32_bf16 v[96:99], v[12:15], v[60:63], 0
	v_mfma_f32_16x16x32_bf16 v[96:99], v[16:19], v[64:67], v[96:99]
	v_mfma_f32_16x16x32_bf16 v[92:95], v[4:7], v[60:63], 0
	v_mfma_f32_16x16x32_bf16 v[92:95], v[8:11], v[64:67], v[92:95]
	s_setprio 0
	s_setprio 1
	v_mfma_f32_16x16x32_bf16 v[100:103], v[20:23], v[36:39], 0
	v_mfma_f32_16x16x32_bf16 v[36:39], v[28:31], v[36:39], 0
	v_mfma_f32_16x16x32_bf16 v[104:107], v[20:23], v[44:47], 0
	v_mfma_f32_16x16x32_bf16 v[44:47], v[28:31], v[44:47], 0
	v_mfma_f32_16x16x32_bf16 v[108:111], v[20:23], v[52:55], 0
	v_mfma_f32_16x16x32_bf16 v[52:55], v[28:31], v[52:55], 0
	v_mfma_f32_16x16x32_bf16 v[112:115], v[20:23], v[60:63], 0
	v_mfma_f32_16x16x32_bf16 v[60:63], v[28:31], v[60:63], 0
	v_mfma_f32_16x16x32_bf16 v[100:103], v[24:27], v[40:43], v[100:103]
	v_mfma_f32_16x16x32_bf16 v[40:43], v[32:35], v[40:43], v[36:39]
	v_mfma_f32_16x16x32_bf16 v[104:107], v[24:27], v[48:51], v[104:107]
	v_mfma_f32_16x16x32_bf16 v[48:51], v[32:35], v[48:51], v[44:47]
	v_mfma_f32_16x16x32_bf16 v[108:111], v[24:27], v[56:59], v[108:111]
	v_mfma_f32_16x16x32_bf16 v[56:59], v[32:35], v[56:59], v[52:55]
	s_setprio 2
	s_barrier
	v_mfma_f32_16x16x32_bf16 v[112:115], v[24:27], v[64:67], v[112:115]
	v_mfma_f32_16x16x32_bf16 v[64:67], v[32:35], v[64:67], v[60:63]
	s_setprio 0
	v_lshl_add_u64 v[186:187], s[12:13], 0, v[2:3]
	s_add_i32 s51, s51, s56
	v_mov_b32_e32 v191, v3
	v_lshl_add_u64 v[134:135], v[186:187], 0, s[74:75]
	s_mov_b32 m0, s51
	v_lshl_add_u64 v[246:247], s[12:13], 0, v[190:191]
	ds_read_b128 v[36:39], v233 offset:16384
	ds_read_b128 v[44:47], v233 offset:17408
	ds_read_b128 v[52:55], v233 offset:18432
	ds_read_b128 v[60:63], v233 offset:19456
	ds_read_b128 v[116:119], v233 offset:20480
	ds_read_b128 v[120:123], v233 offset:21504
	ds_read_b128 v[124:127], v233 offset:22528
	ds_read_b128 v[128:131], v233 offset:23552
	global_load_lds_dwordx4 v[134:135], off
	v_lshl_add_u64 v[134:135], v[246:247], 0, s[74:75]
	s_add_i32 m0, s51, 0x2000
	s_add_i32 s51, s72, s56
	global_load_lds_dwordx4 v[134:135], off
	s_mov_b32 m0, s51
	v_mov_b32_e32 v133, v3
	global_load_lds_dwordx4 v2, s[16:17]
	s_add_i32 m0, s51, 0x2000
	v_lshl_add_u64 v[248:249], s[14:15], 0, v[132:133]
	v_mov_b32_e32 v189, v3
	global_load_lds_dwordx4 v190, s[16:17]
	v_lshl_add_u64 v[134:135], v[248:249], 0, s[74:75]
	s_mov_b32 m0, s57
	v_lshl_add_u64 v[250:251], s[14:15], 0, v[188:189]
	global_load_lds_dwordx4 v[134:135], off
	v_lshl_add_u64 v[134:135], v[250:251], 0, s[74:75]
	s_mov_b32 m0, s58
	s_nop 0
	global_load_lds_dwordx4 v[134:135], off
	s_waitcnt vmcnt(8)
	s_waitcnt lgkmcnt(0)
	s_barrier
	s_setprio 1
	s_waitcnt lgkmcnt(0)
	s_nop 5
	v_mfma_f32_16x16x32_bf16 v[134:137], v[4:7], v[36:39], 0
	v_mfma_f32_16x16x32_bf16 v[138:141], v[12:15], v[36:39], 0
	v_mfma_f32_16x16x32_bf16 v[142:145], v[4:7], v[52:55], 0
	v_mfma_f32_16x16x32_bf16 v[146:149], v[12:15], v[52:55], 0
	v_mfma_f32_16x16x32_bf16 v[150:153], v[4:7], v[116:119], 0
	v_mfma_f32_16x16x32_bf16 v[154:157], v[12:15], v[116:119], 0
	v_mfma_f32_16x16x32_bf16 v[4:7], v[4:7], v[124:127], 0
	v_mfma_f32_16x16x32_bf16 v[12:15], v[12:15], v[124:127], 0
	v_mfma_f32_16x16x32_bf16 v[134:137], v[8:11], v[44:47], v[134:137]
	v_mfma_f32_16x16x32_bf16 v[138:141], v[16:19], v[44:47], v[138:141]
	v_mfma_f32_16x16x32_bf16 v[142:145], v[8:11], v[60:63], v[142:145]
	v_mfma_f32_16x16x32_bf16 v[146:149], v[16:19], v[60:63], v[146:149]
	v_mfma_f32_16x16x32_bf16 v[150:153], v[8:11], v[120:123], v[150:153]
	v_mfma_f32_16x16x32_bf16 v[154:157], v[16:19], v[120:123], v[154:157]
	v_mfma_f32_16x16x32_bf16 v[158:161], v[8:11], v[128:131], v[4:7]
	v_mfma_f32_16x16x32_bf16 v[162:165], v[16:19], v[128:131], v[12:15]
	s_setprio 0
	s_setprio 1
	v_mfma_f32_16x16x32_bf16 v[4:7], v[20:23], v[36:39], 0
	v_mfma_f32_16x16x32_bf16 v[8:11], v[28:31], v[36:39], 0
	v_mfma_f32_16x16x32_bf16 v[12:15], v[20:23], v[52:55], 0
	v_mfma_f32_16x16x32_bf16 v[16:19], v[28:31], v[52:55], 0
	v_mfma_f32_16x16x32_bf16 v[36:39], v[20:23], v[116:119], 0
	v_mfma_f32_16x16x32_bf16 v[52:55], v[28:31], v[116:119], 0
	v_mfma_f32_16x16x32_bf16 v[20:23], v[20:23], v[124:127], 0
	v_mfma_f32_16x16x32_bf16 v[28:31], v[28:31], v[124:127], 0
	v_mfma_f32_16x16x32_bf16 v[116:119], v[24:27], v[44:47], v[4:7]
	v_mfma_f32_16x16x32_bf16 v[124:127], v[32:35], v[44:47], v[8:11]
	v_mfma_f32_16x16x32_bf16 v[174:177], v[24:27], v[120:123], v[36:39]
	v_mfma_f32_16x16x32_bf16 v[120:123], v[32:35], v[120:123], v[52:55]
	v_mfma_f32_16x16x32_bf16 v[178:181], v[24:27], v[128:131], v[20:23]
	v_mfma_f32_16x16x32_bf16 v[128:131], v[32:35], v[128:131], v[28:31]
	s_setprio 2
	s_barrier
	v_mfma_f32_16x16x32_bf16 v[166:169], v[24:27], v[60:63], v[12:15]
	v_mfma_f32_16x16x32_bf16 v[170:173], v[32:35], v[60:63], v[16:19]
	s_setprio 0
	s_add_i32 s51, 0, 0x18000
	v_add_u32_e32 v4, s51, v232
	s_add_i32 s72, 0, 0x1c000
	ds_read_b128 v[182:185], v4
	ds_read_b128 v[192:195], v4 offset:1024
	ds_read_b128 v[196:199], v4 offset:2048
	ds_read_b128 v[200:203], v4 offset:3072
	v_add_u32_e32 v4, s72, v232
	ds_read_b128 v[204:207], v4
	ds_read_b128 v[208:211], v4 offset:1024
	ds_read_b128 v[212:215], v4 offset:2048
	ds_read_b128 v[216:219], v4 offset:3072
	s_mov_b32 m0, s59
	ds_read_b128 v[44:47], v233 offset:32768
	ds_read_b128 v[52:55], v233 offset:33792
	ds_read_b128 v[60:63], v233 offset:34816
	ds_read_b128 v[220:223], v233 offset:35840
	ds_read_b128 v[224:227], v233 offset:36864
	ds_read_b128 v[234:237], v233 offset:37888
	ds_read_b128 v[238:241], v233 offset:38912
	ds_read_b128 v[242:245], v233 offset:39936
	global_load_lds_dwordx4 v132, s[26:27]
	s_mov_b32 m0, s60
	s_nop 0
	global_load_lds_dwordx4 v188, s[26:27]
	s_waitcnt vmcnt(8)
	s_waitcnt lgkmcnt(0)
	s_barrier
	s_setprio 1
	s_waitcnt lgkmcnt(0)
	s_nop 5
	v_mfma_f32_16x16x32_bf16 v[4:7], v[182:185], v[44:47], v[68:71]
	v_mfma_f32_16x16x32_bf16 v[8:11], v[196:199], v[44:47], v[72:75]
	v_mfma_f32_16x16x32_bf16 v[12:15], v[182:185], v[60:63], v[76:79]
	v_mfma_f32_16x16x32_bf16 v[16:19], v[196:199], v[60:63], v[80:83]
	v_mfma_f32_16x16x32_bf16 v[20:23], v[182:185], v[224:227], v[84:87]
	v_mfma_f32_16x16x32_bf16 v[24:27], v[196:199], v[224:227], v[88:91]
	v_mfma_f32_16x16x32_bf16 v[28:31], v[182:185], v[238:241], v[92:95]
	v_mfma_f32_16x16x32_bf16 v[32:35], v[196:199], v[238:241], v[96:99]
	v_mfma_f32_16x16x32_bf16 v[4:7], v[192:195], v[52:55], v[4:7]
	v_mfma_f32_16x16x32_bf16 v[8:11], v[200:203], v[52:55], v[8:11]
	v_mfma_f32_16x16x32_bf16 v[12:15], v[192:195], v[220:223], v[12:15]
	v_mfma_f32_16x16x32_bf16 v[16:19], v[200:203], v[220:223], v[16:19]
	v_mfma_f32_16x16x32_bf16 v[20:23], v[192:195], v[234:237], v[20:23]
	v_mfma_f32_16x16x32_bf16 v[24:27], v[200:203], v[234:237], v[24:27]
	v_mfma_f32_16x16x32_bf16 v[28:31], v[192:195], v[242:245], v[28:31]
	v_mfma_f32_16x16x32_bf16 v[32:35], v[200:203], v[242:245], v[32:35]
	s_setprio 0
	s_setprio 1
	v_mfma_f32_16x16x32_bf16 v[36:39], v[204:207], v[44:47], v[100:103]
	v_mfma_f32_16x16x32_bf16 v[40:43], v[212:215], v[44:47], v[40:43]
	v_mfma_f32_16x16x32_bf16 v[36:39], v[208:211], v[52:55], v[36:39]
	v_mfma_f32_16x16x32_bf16 v[40:43], v[216:219], v[52:55], v[40:43]
	v_mfma_f32_16x16x32_bf16 v[44:47], v[204:207], v[60:63], v[104:107]
	v_mfma_f32_16x16x32_bf16 v[48:51], v[212:215], v[60:63], v[48:51]
	v_mfma_f32_16x16x32_bf16 v[52:55], v[204:207], v[224:227], v[108:111]
	v_mfma_f32_16x16x32_bf16 v[56:59], v[212:215], v[224:227], v[56:59]
	v_mfma_f32_16x16x32_bf16 v[60:63], v[204:207], v[238:241], v[112:115]
	v_mfma_f32_16x16x32_bf16 v[64:67], v[212:215], v[238:241], v[64:67]
	v_mfma_f32_16x16x32_bf16 v[44:47], v[208:211], v[220:223], v[44:47]
	v_mfma_f32_16x16x32_bf16 v[48:51], v[216:219], v[220:223], v[48:51]
	v_mfma_f32_16x16x32_bf16 v[52:55], v[208:211], v[234:237], v[52:55]
	v_mfma_f32_16x16x32_bf16 v[56:59], v[216:219], v[234:237], v[56:59]
	s_setprio 2
	s_barrier
	v_mfma_f32_16x16x32_bf16 v[60:63], v[208:211], v[242:245], v[60:63]
	v_mfma_f32_16x16x32_bf16 v[64:67], v[216:219], v[242:245], v[64:67]
	s_setprio 0
	s_add_i32 s51, s51, s56
	v_lshl_add_u64 v[68:69], v[186:187], 0, s[24:25]
	s_mov_b32 m0, s51
	ds_read_b128 v[104:107], v233 offset:49152
	ds_read_b128 v[108:111], v233 offset:50176
	ds_read_b128 v[112:115], v233 offset:51200
	ds_read_b128 v[220:223], v233 offset:52224
	ds_read_b128 v[224:227], v233 offset:53248
	ds_read_b128 v[234:237], v233 offset:54272
	ds_read_b128 v[238:241], v233 offset:55296
	ds_read_b128 v[242:245], v233 offset:56320
	global_load_lds_dwordx4 v[68:69], off
	v_lshl_add_u64 v[68:69], v[246:247], 0, s[24:25]
	s_add_i32 m0, s51, 0x2000
	s_add_i32 s51, s72, s56
	global_load_lds_dwordx4 v[68:69], off
	s_mov_b32 m0, s51
	v_lshl_add_u64 v[68:69], v[248:249], 0, s[24:25]
	global_load_lds_dwordx4 v2, s[28:29]
	s_add_i32 m0, s51, 0x2000
	s_nop 0
	global_load_lds_dwordx4 v190, s[28:29]
	s_mov_b32 m0, s64
	s_nop 0
	global_load_lds_dwordx4 v[68:69], off
	v_lshl_add_u64 v[68:69], v[250:251], 0, s[24:25]
	s_mov_b32 m0, s65
	s_nop 0
	global_load_lds_dwordx4 v[68:69], off
	s_waitcnt vmcnt(8)
	s_waitcnt lgkmcnt(0)
	s_barrier
	s_setprio 1
	s_waitcnt lgkmcnt(0)
	s_nop 5
	v_mfma_f32_16x16x32_bf16 v[68:71], v[182:185], v[104:107], v[134:137]
	v_mfma_f32_16x16x32_bf16 v[72:75], v[196:199], v[104:107], v[138:141]
	v_mfma_f32_16x16x32_bf16 v[76:79], v[182:185], v[112:115], v[142:145]
	v_mfma_f32_16x16x32_bf16 v[80:83], v[196:199], v[112:115], v[146:149]
	v_mfma_f32_16x16x32_bf16 v[84:87], v[182:185], v[224:227], v[150:153]
	v_mfma_f32_16x16x32_bf16 v[88:91], v[196:199], v[224:227], v[154:157]
	v_mfma_f32_16x16x32_bf16 v[92:95], v[182:185], v[238:241], v[158:161]
	v_mfma_f32_16x16x32_bf16 v[96:99], v[196:199], v[238:241], v[162:165]
	v_mfma_f32_16x16x32_bf16 v[68:71], v[192:195], v[108:111], v[68:71]
	v_mfma_f32_16x16x32_bf16 v[72:75], v[200:203], v[108:111], v[72:75]
	v_mfma_f32_16x16x32_bf16 v[76:79], v[192:195], v[220:223], v[76:79]
	v_mfma_f32_16x16x32_bf16 v[80:83], v[200:203], v[220:223], v[80:83]
	v_mfma_f32_16x16x32_bf16 v[84:87], v[192:195], v[234:237], v[84:87]
	v_mfma_f32_16x16x32_bf16 v[88:91], v[200:203], v[234:237], v[88:91]
	v_mfma_f32_16x16x32_bf16 v[92:95], v[192:195], v[242:245], v[92:95]
	v_mfma_f32_16x16x32_bf16 v[96:99], v[200:203], v[242:245], v[96:99]
	s_setprio 0
	s_setprio 1
	v_mfma_f32_16x16x32_bf16 v[100:103], v[204:207], v[104:107], v[116:119]
	v_mfma_f32_16x16x32_bf16 v[104:107], v[212:215], v[104:107], v[124:127]
	v_mfma_f32_16x16x32_bf16 v[100:103], v[208:211], v[108:111], v[100:103]
	v_mfma_f32_16x16x32_bf16 v[104:107], v[216:219], v[108:111], v[104:107]
	v_mfma_f32_16x16x32_bf16 v[108:111], v[204:207], v[112:115], v[166:169]
	v_mfma_f32_16x16x32_bf16 v[112:115], v[212:215], v[112:115], v[170:173]
	v_mfma_f32_16x16x32_bf16 v[116:119], v[204:207], v[224:227], v[174:177]
	v_mfma_f32_16x16x32_bf16 v[120:123], v[212:215], v[224:227], v[120:123]
	v_mfma_f32_16x16x32_bf16 v[124:127], v[204:207], v[238:241], v[178:181]
	v_mfma_f32_16x16x32_bf16 v[128:131], v[212:215], v[238:241], v[128:131]
	v_mfma_f32_16x16x32_bf16 v[108:111], v[208:211], v[220:223], v[108:111]
	v_mfma_f32_16x16x32_bf16 v[112:115], v[216:219], v[220:223], v[112:115]
	v_mfma_f32_16x16x32_bf16 v[116:119], v[208:211], v[234:237], v[116:119]
	v_mfma_f32_16x16x32_bf16 v[120:123], v[216:219], v[234:237], v[120:123]
	s_setprio 2
	s_barrier
	v_mfma_f32_16x16x32_bf16 v[124:127], v[208:211], v[242:245], v[124:127]
	v_mfma_f32_16x16x32_bf16 v[128:131], v[216:219], v[242:245], v[128:131]
	s_setprio 0
	s_add_i32 s43, s43, 2
	s_cmp_ge_i32 s43, s42
	s_cbranch_scc0 .LBB0_1625
	v_mov_b32_e32 v192, v2
	s_branch .LBB0_1628

.LBB0_1629:
	s_add_u32 s12, s14, 0xfff80080
	s_addc_u32 s13, s15, -1
	s_add_i32 s29, 0, 0x10000
	s_cmp_eq_u32 s28, 28
	s_cselect_b32 s17, s9, s13
	s_cselect_b32 s16, s8, s12
	s_cselect_b32 s13, s11, s27
	s_cselect_b32 s12, s10, s26
	s_add_i32 s51, 0, 0x14000
	v_add_u32_e32 v144, s29, v232
	v_add_u32_e32 v160, s51, v232
	s_waitcnt lgkmcnt(0)
	ds_read_b128 v[132:135], v144
	ds_read_b128 v[136:139], v144 offset:1024
	ds_read_b128 v[140:143], v144 offset:2048
	ds_read_b128 v[144:147], v144 offset:3072
	ds_read_b128 v[148:151], v160
	ds_read_b128 v[152:155], v160 offset:1024
	ds_read_b128 v[156:159], v160 offset:2048
	ds_read_b128 v[160:163], v160 offset:3072
	s_mov_b32 m0, s66
	v_add_u32_e32 v210, 0, v231
	ds_read_b128 v[164:167], v210
	ds_read_b128 v[168:171], v210 offset:1024
	ds_read_b128 v[172:175], v210 offset:2048
	ds_read_b128 v[176:179], v210 offset:3072
	ds_read_b128 v[180:183], v210 offset:4096
	ds_read_b128 v[184:187], v210 offset:5120
	ds_read_b128 v[194:197], v210 offset:6144
	ds_read_b128 v[198:201], v210 offset:7168
	global_load_lds_dwordx4 v2, s[14:15]
	s_mov_b32 m0, s67
	v_mov_b32_e32 v189, v3
	global_load_lds_dwordx4 v188, s[14:15]
	s_waitcnt vmcnt(8)
	s_waitcnt lgkmcnt(0)
	s_barrier
	s_setprio 1
	s_waitcnt lgkmcnt(0)
	s_nop 5
	v_mfma_f32_16x16x32_bf16 v[4:7], v[132:135], v[164:167], v[4:7]
	v_mfma_f32_16x16x32_bf16 v[4:7], v[136:139], v[168:171], v[4:7]
	v_mfma_f32_16x16x32_bf16 v[8:11], v[144:147], v[168:171], v[8:11]
	v_mfma_f32_16x16x32_bf16 v[8:11], v[140:143], v[164:167], v[8:11]
	v_mfma_f32_16x16x32_bf16 v[16:19], v[140:143], v[172:175], v[16:19]
	v_mfma_f32_16x16x32_bf16 v[16:19], v[144:147], v[176:179], v[16:19]
	v_mfma_f32_16x16x32_bf16 v[12:15], v[136:139], v[176:179], v[12:15]
	v_mfma_f32_16x16x32_bf16 v[12:15], v[132:135], v[172:175], v[12:15]
	v_mfma_f32_16x16x32_bf16 v[20:23], v[132:135], v[180:183], v[20:23]
	v_mfma_f32_16x16x32_bf16 v[20:23], v[136:139], v[184:187], v[20:23]
	v_mfma_f32_16x16x32_bf16 v[24:27], v[144:147], v[184:187], v[24:27]
	v_mfma_f32_16x16x32_bf16 v[24:27], v[140:143], v[180:183], v[24:27]
	v_mfma_f32_16x16x32_bf16 v[32:35], v[140:143], v[194:197], v[32:35]
	v_mfma_f32_16x16x32_bf16 v[32:35], v[144:147], v[198:201], v[32:35]
	v_mfma_f32_16x16x32_bf16 v[28:31], v[136:139], v[198:201], v[28:31]
	v_mfma_f32_16x16x32_bf16 v[28:31], v[132:135], v[194:197], v[28:31]
	s_setprio 0
	s_setprio 1
	v_mfma_f32_16x16x32_bf16 v[36:39], v[148:151], v[164:167], v[36:39]
	v_mfma_f32_16x16x32_bf16 v[36:39], v[152:155], v[168:171], v[36:39]
	v_mfma_f32_16x16x32_bf16 v[40:43], v[160:163], v[168:171], v[40:43]
	v_mfma_f32_16x16x32_bf16 v[40:43], v[156:159], v[164:167], v[40:43]
	v_mfma_f32_16x16x32_bf16 v[48:51], v[156:159], v[172:175], v[48:51]
	v_mfma_f32_16x16x32_bf16 v[48:51], v[160:163], v[176:179], v[48:51]
	v_mfma_f32_16x16x32_bf16 v[44:47], v[152:155], v[176:179], v[44:47]
	v_mfma_f32_16x16x32_bf16 v[44:47], v[148:151], v[172:175], v[44:47]
	v_mfma_f32_16x16x32_bf16 v[52:55], v[148:151], v[180:183], v[52:55]
	v_mfma_f32_16x16x32_bf16 v[52:55], v[152:155], v[184:187], v[52:55]
	v_mfma_f32_16x16x32_bf16 v[56:59], v[160:163], v[184:187], v[56:59]
	v_mfma_f32_16x16x32_bf16 v[56:59], v[156:159], v[180:183], v[56:59]
	v_mfma_f32_16x16x32_bf16 v[64:67], v[156:159], v[194:197], v[64:67]
	v_mfma_f32_16x16x32_bf16 v[64:67], v[160:163], v[198:201], v[64:67]
	s_setprio 2
	s_barrier
	v_mfma_f32_16x16x32_bf16 v[60:63], v[152:155], v[198:201], v[60:63]
	v_mfma_f32_16x16x32_bf16 v[60:63], v[148:151], v[194:197], v[60:63]
	s_setprio 0
	s_add_i32 s29, s29, s56
	s_mov_b32 m0, s29
	ds_read_b128 v[164:167], v210 offset:16384
	ds_read_b128 v[168:171], v210 offset:17408
	ds_read_b128 v[172:175], v210 offset:18432
	ds_read_b128 v[176:179], v210 offset:19456
	ds_read_b128 v[180:183], v210 offset:20480
	ds_read_b128 v[184:187], v210 offset:21504
	ds_read_b128 v[194:197], v210 offset:22528
	ds_read_b128 v[198:201], v210 offset:23552
	global_load_lds_dwordx4 v192, s[12:13]
	s_add_i32 m0, s29, 0x2000
	s_add_u32 s42, s12, 0x80000
	s_addc_u32 s43, s13, 0
	s_add_i32 s29, s51, s56
	global_load_lds_dwordx4 v190, s[12:13]
	s_mov_b32 m0, s29
	v_mov_b32_e32 v193, v3
	global_load_lds_dwordx4 v192, s[42:43]
	s_add_i32 m0, s29, 0x2000
	v_mov_b32_e32 v191, v3
	global_load_lds_dwordx4 v190, s[42:43]
	s_mov_b32 m0, s57
	v_lshl_add_u64 v[202:203], s[12:13], 0, v[192:193]
	global_load_lds_dwordx4 v2, s[16:17]
	s_mov_b32 m0, s58
	v_lshl_add_u64 v[204:205], s[12:13], 0, v[190:191]
	global_load_lds_dwordx4 v188, s[16:17]
	s_waitcnt vmcnt(8)
	s_waitcnt lgkmcnt(0)
	v_lshl_add_u64 v[206:207], s[16:17], 0, v[2:3]
	v_lshl_add_u64 v[208:209], s[16:17], 0, v[188:189]
	s_barrier
	s_setprio 1
	s_waitcnt lgkmcnt(0)
	s_nop 5
	v_mfma_f32_16x16x32_bf16 v[68:71], v[132:135], v[164:167], v[68:71]
	v_mfma_f32_16x16x32_bf16 v[68:71], v[136:139], v[168:171], v[68:71]
	v_mfma_f32_16x16x32_bf16 v[72:75], v[144:147], v[168:171], v[72:75]
	v_mfma_f32_16x16x32_bf16 v[72:75], v[140:143], v[164:167], v[72:75]
	v_mfma_f32_16x16x32_bf16 v[80:83], v[140:143], v[172:175], v[80:83]
	v_mfma_f32_16x16x32_bf16 v[80:83], v[144:147], v[176:179], v[80:83]
	v_mfma_f32_16x16x32_bf16 v[76:79], v[136:139], v[176:179], v[76:79]
	v_mfma_f32_16x16x32_bf16 v[76:79], v[132:135], v[172:175], v[76:79]
	v_mfma_f32_16x16x32_bf16 v[84:87], v[132:135], v[180:183], v[84:87]
	v_mfma_f32_16x16x32_bf16 v[84:87], v[136:139], v[184:187], v[84:87]
	v_mfma_f32_16x16x32_bf16 v[88:91], v[144:147], v[184:187], v[88:91]
	v_mfma_f32_16x16x32_bf16 v[88:91], v[140:143], v[180:183], v[88:91]
	v_mfma_f32_16x16x32_bf16 v[96:99], v[140:143], v[194:197], v[96:99]
	v_mfma_f32_16x16x32_bf16 v[96:99], v[144:147], v[198:201], v[96:99]
	v_mfma_f32_16x16x32_bf16 v[92:95], v[136:139], v[198:201], v[92:95]
	v_mfma_f32_16x16x32_bf16 v[92:95], v[132:135], v[194:197], v[92:95]
	s_setprio 0
	s_setprio 1
	v_mfma_f32_16x16x32_bf16 v[100:103], v[148:151], v[164:167], v[100:103]
	v_mfma_f32_16x16x32_bf16 v[100:103], v[152:155], v[168:171], v[100:103]
	v_mfma_f32_16x16x32_bf16 v[104:107], v[160:163], v[168:171], v[104:107]
	v_mfma_f32_16x16x32_bf16 v[104:107], v[156:159], v[164:167], v[104:107]
	v_mfma_f32_16x16x32_bf16 v[112:115], v[156:159], v[172:175], v[112:115]
	v_mfma_f32_16x16x32_bf16 v[112:115], v[160:163], v[176:179], v[112:115]
	v_mfma_f32_16x16x32_bf16 v[108:111], v[152:155], v[176:179], v[108:111]
	v_mfma_f32_16x16x32_bf16 v[108:111], v[148:151], v[172:175], v[108:111]
	v_mfma_f32_16x16x32_bf16 v[116:119], v[148:151], v[180:183], v[116:119]
	v_mfma_f32_16x16x32_bf16 v[116:119], v[152:155], v[184:187], v[116:119]
	v_mfma_f32_16x16x32_bf16 v[120:123], v[160:163], v[184:187], v[120:123]
	v_mfma_f32_16x16x32_bf16 v[120:123], v[156:159], v[180:183], v[120:123]
	v_mfma_f32_16x16x32_bf16 v[128:131], v[156:159], v[194:197], v[128:131]
	v_mfma_f32_16x16x32_bf16 v[128:131], v[160:163], v[198:201], v[128:131]
	s_setprio 2
	s_barrier
	v_mfma_f32_16x16x32_bf16 v[124:127], v[152:155], v[198:201], v[124:127]
	v_mfma_f32_16x16x32_bf16 v[124:127], v[148:151], v[194:197], v[124:127]
	s_setprio 0
	s_add_i32 s29, 0, 0x18000
	s_add_i32 s42, 0, 0x1c000
	v_add_u32_e32 v144, s29, v232
	v_add_u32_e32 v160, s42, v232
	ds_read_b128 v[132:135], v144
	ds_read_b128 v[136:139], v144 offset:1024
	ds_read_b128 v[140:143], v144 offset:2048
	ds_read_b128 v[144:147], v144 offset:3072
	ds_read_b128 v[148:151], v160
	ds_read_b128 v[152:155], v160 offset:1024
	ds_read_b128 v[156:159], v160 offset:2048
	ds_read_b128 v[160:163], v160 offset:3072
	s_add_u32 s16, s16, 0x80000
	s_addc_u32 s17, s17, 0
	s_mov_b32 m0, s59
	ds_read_b128 v[164:167], v210 offset:32768
	ds_read_b128 v[168:171], v210 offset:33792
	ds_read_b128 v[172:175], v210 offset:34816
	ds_read_b128 v[176:179], v210 offset:35840
	ds_read_b128 v[180:183], v210 offset:36864
	ds_read_b128 v[184:187], v210 offset:37888
	ds_read_b128 v[194:197], v210 offset:38912
	ds_read_b128 v[198:201], v210 offset:39936
	global_load_lds_dwordx4 v2, s[16:17]
	s_mov_b32 m0, s60
	s_nop 0
	global_load_lds_dwordx4 v188, s[16:17]
	s_waitcnt vmcnt(8)
	s_waitcnt lgkmcnt(0)
	s_barrier
	s_setprio 1
	s_waitcnt lgkmcnt(0)
	s_nop 5
	v_mfma_f32_16x16x32_bf16 v[4:7], v[132:135], v[164:167], v[4:7]
	v_mfma_f32_16x16x32_bf16 v[4:7], v[136:139], v[168:171], v[4:7]
	v_mfma_f32_16x16x32_bf16 v[8:11], v[144:147], v[168:171], v[8:11]
	v_mfma_f32_16x16x32_bf16 v[8:11], v[140:143], v[164:167], v[8:11]
	v_mfma_f32_16x16x32_bf16 v[16:19], v[140:143], v[172:175], v[16:19]
	v_mfma_f32_16x16x32_bf16 v[16:19], v[144:147], v[176:179], v[16:19]
	v_mfma_f32_16x16x32_bf16 v[12:15], v[136:139], v[176:179], v[12:15]
	v_mfma_f32_16x16x32_bf16 v[12:15], v[132:135], v[172:175], v[12:15]
	v_mfma_f32_16x16x32_bf16 v[20:23], v[132:135], v[180:183], v[20:23]
	v_mfma_f32_16x16x32_bf16 v[20:23], v[136:139], v[184:187], v[20:23]
	v_mfma_f32_16x16x32_bf16 v[24:27], v[144:147], v[184:187], v[24:27]
	v_mfma_f32_16x16x32_bf16 v[24:27], v[140:143], v[180:183], v[24:27]
	v_mfma_f32_16x16x32_bf16 v[32:35], v[140:143], v[194:197], v[32:35]
	v_mfma_f32_16x16x32_bf16 v[32:35], v[144:147], v[198:201], v[32:35]
	v_mfma_f32_16x16x32_bf16 v[28:31], v[136:139], v[198:201], v[28:31]
	v_mfma_f32_16x16x32_bf16 v[28:31], v[132:135], v[194:197], v[28:31]
	s_setprio 0
	s_setprio 1
	v_mfma_f32_16x16x32_bf16 v[36:39], v[148:151], v[164:167], v[36:39]
	v_mfma_f32_16x16x32_bf16 v[36:39], v[152:155], v[168:171], v[36:39]
	v_mfma_f32_16x16x32_bf16 v[40:43], v[160:163], v[168:171], v[40:43]
	v_mfma_f32_16x16x32_bf16 v[40:43], v[156:159], v[164:167], v[40:43]
	v_mfma_f32_16x16x32_bf16 v[48:51], v[156:159], v[172:175], v[48:51]
	v_mfma_f32_16x16x32_bf16 v[48:51], v[160:163], v[176:179], v[48:51]
	v_mfma_f32_16x16x32_bf16 v[44:47], v[152:155], v[176:179], v[44:47]
	v_mfma_f32_16x16x32_bf16 v[44:47], v[148:151], v[172:175], v[44:47]
	v_mfma_f32_16x16x32_bf16 v[52:55], v[148:151], v[180:183], v[52:55]
	v_mfma_f32_16x16x32_bf16 v[52:55], v[152:155], v[184:187], v[52:55]
	v_mfma_f32_16x16x32_bf16 v[56:59], v[160:163], v[184:187], v[56:59]
	v_mfma_f32_16x16x32_bf16 v[56:59], v[156:159], v[180:183], v[56:59]
	v_mfma_f32_16x16x32_bf16 v[64:67], v[156:159], v[194:197], v[64:67]
	v_mfma_f32_16x16x32_bf16 v[64:67], v[160:163], v[198:201], v[64:67]
	s_setprio 2
	s_barrier
	v_mfma_f32_16x16x32_bf16 v[60:63], v[152:155], v[198:201], v[60:63]
	v_mfma_f32_16x16x32_bf16 v[60:63], v[148:151], v[194:197], v[60:63]
	s_setprio 0
	s_add_i32 s16, s29, s56
	v_lshl_add_u64 v[202:203], v[202:203], 0, s[86:87]
	s_mov_b32 m0, s16
	ds_read_b128 v[164:167], v210 offset:49152
	ds_read_b128 v[168:171], v210 offset:50176
	ds_read_b128 v[172:175], v210 offset:51200
	ds_read_b128 v[176:179], v210 offset:52224
	ds_read_b128 v[180:183], v210 offset:53248
	ds_read_b128 v[184:187], v210 offset:54272
	ds_read_b128 v[194:197], v210 offset:55296
	ds_read_b128 v[198:201], v210 offset:56320
	global_load_lds_dwordx4 v[202:203], off
	s_add_i32 m0, s16, 0x2000
	s_add_u32 s12, s12, 0x80080
	v_lshl_add_u64 v[202:203], v[204:205], 0, s[86:87]
	s_addc_u32 s13, s13, 0
	s_add_i32 s16, s42, s56
	global_load_lds_dwordx4 v[202:203], off
	s_mov_b32 m0, s16
	v_lshl_add_u64 v[202:203], v[206:207], 0, s[86:87]
	global_load_lds_dwordx4 v192, s[12:13]
	s_add_i32 m0, s16, 0x2000
	s_nop 0
	global_load_lds_dwordx4 v190, s[12:13]
	s_mov_b32 m0, s64
	s_nop 0
	global_load_lds_dwordx4 v[202:203], off
	v_lshl_add_u64 v[202:203], v[208:209], 0, s[86:87]
	s_mov_b32 m0, s65
	s_nop 0
	global_load_lds_dwordx4 v[202:203], off
	s_waitcnt vmcnt(8)
	s_waitcnt lgkmcnt(0)
	s_barrier
	s_setprio 1
	s_waitcnt lgkmcnt(0)
	s_nop 5
	v_mfma_f32_16x16x32_bf16 v[68:71], v[132:135], v[164:167], v[68:71]
	v_mfma_f32_16x16x32_bf16 v[68:71], v[136:139], v[168:171], v[68:71]
	v_mfma_f32_16x16x32_bf16 v[72:75], v[144:147], v[168:171], v[72:75]
	v_mfma_f32_16x16x32_bf16 v[72:75], v[140:143], v[164:167], v[72:75]
	v_mfma_f32_16x16x32_bf16 v[80:83], v[140:143], v[172:175], v[80:83]
	v_mfma_f32_16x16x32_bf16 v[80:83], v[144:147], v[176:179], v[80:83]
	v_mfma_f32_16x16x32_bf16 v[76:79], v[136:139], v[176:179], v[76:79]
	v_mfma_f32_16x16x32_bf16 v[76:79], v[132:135], v[172:175], v[76:79]
	v_mfma_f32_16x16x32_bf16 v[84:87], v[132:135], v[180:183], v[84:87]
	v_mfma_f32_16x16x32_bf16 v[84:87], v[136:139], v[184:187], v[84:87]
	v_mfma_f32_16x16x32_bf16 v[88:91], v[144:147], v[184:187], v[88:91]
	v_mfma_f32_16x16x32_bf16 v[88:91], v[140:143], v[180:183], v[88:91]
	v_mfma_f32_16x16x32_bf16 v[96:99], v[140:143], v[194:197], v[96:99]
	v_mfma_f32_16x16x32_bf16 v[96:99], v[144:147], v[198:201], v[96:99]
	v_mfma_f32_16x16x32_bf16 v[92:95], v[136:139], v[198:201], v[92:95]
	v_mfma_f32_16x16x32_bf16 v[92:95], v[132:135], v[194:197], v[92:95]
	s_setprio 0
	s_setprio 1
	v_mfma_f32_16x16x32_bf16 v[100:103], v[148:151], v[164:167], v[100:103]
	v_mfma_f32_16x16x32_bf16 v[100:103], v[152:155], v[168:171], v[100:103]
	v_mfma_f32_16x16x32_bf16 v[104:107], v[160:163], v[168:171], v[104:107]
	v_mfma_f32_16x16x32_bf16 v[104:107], v[156:159], v[164:167], v[104:107]
	v_mfma_f32_16x16x32_bf16 v[112:115], v[156:159], v[172:175], v[112:115]
	v_mfma_f32_16x16x32_bf16 v[112:115], v[160:163], v[176:179], v[112:115]
	v_mfma_f32_16x16x32_bf16 v[108:111], v[152:155], v[176:179], v[108:111]
	v_mfma_f32_16x16x32_bf16 v[108:111], v[148:151], v[172:175], v[108:111]
	v_mfma_f32_16x16x32_bf16 v[116:119], v[148:151], v[180:183], v[116:119]
	v_mfma_f32_16x16x32_bf16 v[116:119], v[152:155], v[184:187], v[116:119]
	v_mfma_f32_16x16x32_bf16 v[120:123], v[160:163], v[184:187], v[120:123]
	v_mfma_f32_16x16x32_bf16 v[120:123], v[156:159], v[180:183], v[120:123]
	v_mfma_f32_16x16x32_bf16 v[128:131], v[156:159], v[194:197], v[128:131]
	v_mfma_f32_16x16x32_bf16 v[128:131], v[160:163], v[198:201], v[128:131]
	s_setprio 2
	s_barrier
	v_mfma_f32_16x16x32_bf16 v[124:127], v[152:155], v[198:201], v[124:127]
	v_mfma_f32_16x16x32_bf16 v[124:127], v[148:151], v[194:197], v[124:127]
	s_setprio 0
	s_add_i32 s28, s28, 2
	s_add_u32 s14, s14, 0x100
	s_addc_u32 s15, s15, 0
	s_add_u32 s26, s26, 0x100
	s_addc_u32 s27, s27, 0
	s_cmp_gt_u32 s28, 29
	s_cbranch_scc0 .LBB0_1629
	s_and_b64 vcc, exec, s[48:49]
	s_cbranch_vccz .LBB0_1632
	s_barrier

.LBB0_2065:
	s_add_i32 s51, 0, 0x10000
	s_add_i32 s71, 0, 0x14000
	v_add_u32_e32 v16, s51, v232
	v_add_u32_e32 v32, s71, v232
	ds_read_b128 v[4:7], v16
	ds_read_b128 v[8:11], v16 offset:1024
	ds_read_b128 v[12:15], v16 offset:2048
	ds_read_b128 v[16:19], v16 offset:3072
	ds_read_b128 v[20:23], v32
	ds_read_b128 v[24:27], v32 offset:1024
	ds_read_b128 v[28:31], v32 offset:2048
	ds_read_b128 v[32:35], v32 offset:3072
	v_add_u32_e32 v233, 0, v231
	ds_read_b128 v[36:39], v233
	ds_read_b128 v[40:43], v233 offset:1024
	ds_read_b128 v[44:47], v233 offset:2048
	ds_read_b128 v[48:51], v233 offset:3072
	ds_read_b128 v[52:55], v233 offset:4096
	ds_read_b128 v[56:59], v233 offset:5120
	ds_read_b128 v[60:63], v233 offset:6144
	ds_read_b128 v[64:67], v233 offset:7168
	s_waitcnt vmcnt(8)
	s_waitcnt lgkmcnt(0)
	s_barrier
	s_setprio 1
	s_waitcnt lgkmcnt(0)
	s_nop 5
	v_mfma_f32_16x16x32_bf16 v[68:71], v[4:7], v[36:39], 0
	v_mfma_f32_16x16x32_bf16 v[68:71], v[8:11], v[40:43], v[68:71]
	v_mfma_f32_16x16x32_bf16 v[72:75], v[12:15], v[36:39], 0
	v_mfma_f32_16x16x32_bf16 v[72:75], v[16:19], v[40:43], v[72:75]
	v_mfma_f32_16x16x32_bf16 v[80:83], v[12:15], v[44:47], 0
	v_mfma_f32_16x16x32_bf16 v[80:83], v[16:19], v[48:51], v[80:83]
	v_mfma_f32_16x16x32_bf16 v[76:79], v[4:7], v[44:47], 0
	v_mfma_f32_16x16x32_bf16 v[76:79], v[8:11], v[48:51], v[76:79]
	v_mfma_f32_16x16x32_bf16 v[84:87], v[4:7], v[52:55], 0
	v_mfma_f32_16x16x32_bf16 v[84:87], v[8:11], v[56:59], v[84:87]
	v_mfma_f32_16x16x32_bf16 v[88:91], v[12:15], v[52:55], 0
	v_mfma_f32_16x16x32_bf16 v[88:91], v[16:19], v[56:59], v[88:91]
	v_mfma_f32_16x16x32_bf16 v[96:99], v[12:15], v[60:63], 0
	v_mfma_f32_16x16x32_bf16 v[96:99], v[16:19], v[64:67], v[96:99]
	v_mfma_f32_16x16x32_bf16 v[92:95], v[4:7], v[60:63], 0
	v_mfma_f32_16x16x32_bf16 v[92:95], v[8:11], v[64:67], v[92:95]
	s_setprio 0
	s_setprio 1
	v_mfma_f32_16x16x32_bf16 v[100:103], v[20:23], v[36:39], 0
	v_mfma_f32_16x16x32_bf16 v[36:39], v[28:31], v[36:39], 0
	v_mfma_f32_16x16x32_bf16 v[104:107], v[20:23], v[44:47], 0
	v_mfma_f32_16x16x32_bf16 v[44:47], v[28:31], v[44:47], 0
	v_mfma_f32_16x16x32_bf16 v[108:111], v[20:23], v[52:55], 0
	v_mfma_f32_16x16x32_bf16 v[52:55], v[28:31], v[52:55], 0
	v_mfma_f32_16x16x32_bf16 v[112:115], v[20:23], v[60:63], 0
	v_mfma_f32_16x16x32_bf16 v[60:63], v[28:31], v[60:63], 0
	v_mfma_f32_16x16x32_bf16 v[100:103], v[24:27], v[40:43], v[100:103]
	v_mfma_f32_16x16x32_bf16 v[40:43], v[32:35], v[40:43], v[36:39]
	v_mfma_f32_16x16x32_bf16 v[104:107], v[24:27], v[48:51], v[104:107]
	v_mfma_f32_16x16x32_bf16 v[48:51], v[32:35], v[48:51], v[44:47]
	v_mfma_f32_16x16x32_bf16 v[108:111], v[24:27], v[56:59], v[108:111]
	v_mfma_f32_16x16x32_bf16 v[56:59], v[32:35], v[56:59], v[52:55]
	s_setprio 2
	s_barrier
	v_mfma_f32_16x16x32_bf16 v[112:115], v[24:27], v[64:67], v[112:115]
	v_mfma_f32_16x16x32_bf16 v[64:67], v[32:35], v[64:67], v[60:63]
	s_setprio 0
	v_lshl_add_u64 v[186:187], s[12:13], 0, v[2:3]
	s_add_i32 s51, s51, s38
	v_mov_b32_e32 v191, v3
	v_lshl_add_u64 v[134:135], v[186:187], 0, s[74:75]
	s_mov_b32 m0, s51
	v_lshl_add_u64 v[246:247], s[12:13], 0, v[190:191]
	ds_read_b128 v[36:39], v233 offset:16384
	ds_read_b128 v[44:47], v233 offset:17408
	ds_read_b128 v[52:55], v233 offset:18432
	ds_read_b128 v[60:63], v233 offset:19456
	ds_read_b128 v[116:119], v233 offset:20480
	ds_read_b128 v[120:123], v233 offset:21504
	ds_read_b128 v[124:127], v233 offset:22528
	ds_read_b128 v[128:131], v233 offset:23552
	global_load_lds_dwordx4 v[134:135], off
	v_lshl_add_u64 v[134:135], v[246:247], 0, s[74:75]
	s_add_i32 m0, s51, 0x2000
	s_add_i32 s51, s71, s38
	global_load_lds_dwordx4 v[134:135], off
	s_mov_b32 m0, s51
	v_mov_b32_e32 v133, v3
	global_load_lds_dwordx4 v2, s[16:17]
	s_add_i32 m0, s51, 0x2000
	v_lshl_add_u64 v[248:249], s[14:15], 0, v[132:133]
	v_mov_b32_e32 v189, v3
	global_load_lds_dwordx4 v190, s[16:17]
	v_lshl_add_u64 v[134:135], v[248:249], 0, s[74:75]
	s_mov_b32 m0, s56
	v_lshl_add_u64 v[250:251], s[14:15], 0, v[188:189]
	global_load_lds_dwordx4 v[134:135], off
	v_lshl_add_u64 v[134:135], v[250:251], 0, s[74:75]
	s_mov_b32 m0, s57
	s_nop 0
	global_load_lds_dwordx4 v[134:135], off
	s_waitcnt vmcnt(8)
	s_waitcnt lgkmcnt(0)
	s_barrier
	s_setprio 1
	s_waitcnt lgkmcnt(0)
	s_nop 5
	v_mfma_f32_16x16x32_bf16 v[134:137], v[4:7], v[36:39], 0
	v_mfma_f32_16x16x32_bf16 v[138:141], v[12:15], v[36:39], 0
	v_mfma_f32_16x16x32_bf16 v[142:145], v[4:7], v[52:55], 0
	v_mfma_f32_16x16x32_bf16 v[146:149], v[12:15], v[52:55], 0
	v_mfma_f32_16x16x32_bf16 v[150:153], v[4:7], v[116:119], 0
	v_mfma_f32_16x16x32_bf16 v[154:157], v[12:15], v[116:119], 0
	v_mfma_f32_16x16x32_bf16 v[4:7], v[4:7], v[124:127], 0
	v_mfma_f32_16x16x32_bf16 v[12:15], v[12:15], v[124:127], 0
	v_mfma_f32_16x16x32_bf16 v[134:137], v[8:11], v[44:47], v[134:137]
	v_mfma_f32_16x16x32_bf16 v[138:141], v[16:19], v[44:47], v[138:141]
	v_mfma_f32_16x16x32_bf16 v[142:145], v[8:11], v[60:63], v[142:145]
	v_mfma_f32_16x16x32_bf16 v[146:149], v[16:19], v[60:63], v[146:149]
	v_mfma_f32_16x16x32_bf16 v[150:153], v[8:11], v[120:123], v[150:153]
	v_mfma_f32_16x16x32_bf16 v[154:157], v[16:19], v[120:123], v[154:157]
	v_mfma_f32_16x16x32_bf16 v[158:161], v[8:11], v[128:131], v[4:7]
	v_mfma_f32_16x16x32_bf16 v[162:165], v[16:19], v[128:131], v[12:15]
	s_setprio 0
	s_setprio 1
	v_mfma_f32_16x16x32_bf16 v[4:7], v[20:23], v[36:39], 0
	v_mfma_f32_16x16x32_bf16 v[8:11], v[28:31], v[36:39], 0
	v_mfma_f32_16x16x32_bf16 v[12:15], v[20:23], v[52:55], 0
	v_mfma_f32_16x16x32_bf16 v[16:19], v[28:31], v[52:55], 0
	v_mfma_f32_16x16x32_bf16 v[36:39], v[20:23], v[116:119], 0
	v_mfma_f32_16x16x32_bf16 v[52:55], v[28:31], v[116:119], 0
	v_mfma_f32_16x16x32_bf16 v[20:23], v[20:23], v[124:127], 0
	v_mfma_f32_16x16x32_bf16 v[28:31], v[28:31], v[124:127], 0
	v_mfma_f32_16x16x32_bf16 v[116:119], v[24:27], v[44:47], v[4:7]
	v_mfma_f32_16x16x32_bf16 v[124:127], v[32:35], v[44:47], v[8:11]
	v_mfma_f32_16x16x32_bf16 v[174:177], v[24:27], v[120:123], v[36:39]
	v_mfma_f32_16x16x32_bf16 v[120:123], v[32:35], v[120:123], v[52:55]
	v_mfma_f32_16x16x32_bf16 v[178:181], v[24:27], v[128:131], v[20:23]
	v_mfma_f32_16x16x32_bf16 v[128:131], v[32:35], v[128:131], v[28:31]
	s_setprio 2
	s_barrier
	v_mfma_f32_16x16x32_bf16 v[166:169], v[24:27], v[60:63], v[12:15]
	v_mfma_f32_16x16x32_bf16 v[170:173], v[32:35], v[60:63], v[16:19]
	s_setprio 0
	s_add_i32 s51, 0, 0x18000
	v_add_u32_e32 v4, s51, v232
	s_add_i32 s71, 0, 0x1c000
	ds_read_b128 v[182:185], v4
	ds_read_b128 v[192:195], v4 offset:1024
	ds_read_b128 v[196:199], v4 offset:2048
	ds_read_b128 v[200:203], v4 offset:3072
	v_add_u32_e32 v4, s71, v232
	ds_read_b128 v[204:207], v4
	ds_read_b128 v[208:211], v4 offset:1024
	ds_read_b128 v[212:215], v4 offset:2048
	ds_read_b128 v[216:219], v4 offset:3072
	s_mov_b32 m0, s58
	ds_read_b128 v[44:47], v233 offset:32768
	ds_read_b128 v[52:55], v233 offset:33792
	ds_read_b128 v[60:63], v233 offset:34816
	ds_read_b128 v[220:223], v233 offset:35840
	ds_read_b128 v[224:227], v233 offset:36864
	ds_read_b128 v[234:237], v233 offset:37888
	ds_read_b128 v[238:241], v233 offset:38912
	ds_read_b128 v[242:245], v233 offset:39936
	global_load_lds_dwordx4 v132, s[26:27]
	s_mov_b32 m0, s59
	s_nop 0
	global_load_lds_dwordx4 v188, s[26:27]
	s_waitcnt vmcnt(8)
	s_waitcnt lgkmcnt(0)
	s_barrier
	s_setprio 1
	s_waitcnt lgkmcnt(0)
	s_nop 5
	v_mfma_f32_16x16x32_bf16 v[4:7], v[182:185], v[44:47], v[68:71]
	v_mfma_f32_16x16x32_bf16 v[8:11], v[196:199], v[44:47], v[72:75]
	v_mfma_f32_16x16x32_bf16 v[12:15], v[182:185], v[60:63], v[76:79]
	v_mfma_f32_16x16x32_bf16 v[16:19], v[196:199], v[60:63], v[80:83]
	v_mfma_f32_16x16x32_bf16 v[20:23], v[182:185], v[224:227], v[84:87]
	v_mfma_f32_16x16x32_bf16 v[24:27], v[196:199], v[224:227], v[88:91]
	v_mfma_f32_16x16x32_bf16 v[28:31], v[182:185], v[238:241], v[92:95]
	v_mfma_f32_16x16x32_bf16 v[32:35], v[196:199], v[238:241], v[96:99]
	v_mfma_f32_16x16x32_bf16 v[4:7], v[192:195], v[52:55], v[4:7]
	v_mfma_f32_16x16x32_bf16 v[8:11], v[200:203], v[52:55], v[8:11]
	v_mfma_f32_16x16x32_bf16 v[12:15], v[192:195], v[220:223], v[12:15]
	v_mfma_f32_16x16x32_bf16 v[16:19], v[200:203], v[220:223], v[16:19]
	v_mfma_f32_16x16x32_bf16 v[20:23], v[192:195], v[234:237], v[20:23]
	v_mfma_f32_16x16x32_bf16 v[24:27], v[200:203], v[234:237], v[24:27]
	v_mfma_f32_16x16x32_bf16 v[28:31], v[192:195], v[242:245], v[28:31]
	v_mfma_f32_16x16x32_bf16 v[32:35], v[200:203], v[242:245], v[32:35]
	s_setprio 0
	s_setprio 1
	v_mfma_f32_16x16x32_bf16 v[36:39], v[204:207], v[44:47], v[100:103]
	v_mfma_f32_16x16x32_bf16 v[40:43], v[212:215], v[44:47], v[40:43]
	v_mfma_f32_16x16x32_bf16 v[36:39], v[208:211], v[52:55], v[36:39]
	v_mfma_f32_16x16x32_bf16 v[40:43], v[216:219], v[52:55], v[40:43]
	v_mfma_f32_16x16x32_bf16 v[44:47], v[204:207], v[60:63], v[104:107]
	v_mfma_f32_16x16x32_bf16 v[48:51], v[212:215], v[60:63], v[48:51]
	v_mfma_f32_16x16x32_bf16 v[52:55], v[204:207], v[224:227], v[108:111]
	v_mfma_f32_16x16x32_bf16 v[56:59], v[212:215], v[224:227], v[56:59]
	v_mfma_f32_16x16x32_bf16 v[60:63], v[204:207], v[238:241], v[112:115]
	v_mfma_f32_16x16x32_bf16 v[64:67], v[212:215], v[238:241], v[64:67]
	v_mfma_f32_16x16x32_bf16 v[44:47], v[208:211], v[220:223], v[44:47]
	v_mfma_f32_16x16x32_bf16 v[48:51], v[216:219], v[220:223], v[48:51]
	v_mfma_f32_16x16x32_bf16 v[52:55], v[208:211], v[234:237], v[52:55]
	v_mfma_f32_16x16x32_bf16 v[56:59], v[216:219], v[234:237], v[56:59]
	s_setprio 2
	s_barrier
	v_mfma_f32_16x16x32_bf16 v[60:63], v[208:211], v[242:245], v[60:63]
	v_mfma_f32_16x16x32_bf16 v[64:67], v[216:219], v[242:245], v[64:67]
	s_setprio 0
	s_add_i32 s51, s51, s38
	v_lshl_add_u64 v[68:69], v[186:187], 0, s[24:25]
	s_mov_b32 m0, s51
	ds_read_b128 v[104:107], v233 offset:49152
	ds_read_b128 v[108:111], v233 offset:50176
	ds_read_b128 v[112:115], v233 offset:51200
	ds_read_b128 v[220:223], v233 offset:52224
	ds_read_b128 v[224:227], v233 offset:53248
	ds_read_b128 v[234:237], v233 offset:54272
	ds_read_b128 v[238:241], v233 offset:55296
	ds_read_b128 v[242:245], v233 offset:56320
	global_load_lds_dwordx4 v[68:69], off
	v_lshl_add_u64 v[68:69], v[246:247], 0, s[24:25]
	s_add_i32 m0, s51, 0x2000
	s_add_i32 s51, s71, s38
	global_load_lds_dwordx4 v[68:69], off
	s_mov_b32 m0, s51
	v_lshl_add_u64 v[68:69], v[248:249], 0, s[24:25]
	global_load_lds_dwordx4 v2, s[28:29]
	s_add_i32 m0, s51, 0x2000
	s_nop 0
	global_load_lds_dwordx4 v190, s[28:29]
	s_mov_b32 m0, s63
	s_nop 0
	global_load_lds_dwordx4 v[68:69], off
	v_lshl_add_u64 v[68:69], v[250:251], 0, s[24:25]
	s_mov_b32 m0, s64
	s_nop 0
	global_load_lds_dwordx4 v[68:69], off
	s_waitcnt vmcnt(8)
	s_waitcnt lgkmcnt(0)
	s_barrier
	s_setprio 1
	s_waitcnt lgkmcnt(0)
	s_nop 5
	v_mfma_f32_16x16x32_bf16 v[68:71], v[182:185], v[104:107], v[134:137]
	v_mfma_f32_16x16x32_bf16 v[72:75], v[196:199], v[104:107], v[138:141]
	v_mfma_f32_16x16x32_bf16 v[76:79], v[182:185], v[112:115], v[142:145]
	v_mfma_f32_16x16x32_bf16 v[80:83], v[196:199], v[112:115], v[146:149]
	v_mfma_f32_16x16x32_bf16 v[84:87], v[182:185], v[224:227], v[150:153]
	v_mfma_f32_16x16x32_bf16 v[88:91], v[196:199], v[224:227], v[154:157]
	v_mfma_f32_16x16x32_bf16 v[92:95], v[182:185], v[238:241], v[158:161]
	v_mfma_f32_16x16x32_bf16 v[96:99], v[196:199], v[238:241], v[162:165]
	v_mfma_f32_16x16x32_bf16 v[68:71], v[192:195], v[108:111], v[68:71]
	v_mfma_f32_16x16x32_bf16 v[72:75], v[200:203], v[108:111], v[72:75]
	v_mfma_f32_16x16x32_bf16 v[76:79], v[192:195], v[220:223], v[76:79]
	v_mfma_f32_16x16x32_bf16 v[80:83], v[200:203], v[220:223], v[80:83]
	v_mfma_f32_16x16x32_bf16 v[84:87], v[192:195], v[234:237], v[84:87]
	v_mfma_f32_16x16x32_bf16 v[88:91], v[200:203], v[234:237], v[88:91]
	v_mfma_f32_16x16x32_bf16 v[92:95], v[192:195], v[242:245], v[92:95]
	v_mfma_f32_16x16x32_bf16 v[96:99], v[200:203], v[242:245], v[96:99]
	s_setprio 0
	s_setprio 1
	v_mfma_f32_16x16x32_bf16 v[100:103], v[204:207], v[104:107], v[116:119]
	v_mfma_f32_16x16x32_bf16 v[104:107], v[212:215], v[104:107], v[124:127]
	v_mfma_f32_16x16x32_bf16 v[100:103], v[208:211], v[108:111], v[100:103]
	v_mfma_f32_16x16x32_bf16 v[104:107], v[216:219], v[108:111], v[104:107]
	v_mfma_f32_16x16x32_bf16 v[108:111], v[204:207], v[112:115], v[166:169]
	v_mfma_f32_16x16x32_bf16 v[112:115], v[212:215], v[112:115], v[170:173]
	v_mfma_f32_16x16x32_bf16 v[116:119], v[204:207], v[224:227], v[174:177]
	v_mfma_f32_16x16x32_bf16 v[120:123], v[212:215], v[224:227], v[120:123]
	v_mfma_f32_16x16x32_bf16 v[124:127], v[204:207], v[238:241], v[178:181]
	v_mfma_f32_16x16x32_bf16 v[128:131], v[212:215], v[238:241], v[128:131]
	v_mfma_f32_16x16x32_bf16 v[108:111], v[208:211], v[220:223], v[108:111]
	v_mfma_f32_16x16x32_bf16 v[112:115], v[216:219], v[220:223], v[112:115]
	v_mfma_f32_16x16x32_bf16 v[116:119], v[208:211], v[234:237], v[116:119]
	v_mfma_f32_16x16x32_bf16 v[120:123], v[216:219], v[234:237], v[120:123]
	s_setprio 2
	s_barrier
	v_mfma_f32_16x16x32_bf16 v[124:127], v[208:211], v[242:245], v[124:127]
	v_mfma_f32_16x16x32_bf16 v[128:131], v[216:219], v[242:245], v[128:131]
	s_setprio 0
	s_add_i32 s45, s45, 2
	s_cmp_ge_i32 s45, s44
	s_cbranch_scc0 .LBB0_2065
	v_mov_b32_e32 v192, v2
	s_branch .LBB0_2068

.LBB0_2069:
	s_add_u32 s12, s14, 0xfff80080
	s_addc_u32 s13, s15, -1
	s_add_i32 s29, 0, 0x10000
	s_cmp_eq_u32 s28, 4
	s_cselect_b32 s17, s9, s13
	s_cselect_b32 s16, s8, s12
	s_cselect_b32 s13, s11, s27
	s_cselect_b32 s12, s10, s26
	s_add_i32 s51, 0, 0x14000
	v_add_u32_e32 v144, s29, v232
	v_add_u32_e32 v160, s51, v232
	s_waitcnt lgkmcnt(0)
	ds_read_b128 v[132:135], v144
	ds_read_b128 v[136:139], v144 offset:1024
	ds_read_b128 v[140:143], v144 offset:2048
	ds_read_b128 v[144:147], v144 offset:3072
	ds_read_b128 v[148:151], v160
	ds_read_b128 v[152:155], v160 offset:1024
	ds_read_b128 v[156:159], v160 offset:2048
	ds_read_b128 v[160:163], v160 offset:3072
	s_mov_b32 m0, s65
	v_add_u32_e32 v210, 0, v231
	ds_read_b128 v[164:167], v210
	ds_read_b128 v[168:171], v210 offset:1024
	ds_read_b128 v[172:175], v210 offset:2048
	ds_read_b128 v[176:179], v210 offset:3072
	ds_read_b128 v[180:183], v210 offset:4096
	ds_read_b128 v[184:187], v210 offset:5120
	ds_read_b128 v[194:197], v210 offset:6144
	ds_read_b128 v[198:201], v210 offset:7168
	global_load_lds_dwordx4 v2, s[14:15]
	s_mov_b32 m0, s66
	v_mov_b32_e32 v189, v3
	global_load_lds_dwordx4 v188, s[14:15]
	s_waitcnt vmcnt(8)
	s_waitcnt lgkmcnt(0)
	s_barrier
	s_setprio 1
	s_waitcnt lgkmcnt(0)
	s_nop 5
	v_mfma_f32_16x16x32_bf16 v[4:7], v[132:135], v[164:167], v[4:7]
	v_mfma_f32_16x16x32_bf16 v[4:7], v[136:139], v[168:171], v[4:7]
	v_mfma_f32_16x16x32_bf16 v[8:11], v[144:147], v[168:171], v[8:11]
	v_mfma_f32_16x16x32_bf16 v[8:11], v[140:143], v[164:167], v[8:11]
	v_mfma_f32_16x16x32_bf16 v[16:19], v[140:143], v[172:175], v[16:19]
	v_mfma_f32_16x16x32_bf16 v[16:19], v[144:147], v[176:179], v[16:19]
	v_mfma_f32_16x16x32_bf16 v[12:15], v[136:139], v[176:179], v[12:15]
	v_mfma_f32_16x16x32_bf16 v[12:15], v[132:135], v[172:175], v[12:15]
	v_mfma_f32_16x16x32_bf16 v[20:23], v[132:135], v[180:183], v[20:23]
	v_mfma_f32_16x16x32_bf16 v[20:23], v[136:139], v[184:187], v[20:23]
	v_mfma_f32_16x16x32_bf16 v[24:27], v[144:147], v[184:187], v[24:27]
	v_mfma_f32_16x16x32_bf16 v[24:27], v[140:143], v[180:183], v[24:27]
	v_mfma_f32_16x16x32_bf16 v[32:35], v[140:143], v[194:197], v[32:35]
	v_mfma_f32_16x16x32_bf16 v[32:35], v[144:147], v[198:201], v[32:35]
	v_mfma_f32_16x16x32_bf16 v[28:31], v[136:139], v[198:201], v[28:31]
	v_mfma_f32_16x16x32_bf16 v[28:31], v[132:135], v[194:197], v[28:31]
	s_setprio 0
	s_setprio 1
	v_mfma_f32_16x16x32_bf16 v[36:39], v[148:151], v[164:167], v[36:39]
	v_mfma_f32_16x16x32_bf16 v[36:39], v[152:155], v[168:171], v[36:39]
	v_mfma_f32_16x16x32_bf16 v[40:43], v[160:163], v[168:171], v[40:43]
	v_mfma_f32_16x16x32_bf16 v[40:43], v[156:159], v[164:167], v[40:43]
	v_mfma_f32_16x16x32_bf16 v[48:51], v[156:159], v[172:175], v[48:51]
	v_mfma_f32_16x16x32_bf16 v[48:51], v[160:163], v[176:179], v[48:51]
	v_mfma_f32_16x16x32_bf16 v[44:47], v[152:155], v[176:179], v[44:47]
	v_mfma_f32_16x16x32_bf16 v[44:47], v[148:151], v[172:175], v[44:47]
	v_mfma_f32_16x16x32_bf16 v[52:55], v[148:151], v[180:183], v[52:55]
	v_mfma_f32_16x16x32_bf16 v[52:55], v[152:155], v[184:187], v[52:55]
	v_mfma_f32_16x16x32_bf16 v[56:59], v[160:163], v[184:187], v[56:59]
	v_mfma_f32_16x16x32_bf16 v[56:59], v[156:159], v[180:183], v[56:59]
	v_mfma_f32_16x16x32_bf16 v[64:67], v[156:159], v[194:197], v[64:67]
	v_mfma_f32_16x16x32_bf16 v[64:67], v[160:163], v[198:201], v[64:67]
	s_setprio 2
	s_barrier
	v_mfma_f32_16x16x32_bf16 v[60:63], v[152:155], v[198:201], v[60:63]
	v_mfma_f32_16x16x32_bf16 v[60:63], v[148:151], v[194:197], v[60:63]
	s_setprio 0
	s_add_i32 s29, s29, s38
	s_mov_b32 m0, s29
	ds_read_b128 v[164:167], v210 offset:16384
	ds_read_b128 v[168:171], v210 offset:17408
	ds_read_b128 v[172:175], v210 offset:18432
	ds_read_b128 v[176:179], v210 offset:19456
	ds_read_b128 v[180:183], v210 offset:20480
	ds_read_b128 v[184:187], v210 offset:21504
	ds_read_b128 v[194:197], v210 offset:22528
	ds_read_b128 v[198:201], v210 offset:23552
	global_load_lds_dwordx4 v192, s[12:13]
	s_add_i32 m0, s29, 0x2000
	s_add_u32 s44, s12, 0x20000
	s_addc_u32 s45, s13, 0
	s_add_i32 s29, s51, s38
	global_load_lds_dwordx4 v190, s[12:13]
	s_mov_b32 m0, s29
	v_mov_b32_e32 v193, v3
	global_load_lds_dwordx4 v192, s[44:45]
	s_add_i32 m0, s29, 0x2000
	v_mov_b32_e32 v191, v3
	global_load_lds_dwordx4 v190, s[44:45]
	s_mov_b32 m0, s56
	v_lshl_add_u64 v[202:203], s[12:13], 0, v[192:193]
	global_load_lds_dwordx4 v2, s[16:17]
	s_mov_b32 m0, s57
	v_lshl_add_u64 v[204:205], s[12:13], 0, v[190:191]
	global_load_lds_dwordx4 v188, s[16:17]
	s_waitcnt vmcnt(8)
	s_waitcnt lgkmcnt(0)
	v_lshl_add_u64 v[206:207], s[16:17], 0, v[2:3]
	v_lshl_add_u64 v[208:209], s[16:17], 0, v[188:189]
	s_barrier
	s_setprio 1
	s_waitcnt lgkmcnt(0)
	s_nop 5
	v_mfma_f32_16x16x32_bf16 v[68:71], v[132:135], v[164:167], v[68:71]
	v_mfma_f32_16x16x32_bf16 v[68:71], v[136:139], v[168:171], v[68:71]
	v_mfma_f32_16x16x32_bf16 v[72:75], v[144:147], v[168:171], v[72:75]
	v_mfma_f32_16x16x32_bf16 v[72:75], v[140:143], v[164:167], v[72:75]
	v_mfma_f32_16x16x32_bf16 v[80:83], v[140:143], v[172:175], v[80:83]
	v_mfma_f32_16x16x32_bf16 v[80:83], v[144:147], v[176:179], v[80:83]
	v_mfma_f32_16x16x32_bf16 v[76:79], v[136:139], v[176:179], v[76:79]
	v_mfma_f32_16x16x32_bf16 v[76:79], v[132:135], v[172:175], v[76:79]
	v_mfma_f32_16x16x32_bf16 v[84:87], v[132:135], v[180:183], v[84:87]
	v_mfma_f32_16x16x32_bf16 v[84:87], v[136:139], v[184:187], v[84:87]
	v_mfma_f32_16x16x32_bf16 v[88:91], v[144:147], v[184:187], v[88:91]
	v_mfma_f32_16x16x32_bf16 v[88:91], v[140:143], v[180:183], v[88:91]
	v_mfma_f32_16x16x32_bf16 v[96:99], v[140:143], v[194:197], v[96:99]
	v_mfma_f32_16x16x32_bf16 v[96:99], v[144:147], v[198:201], v[96:99]
	v_mfma_f32_16x16x32_bf16 v[92:95], v[136:139], v[198:201], v[92:95]
	v_mfma_f32_16x16x32_bf16 v[92:95], v[132:135], v[194:197], v[92:95]
	s_setprio 0
	s_setprio 1
	v_mfma_f32_16x16x32_bf16 v[100:103], v[148:151], v[164:167], v[100:103]
	v_mfma_f32_16x16x32_bf16 v[100:103], v[152:155], v[168:171], v[100:103]
	v_mfma_f32_16x16x32_bf16 v[104:107], v[160:163], v[168:171], v[104:107]
	v_mfma_f32_16x16x32_bf16 v[104:107], v[156:159], v[164:167], v[104:107]
	v_mfma_f32_16x16x32_bf16 v[112:115], v[156:159], v[172:175], v[112:115]
	v_mfma_f32_16x16x32_bf16 v[112:115], v[160:163], v[176:179], v[112:115]
	v_mfma_f32_16x16x32_bf16 v[108:111], v[152:155], v[176:179], v[108:111]
	v_mfma_f32_16x16x32_bf16 v[108:111], v[148:151], v[172:175], v[108:111]
	v_mfma_f32_16x16x32_bf16 v[116:119], v[148:151], v[180:183], v[116:119]
	v_mfma_f32_16x16x32_bf16 v[116:119], v[152:155], v[184:187], v[116:119]
	v_mfma_f32_16x16x32_bf16 v[120:123], v[160:163], v[184:187], v[120:123]
	v_mfma_f32_16x16x32_bf16 v[120:123], v[156:159], v[180:183], v[120:123]
	v_mfma_f32_16x16x32_bf16 v[128:131], v[156:159], v[194:197], v[128:131]
	v_mfma_f32_16x16x32_bf16 v[128:131], v[160:163], v[198:201], v[128:131]
	s_setprio 2
	s_barrier
	v_mfma_f32_16x16x32_bf16 v[124:127], v[152:155], v[198:201], v[124:127]
	v_mfma_f32_16x16x32_bf16 v[124:127], v[148:151], v[194:197], v[124:127]
	s_setprio 0
	s_add_i32 s29, 0, 0x18000
	s_add_i32 s44, 0, 0x1c000
	v_add_u32_e32 v144, s29, v232
	v_add_u32_e32 v160, s44, v232
	ds_read_b128 v[132:135], v144
	ds_read_b128 v[136:139], v144 offset:1024
	ds_read_b128 v[140:143], v144 offset:2048
	ds_read_b128 v[144:147], v144 offset:3072
	ds_read_b128 v[148:151], v160
	ds_read_b128 v[152:155], v160 offset:1024
	ds_read_b128 v[156:159], v160 offset:2048
	ds_read_b128 v[160:163], v160 offset:3072
	s_add_u32 s16, s16, 0x80000
	s_addc_u32 s17, s17, 0
	s_mov_b32 m0, s58
	ds_read_b128 v[164:167], v210 offset:32768
	ds_read_b128 v[168:171], v210 offset:33792
	ds_read_b128 v[172:175], v210 offset:34816
	ds_read_b128 v[176:179], v210 offset:35840
	ds_read_b128 v[180:183], v210 offset:36864
	ds_read_b128 v[184:187], v210 offset:37888
	ds_read_b128 v[194:197], v210 offset:38912
	ds_read_b128 v[198:201], v210 offset:39936
	global_load_lds_dwordx4 v2, s[16:17]
	s_mov_b32 m0, s59
	s_nop 0
	global_load_lds_dwordx4 v188, s[16:17]
	s_waitcnt vmcnt(8)
	s_waitcnt lgkmcnt(0)
	s_barrier
	s_setprio 1
	s_waitcnt lgkmcnt(0)
	s_nop 5
	v_mfma_f32_16x16x32_bf16 v[4:7], v[132:135], v[164:167], v[4:7]
	v_mfma_f32_16x16x32_bf16 v[4:7], v[136:139], v[168:171], v[4:7]
	v_mfma_f32_16x16x32_bf16 v[8:11], v[144:147], v[168:171], v[8:11]
	v_mfma_f32_16x16x32_bf16 v[8:11], v[140:143], v[164:167], v[8:11]
	v_mfma_f32_16x16x32_bf16 v[16:19], v[140:143], v[172:175], v[16:19]
	v_mfma_f32_16x16x32_bf16 v[16:19], v[144:147], v[176:179], v[16:19]
	v_mfma_f32_16x16x32_bf16 v[12:15], v[136:139], v[176:179], v[12:15]
	v_mfma_f32_16x16x32_bf16 v[12:15], v[132:135], v[172:175], v[12:15]
	v_mfma_f32_16x16x32_bf16 v[20:23], v[132:135], v[180:183], v[20:23]
	v_mfma_f32_16x16x32_bf16 v[20:23], v[136:139], v[184:187], v[20:23]
	v_mfma_f32_16x16x32_bf16 v[24:27], v[144:147], v[184:187], v[24:27]
	v_mfma_f32_16x16x32_bf16 v[24:27], v[140:143], v[180:183], v[24:27]
	v_mfma_f32_16x16x32_bf16 v[32:35], v[140:143], v[194:197], v[32:35]
	v_mfma_f32_16x16x32_bf16 v[32:35], v[144:147], v[198:201], v[32:35]
	v_mfma_f32_16x16x32_bf16 v[28:31], v[136:139], v[198:201], v[28:31]
	v_mfma_f32_16x16x32_bf16 v[28:31], v[132:135], v[194:197], v[28:31]
	s_setprio 0
	s_setprio 1
	v_mfma_f32_16x16x32_bf16 v[36:39], v[148:151], v[164:167], v[36:39]
	v_mfma_f32_16x16x32_bf16 v[36:39], v[152:155], v[168:171], v[36:39]
	v_mfma_f32_16x16x32_bf16 v[40:43], v[160:163], v[168:171], v[40:43]
	v_mfma_f32_16x16x32_bf16 v[40:43], v[156:159], v[164:167], v[40:43]
	v_mfma_f32_16x16x32_bf16 v[48:51], v[156:159], v[172:175], v[48:51]
	v_mfma_f32_16x16x32_bf16 v[48:51], v[160:163], v[176:179], v[48:51]
	v_mfma_f32_16x16x32_bf16 v[44:47], v[152:155], v[176:179], v[44:47]
	v_mfma_f32_16x16x32_bf16 v[44:47], v[148:151], v[172:175], v[44:47]
	v_mfma_f32_16x16x32_bf16 v[52:55], v[148:151], v[180:183], v[52:55]
	v_mfma_f32_16x16x32_bf16 v[52:55], v[152:155], v[184:187], v[52:55]
	v_mfma_f32_16x16x32_bf16 v[56:59], v[160:163], v[184:187], v[56:59]
	v_mfma_f32_16x16x32_bf16 v[56:59], v[156:159], v[180:183], v[56:59]
	v_mfma_f32_16x16x32_bf16 v[64:67], v[156:159], v[194:197], v[64:67]
	v_mfma_f32_16x16x32_bf16 v[64:67], v[160:163], v[198:201], v[64:67]
	s_setprio 2
	s_barrier
	v_mfma_f32_16x16x32_bf16 v[60:63], v[152:155], v[198:201], v[60:63]
	v_mfma_f32_16x16x32_bf16 v[60:63], v[148:151], v[194:197], v[60:63]
	s_setprio 0
	s_add_i32 s16, s29, s38
	v_lshl_add_u64 v[202:203], v[202:203], 0, s[86:87]
	s_mov_b32 m0, s16
	ds_read_b128 v[164:167], v210 offset:49152
	ds_read_b128 v[168:171], v210 offset:50176
	ds_read_b128 v[172:175], v210 offset:51200
	ds_read_b128 v[176:179], v210 offset:52224
	ds_read_b128 v[180:183], v210 offset:53248
	ds_read_b128 v[184:187], v210 offset:54272
	ds_read_b128 v[194:197], v210 offset:55296
	ds_read_b128 v[198:201], v210 offset:56320
	global_load_lds_dwordx4 v[202:203], off
	s_add_i32 m0, s16, 0x2000
	s_add_u32 s12, s12, 0x20080
	v_lshl_add_u64 v[202:203], v[204:205], 0, s[86:87]
	s_addc_u32 s13, s13, 0
	s_add_i32 s16, s44, s38
	global_load_lds_dwordx4 v[202:203], off
	s_mov_b32 m0, s16
	v_lshl_add_u64 v[202:203], v[206:207], 0, s[86:87]
	global_load_lds_dwordx4 v192, s[12:13]
	s_add_i32 m0, s16, 0x2000
	s_nop 0
	global_load_lds_dwordx4 v190, s[12:13]
	s_mov_b32 m0, s63
	s_nop 0
	global_load_lds_dwordx4 v[202:203], off
	v_lshl_add_u64 v[202:203], v[208:209], 0, s[86:87]
	s_mov_b32 m0, s64
	s_nop 0
	global_load_lds_dwordx4 v[202:203], off
	s_waitcnt vmcnt(8)
	s_waitcnt lgkmcnt(0)
	s_barrier
	s_setprio 1
	s_waitcnt lgkmcnt(0)
	s_nop 5
	v_mfma_f32_16x16x32_bf16 v[68:71], v[132:135], v[164:167], v[68:71]
	v_mfma_f32_16x16x32_bf16 v[68:71], v[136:139], v[168:171], v[68:71]
	v_mfma_f32_16x16x32_bf16 v[72:75], v[144:147], v[168:171], v[72:75]
	v_mfma_f32_16x16x32_bf16 v[72:75], v[140:143], v[164:167], v[72:75]
	v_mfma_f32_16x16x32_bf16 v[80:83], v[140:143], v[172:175], v[80:83]
	v_mfma_f32_16x16x32_bf16 v[80:83], v[144:147], v[176:179], v[80:83]
	v_mfma_f32_16x16x32_bf16 v[76:79], v[136:139], v[176:179], v[76:79]
	v_mfma_f32_16x16x32_bf16 v[76:79], v[132:135], v[172:175], v[76:79]
	v_mfma_f32_16x16x32_bf16 v[84:87], v[132:135], v[180:183], v[84:87]
	v_mfma_f32_16x16x32_bf16 v[84:87], v[136:139], v[184:187], v[84:87]
	v_mfma_f32_16x16x32_bf16 v[88:91], v[144:147], v[184:187], v[88:91]
	v_mfma_f32_16x16x32_bf16 v[88:91], v[140:143], v[180:183], v[88:91]
	v_mfma_f32_16x16x32_bf16 v[96:99], v[140:143], v[194:197], v[96:99]
	v_mfma_f32_16x16x32_bf16 v[96:99], v[144:147], v[198:201], v[96:99]
	v_mfma_f32_16x16x32_bf16 v[92:95], v[136:139], v[198:201], v[92:95]
	v_mfma_f32_16x16x32_bf16 v[92:95], v[132:135], v[194:197], v[92:95]
	s_setprio 0
	s_setprio 1
	v_mfma_f32_16x16x32_bf16 v[100:103], v[148:151], v[164:167], v[100:103]
	v_mfma_f32_16x16x32_bf16 v[100:103], v[152:155], v[168:171], v[100:103]
	v_mfma_f32_16x16x32_bf16 v[104:107], v[160:163], v[168:171], v[104:107]
	v_mfma_f32_16x16x32_bf16 v[104:107], v[156:159], v[164:167], v[104:107]
	v_mfma_f32_16x16x32_bf16 v[112:115], v[156:159], v[172:175], v[112:115]
	v_mfma_f32_16x16x32_bf16 v[112:115], v[160:163], v[176:179], v[112:115]
	v_mfma_f32_16x16x32_bf16 v[108:111], v[152:155], v[176:179], v[108:111]
	v_mfma_f32_16x16x32_bf16 v[108:111], v[148:151], v[172:175], v[108:111]
	v_mfma_f32_16x16x32_bf16 v[116:119], v[148:151], v[180:183], v[116:119]
	v_mfma_f32_16x16x32_bf16 v[116:119], v[152:155], v[184:187], v[116:119]
	v_mfma_f32_16x16x32_bf16 v[120:123], v[160:163], v[184:187], v[120:123]
	v_mfma_f32_16x16x32_bf16 v[120:123], v[156:159], v[180:183], v[120:123]
	v_mfma_f32_16x16x32_bf16 v[128:131], v[156:159], v[194:197], v[128:131]
	v_mfma_f32_16x16x32_bf16 v[128:131], v[160:163], v[198:201], v[128:131]
	s_setprio 2
	s_barrier
	v_mfma_f32_16x16x32_bf16 v[124:127], v[152:155], v[198:201], v[124:127]
	v_mfma_f32_16x16x32_bf16 v[124:127], v[148:151], v[194:197], v[124:127]
	s_setprio 0
	s_add_i32 s28, s28, 2
	s_add_u32 s14, s14, 0x100
	s_addc_u32 s15, s15, 0
	s_add_u32 s26, s26, 0x100
	s_addc_u32 s27, s27, 0
	s_cmp_gt_u32 s28, 5
	s_cbranch_scc0 .LBB0_2069
	s_and_b64 vcc, exec, s[48:49]
	s_cbranch_vccz .LBB0_2072
	s_barrier

.LBB0_2159:
	s_add_i32 s68, 0, 0x10000
	s_add_i32 s69, 0, 0x14000
	v_add_u32_e32 v16, s68, v143
	v_add_u32_e32 v32, s69, v143
	ds_read_b128 v[4:7], v16
	ds_read_b128 v[8:11], v16 offset:1024
	ds_read_b128 v[12:15], v16 offset:2048
	ds_read_b128 v[16:19], v16 offset:3072
	ds_read_b128 v[20:23], v32
	ds_read_b128 v[24:27], v32 offset:1024
	ds_read_b128 v[28:31], v32 offset:2048
	ds_read_b128 v[32:35], v32 offset:3072
	v_add_u32_e32 v231, 0, v142
	ds_read_b128 v[36:39], v231
	ds_read_b128 v[40:43], v231 offset:1024
	ds_read_b128 v[44:47], v231 offset:2048
	ds_read_b128 v[48:51], v231 offset:3072
	ds_read_b128 v[52:55], v231 offset:4096
	ds_read_b128 v[56:59], v231 offset:5120
	ds_read_b128 v[60:63], v231 offset:6144
	ds_read_b128 v[64:67], v231 offset:7168
	s_waitcnt vmcnt(8)
	s_waitcnt lgkmcnt(0)
	s_barrier
	s_setprio 1
	s_waitcnt lgkmcnt(0)
	s_nop 5
	v_mfma_f32_16x16x32_f16 v[68:71], v[4:7], v[36:39], 0
	v_mfma_f32_16x16x32_f16 v[72:75], v[12:15], v[36:39], 0
	v_mfma_f32_16x16x32_f16 v[76:79], v[4:7], v[44:47], 0
	v_mfma_f32_16x16x32_f16 v[80:83], v[12:15], v[44:47], 0
	v_mfma_f32_16x16x32_f16 v[84:87], v[4:7], v[52:55], 0
	v_mfma_f32_16x16x32_f16 v[88:91], v[12:15], v[52:55], 0
	v_mfma_f32_16x16x32_f16 v[92:95], v[4:7], v[60:63], 0
	v_mfma_f32_16x16x32_f16 v[96:99], v[12:15], v[60:63], 0
	v_mfma_f32_16x16x32_f16 v[68:71], v[8:11], v[40:43], v[68:71]
	v_mfma_f32_16x16x32_f16 v[72:75], v[16:19], v[40:43], v[72:75]
	v_mfma_f32_16x16x32_f16 v[76:79], v[8:11], v[48:51], v[76:79]
	v_mfma_f32_16x16x32_f16 v[80:83], v[16:19], v[48:51], v[80:83]
	v_mfma_f32_16x16x32_f16 v[84:87], v[8:11], v[56:59], v[84:87]
	v_mfma_f32_16x16x32_f16 v[88:91], v[16:19], v[56:59], v[88:91]
	v_mfma_f32_16x16x32_f16 v[92:95], v[8:11], v[64:67], v[92:95]
	v_mfma_f32_16x16x32_f16 v[100:103], v[16:19], v[64:67], v[96:99]
	s_setprio 0
	s_setprio 1
	v_mfma_f32_16x16x32_f16 v[96:99], v[20:23], v[36:39], 0
	v_mfma_f32_16x16x32_f16 v[36:39], v[28:31], v[36:39], 0
	v_mfma_f32_16x16x32_f16 v[104:107], v[20:23], v[44:47], 0
	v_mfma_f32_16x16x32_f16 v[44:47], v[28:31], v[44:47], 0
	v_mfma_f32_16x16x32_f16 v[108:111], v[20:23], v[52:55], 0
	v_mfma_f32_16x16x32_f16 v[52:55], v[28:31], v[52:55], 0
	v_mfma_f32_16x16x32_f16 v[112:115], v[20:23], v[60:63], 0
	v_mfma_f32_16x16x32_f16 v[60:63], v[28:31], v[60:63], 0
	v_mfma_f32_16x16x32_f16 v[116:119], v[24:27], v[40:43], v[96:99]
	v_mfma_f32_16x16x32_f16 v[36:39], v[32:35], v[40:43], v[36:39]
	v_mfma_f32_16x16x32_f16 v[40:43], v[24:27], v[48:51], v[104:107]
	v_mfma_f32_16x16x32_f16 v[44:47], v[32:35], v[48:51], v[44:47]
	v_mfma_f32_16x16x32_f16 v[48:51], v[24:27], v[56:59], v[108:111]
	v_mfma_f32_16x16x32_f16 v[52:55], v[32:35], v[56:59], v[52:55]
	s_setprio 2
	s_barrier
	v_mfma_f32_16x16x32_f16 v[56:59], v[24:27], v[64:67], v[112:115]
	v_mfma_f32_16x16x32_f16 v[60:63], v[32:35], v[64:67], v[60:63]
	s_setprio 0
	v_lshl_add_u64 v[138:139], s[8:9], 0, v[2:3]
	s_add_i32 s68, s68, s53
	v_mov_b32_e32 v135, v3
	v_lshl_add_u64 v[144:145], v[138:139], 0, s[74:75]
	s_mov_b32 m0, s68
	v_lshl_add_u64 v[192:193], s[8:9], 0, v[134:135]
	ds_read_b128 v[64:67], v231 offset:16384
	ds_read_b128 v[96:99], v231 offset:17408
	ds_read_b128 v[104:107], v231 offset:18432
	ds_read_b128 v[108:111], v231 offset:19456
	ds_read_b128 v[112:115], v231 offset:20480
	ds_read_b128 v[120:123], v231 offset:21504
	ds_read_b128 v[124:127], v231 offset:22528
	ds_read_b128 v[128:131], v231 offset:23552
	global_load_lds_dwordx4 v[144:145], off
	v_lshl_add_u64 v[144:145], v[192:193], 0, s[74:75]
	s_add_i32 m0, s68, 0x2000
	s_add_i32 s68, s69, s53
	global_load_lds_dwordx4 v[144:145], off
	s_mov_b32 m0, s68
	v_mov_b32_e32 v137, v3
	global_load_lds_dwordx4 v2, s[40:41]
	s_add_i32 m0, s68, 0x2000
	v_lshl_add_u64 v[248:249], s[6:7], 0, v[136:137]
	v_mov_b32_e32 v133, v3
	global_load_lds_dwordx4 v134, s[40:41]
	v_lshl_add_u64 v[144:145], v[248:249], 0, s[74:75]
	s_mov_b32 m0, s54
	v_lshl_add_u64 v[250:251], s[6:7], 0, v[132:133]
	global_load_lds_dwordx4 v[144:145], off
	v_lshl_add_u64 v[144:145], v[250:251], 0, s[74:75]
	s_mov_b32 m0, s55
	s_nop 0
	global_load_lds_dwordx4 v[144:145], off
	s_waitcnt vmcnt(8)
	s_waitcnt lgkmcnt(0)
	s_barrier
	s_setprio 1
	s_waitcnt lgkmcnt(0)
	s_nop 5
	v_mfma_f32_16x16x32_f16 v[144:147], v[4:7], v[64:67], 0
	v_mfma_f32_16x16x32_f16 v[148:151], v[12:15], v[64:67], 0
	v_mfma_f32_16x16x32_f16 v[152:155], v[4:7], v[104:107], 0
	v_mfma_f32_16x16x32_f16 v[156:159], v[12:15], v[104:107], 0
	v_mfma_f32_16x16x32_f16 v[160:163], v[4:7], v[112:115], 0
	v_mfma_f32_16x16x32_f16 v[164:167], v[12:15], v[112:115], 0
	v_mfma_f32_16x16x32_f16 v[4:7], v[4:7], v[124:127], 0
	v_mfma_f32_16x16x32_f16 v[12:15], v[12:15], v[124:127], 0
	v_mfma_f32_16x16x32_f16 v[144:147], v[8:11], v[96:99], v[144:147]
	v_mfma_f32_16x16x32_f16 v[152:155], v[8:11], v[108:111], v[152:155]
	v_mfma_f32_16x16x32_f16 v[160:163], v[8:11], v[120:123], v[160:163]
	v_mfma_f32_16x16x32_f16 v[4:7], v[8:11], v[128:131], v[4:7]
	v_mfma_f32_16x16x32_f16 v[8:11], v[16:19], v[128:131], v[12:15]
	v_mfma_f32_16x16x32_f16 v[148:151], v[16:19], v[96:99], v[148:151]
	v_mfma_f32_16x16x32_f16 v[156:159], v[16:19], v[108:111], v[156:159]
	v_mfma_f32_16x16x32_f16 v[164:167], v[16:19], v[120:123], v[164:167]
	s_setprio 0
	s_setprio 1
	v_mfma_f32_16x16x32_f16 v[12:15], v[20:23], v[64:67], 0
	v_mfma_f32_16x16x32_f16 v[16:19], v[28:31], v[64:67], 0
	v_mfma_f32_16x16x32_f16 v[64:67], v[20:23], v[104:107], 0
	v_mfma_f32_16x16x32_f16 v[104:107], v[28:31], v[104:107], 0
	v_mfma_f32_16x16x32_f16 v[168:171], v[20:23], v[112:115], 0
	v_mfma_f32_16x16x32_f16 v[112:115], v[28:31], v[112:115], 0
	v_mfma_f32_16x16x32_f16 v[20:23], v[20:23], v[124:127], 0
	v_mfma_f32_16x16x32_f16 v[28:31], v[28:31], v[124:127], 0
	v_mfma_f32_16x16x32_f16 v[12:15], v[24:27], v[96:99], v[12:15]
	v_mfma_f32_16x16x32_f16 v[172:175], v[32:35], v[96:99], v[16:19]
	v_mfma_f32_16x16x32_f16 v[176:179], v[24:27], v[108:111], v[64:67]
	v_mfma_f32_16x16x32_f16 v[180:183], v[32:35], v[108:111], v[104:107]
	v_mfma_f32_16x16x32_f16 v[168:171], v[24:27], v[120:123], v[168:171]
	v_mfma_f32_16x16x32_f16 v[184:187], v[32:35], v[120:123], v[112:115]
	s_setprio 2
	s_barrier
	v_mfma_f32_16x16x32_f16 v[188:191], v[24:27], v[128:131], v[20:23]
	v_mfma_f32_16x16x32_f16 v[196:199], v[32:35], v[128:131], v[28:31]
	s_setprio 0
	s_add_i32 s68, 0, 0x18000
	v_add_u32_e32 v24, s68, v143
	s_add_i32 s69, 0, 0x1c000
	ds_read_b128 v[16:19], v24
	ds_read_b128 v[20:23], v24 offset:1024
	ds_read_b128 v[28:31], v24 offset:2048
	ds_read_b128 v[200:203], v24 offset:3072
	v_add_u32_e32 v24, s69, v143
	ds_read_b128 v[204:207], v24
	ds_read_b128 v[208:211], v24 offset:1024
	ds_read_b128 v[212:215], v24 offset:2048
	ds_read_b128 v[216:219], v24 offset:3072
	s_mov_b32 m0, s56
	ds_read_b128 v[24:27], v231 offset:32768
	ds_read_b128 v[32:35], v231 offset:33792
	ds_read_b128 v[64:67], v231 offset:34816
	ds_read_b128 v[220:223], v231 offset:35840
	ds_read_b128 v[224:227], v231 offset:36864
	ds_read_b128 v[232:235], v231 offset:37888
	ds_read_b128 v[236:239], v231 offset:38912
	ds_read_b128 v[240:243], v231 offset:39936
	global_load_lds_dwordx4 v136, s[42:43]
	s_mov_b32 m0, s57
	s_nop 0
	global_load_lds_dwordx4 v132, s[42:43]
	s_waitcnt vmcnt(8)
	s_waitcnt lgkmcnt(0)
	s_barrier
	s_setprio 1
	s_waitcnt lgkmcnt(0)
	s_nop 5
	v_mfma_f32_16x16x32_f16 v[68:71], v[16:19], v[24:27], v[68:71]
	v_mfma_f32_16x16x32_f16 v[128:131], v[20:23], v[32:35], v[68:71]
	v_mfma_f32_16x16x32_f16 v[68:71], v[28:31], v[24:27], v[72:75]
	v_mfma_f32_16x16x32_f16 v[120:123], v[200:203], v[32:35], v[68:71]
	v_mfma_f32_16x16x32_f16 v[68:71], v[16:19], v[64:67], v[76:79]
	v_mfma_f32_16x16x32_f16 v[112:115], v[20:23], v[220:223], v[68:71]
	v_mfma_f32_16x16x32_f16 v[68:71], v[28:31], v[64:67], v[80:83]
	v_mfma_f32_16x16x32_f16 v[104:107], v[200:203], v[220:223], v[68:71]
	v_mfma_f32_16x16x32_f16 v[68:71], v[16:19], v[224:227], v[84:87]
	v_mfma_f32_16x16x32_f16 v[96:99], v[20:23], v[232:235], v[68:71]
	v_mfma_f32_16x16x32_f16 v[68:71], v[28:31], v[224:227], v[88:91]
	v_mfma_f32_16x16x32_f16 v[88:91], v[200:203], v[232:235], v[68:71]
	v_mfma_f32_16x16x32_f16 v[68:71], v[16:19], v[236:239], v[92:95]
	v_mfma_f32_16x16x32_f16 v[80:83], v[20:23], v[240:243], v[68:71]
	v_mfma_f32_16x16x32_f16 v[68:71], v[28:31], v[236:239], v[100:103]
	v_mfma_f32_16x16x32_f16 v[72:75], v[200:203], v[240:243], v[68:71]
	s_setprio 0
	s_setprio 1
	v_mfma_f32_16x16x32_f16 v[68:71], v[204:207], v[24:27], v[116:119]
	v_mfma_f32_16x16x32_f16 v[24:27], v[212:215], v[24:27], v[36:39]
	v_mfma_f32_16x16x32_f16 v[116:119], v[216:219], v[32:35], v[24:27]
	v_mfma_f32_16x16x32_f16 v[24:27], v[204:207], v[64:67], v[40:43]
	v_mfma_f32_16x16x32_f16 v[108:111], v[208:211], v[220:223], v[24:27]
	v_mfma_f32_16x16x32_f16 v[24:27], v[212:215], v[64:67], v[44:47]
	v_mfma_f32_16x16x32_f16 v[100:103], v[216:219], v[220:223], v[24:27]
	v_mfma_f32_16x16x32_f16 v[24:27], v[204:207], v[224:227], v[48:51]
	v_mfma_f32_16x16x32_f16 v[92:95], v[208:211], v[232:235], v[24:27]
	v_mfma_f32_16x16x32_f16 v[24:27], v[212:215], v[224:227], v[52:55]
	v_mfma_f32_16x16x32_f16 v[84:87], v[216:219], v[232:235], v[24:27]
	v_mfma_f32_16x16x32_f16 v[24:27], v[204:207], v[236:239], v[56:59]
	v_mfma_f32_16x16x32_f16 v[76:79], v[208:211], v[240:243], v[24:27]
	v_mfma_f32_16x16x32_f16 v[24:27], v[212:215], v[236:239], v[60:63]
	s_setprio 2
	s_barrier
	v_mfma_f32_16x16x32_f16 v[124:127], v[208:211], v[32:35], v[68:71]
	v_mfma_f32_16x16x32_f16 v[68:71], v[216:219], v[240:243], v[24:27]
	s_setprio 0
	s_add_i32 s68, s68, s53
	s_nop 2
	v_lshl_add_u64 v[24:25], v[138:139], 0, s[24:25]
	s_mov_b32 m0, s68
	ds_read_b128 v[36:39], v231 offset:49152
	ds_read_b128 v[44:47], v231 offset:50176
	ds_read_b128 v[220:223], v231 offset:51200
	ds_read_b128 v[224:227], v231 offset:52224
	ds_read_b128 v[232:235], v231 offset:53248
	ds_read_b128 v[236:239], v231 offset:54272
	ds_read_b128 v[240:243], v231 offset:55296
	ds_read_b128 v[244:247], v231 offset:56320
	global_load_lds_dwordx4 v[24:25], off
	v_lshl_add_u64 v[24:25], v[192:193], 0, s[24:25]
	s_add_i32 m0, s68, 0x2000
	s_add_i32 s68, s69, s53
	global_load_lds_dwordx4 v[24:25], off
	s_mov_b32 m0, s68
	v_lshl_add_u64 v[24:25], v[248:249], 0, s[24:25]
	global_load_lds_dwordx4 v2, s[44:45]
	s_add_i32 m0, s68, 0x2000
	s_nop 0
	global_load_lds_dwordx4 v134, s[44:45]
	s_mov_b32 m0, s59
	s_nop 0
	global_load_lds_dwordx4 v[24:25], off
	v_lshl_add_u64 v[24:25], v[250:251], 0, s[24:25]
	s_mov_b32 m0, s60
	s_nop 0
	global_load_lds_dwordx4 v[24:25], off
	s_waitcnt vmcnt(8)
	s_waitcnt lgkmcnt(0)
	s_barrier
	s_setprio 1
	s_waitcnt lgkmcnt(0)
	s_nop 5
	v_mfma_f32_16x16x32_f16 v[24:27], v[16:19], v[36:39], v[144:147]
	v_mfma_f32_16x16x32_f16 v[64:67], v[20:23], v[44:47], v[24:27]
	v_mfma_f32_16x16x32_f16 v[24:27], v[28:31], v[36:39], v[148:151]
	v_mfma_f32_16x16x32_f16 v[56:59], v[200:203], v[44:47], v[24:27]
	v_mfma_f32_16x16x32_f16 v[24:27], v[16:19], v[220:223], v[152:155]
	v_mfma_f32_16x16x32_f16 v[48:51], v[20:23], v[224:227], v[24:27]
	v_mfma_f32_16x16x32_f16 v[24:27], v[28:31], v[220:223], v[156:159]
	v_mfma_f32_16x16x32_f16 v[40:43], v[200:203], v[224:227], v[24:27]
	v_mfma_f32_16x16x32_f16 v[24:27], v[16:19], v[232:235], v[160:163]
	v_mfma_f32_16x16x32_f16 v[4:7], v[16:19], v[240:243], v[4:7]
	v_mfma_f32_16x16x32_f16 v[32:35], v[20:23], v[236:239], v[24:27]
	v_mfma_f32_16x16x32_f16 v[24:27], v[28:31], v[232:235], v[164:167]
	v_mfma_f32_16x16x32_f16 v[16:19], v[20:23], v[244:247], v[4:7]
	v_mfma_f32_16x16x32_f16 v[4:7], v[28:31], v[240:243], v[8:11]
	v_mfma_f32_16x16x32_f16 v[24:27], v[200:203], v[236:239], v[24:27]
	v_mfma_f32_16x16x32_f16 v[8:11], v[200:203], v[244:247], v[4:7]
	s_setprio 0
	s_setprio 1
	v_mfma_f32_16x16x32_f16 v[4:7], v[204:207], v[36:39], v[12:15]
	v_mfma_f32_16x16x32_f16 v[60:63], v[208:211], v[44:47], v[4:7]
	v_mfma_f32_16x16x32_f16 v[4:7], v[212:215], v[36:39], v[172:175]
	v_mfma_f32_16x16x32_f16 v[52:55], v[216:219], v[44:47], v[4:7]
	v_mfma_f32_16x16x32_f16 v[4:7], v[204:207], v[220:223], v[176:179]
	v_mfma_f32_16x16x32_f16 v[44:47], v[208:211], v[224:227], v[4:7]
	v_mfma_f32_16x16x32_f16 v[4:7], v[212:215], v[220:223], v[180:183]
	v_mfma_f32_16x16x32_f16 v[36:39], v[216:219], v[224:227], v[4:7]
	v_mfma_f32_16x16x32_f16 v[4:7], v[204:207], v[232:235], v[168:171]
	v_mfma_f32_16x16x32_f16 v[28:31], v[208:211], v[236:239], v[4:7]
	v_mfma_f32_16x16x32_f16 v[4:7], v[212:215], v[232:235], v[184:187]
	v_mfma_f32_16x16x32_f16 v[20:23], v[216:219], v[236:239], v[4:7]
	v_mfma_f32_16x16x32_f16 v[4:7], v[204:207], v[240:243], v[188:191]
	v_mfma_f32_16x16x32_f16 v[12:15], v[208:211], v[244:247], v[4:7]
	s_setprio 2
	s_barrier
	v_mfma_f32_16x16x32_f16 v[4:7], v[212:215], v[240:243], v[196:199]
	v_mfma_f32_16x16x32_f16 v[4:7], v[216:219], v[244:247], v[4:7]
	s_setprio 0
	s_add_i32 s67, s67, 2
	s_cmp_ge_i32 s67, s11
	s_cbranch_scc0 .LBB0_2159

.LBB0_2161:
	s_add_u32 s68, s6, s40
	s_addc_u32 s69, s7, s41
	s_add_u32 s42, s68, 0x200
	s_addc_u32 s43, s69, 0
	s_add_u32 s44, s8, s40
	s_addc_u32 s45, s9, s41
	s_add_u32 s67, s44, 0x200
	s_addc_u32 s70, s45, 0
	s_add_i32 s71, 0, 0x10000
	s_cmp_eq_u32 s11, 28
	s_cselect_b32 s45, s29, s43
	s_cselect_b32 s44, s28, s42
	v_add_u32_e32 v133, s71, v143
	s_cselect_b32 s43, s37, s70
	s_cselect_b32 s42, s36, s67
	s_add_i32 s67, 0, 0x14000
	ds_read_b128 v[144:147], v133
	ds_read_b128 v[148:151], v133 offset:1024
	ds_read_b128 v[152:155], v133 offset:2048
	ds_read_b128 v[156:159], v133 offset:3072
	v_add_u32_e32 v133, s67, v143
	ds_read_b128 v[160:163], v133
	ds_read_b128 v[164:167], v133 offset:1024
	ds_read_b128 v[168:171], v133 offset:2048
	ds_read_b128 v[172:175], v133 offset:3072
	v_lshl_add_u64 v[136:137], s[68:69], 0, v[2:3]
	s_mov_b32 m0, s61
	v_add_u32_e32 v216, 0, v142
	v_lshl_add_u64 v[136:137], v[136:137], 0, s[34:35]
	v_mov_b32_e32 v133, v3
	ds_read_b128 v[176:179], v216
	ds_read_b128 v[180:183], v216 offset:1024
	ds_read_b128 v[184:187], v216 offset:2048
	ds_read_b128 v[188:191], v216 offset:3072
	ds_read_b128 v[196:199], v216 offset:4096
	ds_read_b128 v[200:203], v216 offset:5120
	ds_read_b128 v[204:207], v216 offset:6144
	ds_read_b128 v[208:211], v216 offset:7168
	global_load_lds_dwordx4 v[136:137], off
	v_lshl_add_u64 v[136:137], s[68:69], 0, v[132:133]
	v_lshl_add_u64 v[136:137], v[136:137], 0, s[34:35]
	s_mov_b32 m0, s62
	s_nop 0
	global_load_lds_dwordx4 v[136:137], off
	s_waitcnt vmcnt(8)
	s_waitcnt lgkmcnt(0)
	s_barrier
	s_setprio 1
	s_waitcnt lgkmcnt(0)
	s_nop 5
	v_mfma_f32_16x16x32_f16 v[128:131], v[144:147], v[176:179], v[128:131]
	v_mfma_f32_16x16x32_f16 v[128:131], v[148:151], v[180:183], v[128:131]
	v_mfma_f32_16x16x32_f16 v[120:123], v[156:159], v[180:183], v[120:123]
	v_mfma_f32_16x16x32_f16 v[120:123], v[152:155], v[176:179], v[120:123]
	v_mfma_f32_16x16x32_f16 v[104:107], v[152:155], v[184:187], v[104:107]
	v_mfma_f32_16x16x32_f16 v[104:107], v[156:159], v[188:191], v[104:107]
	v_mfma_f32_16x16x32_f16 v[112:115], v[148:151], v[188:191], v[112:115]
	v_mfma_f32_16x16x32_f16 v[112:115], v[144:147], v[184:187], v[112:115]
	v_mfma_f32_16x16x32_f16 v[96:99], v[144:147], v[196:199], v[96:99]
	v_mfma_f32_16x16x32_f16 v[96:99], v[148:151], v[200:203], v[96:99]
	v_mfma_f32_16x16x32_f16 v[88:91], v[156:159], v[200:203], v[88:91]
	v_mfma_f32_16x16x32_f16 v[88:91], v[152:155], v[196:199], v[88:91]
	v_mfma_f32_16x16x32_f16 v[72:75], v[152:155], v[204:207], v[72:75]
	v_mfma_f32_16x16x32_f16 v[72:75], v[156:159], v[208:211], v[72:75]
	v_mfma_f32_16x16x32_f16 v[80:83], v[148:151], v[208:211], v[80:83]
	v_mfma_f32_16x16x32_f16 v[80:83], v[144:147], v[204:207], v[80:83]
	s_setprio 0
	s_setprio 1
	v_mfma_f32_16x16x32_f16 v[124:127], v[160:163], v[176:179], v[124:127]
	v_mfma_f32_16x16x32_f16 v[124:127], v[164:167], v[180:183], v[124:127]
	v_mfma_f32_16x16x32_f16 v[116:119], v[172:175], v[180:183], v[116:119]
	v_mfma_f32_16x16x32_f16 v[116:119], v[168:171], v[176:179], v[116:119]
	v_mfma_f32_16x16x32_f16 v[100:103], v[168:171], v[184:187], v[100:103]
	v_mfma_f32_16x16x32_f16 v[100:103], v[172:175], v[188:191], v[100:103]
	v_mfma_f32_16x16x32_f16 v[108:111], v[164:167], v[188:191], v[108:111]
	v_mfma_f32_16x16x32_f16 v[108:111], v[160:163], v[184:187], v[108:111]
	v_mfma_f32_16x16x32_f16 v[92:95], v[160:163], v[196:199], v[92:95]
	v_mfma_f32_16x16x32_f16 v[92:95], v[164:167], v[200:203], v[92:95]
	v_mfma_f32_16x16x32_f16 v[84:87], v[172:175], v[200:203], v[84:87]
	v_mfma_f32_16x16x32_f16 v[84:87], v[168:171], v[196:199], v[84:87]
	v_mfma_f32_16x16x32_f16 v[68:71], v[168:171], v[204:207], v[68:71]
	v_mfma_f32_16x16x32_f16 v[68:71], v[172:175], v[208:211], v[68:71]
	s_setprio 2
	s_barrier
	v_mfma_f32_16x16x32_f16 v[76:79], v[164:167], v[208:211], v[76:79]
	v_mfma_f32_16x16x32_f16 v[76:79], v[160:163], v[204:207], v[76:79]
	s_setprio 0
	s_add_i32 s68, s71, s53
	s_mov_b32 m0, s68
	ds_read_b128 v[176:179], v216 offset:16384
	ds_read_b128 v[180:183], v216 offset:17408
	ds_read_b128 v[184:187], v216 offset:18432
	ds_read_b128 v[188:191], v216 offset:19456
	ds_read_b128 v[196:199], v216 offset:20480
	ds_read_b128 v[200:203], v216 offset:21504
	ds_read_b128 v[204:207], v216 offset:22528
	ds_read_b128 v[208:211], v216 offset:23552
	global_load_lds_dwordx4 v138, s[42:43]
	s_add_i32 m0, s68, 0x2000
	s_add_u32 s68, s42, 0x80000
	s_addc_u32 s69, s43, 0
	s_add_i32 s67, s67, s53
	global_load_lds_dwordx4 v134, s[42:43]
	s_mov_b32 m0, s67
	v_mov_b32_e32 v139, v3
	global_load_lds_dwordx4 v138, s[68:69]
	s_add_i32 m0, s67, 0x2000
	v_mov_b32_e32 v135, v3
	global_load_lds_dwordx4 v134, s[68:69]
	s_mov_b32 m0, s54
	v_lshl_add_u64 v[136:137], s[42:43], 0, v[138:139]
	global_load_lds_dwordx4 v2, s[44:45]
	s_mov_b32 m0, s55
	v_lshl_add_u64 v[192:193], s[42:43], 0, v[134:135]
	global_load_lds_dwordx4 v132, s[44:45]
	s_waitcnt vmcnt(8)
	s_waitcnt lgkmcnt(0)
	v_lshl_add_u64 v[212:213], s[44:45], 0, v[2:3]
	v_lshl_add_u64 v[214:215], s[44:45], 0, v[132:133]
	s_barrier
	s_setprio 1
	s_waitcnt lgkmcnt(0)
	s_nop 5
	v_mfma_f32_16x16x32_f16 v[64:67], v[144:147], v[176:179], v[64:67]
	v_mfma_f32_16x16x32_f16 v[64:67], v[148:151], v[180:183], v[64:67]
	v_mfma_f32_16x16x32_f16 v[56:59], v[156:159], v[180:183], v[56:59]
	v_mfma_f32_16x16x32_f16 v[56:59], v[152:155], v[176:179], v[56:59]
	v_mfma_f32_16x16x32_f16 v[40:43], v[152:155], v[184:187], v[40:43]
	v_mfma_f32_16x16x32_f16 v[40:43], v[156:159], v[188:191], v[40:43]
	v_mfma_f32_16x16x32_f16 v[48:51], v[148:151], v[188:191], v[48:51]
	v_mfma_f32_16x16x32_f16 v[48:51], v[144:147], v[184:187], v[48:51]
	v_mfma_f32_16x16x32_f16 v[32:35], v[144:147], v[196:199], v[32:35]
	v_mfma_f32_16x16x32_f16 v[32:35], v[148:151], v[200:203], v[32:35]
	v_mfma_f32_16x16x32_f16 v[24:27], v[156:159], v[200:203], v[24:27]
	v_mfma_f32_16x16x32_f16 v[24:27], v[152:155], v[196:199], v[24:27]
	v_mfma_f32_16x16x32_f16 v[8:11], v[152:155], v[204:207], v[8:11]
	v_mfma_f32_16x16x32_f16 v[8:11], v[156:159], v[208:211], v[8:11]
	v_mfma_f32_16x16x32_f16 v[16:19], v[148:151], v[208:211], v[16:19]
	v_mfma_f32_16x16x32_f16 v[16:19], v[144:147], v[204:207], v[16:19]
	s_setprio 0
	s_setprio 1
	v_mfma_f32_16x16x32_f16 v[60:63], v[160:163], v[176:179], v[60:63]
	v_mfma_f32_16x16x32_f16 v[60:63], v[164:167], v[180:183], v[60:63]
	v_mfma_f32_16x16x32_f16 v[52:55], v[172:175], v[180:183], v[52:55]
	v_mfma_f32_16x16x32_f16 v[52:55], v[168:171], v[176:179], v[52:55]
	v_mfma_f32_16x16x32_f16 v[36:39], v[168:171], v[184:187], v[36:39]
	v_mfma_f32_16x16x32_f16 v[36:39], v[172:175], v[188:191], v[36:39]
	v_mfma_f32_16x16x32_f16 v[44:47], v[164:167], v[188:191], v[44:47]
	v_mfma_f32_16x16x32_f16 v[44:47], v[160:163], v[184:187], v[44:47]
	v_mfma_f32_16x16x32_f16 v[28:31], v[160:163], v[196:199], v[28:31]
	v_mfma_f32_16x16x32_f16 v[28:31], v[164:167], v[200:203], v[28:31]
	v_mfma_f32_16x16x32_f16 v[20:23], v[172:175], v[200:203], v[20:23]
	v_mfma_f32_16x16x32_f16 v[20:23], v[168:171], v[196:199], v[20:23]
	v_mfma_f32_16x16x32_f16 v[4:7], v[168:171], v[204:207], v[4:7]
	v_mfma_f32_16x16x32_f16 v[4:7], v[172:175], v[208:211], v[4:7]
	s_setprio 2
	s_barrier
	v_mfma_f32_16x16x32_f16 v[12:15], v[164:167], v[208:211], v[12:15]
	v_mfma_f32_16x16x32_f16 v[12:15], v[160:163], v[204:207], v[12:15]
	s_setprio 0
	s_add_i32 s67, 0, 0x18000
	v_add_u32_e32 v135, s67, v143
	s_add_i32 s68, 0, 0x1c000
	ds_read_b128 v[144:147], v135
	ds_read_b128 v[148:151], v135 offset:1024
	ds_read_b128 v[152:155], v135 offset:2048
	ds_read_b128 v[156:159], v135 offset:3072
	v_add_u32_e32 v135, s68, v143
	ds_read_b128 v[160:163], v135
	ds_read_b128 v[164:167], v135 offset:1024
	ds_read_b128 v[168:171], v135 offset:2048
	ds_read_b128 v[172:175], v135 offset:3072
	s_add_u32 s44, s44, 0x80000
	s_addc_u32 s45, s45, 0
	s_mov_b32 m0, s56
	ds_read_b128 v[176:179], v216 offset:32768
	ds_read_b128 v[180:183], v216 offset:33792
	ds_read_b128 v[184:187], v216 offset:34816
	ds_read_b128 v[188:191], v216 offset:35840
	ds_read_b128 v[196:199], v216 offset:36864
	ds_read_b128 v[200:203], v216 offset:37888
	ds_read_b128 v[204:207], v216 offset:38912
	ds_read_b128 v[208:211], v216 offset:39936
	global_load_lds_dwordx4 v2, s[44:45]
	s_mov_b32 m0, s57
	s_nop 0
	global_load_lds_dwordx4 v132, s[44:45]
	s_waitcnt vmcnt(8)
	s_waitcnt lgkmcnt(0)
	s_barrier
	s_setprio 1
	s_waitcnt lgkmcnt(0)
	s_nop 5
	v_mfma_f32_16x16x32_f16 v[128:131], v[144:147], v[176:179], v[128:131]
	v_mfma_f32_16x16x32_f16 v[128:131], v[148:151], v[180:183], v[128:131]
	v_mfma_f32_16x16x32_f16 v[120:123], v[156:159], v[180:183], v[120:123]
	v_mfma_f32_16x16x32_f16 v[120:123], v[152:155], v[176:179], v[120:123]
	v_mfma_f32_16x16x32_f16 v[104:107], v[152:155], v[184:187], v[104:107]
	v_mfma_f32_16x16x32_f16 v[104:107], v[156:159], v[188:191], v[104:107]
	v_mfma_f32_16x16x32_f16 v[112:115], v[148:151], v[188:191], v[112:115]
	v_mfma_f32_16x16x32_f16 v[112:115], v[144:147], v[184:187], v[112:115]
	v_mfma_f32_16x16x32_f16 v[96:99], v[144:147], v[196:199], v[96:99]
	v_mfma_f32_16x16x32_f16 v[96:99], v[148:151], v[200:203], v[96:99]
	v_mfma_f32_16x16x32_f16 v[88:91], v[156:159], v[200:203], v[88:91]
	v_mfma_f32_16x16x32_f16 v[88:91], v[152:155], v[196:199], v[88:91]
	v_mfma_f32_16x16x32_f16 v[72:75], v[152:155], v[204:207], v[72:75]
	v_mfma_f32_16x16x32_f16 v[72:75], v[156:159], v[208:211], v[72:75]
	v_mfma_f32_16x16x32_f16 v[80:83], v[148:151], v[208:211], v[80:83]
	v_mfma_f32_16x16x32_f16 v[80:83], v[144:147], v[204:207], v[80:83]
	s_setprio 0
	s_setprio 1
	v_mfma_f32_16x16x32_f16 v[124:127], v[160:163], v[176:179], v[124:127]
	v_mfma_f32_16x16x32_f16 v[124:127], v[164:167], v[180:183], v[124:127]
	v_mfma_f32_16x16x32_f16 v[116:119], v[172:175], v[180:183], v[116:119]
	v_mfma_f32_16x16x32_f16 v[116:119], v[168:171], v[176:179], v[116:119]
	v_mfma_f32_16x16x32_f16 v[100:103], v[168:171], v[184:187], v[100:103]
	v_mfma_f32_16x16x32_f16 v[100:103], v[172:175], v[188:191], v[100:103]
	v_mfma_f32_16x16x32_f16 v[108:111], v[164:167], v[188:191], v[108:111]
	v_mfma_f32_16x16x32_f16 v[108:111], v[160:163], v[184:187], v[108:111]
	v_mfma_f32_16x16x32_f16 v[92:95], v[160:163], v[196:199], v[92:95]
	v_mfma_f32_16x16x32_f16 v[92:95], v[164:167], v[200:203], v[92:95]
	v_mfma_f32_16x16x32_f16 v[84:87], v[172:175], v[200:203], v[84:87]
	v_mfma_f32_16x16x32_f16 v[84:87], v[168:171], v[196:199], v[84:87]
	v_mfma_f32_16x16x32_f16 v[68:71], v[168:171], v[204:207], v[68:71]
	v_mfma_f32_16x16x32_f16 v[68:71], v[172:175], v[208:211], v[68:71]
	s_setprio 2
	s_barrier
	v_mfma_f32_16x16x32_f16 v[76:79], v[164:167], v[208:211], v[76:79]
	v_mfma_f32_16x16x32_f16 v[76:79], v[160:163], v[204:207], v[76:79]
	s_setprio 0
	s_add_i32 s44, s67, s53
	v_lshl_add_u64 v[136:137], v[136:137], 0, s[86:87]
	s_mov_b32 m0, s44
	ds_read_b128 v[176:179], v216 offset:49152
	ds_read_b128 v[180:183], v216 offset:50176
	ds_read_b128 v[184:187], v216 offset:51200
	ds_read_b128 v[188:191], v216 offset:52224
	ds_read_b128 v[196:199], v216 offset:53248
	ds_read_b128 v[200:203], v216 offset:54272
	ds_read_b128 v[204:207], v216 offset:55296
	ds_read_b128 v[208:211], v216 offset:56320
	global_load_lds_dwordx4 v[136:137], off
	s_add_i32 m0, s44, 0x2000
	s_add_u32 s42, s42, 0x80080
	v_lshl_add_u64 v[136:137], v[192:193], 0, s[86:87]
	s_addc_u32 s43, s43, 0
	s_add_i32 s44, s68, s53
	global_load_lds_dwordx4 v[136:137], off
	s_mov_b32 m0, s44
	v_lshl_add_u64 v[136:137], v[212:213], 0, s[86:87]
	global_load_lds_dwordx4 v138, s[42:43]
	s_add_i32 m0, s44, 0x2000
	s_nop 0
	global_load_lds_dwordx4 v134, s[42:43]
	s_mov_b32 m0, s59
	s_nop 0
	global_load_lds_dwordx4 v[136:137], off
	v_lshl_add_u64 v[136:137], v[214:215], 0, s[86:87]
	s_mov_b32 m0, s60
	s_nop 0
	global_load_lds_dwordx4 v[136:137], off
	s_waitcnt vmcnt(8)
	s_waitcnt lgkmcnt(0)
	s_barrier
	s_setprio 1
	s_waitcnt lgkmcnt(0)
	s_nop 5
	v_mfma_f32_16x16x32_f16 v[64:67], v[144:147], v[176:179], v[64:67]
	v_mfma_f32_16x16x32_f16 v[64:67], v[148:151], v[180:183], v[64:67]
	v_mfma_f32_16x16x32_f16 v[56:59], v[156:159], v[180:183], v[56:59]
	v_mfma_f32_16x16x32_f16 v[56:59], v[152:155], v[176:179], v[56:59]
	v_mfma_f32_16x16x32_f16 v[40:43], v[152:155], v[184:187], v[40:43]
	v_mfma_f32_16x16x32_f16 v[40:43], v[156:159], v[188:191], v[40:43]
	v_mfma_f32_16x16x32_f16 v[48:51], v[148:151], v[188:191], v[48:51]
	v_mfma_f32_16x16x32_f16 v[48:51], v[144:147], v[184:187], v[48:51]
	v_mfma_f32_16x16x32_f16 v[32:35], v[144:147], v[196:199], v[32:35]
	v_mfma_f32_16x16x32_f16 v[32:35], v[148:151], v[200:203], v[32:35]
	v_mfma_f32_16x16x32_f16 v[24:27], v[156:159], v[200:203], v[24:27]
	v_mfma_f32_16x16x32_f16 v[24:27], v[152:155], v[196:199], v[24:27]
	v_mfma_f32_16x16x32_f16 v[8:11], v[152:155], v[204:207], v[8:11]
	v_mfma_f32_16x16x32_f16 v[8:11], v[156:159], v[208:211], v[8:11]
	v_mfma_f32_16x16x32_f16 v[16:19], v[148:151], v[208:211], v[16:19]
	v_mfma_f32_16x16x32_f16 v[16:19], v[144:147], v[204:207], v[16:19]
	s_setprio 0
	s_setprio 1
	v_mfma_f32_16x16x32_f16 v[60:63], v[160:163], v[176:179], v[60:63]
	v_mfma_f32_16x16x32_f16 v[60:63], v[164:167], v[180:183], v[60:63]
	v_mfma_f32_16x16x32_f16 v[52:55], v[172:175], v[180:183], v[52:55]
	v_mfma_f32_16x16x32_f16 v[52:55], v[168:171], v[176:179], v[52:55]
	v_mfma_f32_16x16x32_f16 v[36:39], v[168:171], v[184:187], v[36:39]
	v_mfma_f32_16x16x32_f16 v[36:39], v[172:175], v[188:191], v[36:39]
	v_mfma_f32_16x16x32_f16 v[44:47], v[164:167], v[188:191], v[44:47]
	v_mfma_f32_16x16x32_f16 v[44:47], v[160:163], v[184:187], v[44:47]
	v_mfma_f32_16x16x32_f16 v[28:31], v[160:163], v[196:199], v[28:31]
	v_mfma_f32_16x16x32_f16 v[28:31], v[164:167], v[200:203], v[28:31]
	v_mfma_f32_16x16x32_f16 v[20:23], v[172:175], v[200:203], v[20:23]
	v_mfma_f32_16x16x32_f16 v[20:23], v[168:171], v[196:199], v[20:23]
	v_mfma_f32_16x16x32_f16 v[4:7], v[168:171], v[204:207], v[4:7]
	v_mfma_f32_16x16x32_f16 v[4:7], v[172:175], v[208:211], v[4:7]
	s_setprio 2
	s_barrier
	v_mfma_f32_16x16x32_f16 v[12:15], v[164:167], v[208:211], v[12:15]
	v_mfma_f32_16x16x32_f16 v[12:15], v[160:163], v[204:207], v[12:15]
	s_setprio 0
	s_add_i32 s11, s11, 2
	s_add_u32 s40, s40, 0x100
	s_addc_u32 s41, s41, 0
	s_cmp_gt_u32 s11, 29
	s_cbranch_scc0 .LBB0_2161
	s_andn2_b64 vcc, exec, s[26:27]
	s_cbranch_vccnz .LBB0_2164
	s_add_u32 s6, s28, 0x80080
	s_addc_u32 s7, s29, 0
	s_mov_b32 m0, s61
	v_lshl_add_u64 v[144:145], s[6:7], 0, v[2:3]
	v_lshl_add_u64 v[136:137], s[6:7], 0, v[132:133]
	global_load_lds_dwordx4 v[144:145], off
	s_mov_b32 m0, s62
	s_mov_b32 s47, s65
	global_load_lds_dwordx4 v[136:137], off
	s_mov_b32 s64, s10
	s_mov_b64 s[8:9], s[14:15]
	s_mov_b64 s[6:7], s[12:13]
	s_mov_b32 s63, s66

.LBB0_2269:
	s_add_i32 s51, 0, 0x10000
	s_add_i32 s71, 0, 0x14000
	v_add_u32_e32 v16, s51, v232
	v_add_u32_e32 v32, s71, v232
	ds_read_b128 v[4:7], v16
	ds_read_b128 v[8:11], v16 offset:1024
	ds_read_b128 v[12:15], v16 offset:2048
	ds_read_b128 v[16:19], v16 offset:3072
	ds_read_b128 v[20:23], v32
	ds_read_b128 v[24:27], v32 offset:1024
	ds_read_b128 v[28:31], v32 offset:2048
	ds_read_b128 v[32:35], v32 offset:3072
	v_add_u32_e32 v233, 0, v231
	ds_read_b128 v[36:39], v233
	ds_read_b128 v[40:43], v233 offset:1024
	ds_read_b128 v[44:47], v233 offset:2048
	ds_read_b128 v[48:51], v233 offset:3072
	ds_read_b128 v[52:55], v233 offset:4096
	ds_read_b128 v[56:59], v233 offset:5120
	ds_read_b128 v[60:63], v233 offset:6144
	ds_read_b128 v[64:67], v233 offset:7168
	s_waitcnt vmcnt(8)
	s_waitcnt lgkmcnt(0)
	s_barrier
	s_setprio 1
	s_waitcnt lgkmcnt(0)
	s_nop 5
	v_mfma_f32_16x16x32_bf16 v[68:71], v[4:7], v[36:39], 0
	v_mfma_f32_16x16x32_bf16 v[68:71], v[8:11], v[40:43], v[68:71]
	v_mfma_f32_16x16x32_bf16 v[72:75], v[12:15], v[36:39], 0
	v_mfma_f32_16x16x32_bf16 v[72:75], v[16:19], v[40:43], v[72:75]
	v_mfma_f32_16x16x32_bf16 v[80:83], v[12:15], v[44:47], 0
	v_mfma_f32_16x16x32_bf16 v[80:83], v[16:19], v[48:51], v[80:83]
	v_mfma_f32_16x16x32_bf16 v[76:79], v[4:7], v[44:47], 0
	v_mfma_f32_16x16x32_bf16 v[76:79], v[8:11], v[48:51], v[76:79]
	v_mfma_f32_16x16x32_bf16 v[84:87], v[4:7], v[52:55], 0
	v_mfma_f32_16x16x32_bf16 v[84:87], v[8:11], v[56:59], v[84:87]
	v_mfma_f32_16x16x32_bf16 v[88:91], v[12:15], v[52:55], 0
	v_mfma_f32_16x16x32_bf16 v[88:91], v[16:19], v[56:59], v[88:91]
	v_mfma_f32_16x16x32_bf16 v[96:99], v[12:15], v[60:63], 0
	v_mfma_f32_16x16x32_bf16 v[96:99], v[16:19], v[64:67], v[96:99]
	v_mfma_f32_16x16x32_bf16 v[92:95], v[4:7], v[60:63], 0
	v_mfma_f32_16x16x32_bf16 v[92:95], v[8:11], v[64:67], v[92:95]
	s_setprio 0
	s_setprio 1
	v_mfma_f32_16x16x32_bf16 v[100:103], v[20:23], v[36:39], 0
	v_mfma_f32_16x16x32_bf16 v[36:39], v[28:31], v[36:39], 0
	v_mfma_f32_16x16x32_bf16 v[104:107], v[20:23], v[44:47], 0
	v_mfma_f32_16x16x32_bf16 v[44:47], v[28:31], v[44:47], 0
	v_mfma_f32_16x16x32_bf16 v[108:111], v[20:23], v[52:55], 0
	v_mfma_f32_16x16x32_bf16 v[52:55], v[28:31], v[52:55], 0
	v_mfma_f32_16x16x32_bf16 v[112:115], v[20:23], v[60:63], 0
	v_mfma_f32_16x16x32_bf16 v[60:63], v[28:31], v[60:63], 0
	v_mfma_f32_16x16x32_bf16 v[100:103], v[24:27], v[40:43], v[100:103]
	v_mfma_f32_16x16x32_bf16 v[40:43], v[32:35], v[40:43], v[36:39]
	v_mfma_f32_16x16x32_bf16 v[104:107], v[24:27], v[48:51], v[104:107]
	v_mfma_f32_16x16x32_bf16 v[48:51], v[32:35], v[48:51], v[44:47]
	v_mfma_f32_16x16x32_bf16 v[108:111], v[24:27], v[56:59], v[108:111]
	v_mfma_f32_16x16x32_bf16 v[56:59], v[32:35], v[56:59], v[52:55]
	s_setprio 2
	s_barrier
	v_mfma_f32_16x16x32_bf16 v[112:115], v[24:27], v[64:67], v[112:115]
	v_mfma_f32_16x16x32_bf16 v[64:67], v[32:35], v[64:67], v[60:63]
	s_setprio 0
	v_lshl_add_u64 v[186:187], s[12:13], 0, v[2:3]
	s_add_i32 s51, s51, s38
	v_mov_b32_e32 v191, v3
	v_lshl_add_u64 v[134:135], v[186:187], 0, s[74:75]
	s_mov_b32 m0, s51
	v_lshl_add_u64 v[246:247], s[12:13], 0, v[190:191]
	ds_read_b128 v[36:39], v233 offset:16384
	ds_read_b128 v[44:47], v233 offset:17408
	ds_read_b128 v[52:55], v233 offset:18432
	ds_read_b128 v[60:63], v233 offset:19456
	ds_read_b128 v[116:119], v233 offset:20480
	ds_read_b128 v[120:123], v233 offset:21504
	ds_read_b128 v[124:127], v233 offset:22528
	ds_read_b128 v[128:131], v233 offset:23552
	global_load_lds_dwordx4 v[134:135], off
	v_lshl_add_u64 v[134:135], v[246:247], 0, s[74:75]
	s_add_i32 m0, s51, 0x2000
	s_add_i32 s51, s71, s38
	global_load_lds_dwordx4 v[134:135], off
	s_mov_b32 m0, s51
	v_mov_b32_e32 v133, v3
	global_load_lds_dwordx4 v2, s[16:17]
	s_add_i32 m0, s51, 0x2000
	v_lshl_add_u64 v[248:249], s[14:15], 0, v[132:133]
	v_mov_b32_e32 v189, v3
	global_load_lds_dwordx4 v190, s[16:17]
	v_lshl_add_u64 v[134:135], v[248:249], 0, s[74:75]
	s_mov_b32 m0, s56
	v_lshl_add_u64 v[250:251], s[14:15], 0, v[188:189]
	global_load_lds_dwordx4 v[134:135], off
	v_lshl_add_u64 v[134:135], v[250:251], 0, s[74:75]
	s_mov_b32 m0, s57
	s_nop 0
	global_load_lds_dwordx4 v[134:135], off
	s_waitcnt vmcnt(8)
	s_waitcnt lgkmcnt(0)
	s_barrier
	s_setprio 1
	s_waitcnt lgkmcnt(0)
	s_nop 5
	v_mfma_f32_16x16x32_bf16 v[134:137], v[4:7], v[36:39], 0
	v_mfma_f32_16x16x32_bf16 v[138:141], v[12:15], v[36:39], 0
	v_mfma_f32_16x16x32_bf16 v[142:145], v[4:7], v[52:55], 0
	v_mfma_f32_16x16x32_bf16 v[146:149], v[12:15], v[52:55], 0
	v_mfma_f32_16x16x32_bf16 v[150:153], v[4:7], v[116:119], 0
	v_mfma_f32_16x16x32_bf16 v[154:157], v[12:15], v[116:119], 0
	v_mfma_f32_16x16x32_bf16 v[4:7], v[4:7], v[124:127], 0
	v_mfma_f32_16x16x32_bf16 v[12:15], v[12:15], v[124:127], 0
	v_mfma_f32_16x16x32_bf16 v[134:137], v[8:11], v[44:47], v[134:137]
	v_mfma_f32_16x16x32_bf16 v[138:141], v[16:19], v[44:47], v[138:141]
	v_mfma_f32_16x16x32_bf16 v[142:145], v[8:11], v[60:63], v[142:145]
	v_mfma_f32_16x16x32_bf16 v[146:149], v[16:19], v[60:63], v[146:149]
	v_mfma_f32_16x16x32_bf16 v[150:153], v[8:11], v[120:123], v[150:153]
	v_mfma_f32_16x16x32_bf16 v[154:157], v[16:19], v[120:123], v[154:157]
	v_mfma_f32_16x16x32_bf16 v[158:161], v[8:11], v[128:131], v[4:7]
	v_mfma_f32_16x16x32_bf16 v[162:165], v[16:19], v[128:131], v[12:15]
	s_setprio 0
	s_setprio 1
	v_mfma_f32_16x16x32_bf16 v[4:7], v[20:23], v[36:39], 0
	v_mfma_f32_16x16x32_bf16 v[8:11], v[28:31], v[36:39], 0
	v_mfma_f32_16x16x32_bf16 v[12:15], v[20:23], v[52:55], 0
	v_mfma_f32_16x16x32_bf16 v[16:19], v[28:31], v[52:55], 0
	v_mfma_f32_16x16x32_bf16 v[36:39], v[20:23], v[116:119], 0
	v_mfma_f32_16x16x32_bf16 v[52:55], v[28:31], v[116:119], 0
	v_mfma_f32_16x16x32_bf16 v[20:23], v[20:23], v[124:127], 0
	v_mfma_f32_16x16x32_bf16 v[28:31], v[28:31], v[124:127], 0
	v_mfma_f32_16x16x32_bf16 v[116:119], v[24:27], v[44:47], v[4:7]
	v_mfma_f32_16x16x32_bf16 v[124:127], v[32:35], v[44:47], v[8:11]
	v_mfma_f32_16x16x32_bf16 v[174:177], v[24:27], v[120:123], v[36:39]
	v_mfma_f32_16x16x32_bf16 v[120:123], v[32:35], v[120:123], v[52:55]
	v_mfma_f32_16x16x32_bf16 v[178:181], v[24:27], v[128:131], v[20:23]
	v_mfma_f32_16x16x32_bf16 v[128:131], v[32:35], v[128:131], v[28:31]
	s_setprio 2
	s_barrier
	v_mfma_f32_16x16x32_bf16 v[166:169], v[24:27], v[60:63], v[12:15]
	v_mfma_f32_16x16x32_bf16 v[170:173], v[32:35], v[60:63], v[16:19]
	s_setprio 0
	s_add_i32 s51, 0, 0x18000
	v_add_u32_e32 v4, s51, v232
	s_add_i32 s71, 0, 0x1c000
	ds_read_b128 v[182:185], v4
	ds_read_b128 v[192:195], v4 offset:1024
	ds_read_b128 v[196:199], v4 offset:2048
	ds_read_b128 v[200:203], v4 offset:3072
	v_add_u32_e32 v4, s71, v232
	ds_read_b128 v[204:207], v4
	ds_read_b128 v[208:211], v4 offset:1024
	ds_read_b128 v[212:215], v4 offset:2048
	ds_read_b128 v[216:219], v4 offset:3072
	s_mov_b32 m0, s58
	ds_read_b128 v[44:47], v233 offset:32768
	ds_read_b128 v[52:55], v233 offset:33792
	ds_read_b128 v[60:63], v233 offset:34816
	ds_read_b128 v[220:223], v233 offset:35840
	ds_read_b128 v[224:227], v233 offset:36864
	ds_read_b128 v[234:237], v233 offset:37888
	ds_read_b128 v[238:241], v233 offset:38912
	ds_read_b128 v[242:245], v233 offset:39936
	global_load_lds_dwordx4 v132, s[26:27]
	s_mov_b32 m0, s59
	s_nop 0
	global_load_lds_dwordx4 v188, s[26:27]
	s_waitcnt vmcnt(8)
	s_waitcnt lgkmcnt(0)
	s_barrier
	s_setprio 1
	s_waitcnt lgkmcnt(0)
	s_nop 5
	v_mfma_f32_16x16x32_bf16 v[4:7], v[182:185], v[44:47], v[68:71]
	v_mfma_f32_16x16x32_bf16 v[8:11], v[196:199], v[44:47], v[72:75]
	v_mfma_f32_16x16x32_bf16 v[12:15], v[182:185], v[60:63], v[76:79]
	v_mfma_f32_16x16x32_bf16 v[16:19], v[196:199], v[60:63], v[80:83]
	v_mfma_f32_16x16x32_bf16 v[20:23], v[182:185], v[224:227], v[84:87]
	v_mfma_f32_16x16x32_bf16 v[24:27], v[196:199], v[224:227], v[88:91]
	v_mfma_f32_16x16x32_bf16 v[28:31], v[182:185], v[238:241], v[92:95]
	v_mfma_f32_16x16x32_bf16 v[32:35], v[196:199], v[238:241], v[96:99]
	v_mfma_f32_16x16x32_bf16 v[4:7], v[192:195], v[52:55], v[4:7]
	v_mfma_f32_16x16x32_bf16 v[8:11], v[200:203], v[52:55], v[8:11]
	v_mfma_f32_16x16x32_bf16 v[12:15], v[192:195], v[220:223], v[12:15]
	v_mfma_f32_16x16x32_bf16 v[16:19], v[200:203], v[220:223], v[16:19]
	v_mfma_f32_16x16x32_bf16 v[20:23], v[192:195], v[234:237], v[20:23]
	v_mfma_f32_16x16x32_bf16 v[24:27], v[200:203], v[234:237], v[24:27]
	v_mfma_f32_16x16x32_bf16 v[28:31], v[192:195], v[242:245], v[28:31]
	v_mfma_f32_16x16x32_bf16 v[32:35], v[200:203], v[242:245], v[32:35]
	s_setprio 0
	s_setprio 1
	v_mfma_f32_16x16x32_bf16 v[36:39], v[204:207], v[44:47], v[100:103]
	v_mfma_f32_16x16x32_bf16 v[40:43], v[212:215], v[44:47], v[40:43]
	v_mfma_f32_16x16x32_bf16 v[36:39], v[208:211], v[52:55], v[36:39]
	v_mfma_f32_16x16x32_bf16 v[40:43], v[216:219], v[52:55], v[40:43]
	v_mfma_f32_16x16x32_bf16 v[44:47], v[204:207], v[60:63], v[104:107]
	v_mfma_f32_16x16x32_bf16 v[48:51], v[212:215], v[60:63], v[48:51]
	v_mfma_f32_16x16x32_bf16 v[52:55], v[204:207], v[224:227], v[108:111]
	v_mfma_f32_16x16x32_bf16 v[56:59], v[212:215], v[224:227], v[56:59]
	v_mfma_f32_16x16x32_bf16 v[60:63], v[204:207], v[238:241], v[112:115]
	v_mfma_f32_16x16x32_bf16 v[64:67], v[212:215], v[238:241], v[64:67]
	v_mfma_f32_16x16x32_bf16 v[44:47], v[208:211], v[220:223], v[44:47]
	v_mfma_f32_16x16x32_bf16 v[48:51], v[216:219], v[220:223], v[48:51]
	v_mfma_f32_16x16x32_bf16 v[52:55], v[208:211], v[234:237], v[52:55]
	v_mfma_f32_16x16x32_bf16 v[56:59], v[216:219], v[234:237], v[56:59]
	s_setprio 2
	s_barrier
	v_mfma_f32_16x16x32_bf16 v[60:63], v[208:211], v[242:245], v[60:63]
	v_mfma_f32_16x16x32_bf16 v[64:67], v[216:219], v[242:245], v[64:67]
	s_setprio 0
	s_add_i32 s51, s51, s38
	v_lshl_add_u64 v[68:69], v[186:187], 0, s[24:25]
	s_mov_b32 m0, s51
	ds_read_b128 v[104:107], v233 offset:49152
	ds_read_b128 v[108:111], v233 offset:50176
	ds_read_b128 v[112:115], v233 offset:51200
	ds_read_b128 v[220:223], v233 offset:52224
	ds_read_b128 v[224:227], v233 offset:53248
	ds_read_b128 v[234:237], v233 offset:54272
	ds_read_b128 v[238:241], v233 offset:55296
	ds_read_b128 v[242:245], v233 offset:56320
	global_load_lds_dwordx4 v[68:69], off
	v_lshl_add_u64 v[68:69], v[246:247], 0, s[24:25]
	s_add_i32 m0, s51, 0x2000
	s_add_i32 s51, s71, s38
	global_load_lds_dwordx4 v[68:69], off
	s_mov_b32 m0, s51
	v_lshl_add_u64 v[68:69], v[248:249], 0, s[24:25]
	global_load_lds_dwordx4 v2, s[28:29]
	s_add_i32 m0, s51, 0x2000
	s_nop 0
	global_load_lds_dwordx4 v190, s[28:29]
	s_mov_b32 m0, s63
	s_nop 0
	global_load_lds_dwordx4 v[68:69], off
	v_lshl_add_u64 v[68:69], v[250:251], 0, s[24:25]
	s_mov_b32 m0, s64
	s_nop 0
	global_load_lds_dwordx4 v[68:69], off
	s_waitcnt vmcnt(8)
	s_waitcnt lgkmcnt(0)
	s_barrier
	s_setprio 1
	s_waitcnt lgkmcnt(0)
	s_nop 5
	v_mfma_f32_16x16x32_bf16 v[68:71], v[182:185], v[104:107], v[134:137]
	v_mfma_f32_16x16x32_bf16 v[72:75], v[196:199], v[104:107], v[138:141]
	v_mfma_f32_16x16x32_bf16 v[76:79], v[182:185], v[112:115], v[142:145]
	v_mfma_f32_16x16x32_bf16 v[80:83], v[196:199], v[112:115], v[146:149]
	v_mfma_f32_16x16x32_bf16 v[84:87], v[182:185], v[224:227], v[150:153]
	v_mfma_f32_16x16x32_bf16 v[88:91], v[196:199], v[224:227], v[154:157]
	v_mfma_f32_16x16x32_bf16 v[92:95], v[182:185], v[238:241], v[158:161]
	v_mfma_f32_16x16x32_bf16 v[96:99], v[196:199], v[238:241], v[162:165]
	v_mfma_f32_16x16x32_bf16 v[68:71], v[192:195], v[108:111], v[68:71]
	v_mfma_f32_16x16x32_bf16 v[72:75], v[200:203], v[108:111], v[72:75]
	v_mfma_f32_16x16x32_bf16 v[76:79], v[192:195], v[220:223], v[76:79]
	v_mfma_f32_16x16x32_bf16 v[80:83], v[200:203], v[220:223], v[80:83]
	v_mfma_f32_16x16x32_bf16 v[84:87], v[192:195], v[234:237], v[84:87]
	v_mfma_f32_16x16x32_bf16 v[88:91], v[200:203], v[234:237], v[88:91]
	v_mfma_f32_16x16x32_bf16 v[92:95], v[192:195], v[242:245], v[92:95]
	v_mfma_f32_16x16x32_bf16 v[96:99], v[200:203], v[242:245], v[96:99]
	s_setprio 0
	s_setprio 1
	v_mfma_f32_16x16x32_bf16 v[100:103], v[204:207], v[104:107], v[116:119]
	v_mfma_f32_16x16x32_bf16 v[104:107], v[212:215], v[104:107], v[124:127]
	v_mfma_f32_16x16x32_bf16 v[100:103], v[208:211], v[108:111], v[100:103]
	v_mfma_f32_16x16x32_bf16 v[104:107], v[216:219], v[108:111], v[104:107]
	v_mfma_f32_16x16x32_bf16 v[108:111], v[204:207], v[112:115], v[166:169]
	v_mfma_f32_16x16x32_bf16 v[112:115], v[212:215], v[112:115], v[170:173]
	v_mfma_f32_16x16x32_bf16 v[116:119], v[204:207], v[224:227], v[174:177]
	v_mfma_f32_16x16x32_bf16 v[120:123], v[212:215], v[224:227], v[120:123]
	v_mfma_f32_16x16x32_bf16 v[124:127], v[204:207], v[238:241], v[178:181]
	v_mfma_f32_16x16x32_bf16 v[128:131], v[212:215], v[238:241], v[128:131]
	v_mfma_f32_16x16x32_bf16 v[108:111], v[208:211], v[220:223], v[108:111]
	v_mfma_f32_16x16x32_bf16 v[112:115], v[216:219], v[220:223], v[112:115]
	v_mfma_f32_16x16x32_bf16 v[116:119], v[208:211], v[234:237], v[116:119]
	v_mfma_f32_16x16x32_bf16 v[120:123], v[216:219], v[234:237], v[120:123]
	s_setprio 2
	s_barrier
	v_mfma_f32_16x16x32_bf16 v[124:127], v[208:211], v[242:245], v[124:127]
	v_mfma_f32_16x16x32_bf16 v[128:131], v[216:219], v[242:245], v[128:131]
	s_setprio 0
	s_add_i32 s41, s41, 2
	s_cmp_ge_i32 s41, s40
	s_cbranch_scc0 .LBB0_2269
	v_mov_b32_e32 v192, v2
	s_branch .LBB0_2272

.LBB0_2273:
	s_add_u32 s12, s14, 0xfffc0080
	s_addc_u32 s13, s15, -1
	s_add_i32 s29, 0, 0x10000
	s_cmp_eq_u32 s28, 12
	s_cselect_b32 s17, s9, s13
	s_cselect_b32 s16, s8, s12
	s_cselect_b32 s13, s11, s27
	s_cselect_b32 s12, s10, s26
	s_add_i32 s51, 0, 0x14000
	v_add_u32_e32 v144, s29, v232
	v_add_u32_e32 v160, s51, v232
	s_waitcnt lgkmcnt(0)
	ds_read_b128 v[132:135], v144
	ds_read_b128 v[136:139], v144 offset:1024
	ds_read_b128 v[140:143], v144 offset:2048
	ds_read_b128 v[144:147], v144 offset:3072
	ds_read_b128 v[148:151], v160
	ds_read_b128 v[152:155], v160 offset:1024
	ds_read_b128 v[156:159], v160 offset:2048
	ds_read_b128 v[160:163], v160 offset:3072
	s_mov_b32 m0, s65
	v_add_u32_e32 v210, 0, v231
	ds_read_b128 v[164:167], v210
	ds_read_b128 v[168:171], v210 offset:1024
	ds_read_b128 v[172:175], v210 offset:2048
	ds_read_b128 v[176:179], v210 offset:3072
	ds_read_b128 v[180:183], v210 offset:4096
	ds_read_b128 v[184:187], v210 offset:5120
	ds_read_b128 v[194:197], v210 offset:6144
	ds_read_b128 v[198:201], v210 offset:7168
	global_load_lds_dwordx4 v2, s[14:15]
	s_mov_b32 m0, s66
	v_mov_b32_e32 v189, v3
	global_load_lds_dwordx4 v188, s[14:15]
	s_waitcnt vmcnt(8)
	s_waitcnt lgkmcnt(0)
	s_barrier
	s_setprio 1
	s_waitcnt lgkmcnt(0)
	s_nop 5
	v_mfma_f32_16x16x32_bf16 v[4:7], v[132:135], v[164:167], v[4:7]
	v_mfma_f32_16x16x32_bf16 v[4:7], v[136:139], v[168:171], v[4:7]
	v_mfma_f32_16x16x32_bf16 v[8:11], v[144:147], v[168:171], v[8:11]
	v_mfma_f32_16x16x32_bf16 v[8:11], v[140:143], v[164:167], v[8:11]
	v_mfma_f32_16x16x32_bf16 v[16:19], v[140:143], v[172:175], v[16:19]
	v_mfma_f32_16x16x32_bf16 v[16:19], v[144:147], v[176:179], v[16:19]
	v_mfma_f32_16x16x32_bf16 v[12:15], v[136:139], v[176:179], v[12:15]
	v_mfma_f32_16x16x32_bf16 v[12:15], v[132:135], v[172:175], v[12:15]
	v_mfma_f32_16x16x32_bf16 v[20:23], v[132:135], v[180:183], v[20:23]
	v_mfma_f32_16x16x32_bf16 v[20:23], v[136:139], v[184:187], v[20:23]
	v_mfma_f32_16x16x32_bf16 v[24:27], v[144:147], v[184:187], v[24:27]
	v_mfma_f32_16x16x32_bf16 v[24:27], v[140:143], v[180:183], v[24:27]
	v_mfma_f32_16x16x32_bf16 v[32:35], v[140:143], v[194:197], v[32:35]
	v_mfma_f32_16x16x32_bf16 v[32:35], v[144:147], v[198:201], v[32:35]
	v_mfma_f32_16x16x32_bf16 v[28:31], v[136:139], v[198:201], v[28:31]
	v_mfma_f32_16x16x32_bf16 v[28:31], v[132:135], v[194:197], v[28:31]
	s_setprio 0
	s_setprio 1
	v_mfma_f32_16x16x32_bf16 v[36:39], v[148:151], v[164:167], v[36:39]
	v_mfma_f32_16x16x32_bf16 v[36:39], v[152:155], v[168:171], v[36:39]
	v_mfma_f32_16x16x32_bf16 v[40:43], v[160:163], v[168:171], v[40:43]
	v_mfma_f32_16x16x32_bf16 v[40:43], v[156:159], v[164:167], v[40:43]
	v_mfma_f32_16x16x32_bf16 v[48:51], v[156:159], v[172:175], v[48:51]
	v_mfma_f32_16x16x32_bf16 v[48:51], v[160:163], v[176:179], v[48:51]
	v_mfma_f32_16x16x32_bf16 v[44:47], v[152:155], v[176:179], v[44:47]
	v_mfma_f32_16x16x32_bf16 v[44:47], v[148:151], v[172:175], v[44:47]
	v_mfma_f32_16x16x32_bf16 v[52:55], v[148:151], v[180:183], v[52:55]
	v_mfma_f32_16x16x32_bf16 v[52:55], v[152:155], v[184:187], v[52:55]
	v_mfma_f32_16x16x32_bf16 v[56:59], v[160:163], v[184:187], v[56:59]
	v_mfma_f32_16x16x32_bf16 v[56:59], v[156:159], v[180:183], v[56:59]
	v_mfma_f32_16x16x32_bf16 v[64:67], v[156:159], v[194:197], v[64:67]
	v_mfma_f32_16x16x32_bf16 v[64:67], v[160:163], v[198:201], v[64:67]
	s_setprio 2
	s_barrier
	v_mfma_f32_16x16x32_bf16 v[60:63], v[152:155], v[198:201], v[60:63]
	v_mfma_f32_16x16x32_bf16 v[60:63], v[148:151], v[194:197], v[60:63]
	s_setprio 0
	s_add_i32 s29, s29, s38
	s_mov_b32 m0, s29
	ds_read_b128 v[164:167], v210 offset:16384
	ds_read_b128 v[168:171], v210 offset:17408
	ds_read_b128 v[172:175], v210 offset:18432
	ds_read_b128 v[176:179], v210 offset:19456
	ds_read_b128 v[180:183], v210 offset:20480
	ds_read_b128 v[184:187], v210 offset:21504
	ds_read_b128 v[194:197], v210 offset:22528
	ds_read_b128 v[198:201], v210 offset:23552
	global_load_lds_dwordx4 v192, s[12:13]
	s_add_i32 m0, s29, 0x2000
	s_add_u32 s40, s12, 0x100000
	s_addc_u32 s41, s13, 0
	s_add_i32 s29, s51, s38
	global_load_lds_dwordx4 v190, s[12:13]
	s_mov_b32 m0, s29
	v_mov_b32_e32 v193, v3
	global_load_lds_dwordx4 v192, s[40:41]
	s_add_i32 m0, s29, 0x2000
	v_mov_b32_e32 v191, v3
	global_load_lds_dwordx4 v190, s[40:41]
	s_mov_b32 m0, s56
	v_lshl_add_u64 v[202:203], s[12:13], 0, v[192:193]
	global_load_lds_dwordx4 v2, s[16:17]
	s_mov_b32 m0, s57
	v_lshl_add_u64 v[204:205], s[12:13], 0, v[190:191]
	global_load_lds_dwordx4 v188, s[16:17]
	s_waitcnt vmcnt(8)
	s_waitcnt lgkmcnt(0)
	v_lshl_add_u64 v[206:207], s[16:17], 0, v[2:3]
	v_lshl_add_u64 v[208:209], s[16:17], 0, v[188:189]
	s_barrier
	s_setprio 1
	s_waitcnt lgkmcnt(0)
	s_nop 5
	v_mfma_f32_16x16x32_bf16 v[68:71], v[132:135], v[164:167], v[68:71]
	v_mfma_f32_16x16x32_bf16 v[68:71], v[136:139], v[168:171], v[68:71]
	v_mfma_f32_16x16x32_bf16 v[72:75], v[144:147], v[168:171], v[72:75]
	v_mfma_f32_16x16x32_bf16 v[72:75], v[140:143], v[164:167], v[72:75]
	v_mfma_f32_16x16x32_bf16 v[80:83], v[140:143], v[172:175], v[80:83]
	v_mfma_f32_16x16x32_bf16 v[80:83], v[144:147], v[176:179], v[80:83]
	v_mfma_f32_16x16x32_bf16 v[76:79], v[136:139], v[176:179], v[76:79]
	v_mfma_f32_16x16x32_bf16 v[76:79], v[132:135], v[172:175], v[76:79]
	v_mfma_f32_16x16x32_bf16 v[84:87], v[132:135], v[180:183], v[84:87]
	v_mfma_f32_16x16x32_bf16 v[84:87], v[136:139], v[184:187], v[84:87]
	v_mfma_f32_16x16x32_bf16 v[88:91], v[144:147], v[184:187], v[88:91]
	v_mfma_f32_16x16x32_bf16 v[88:91], v[140:143], v[180:183], v[88:91]
	v_mfma_f32_16x16x32_bf16 v[96:99], v[140:143], v[194:197], v[96:99]
	v_mfma_f32_16x16x32_bf16 v[96:99], v[144:147], v[198:201], v[96:99]
	v_mfma_f32_16x16x32_bf16 v[92:95], v[136:139], v[198:201], v[92:95]
	v_mfma_f32_16x16x32_bf16 v[92:95], v[132:135], v[194:197], v[92:95]
	s_setprio 0
	s_setprio 1
	v_mfma_f32_16x16x32_bf16 v[100:103], v[148:151], v[164:167], v[100:103]
	v_mfma_f32_16x16x32_bf16 v[100:103], v[152:155], v[168:171], v[100:103]
	v_mfma_f32_16x16x32_bf16 v[104:107], v[160:163], v[168:171], v[104:107]
	v_mfma_f32_16x16x32_bf16 v[104:107], v[156:159], v[164:167], v[104:107]
	v_mfma_f32_16x16x32_bf16 v[112:115], v[156:159], v[172:175], v[112:115]
	v_mfma_f32_16x16x32_bf16 v[112:115], v[160:163], v[176:179], v[112:115]
	v_mfma_f32_16x16x32_bf16 v[108:111], v[152:155], v[176:179], v[108:111]
	v_mfma_f32_16x16x32_bf16 v[108:111], v[148:151], v[172:175], v[108:111]
	v_mfma_f32_16x16x32_bf16 v[116:119], v[148:151], v[180:183], v[116:119]
	v_mfma_f32_16x16x32_bf16 v[116:119], v[152:155], v[184:187], v[116:119]
	v_mfma_f32_16x16x32_bf16 v[120:123], v[160:163], v[184:187], v[120:123]
	v_mfma_f32_16x16x32_bf16 v[120:123], v[156:159], v[180:183], v[120:123]
	v_mfma_f32_16x16x32_bf16 v[128:131], v[156:159], v[194:197], v[128:131]
	v_mfma_f32_16x16x32_bf16 v[128:131], v[160:163], v[198:201], v[128:131]
	s_setprio 2
	s_barrier
	v_mfma_f32_16x16x32_bf16 v[124:127], v[152:155], v[198:201], v[124:127]
	v_mfma_f32_16x16x32_bf16 v[124:127], v[148:151], v[194:197], v[124:127]
	s_setprio 0
	s_add_i32 s29, 0, 0x18000
	s_add_i32 s40, 0, 0x1c000
	v_add_u32_e32 v144, s29, v232
	v_add_u32_e32 v160, s40, v232
	ds_read_b128 v[132:135], v144
	ds_read_b128 v[136:139], v144 offset:1024
	ds_read_b128 v[140:143], v144 offset:2048
	ds_read_b128 v[144:147], v144 offset:3072
	ds_read_b128 v[148:151], v160
	ds_read_b128 v[152:155], v160 offset:1024
	ds_read_b128 v[156:159], v160 offset:2048
	ds_read_b128 v[160:163], v160 offset:3072
	s_add_u32 s16, s16, 0x40000
	s_addc_u32 s17, s17, 0
	s_mov_b32 m0, s58
	ds_read_b128 v[164:167], v210 offset:32768
	ds_read_b128 v[168:171], v210 offset:33792
	ds_read_b128 v[172:175], v210 offset:34816
	ds_read_b128 v[176:179], v210 offset:35840
	ds_read_b128 v[180:183], v210 offset:36864
	ds_read_b128 v[184:187], v210 offset:37888
	ds_read_b128 v[194:197], v210 offset:38912
	ds_read_b128 v[198:201], v210 offset:39936
	global_load_lds_dwordx4 v2, s[16:17]
	s_mov_b32 m0, s59
	s_nop 0
	global_load_lds_dwordx4 v188, s[16:17]
	s_waitcnt vmcnt(8)
	s_waitcnt lgkmcnt(0)
	s_barrier
	s_setprio 1
	s_waitcnt lgkmcnt(0)
	s_nop 5
	v_mfma_f32_16x16x32_bf16 v[4:7], v[132:135], v[164:167], v[4:7]
	v_mfma_f32_16x16x32_bf16 v[4:7], v[136:139], v[168:171], v[4:7]
	v_mfma_f32_16x16x32_bf16 v[8:11], v[144:147], v[168:171], v[8:11]
	v_mfma_f32_16x16x32_bf16 v[8:11], v[140:143], v[164:167], v[8:11]
	v_mfma_f32_16x16x32_bf16 v[16:19], v[140:143], v[172:175], v[16:19]
	v_mfma_f32_16x16x32_bf16 v[16:19], v[144:147], v[176:179], v[16:19]
	v_mfma_f32_16x16x32_bf16 v[12:15], v[136:139], v[176:179], v[12:15]
	v_mfma_f32_16x16x32_bf16 v[12:15], v[132:135], v[172:175], v[12:15]
	v_mfma_f32_16x16x32_bf16 v[20:23], v[132:135], v[180:183], v[20:23]
	v_mfma_f32_16x16x32_bf16 v[20:23], v[136:139], v[184:187], v[20:23]
	v_mfma_f32_16x16x32_bf16 v[24:27], v[144:147], v[184:187], v[24:27]
	v_mfma_f32_16x16x32_bf16 v[24:27], v[140:143], v[180:183], v[24:27]
	v_mfma_f32_16x16x32_bf16 v[32:35], v[140:143], v[194:197], v[32:35]
	v_mfma_f32_16x16x32_bf16 v[32:35], v[144:147], v[198:201], v[32:35]
	v_mfma_f32_16x16x32_bf16 v[28:31], v[136:139], v[198:201], v[28:31]
	v_mfma_f32_16x16x32_bf16 v[28:31], v[132:135], v[194:197], v[28:31]
	s_setprio 0
	s_setprio 1
	v_mfma_f32_16x16x32_bf16 v[36:39], v[148:151], v[164:167], v[36:39]
	v_mfma_f32_16x16x32_bf16 v[36:39], v[152:155], v[168:171], v[36:39]
	v_mfma_f32_16x16x32_bf16 v[40:43], v[160:163], v[168:171], v[40:43]
	v_mfma_f32_16x16x32_bf16 v[40:43], v[156:159], v[164:167], v[40:43]
	v_mfma_f32_16x16x32_bf16 v[48:51], v[156:159], v[172:175], v[48:51]
	v_mfma_f32_16x16x32_bf16 v[48:51], v[160:163], v[176:179], v[48:51]
	v_mfma_f32_16x16x32_bf16 v[44:47], v[152:155], v[176:179], v[44:47]
	v_mfma_f32_16x16x32_bf16 v[44:47], v[148:151], v[172:175], v[44:47]
	v_mfma_f32_16x16x32_bf16 v[52:55], v[148:151], v[180:183], v[52:55]
	v_mfma_f32_16x16x32_bf16 v[52:55], v[152:155], v[184:187], v[52:55]
	v_mfma_f32_16x16x32_bf16 v[56:59], v[160:163], v[184:187], v[56:59]
	v_mfma_f32_16x16x32_bf16 v[56:59], v[156:159], v[180:183], v[56:59]
	v_mfma_f32_16x16x32_bf16 v[64:67], v[156:159], v[194:197], v[64:67]
	v_mfma_f32_16x16x32_bf16 v[64:67], v[160:163], v[198:201], v[64:67]
	s_setprio 2
	s_barrier
	v_mfma_f32_16x16x32_bf16 v[60:63], v[152:155], v[198:201], v[60:63]
	v_mfma_f32_16x16x32_bf16 v[60:63], v[148:151], v[194:197], v[60:63]
	s_setprio 0
	s_add_i32 s16, s29, s38
	v_lshl_add_u64 v[202:203], v[202:203], 0, s[86:87]
	s_mov_b32 m0, s16
	ds_read_b128 v[164:167], v210 offset:49152
	ds_read_b128 v[168:171], v210 offset:50176
	ds_read_b128 v[172:175], v210 offset:51200
	ds_read_b128 v[176:179], v210 offset:52224
	ds_read_b128 v[180:183], v210 offset:53248
	ds_read_b128 v[184:187], v210 offset:54272
	ds_read_b128 v[194:197], v210 offset:55296
	ds_read_b128 v[198:201], v210 offset:56320
	global_load_lds_dwordx4 v[202:203], off
	s_add_i32 m0, s16, 0x2000
	s_add_u32 s12, s12, 0x100080
	v_lshl_add_u64 v[202:203], v[204:205], 0, s[86:87]
	s_addc_u32 s13, s13, 0
	s_add_i32 s16, s40, s38
	global_load_lds_dwordx4 v[202:203], off
	s_mov_b32 m0, s16
	v_lshl_add_u64 v[202:203], v[206:207], 0, s[86:87]
	global_load_lds_dwordx4 v192, s[12:13]
	s_add_i32 m0, s16, 0x2000
	s_nop 0
	global_load_lds_dwordx4 v190, s[12:13]
	s_mov_b32 m0, s63
	s_nop 0
	global_load_lds_dwordx4 v[202:203], off
	v_lshl_add_u64 v[202:203], v[208:209], 0, s[86:87]
	s_mov_b32 m0, s64
	s_nop 0
	global_load_lds_dwordx4 v[202:203], off
	s_waitcnt vmcnt(8)
	s_waitcnt lgkmcnt(0)
	s_barrier
	s_setprio 1
	s_waitcnt lgkmcnt(0)
	s_nop 5
	v_mfma_f32_16x16x32_bf16 v[68:71], v[132:135], v[164:167], v[68:71]
	v_mfma_f32_16x16x32_bf16 v[68:71], v[136:139], v[168:171], v[68:71]
	v_mfma_f32_16x16x32_bf16 v[72:75], v[144:147], v[168:171], v[72:75]
	v_mfma_f32_16x16x32_bf16 v[72:75], v[140:143], v[164:167], v[72:75]
	v_mfma_f32_16x16x32_bf16 v[80:83], v[140:143], v[172:175], v[80:83]
	v_mfma_f32_16x16x32_bf16 v[80:83], v[144:147], v[176:179], v[80:83]
	v_mfma_f32_16x16x32_bf16 v[76:79], v[136:139], v[176:179], v[76:79]
	v_mfma_f32_16x16x32_bf16 v[76:79], v[132:135], v[172:175], v[76:79]
	v_mfma_f32_16x16x32_bf16 v[84:87], v[132:135], v[180:183], v[84:87]
	v_mfma_f32_16x16x32_bf16 v[84:87], v[136:139], v[184:187], v[84:87]
	v_mfma_f32_16x16x32_bf16 v[88:91], v[144:147], v[184:187], v[88:91]
	v_mfma_f32_16x16x32_bf16 v[88:91], v[140:143], v[180:183], v[88:91]
	v_mfma_f32_16x16x32_bf16 v[96:99], v[140:143], v[194:197], v[96:99]
	v_mfma_f32_16x16x32_bf16 v[96:99], v[144:147], v[198:201], v[96:99]
	v_mfma_f32_16x16x32_bf16 v[92:95], v[136:139], v[198:201], v[92:95]
	v_mfma_f32_16x16x32_bf16 v[92:95], v[132:135], v[194:197], v[92:95]
	s_setprio 0
	s_setprio 1
	v_mfma_f32_16x16x32_bf16 v[100:103], v[148:151], v[164:167], v[100:103]
	v_mfma_f32_16x16x32_bf16 v[100:103], v[152:155], v[168:171], v[100:103]
	v_mfma_f32_16x16x32_bf16 v[104:107], v[160:163], v[168:171], v[104:107]
	v_mfma_f32_16x16x32_bf16 v[104:107], v[156:159], v[164:167], v[104:107]
	v_mfma_f32_16x16x32_bf16 v[112:115], v[156:159], v[172:175], v[112:115]
	v_mfma_f32_16x16x32_bf16 v[112:115], v[160:163], v[176:179], v[112:115]
	v_mfma_f32_16x16x32_bf16 v[108:111], v[152:155], v[176:179], v[108:111]
	v_mfma_f32_16x16x32_bf16 v[108:111], v[148:151], v[172:175], v[108:111]
	v_mfma_f32_16x16x32_bf16 v[116:119], v[148:151], v[180:183], v[116:119]
	v_mfma_f32_16x16x32_bf16 v[116:119], v[152:155], v[184:187], v[116:119]
	v_mfma_f32_16x16x32_bf16 v[120:123], v[160:163], v[184:187], v[120:123]
	v_mfma_f32_16x16x32_bf16 v[120:123], v[156:159], v[180:183], v[120:123]
	v_mfma_f32_16x16x32_bf16 v[128:131], v[156:159], v[194:197], v[128:131]
	v_mfma_f32_16x16x32_bf16 v[128:131], v[160:163], v[198:201], v[128:131]
	s_setprio 2
	s_barrier
	v_mfma_f32_16x16x32_bf16 v[124:127], v[152:155], v[198:201], v[124:127]
	v_mfma_f32_16x16x32_bf16 v[124:127], v[148:151], v[194:197], v[124:127]
	s_setprio 0
	s_add_i32 s28, s28, 2
	s_add_u32 s14, s14, 0x100
	s_addc_u32 s15, s15, 0
	s_add_u32 s26, s26, 0x100
	s_addc_u32 s27, s27, 0
	s_cmp_gt_u32 s28, 13
	s_cbranch_scc0 .LBB0_2273
	s_and_b64 vcc, exec, s[48:49]
	s_cbranch_vccz .LBB0_2276
	s_barrier
